# loop-edge edit: K-loop pointer/counter increments moved from the head of the first load segment to the end of the last load segment
# speedup vs baseline: 1.0016x; 1.0016x over previous
; #define PG8_STAGE(bufoff, gbase, voff) do { _Pragma("unroll") for (int _i = 0; _i < 2; ++_i) \
;         __builtin_amdgcn_global_load_lds((const unsigned*)((const char*)(gbase) + (voff)[_i]), (PG8_LAS unsigned*)(lds + (bufoff) + ldsw + _i * 8192), 16, 0, 0); } while (0)
; #define PG8_LDA(dst, b, h) do { _Pragma("unroll") for (int m = 0; m < 4; ++m) _Pragma("unroll") for (int k = 0; k < 2; ++k) dst[m][k] = *(const PG8_LAS bf16x8*)(lds + PG8_SA(b, h) + aoff + m * 2048 + k * 1024); } while (0)
; #define PG8_LDB(dst, b, h) do { _Pragma("unroll") for (int n = 0; n < 2; ++n) _Pragma("unroll") for (int k = 0; k < 2; ++k) dst[n][k] = *(const PG8_LAS bf16x8*)(lds + PG8_SB(b, h) + boff + n * 2048 + k * 1024); } while (0)
; template <class Epi, class Sched, bool ALIGN_EPI = false, bool SP2 = false>
; __device__ __forceinline__ void gemm_phase(PG8_LAS unsigned char* lds, const Gemm g, const Sched& S, const Epi& E) {
;     ...
;         for (int t = 0; t < nt; t += 2) {
;             const bool last = (t == nt - 2);
;             const char* a1 = cA + (size_t)(t + 1) * kstep;
;             const char* a2 = last ? nA : cA + (size_t)(t + 2) * kstep; const char* b2 = last ? nB : cB + (size_t)(t + 2) * kstep;
;             const char* a3 = a2 + kstep; const char* b3 = b2 + kstep;
;             if (last && has_next) S.a_ready(nxt);
;             if constexpr (SP2) {
;             PG8_LDB(B0, 0, 0); PG8_LDB(B1, 0, 1); PG8_SCHED; PG8_LDA(At, 0, 0); PG8_STAGE(PG8_SA(1, 1), a1 + hstep, voffA);
;             PG8_WAIT_V(8); PG8_WAIT_L(0); PG8_BAR; PG8_MMA(0, 0, At, B0); PG8_MMA(0, 1, At, B1); PG8_BAR; PG8_SCHED;
;             PG8_LDA(At, 0, 1); PG8_STAGE(PG8_SB(0, 0), b2, voffB); PG8_STAGE(PG8_SB(0, 1), b2 + hstep, voffB); PG8_STAGE(PG8_SA(0, 0), a2, voffA);
;             PG8_WAIT_V(8); PG8_WAIT_L(0); PG8_BAR; PG8_MMA(1, 0, At, B0); PG8_MMA(1, 1, At, B1); PG8_BAR; PG8_SCHED;
;             PG8_LDB(B0, 1, 0); PG8_LDB(B1, 1, 1); PG8_SCHED; PG8_LDA(At, 1, 0); PG8_STAGE(PG8_SA(0, 1), a2 + hstep, voffA);
;             PG8_WAIT_V(8); PG8_WAIT_L(0); PG8_BAR; PG8_MMA(0, 0, At, B0); PG8_MMA(0, 1, At, B1); PG8_BAR; PG8_SCHED;
;             PG8_LDA(At, 1, 1); PG8_STAGE(PG8_SB(1, 0), b3, voffB); PG8_STAGE(PG8_SB(1, 1), b3 + hstep, voffB); PG8_STAGE(PG8_SA(1, 0), a3, voffA);
;             PG8_WAIT_V(8); PG8_WAIT_L(0); PG8_BAR; PG8_MMA(1, 0, At, B0); PG8_MMA(1, 1, At, B1); PG8_BAR; PG8_SCHED;
.LBB0_110:
	ds_read_b128 v[136:139], v161
	ds_read_b128 v[140:143], v161 offset:1024
	ds_read_b128 v[176:179], v161 offset:2048
	ds_read_b128 v[180:183], v161 offset:3072
	ds_read_b128 v[184:187], v162
	ds_read_b128 v[202:205], v162 offset:1024
	ds_read_b128 v[206:209], v162 offset:2048
	ds_read_b128 v[210:213], v162 offset:3072
	s_add_u32 s28, s52, 0xfff80080
	s_addc_u32 s29, s53, -1
	s_cmp_eq_u32 s74, 28
	s_cselect_b32 s49, s25, s29
	s_cselect_b32 s48, s34, s28
	s_cselect_b32 s29, s23, s73
	s_cselect_b32 s28, s35, s72
	v_lshl_add_u64 v[246:247], s[52:53], 0, v[128:129]
	s_add_i32 m0, s9, 0xc000
	ds_read_b128 v[214:217], v163
	ds_read_b128 v[218:221], v163 offset:1024
	ds_read_b128 v[222:225], v163 offset:2048
	ds_read_b128 v[226:229], v163 offset:3072
	ds_read_b128 v[230:233], v163 offset:4096
	ds_read_b128 v[234:237], v163 offset:5120
	ds_read_b128 v[238:241], v163 offset:6144
	ds_read_b128 v[242:245], v163 offset:7168
	global_load_lds_dwordx4 v[246:247], off
	v_lshl_add_u64 v[246:247], s[52:53], 0, v[130:131]
	s_add_i32 m0, s9, 0xe000
	s_nop 0
	global_load_lds_dwordx4 v[246:247], off
	s_waitcnt vmcnt(8)
	s_waitcnt lgkmcnt(0)
	s_barrier
	s_setprio 1
	s_waitcnt lgkmcnt(0)
	v_mfma_f32_16x16x32_bf16 v[124:127], v[136:139], v[214:217], v[124:127]
	v_mfma_f32_16x16x32_bf16 v[124:127], v[140:143], v[218:221], v[124:127]
	v_mfma_f32_16x16x32_bf16 v[120:123], v[180:183], v[218:221], v[120:123]
	v_mfma_f32_16x16x32_bf16 v[120:123], v[176:179], v[214:217], v[120:123]
	v_mfma_f32_16x16x32_bf16 v[116:119], v[184:187], v[214:217], v[116:119]
	v_mfma_f32_16x16x32_bf16 v[116:119], v[202:205], v[218:221], v[116:119]
	v_mfma_f32_16x16x32_bf16 v[112:115], v[210:213], v[218:221], v[112:115]
	v_mfma_f32_16x16x32_bf16 v[112:115], v[206:209], v[214:217], v[112:115]
	v_mfma_f32_16x16x32_bf16 v[92:95], v[206:209], v[222:225], v[92:95]
	v_mfma_f32_16x16x32_bf16 v[92:95], v[210:213], v[226:229], v[92:95]
	v_mfma_f32_16x16x32_bf16 v[100:103], v[202:205], v[226:229], v[100:103]
	v_mfma_f32_16x16x32_bf16 v[100:103], v[184:187], v[222:225], v[100:103]
	v_mfma_f32_16x16x32_bf16 v[104:107], v[176:179], v[222:225], v[104:107]
	v_mfma_f32_16x16x32_bf16 v[104:107], v[180:183], v[226:229], v[104:107]
	v_mfma_f32_16x16x32_bf16 v[108:111], v[140:143], v[226:229], v[108:111]
	v_mfma_f32_16x16x32_bf16 v[108:111], v[136:139], v[222:225], v[108:111]
	s_setprio 0
	s_setprio 1
	v_mfma_f32_16x16x32_bf16 v[96:99], v[136:139], v[230:233], v[96:99]
	v_mfma_f32_16x16x32_bf16 v[96:99], v[140:143], v[234:237], v[96:99]
	v_mfma_f32_16x16x32_bf16 v[88:91], v[180:183], v[234:237], v[88:91]
	v_mfma_f32_16x16x32_bf16 v[88:91], v[176:179], v[230:233], v[88:91]
	v_mfma_f32_16x16x32_bf16 v[84:87], v[184:187], v[230:233], v[84:87]
	v_mfma_f32_16x16x32_bf16 v[84:87], v[202:205], v[234:237], v[84:87]
	v_mfma_f32_16x16x32_bf16 v[76:79], v[210:213], v[234:237], v[76:79]
	v_mfma_f32_16x16x32_bf16 v[76:79], v[206:209], v[230:233], v[76:79]
	v_mfma_f32_16x16x32_bf16 v[64:67], v[206:209], v[238:241], v[64:67]
	v_mfma_f32_16x16x32_bf16 v[64:67], v[210:213], v[242:245], v[64:67]
	v_mfma_f32_16x16x32_bf16 v[68:71], v[202:205], v[242:245], v[68:71]
	v_mfma_f32_16x16x32_bf16 v[68:71], v[184:187], v[238:241], v[68:71]
	v_mfma_f32_16x16x32_bf16 v[72:75], v[176:179], v[238:241], v[72:75]
	v_mfma_f32_16x16x32_bf16 v[72:75], v[180:183], v[242:245], v[72:75]
	s_setprio 2
	s_barrier
	v_mfma_f32_16x16x32_bf16 v[80:83], v[140:143], v[242:245], v[80:83]
	v_mfma_f32_16x16x32_bf16 v[80:83], v[136:139], v[238:241], v[80:83]
	s_setprio 0
	s_add_i32 s75, s63, s45
	v_lshl_add_u64 v[246:247], s[28:29], 0, v[166:167]
	s_mov_b32 m0, s75
	ds_read_b128 v[214:217], v163 offset:16384
	ds_read_b128 v[218:221], v163 offset:17408
	ds_read_b128 v[222:225], v163 offset:18432
	ds_read_b128 v[226:229], v163 offset:19456
	ds_read_b128 v[230:233], v163 offset:20480
	ds_read_b128 v[234:237], v163 offset:21504
	ds_read_b128 v[238:241], v163 offset:22528
	ds_read_b128 v[242:245], v163 offset:23552
	global_load_lds_dwordx4 v[246:247], off
	s_add_i32 m0, s75, 0x2000
	s_add_u32 s76, s28, 0x80000
	v_lshl_add_u64 v[248:249], s[28:29], 0, v[170:171]
	s_addc_u32 s77, s29, 0
	s_add_i32 s75, s64, s45
	global_load_lds_dwordx4 v[248:249], off
	v_lshl_add_u64 v[250:251], s[76:77], 0, v[166:167]
	s_mov_b32 m0, s75
	v_lshl_add_u64 v[252:253], s[48:49], 0, v[168:169]
	global_load_lds_dwordx4 v[250:251], off
	v_lshl_add_u64 v[250:251], s[76:77], 0, v[170:171]
	s_add_i32 m0, s75, 0x2000
	s_nop 0
	global_load_lds_dwordx4 v[250:251], off
	v_lshl_add_u64 v[250:251], s[48:49], 0, v[164:165]
	s_mov_b32 m0, s9
	s_nop 0
	global_load_lds_dwordx4 v[250:251], off
	s_mov_b32 m0, s57
	s_nop 0
	global_load_lds_dwordx4 v[252:253], off
	s_waitcnt vmcnt(8)
	s_waitcnt lgkmcnt(0)
	s_barrier
; #define PG8_STAGE(bufoff, gbase, voff) do { _Pragma("unroll") for (int _i = 0; _i < 2; ++_i) \
;         __builtin_amdgcn_global_load_lds((const unsigned*)((const char*)(gbase) + (voff)[_i]), (PG8_LAS unsigned*)(lds + (bufoff) + ldsw + _i * 8192), 16, 0, 0); } while (0)
; #define PG8_LDA(dst, b, h) do { _Pragma("unroll") for (int m = 0; m < 4; ++m) _Pragma("unroll") for (int k = 0; k < 2; ++k) dst[m][k] = *(const PG8_LAS bf16x8*)(lds + PG8_SA(b, h) + aoff + m * 2048 + k * 1024); } while (0)
; #define PG8_LDB(dst, b, h) do { _Pragma("unroll") for (int n = 0; n < 2; ++n) _Pragma("unroll") for (int k = 0; k < 2; ++k) dst[n][k] = *(const PG8_LAS bf16x8*)(lds + PG8_SB(b, h) + boff + n * 2048 + k * 1024); } while (0)
; template <class Epi, class Sched, bool ALIGN_EPI = false, bool SP2 = false>
; __device__ __forceinline__ void gemm_phase(PG8_LAS unsigned char* lds, const Gemm g, const Sched& S, const Epi& E) {
;     ...
;         for (int t = 0; t < nt; t += 2) {
;             const bool last = (t == nt - 2);
;             const char* a1 = cA + (size_t)(t + 1) * kstep;
;             const char* a2 = last ? nA : cA + (size_t)(t + 2) * kstep; const char* b2 = last ? nB : cB + (size_t)(t + 2) * kstep;
;             const char* a3 = a2 + kstep; const char* b3 = b2 + kstep;
;             if (last && has_next) S.a_ready(nxt);
;             if constexpr (SP2) {
;             PG8_LDB(B0, 0, 0); PG8_LDB(B1, 0, 1); PG8_SCHED; PG8_LDA(At, 0, 0); PG8_STAGE(PG8_SA(1, 1), a1 + hstep, voffA);
;             PG8_WAIT_V(8); PG8_WAIT_L(0); PG8_BAR; PG8_MMA(0, 0, At, B0); PG8_MMA(0, 1, At, B1); PG8_BAR; PG8_SCHED;
;             PG8_LDA(At, 0, 1); PG8_STAGE(PG8_SB(0, 0), b2, voffB); PG8_STAGE(PG8_SB(0, 1), b2 + hstep, voffB); PG8_STAGE(PG8_SA(0, 0), a2, voffA);
;             PG8_WAIT_V(8); PG8_WAIT_L(0); PG8_BAR; PG8_MMA(1, 0, At, B0); PG8_MMA(1, 1, At, B1); PG8_BAR; PG8_SCHED;
;             PG8_LDB(B0, 1, 0); PG8_LDB(B1, 1, 1); PG8_SCHED; PG8_LDA(At, 1, 0); PG8_STAGE(PG8_SA(0, 1), a2 + hstep, voffA);
;             PG8_WAIT_V(8); PG8_WAIT_L(0); PG8_BAR; PG8_MMA(0, 0, At, B0); PG8_MMA(0, 1, At, B1); PG8_BAR; PG8_SCHED;
;             PG8_LDA(At, 1, 1); PG8_STAGE(PG8_SB(1, 0), b3, voffB); PG8_STAGE(PG8_SB(1, 1), b3 + hstep, voffB); PG8_STAGE(PG8_SA(1, 0), a3, voffA);
;             PG8_WAIT_V(8); PG8_WAIT_L(0); PG8_BAR; PG8_MMA(1, 0, At, B0); PG8_MMA(1, 1, At, B1); PG8_BAR; PG8_SCHED;
	s_setprio 1
	s_waitcnt lgkmcnt(0)
	v_mfma_f32_16x16x32_bf16 v[60:63], v[136:139], v[214:217], v[60:63]
	v_mfma_f32_16x16x32_bf16 v[60:63], v[140:143], v[218:221], v[60:63]
	v_mfma_f32_16x16x32_bf16 v[56:59], v[180:183], v[218:221], v[56:59]
	v_mfma_f32_16x16x32_bf16 v[56:59], v[176:179], v[214:217], v[56:59]
	v_mfma_f32_16x16x32_bf16 v[52:55], v[184:187], v[214:217], v[52:55]
	v_mfma_f32_16x16x32_bf16 v[52:55], v[202:205], v[218:221], v[52:55]
	v_mfma_f32_16x16x32_bf16 v[44:47], v[210:213], v[218:221], v[44:47]
	v_mfma_f32_16x16x32_bf16 v[44:47], v[206:209], v[214:217], v[44:47]
	v_mfma_f32_16x16x32_bf16 v[28:31], v[206:209], v[222:225], v[28:31]
	v_mfma_f32_16x16x32_bf16 v[28:31], v[210:213], v[226:229], v[28:31]
	v_mfma_f32_16x16x32_bf16 v[36:39], v[202:205], v[226:229], v[36:39]
	v_mfma_f32_16x16x32_bf16 v[36:39], v[184:187], v[222:225], v[36:39]
	v_mfma_f32_16x16x32_bf16 v[40:43], v[176:179], v[222:225], v[40:43]
	v_mfma_f32_16x16x32_bf16 v[40:43], v[180:183], v[226:229], v[40:43]
	v_mfma_f32_16x16x32_bf16 v[48:51], v[140:143], v[226:229], v[48:51]
	v_mfma_f32_16x16x32_bf16 v[48:51], v[136:139], v[222:225], v[48:51]
	s_setprio 0
	s_setprio 1
	v_mfma_f32_16x16x32_bf16 v[32:35], v[136:139], v[230:233], v[32:35]
	v_mfma_f32_16x16x32_bf16 v[32:35], v[140:143], v[234:237], v[32:35]
	v_mfma_f32_16x16x32_bf16 v[24:27], v[180:183], v[234:237], v[24:27]
	v_mfma_f32_16x16x32_bf16 v[24:27], v[176:179], v[230:233], v[24:27]
	v_mfma_f32_16x16x32_bf16 v[20:23], v[184:187], v[230:233], v[20:23]
	v_mfma_f32_16x16x32_bf16 v[20:23], v[202:205], v[234:237], v[20:23]
	v_mfma_f32_16x16x32_bf16 v[16:19], v[210:213], v[234:237], v[16:19]
	v_mfma_f32_16x16x32_bf16 v[16:19], v[206:209], v[230:233], v[16:19]
	v_mfma_f32_16x16x32_bf16 v[0:3], v[206:209], v[238:241], v[0:3]
	v_mfma_f32_16x16x32_bf16 v[0:3], v[210:213], v[242:245], v[0:3]
	v_mfma_f32_16x16x32_bf16 v[4:7], v[202:205], v[242:245], v[4:7]
	v_mfma_f32_16x16x32_bf16 v[4:7], v[184:187], v[238:241], v[4:7]
	v_mfma_f32_16x16x32_bf16 v[8:11], v[176:179], v[238:241], v[8:11]
	v_mfma_f32_16x16x32_bf16 v[8:11], v[180:183], v[242:245], v[8:11]
	s_setprio 2
	s_barrier
	v_mfma_f32_16x16x32_bf16 v[12:15], v[140:143], v[242:245], v[12:15]
	v_mfma_f32_16x16x32_bf16 v[12:15], v[136:139], v[238:241], v[12:15]
	s_setprio 0
	s_add_i32 s75, 0, 0x18000
	v_add_u32_e32 v144, s75, v151
	s_add_i32 s76, 0, 0x1c000
	ds_read_b128 v[136:139], v144
	ds_read_b128 v[140:143], v144 offset:1024
	ds_read_b128 v[176:179], v144 offset:2048
	ds_read_b128 v[180:183], v144 offset:3072
	v_add_u32_e32 v144, s76, v151
	ds_read_b128 v[184:187], v144
	ds_read_b128 v[202:205], v144 offset:1024
	ds_read_b128 v[206:209], v144 offset:2048
	ds_read_b128 v[210:213], v144 offset:3072
	s_add_u32 s48, s48, 0x80000
	s_addc_u32 s49, s49, 0
	s_mov_b32 m0, s58
	v_lshl_add_u64 v[200:201], s[48:49], 0, v[164:165]
	ds_read_b128 v[214:217], v163 offset:32768
	ds_read_b128 v[218:221], v163 offset:33792
	ds_read_b128 v[222:225], v163 offset:34816
	ds_read_b128 v[226:229], v163 offset:35840
	ds_read_b128 v[230:233], v163 offset:36864
	ds_read_b128 v[234:237], v163 offset:37888
	ds_read_b128 v[238:241], v163 offset:38912
	ds_read_b128 v[242:245], v163 offset:39936
	global_load_lds_dwordx4 v[200:201], off
	v_lshl_add_u64 v[200:201], s[48:49], 0, v[168:169]
	s_mov_b32 m0, s59
	s_nop 0
	global_load_lds_dwordx4 v[200:201], off
	s_waitcnt vmcnt(8)
	s_waitcnt lgkmcnt(0)
	s_barrier
	s_setprio 1
	s_waitcnt lgkmcnt(0)
	v_mfma_f32_16x16x32_bf16 v[124:127], v[136:139], v[214:217], v[124:127]
	v_mfma_f32_16x16x32_bf16 v[124:127], v[140:143], v[218:221], v[124:127]
	v_mfma_f32_16x16x32_bf16 v[120:123], v[180:183], v[218:221], v[120:123]
	v_mfma_f32_16x16x32_bf16 v[120:123], v[176:179], v[214:217], v[120:123]
	v_mfma_f32_16x16x32_bf16 v[116:119], v[184:187], v[214:217], v[116:119]
	v_mfma_f32_16x16x32_bf16 v[116:119], v[202:205], v[218:221], v[116:119]
	v_mfma_f32_16x16x32_bf16 v[112:115], v[210:213], v[218:221], v[112:115]
	v_mfma_f32_16x16x32_bf16 v[112:115], v[206:209], v[214:217], v[112:115]
	v_mfma_f32_16x16x32_bf16 v[92:95], v[206:209], v[222:225], v[92:95]
	v_mfma_f32_16x16x32_bf16 v[92:95], v[210:213], v[226:229], v[92:95]
	v_mfma_f32_16x16x32_bf16 v[100:103], v[202:205], v[226:229], v[100:103]
	v_mfma_f32_16x16x32_bf16 v[100:103], v[184:187], v[222:225], v[100:103]
	v_mfma_f32_16x16x32_bf16 v[104:107], v[176:179], v[222:225], v[104:107]
	v_mfma_f32_16x16x32_bf16 v[104:107], v[180:183], v[226:229], v[104:107]
	v_mfma_f32_16x16x32_bf16 v[108:111], v[140:143], v[226:229], v[108:111]
	v_mfma_f32_16x16x32_bf16 v[108:111], v[136:139], v[222:225], v[108:111]
	s_setprio 0
	s_setprio 1
	v_mfma_f32_16x16x32_bf16 v[96:99], v[136:139], v[230:233], v[96:99]
	v_mfma_f32_16x16x32_bf16 v[96:99], v[140:143], v[234:237], v[96:99]
	v_mfma_f32_16x16x32_bf16 v[88:91], v[180:183], v[234:237], v[88:91]
	v_mfma_f32_16x16x32_bf16 v[88:91], v[176:179], v[230:233], v[88:91]
	v_mfma_f32_16x16x32_bf16 v[84:87], v[184:187], v[230:233], v[84:87]
	v_mfma_f32_16x16x32_bf16 v[84:87], v[202:205], v[234:237], v[84:87]
	v_mfma_f32_16x16x32_bf16 v[76:79], v[210:213], v[234:237], v[76:79]
	v_mfma_f32_16x16x32_bf16 v[76:79], v[206:209], v[230:233], v[76:79]
	v_mfma_f32_16x16x32_bf16 v[64:67], v[206:209], v[238:241], v[64:67]
	v_mfma_f32_16x16x32_bf16 v[64:67], v[210:213], v[242:245], v[64:67]
	v_mfma_f32_16x16x32_bf16 v[68:71], v[202:205], v[242:245], v[68:71]
	v_mfma_f32_16x16x32_bf16 v[68:71], v[184:187], v[238:241], v[68:71]
	v_mfma_f32_16x16x32_bf16 v[72:75], v[176:179], v[238:241], v[72:75]
	v_mfma_f32_16x16x32_bf16 v[72:75], v[180:183], v[242:245], v[72:75]
	s_setprio 2
	s_barrier
; #define PG8_STAGE(bufoff, gbase, voff) do { _Pragma("unroll") for (int _i = 0; _i < 2; ++_i) \
;         __builtin_amdgcn_global_load_lds((const unsigned*)((const char*)(gbase) + (voff)[_i]), (PG8_LAS unsigned*)(lds + (bufoff) + ldsw + _i * 8192), 16, 0, 0); } while (0)
; #define PG8_LDA(dst, b, h) do { _Pragma("unroll") for (int m = 0; m < 4; ++m) _Pragma("unroll") for (int k = 0; k < 2; ++k) dst[m][k] = *(const PG8_LAS bf16x8*)(lds + PG8_SA(b, h) + aoff + m * 2048 + k * 1024); } while (0)
; #define PG8_LDB(dst, b, h) do { _Pragma("unroll") for (int n = 0; n < 2; ++n) _Pragma("unroll") for (int k = 0; k < 2; ++k) dst[n][k] = *(const PG8_LAS bf16x8*)(lds + PG8_SB(b, h) + boff + n * 2048 + k * 1024); } while (0)
; template <class Epi, class Sched, bool ALIGN_EPI = false, bool SP2 = false>
; __device__ __forceinline__ void gemm_phase(PG8_LAS unsigned char* lds, const Gemm g, const Sched& S, const Epi& E) {
;     ...
;         for (int t = 0; t < nt; t += 2) {
;             const bool last = (t == nt - 2);
;             const char* a1 = cA + (size_t)(t + 1) * kstep;
;             const char* a2 = last ? nA : cA + (size_t)(t + 2) * kstep; const char* b2 = last ? nB : cB + (size_t)(t + 2) * kstep;
;             const char* a3 = a2 + kstep; const char* b3 = b2 + kstep;
;             if (last && has_next) S.a_ready(nxt);
;             if constexpr (SP2) {
;             PG8_LDB(B0, 0, 0); PG8_LDB(B1, 0, 1); PG8_SCHED; PG8_LDA(At, 0, 0); PG8_STAGE(PG8_SA(1, 1), a1 + hstep, voffA);
;             PG8_WAIT_V(8); PG8_WAIT_L(0); PG8_BAR; PG8_MMA(0, 0, At, B0); PG8_MMA(0, 1, At, B1); PG8_BAR; PG8_SCHED;
;             PG8_LDA(At, 0, 1); PG8_STAGE(PG8_SB(0, 0), b2, voffB); PG8_STAGE(PG8_SB(0, 1), b2 + hstep, voffB); PG8_STAGE(PG8_SA(0, 0), a2, voffA);
;             PG8_WAIT_V(8); PG8_WAIT_L(0); PG8_BAR; PG8_MMA(1, 0, At, B0); PG8_MMA(1, 1, At, B1); PG8_BAR; PG8_SCHED;
;             PG8_LDB(B0, 1, 0); PG8_LDB(B1, 1, 1); PG8_SCHED; PG8_LDA(At, 1, 0); PG8_STAGE(PG8_SA(0, 1), a2 + hstep, voffA);
;             PG8_WAIT_V(8); PG8_WAIT_L(0); PG8_BAR; PG8_MMA(0, 0, At, B0); PG8_MMA(0, 1, At, B1); PG8_BAR; PG8_SCHED;
;             PG8_LDA(At, 1, 1); PG8_STAGE(PG8_SB(1, 0), b3, voffB); PG8_STAGE(PG8_SB(1, 1), b3 + hstep, voffB); PG8_STAGE(PG8_SA(1, 0), a3, voffA);
;             PG8_WAIT_V(8); PG8_WAIT_L(0); PG8_BAR; PG8_MMA(1, 0, At, B0); PG8_MMA(1, 1, At, B1); PG8_BAR; PG8_SCHED;
	v_mfma_f32_16x16x32_bf16 v[80:83], v[140:143], v[242:245], v[80:83]
	v_mfma_f32_16x16x32_bf16 v[80:83], v[136:139], v[238:241], v[80:83]
	s_setprio 0
	s_add_i32 s48, s75, s45
	v_lshl_add_u64 v[200:201], v[246:247], 0, s[18:19]
	s_mov_b32 m0, s48
	ds_read_b128 v[214:217], v163 offset:49152
	ds_read_b128 v[218:221], v163 offset:50176
	ds_read_b128 v[222:225], v163 offset:51200
	ds_read_b128 v[226:229], v163 offset:52224
	ds_read_b128 v[230:233], v163 offset:53248
	ds_read_b128 v[234:237], v163 offset:54272
	ds_read_b128 v[238:241], v163 offset:55296
	ds_read_b128 v[242:245], v163 offset:56320
	global_load_lds_dwordx4 v[200:201], off
	s_add_i32 m0, s48, 0x2000
	s_add_u32 s28, s28, 0x80080
	v_lshl_add_u64 v[200:201], v[248:249], 0, s[18:19]
	s_addc_u32 s29, s29, 0
	s_add_i32 s48, s76, s45
	global_load_lds_dwordx4 v[200:201], off
	v_lshl_add_u64 v[200:201], s[28:29], 0, v[166:167]
	s_mov_b32 m0, s48
	s_nop 0
	global_load_lds_dwordx4 v[200:201], off
	v_lshl_add_u64 v[200:201], s[28:29], 0, v[170:171]
	s_add_i32 m0, s48, 0x2000
	s_nop 0
	global_load_lds_dwordx4 v[200:201], off
	v_lshl_add_u64 v[200:201], v[250:251], 0, s[18:19]
	s_mov_b32 m0, s61
	s_nop 0
	global_load_lds_dwordx4 v[200:201], off
	v_lshl_add_u64 v[200:201], v[252:253], 0, s[18:19]
	s_mov_b32 m0, s62
	s_nop 0
	global_load_lds_dwordx4 v[200:201], off
	s_add_i32 s74, s74, 2
	s_add_u32 s52, s52, 0x100
	s_addc_u32 s53, s53, 0
	s_add_u32 s72, s72, 0x100
	s_addc_u32 s73, s73, 0
	s_waitcnt vmcnt(8)
	s_waitcnt lgkmcnt(0)
	s_barrier
	s_setprio 1
	s_waitcnt lgkmcnt(0)
	v_mfma_f32_16x16x32_bf16 v[60:63], v[136:139], v[214:217], v[60:63]
	v_mfma_f32_16x16x32_bf16 v[60:63], v[140:143], v[218:221], v[60:63]
	v_mfma_f32_16x16x32_bf16 v[56:59], v[180:183], v[218:221], v[56:59]
	v_mfma_f32_16x16x32_bf16 v[56:59], v[176:179], v[214:217], v[56:59]
	v_mfma_f32_16x16x32_bf16 v[52:55], v[184:187], v[214:217], v[52:55]
	v_mfma_f32_16x16x32_bf16 v[52:55], v[202:205], v[218:221], v[52:55]
	v_mfma_f32_16x16x32_bf16 v[44:47], v[210:213], v[218:221], v[44:47]
	v_mfma_f32_16x16x32_bf16 v[44:47], v[206:209], v[214:217], v[44:47]
	v_mfma_f32_16x16x32_bf16 v[28:31], v[206:209], v[222:225], v[28:31]
	v_mfma_f32_16x16x32_bf16 v[28:31], v[210:213], v[226:229], v[28:31]
	v_mfma_f32_16x16x32_bf16 v[36:39], v[202:205], v[226:229], v[36:39]
	v_mfma_f32_16x16x32_bf16 v[36:39], v[184:187], v[222:225], v[36:39]
	v_mfma_f32_16x16x32_bf16 v[40:43], v[176:179], v[222:225], v[40:43]
	v_mfma_f32_16x16x32_bf16 v[40:43], v[180:183], v[226:229], v[40:43]
	v_mfma_f32_16x16x32_bf16 v[48:51], v[140:143], v[226:229], v[48:51]
	v_mfma_f32_16x16x32_bf16 v[48:51], v[136:139], v[222:225], v[48:51]
	s_setprio 0
	s_setprio 1
	v_mfma_f32_16x16x32_bf16 v[32:35], v[136:139], v[230:233], v[32:35]
	v_mfma_f32_16x16x32_bf16 v[32:35], v[140:143], v[234:237], v[32:35]
	v_mfma_f32_16x16x32_bf16 v[24:27], v[180:183], v[234:237], v[24:27]
	v_mfma_f32_16x16x32_bf16 v[24:27], v[176:179], v[230:233], v[24:27]
	v_mfma_f32_16x16x32_bf16 v[20:23], v[184:187], v[230:233], v[20:23]
	v_mfma_f32_16x16x32_bf16 v[20:23], v[202:205], v[234:237], v[20:23]
	v_mfma_f32_16x16x32_bf16 v[16:19], v[210:213], v[234:237], v[16:19]
	v_mfma_f32_16x16x32_bf16 v[16:19], v[206:209], v[230:233], v[16:19]
	v_mfma_f32_16x16x32_bf16 v[0:3], v[206:209], v[238:241], v[0:3]
	v_mfma_f32_16x16x32_bf16 v[0:3], v[210:213], v[242:245], v[0:3]
	v_mfma_f32_16x16x32_bf16 v[4:7], v[202:205], v[242:245], v[4:7]
	v_mfma_f32_16x16x32_bf16 v[4:7], v[184:187], v[238:241], v[4:7]
	v_mfma_f32_16x16x32_bf16 v[8:11], v[176:179], v[238:241], v[8:11]
	v_mfma_f32_16x16x32_bf16 v[8:11], v[180:183], v[242:245], v[8:11]
	s_setprio 2
	s_barrier
	v_mfma_f32_16x16x32_bf16 v[12:15], v[140:143], v[242:245], v[12:15]
	v_mfma_f32_16x16x32_bf16 v[12:15], v[136:139], v[238:241], v[12:15]
	s_setprio 0
	s_cmp_gt_u32 s74, 29
	s_cbranch_scc0 .LBB0_110
	s_and_b64 vcc, exec, s[20:21]
	s_cbranch_vccz .LBB0_113
	s_barrier

; #define PG8_STAGE(bufoff, gbase, voff) do { _Pragma("unroll") for (int _i = 0; _i < 2; ++_i) \
;         __builtin_amdgcn_global_load_lds((const unsigned*)((const char*)(gbase) + (voff)[_i]), (PG8_LAS unsigned*)(lds + (bufoff) + ldsw + _i * 8192), 16, 0, 0); } while (0)
; #define PG8_LDA(dst, b, h) do { _Pragma("unroll") for (int m = 0; m < 4; ++m) _Pragma("unroll") for (int k = 0; k < 2; ++k) dst[m][k] = *(const PG8_LAS bf16x8*)(lds + PG8_SA(b, h) + aoff + m * 2048 + k * 1024); } while (0)
; #define PG8_LDB(dst, b, h) do { _Pragma("unroll") for (int n = 0; n < 2; ++n) _Pragma("unroll") for (int k = 0; k < 2; ++k) dst[n][k] = *(const PG8_LAS bf16x8*)(lds + PG8_SB(b, h) + boff + n * 2048 + k * 1024); } while (0)
; template <class Epi, class Sched, bool ALIGN_EPI = false, bool SP2 = false>
; __device__ __forceinline__ void gemm_phase(PG8_LAS unsigned char* lds, const Gemm g, const Sched& S, const Epi& E) {
;     ...
;         for (int t = 0; t < nt; t += 2) {
;             const bool last = (t == nt - 2);
;             const char* a1 = cA + (size_t)(t + 1) * kstep;
;             const char* a2 = last ? nA : cA + (size_t)(t + 2) * kstep; const char* b2 = last ? nB : cB + (size_t)(t + 2) * kstep;
;             const char* a3 = a2 + kstep; const char* b3 = b2 + kstep;
;             if (last && has_next) S.a_ready(nxt);
;             if constexpr (SP2) {
;             PG8_LDB(B0, 0, 0); PG8_LDB(B1, 0, 1); PG8_SCHED; PG8_LDA(At, 0, 0); PG8_STAGE(PG8_SA(1, 1), a1 + hstep, voffA);
;             PG8_WAIT_V(8); PG8_WAIT_L(0); PG8_BAR; PG8_MMA(0, 0, At, B0); PG8_MMA(0, 1, At, B1); PG8_BAR; PG8_SCHED;
;             PG8_LDA(At, 0, 1); PG8_STAGE(PG8_SB(0, 0), b2, voffB); PG8_STAGE(PG8_SB(0, 1), b2 + hstep, voffB); PG8_STAGE(PG8_SA(0, 0), a2, voffA);
;             PG8_WAIT_V(8); PG8_WAIT_L(0); PG8_BAR; PG8_MMA(1, 0, At, B0); PG8_MMA(1, 1, At, B1); PG8_BAR; PG8_SCHED;
;             PG8_LDB(B0, 1, 0); PG8_LDB(B1, 1, 1); PG8_SCHED; PG8_LDA(At, 1, 0); PG8_STAGE(PG8_SA(0, 1), a2 + hstep, voffA);
;             PG8_WAIT_V(8); PG8_WAIT_L(0); PG8_BAR; PG8_MMA(0, 0, At, B0); PG8_MMA(0, 1, At, B1); PG8_BAR; PG8_SCHED;
;             PG8_LDA(At, 1, 1); PG8_STAGE(PG8_SB(1, 0), b3, voffB); PG8_STAGE(PG8_SB(1, 1), b3 + hstep, voffB); PG8_STAGE(PG8_SA(1, 0), a3, voffA);
;             PG8_WAIT_V(8); PG8_WAIT_L(0); PG8_BAR; PG8_MMA(1, 0, At, B0); PG8_MMA(1, 1, At, B1); PG8_BAR; PG8_SCHED;
.LBB0_177:
	ds_read_b128 v[80:83], v171
	ds_read_b128 v[84:87], v171 offset:1024
	ds_read_b128 v[92:95], v171 offset:2048
	ds_read_b128 v[100:103], v171 offset:3072
	ds_read_b128 v[144:147], v206
	ds_read_b128 v[148:151], v206 offset:1024
	ds_read_b128 v[152:155], v206 offset:2048
	ds_read_b128 v[156:159], v206 offset:3072
	s_add_u32 s28, s72, 0xffea0080
	s_addc_u32 s29, s73, -1
	s_cmpk_eq_i32 s76, 0x54
	s_cselect_b32 s49, s69, s29
	s_cselect_b32 s48, s68, s28
	s_cselect_b32 s29, s71, s35
	s_cselect_b32 s28, s70, s34
	v_lshl_add_u64 v[234:235], s[72:73], 0, v[174:175]
	s_add_i32 m0, s40, 0xc000
	ds_read_b128 v[180:183], v207
	ds_read_b128 v[184:187], v207 offset:1024
	ds_read_b128 v[210:213], v207 offset:2048
	ds_read_b128 v[214:217], v207 offset:3072
	ds_read_b128 v[218:221], v207 offset:4096
	ds_read_b128 v[222:225], v207 offset:5120
	ds_read_b128 v[226:229], v207 offset:6144
	ds_read_b128 v[230:233], v207 offset:7168
	global_load_lds_dwordx4 v[234:235], off
	v_lshl_add_u64 v[234:235], s[72:73], 0, v[176:177]
	s_add_i32 m0, s40, 0xe000
	s_nop 0
	global_load_lds_dwordx4 v[234:235], off
	s_waitcnt vmcnt(8)
	s_waitcnt lgkmcnt(0)
	s_barrier
	s_setprio 1
	s_waitcnt lgkmcnt(0)
	v_mfma_f32_16x16x32_bf16 v[140:143], v[80:83], v[180:183], v[140:143]
	v_mfma_f32_16x16x32_bf16 v[140:143], v[84:87], v[184:187], v[140:143]
	v_mfma_f32_16x16x32_bf16 v[136:139], v[100:103], v[184:187], v[136:139]
	v_mfma_f32_16x16x32_bf16 v[136:139], v[92:95], v[180:183], v[136:139]
	v_mfma_f32_16x16x32_bf16 v[132:135], v[144:147], v[180:183], v[132:135]
	v_mfma_f32_16x16x32_bf16 v[132:135], v[148:151], v[184:187], v[132:135]
	v_mfma_f32_16x16x32_bf16 v[128:131], v[156:159], v[184:187], v[128:131]
	v_mfma_f32_16x16x32_bf16 v[128:131], v[152:155], v[180:183], v[128:131]
	v_mfma_f32_16x16x32_bf16 v[112:115], v[152:155], v[210:213], v[112:115]
	v_mfma_f32_16x16x32_bf16 v[112:115], v[156:159], v[214:217], v[112:115]
	v_mfma_f32_16x16x32_bf16 v[116:119], v[148:151], v[214:217], v[116:119]
	v_mfma_f32_16x16x32_bf16 v[116:119], v[144:147], v[210:213], v[116:119]
	v_mfma_f32_16x16x32_bf16 v[120:123], v[92:95], v[210:213], v[120:123]
	v_mfma_f32_16x16x32_bf16 v[120:123], v[100:103], v[214:217], v[120:123]
	v_mfma_f32_16x16x32_bf16 v[124:127], v[84:87], v[214:217], v[124:127]
	v_mfma_f32_16x16x32_bf16 v[124:127], v[80:83], v[210:213], v[124:127]
	s_setprio 0
	s_setprio 1
	v_mfma_f32_16x16x32_bf16 v[108:111], v[80:83], v[218:221], v[108:111]
	v_mfma_f32_16x16x32_bf16 v[108:111], v[84:87], v[222:225], v[108:111]
	v_mfma_f32_16x16x32_bf16 v[104:107], v[100:103], v[222:225], v[104:107]
	v_mfma_f32_16x16x32_bf16 v[104:107], v[92:95], v[218:221], v[104:107]
	v_mfma_f32_16x16x32_bf16 v[96:99], v[144:147], v[218:221], v[96:99]
	v_mfma_f32_16x16x32_bf16 v[96:99], v[148:151], v[222:225], v[96:99]
	v_mfma_f32_16x16x32_bf16 v[88:91], v[156:159], v[222:225], v[88:91]
	v_mfma_f32_16x16x32_bf16 v[88:91], v[152:155], v[218:221], v[88:91]
	v_mfma_f32_16x16x32_bf16 v[64:67], v[152:155], v[226:229], v[64:67]
	v_mfma_f32_16x16x32_bf16 v[64:67], v[156:159], v[230:233], v[64:67]
	v_mfma_f32_16x16x32_bf16 v[68:71], v[148:151], v[230:233], v[68:71]
	v_mfma_f32_16x16x32_bf16 v[68:71], v[144:147], v[226:229], v[68:71]
	v_mfma_f32_16x16x32_bf16 v[72:75], v[92:95], v[226:229], v[72:75]
	v_mfma_f32_16x16x32_bf16 v[72:75], v[100:103], v[230:233], v[72:75]
	s_setprio 2
	s_barrier
	v_mfma_f32_16x16x32_bf16 v[76:79], v[84:87], v[230:233], v[76:79]
	v_mfma_f32_16x16x32_bf16 v[76:79], v[80:83], v[226:229], v[76:79]
	s_setprio 0
	s_add_i32 s77, s61, s13
	v_lshl_add_u64 v[234:235], s[28:29], 0, v[160:161]
	s_mov_b32 m0, s77
	ds_read_b128 v[180:183], v207 offset:16384
	ds_read_b128 v[184:187], v207 offset:17408
	ds_read_b128 v[210:213], v207 offset:18432
	ds_read_b128 v[214:217], v207 offset:19456
	ds_read_b128 v[218:221], v207 offset:20480
	ds_read_b128 v[222:225], v207 offset:21504
	ds_read_b128 v[226:229], v207 offset:22528
	ds_read_b128 v[230:233], v207 offset:23552
	global_load_lds_dwordx4 v[234:235], off
	s_add_i32 m0, s77, 0x2000
	s_add_u32 s78, s28, 0x160000
	v_lshl_add_u64 v[236:237], s[28:29], 0, v[162:163]
	s_addc_u32 s79, s29, 0
	s_add_i32 s77, s62, s13
	global_load_lds_dwordx4 v[236:237], off
	v_lshl_add_u64 v[238:239], s[78:79], 0, v[160:161]
	s_mov_b32 m0, s77
	v_lshl_add_u64 v[240:241], s[48:49], 0, v[162:163]
	global_load_lds_dwordx4 v[238:239], off
	v_lshl_add_u64 v[238:239], s[78:79], 0, v[162:163]
	s_add_i32 m0, s77, 0x2000
	s_nop 0
	global_load_lds_dwordx4 v[238:239], off
	v_lshl_add_u64 v[238:239], s[48:49], 0, v[160:161]
	s_mov_b32 m0, s40
	s_nop 0
	global_load_lds_dwordx4 v[238:239], off
	s_mov_b32 m0, s41
	s_nop 0
	global_load_lds_dwordx4 v[240:241], off
	s_waitcnt vmcnt(8)
	s_waitcnt lgkmcnt(0)
	s_barrier
; #define PG8_STAGE(bufoff, gbase, voff) do { _Pragma("unroll") for (int _i = 0; _i < 2; ++_i) \
;         __builtin_amdgcn_global_load_lds((const unsigned*)((const char*)(gbase) + (voff)[_i]), (PG8_LAS unsigned*)(lds + (bufoff) + ldsw + _i * 8192), 16, 0, 0); } while (0)
; #define PG8_LDA(dst, b, h) do { _Pragma("unroll") for (int m = 0; m < 4; ++m) _Pragma("unroll") for (int k = 0; k < 2; ++k) dst[m][k] = *(const PG8_LAS bf16x8*)(lds + PG8_SA(b, h) + aoff + m * 2048 + k * 1024); } while (0)
; #define PG8_LDB(dst, b, h) do { _Pragma("unroll") for (int n = 0; n < 2; ++n) _Pragma("unroll") for (int k = 0; k < 2; ++k) dst[n][k] = *(const PG8_LAS bf16x8*)(lds + PG8_SB(b, h) + boff + n * 2048 + k * 1024); } while (0)
; template <class Epi, class Sched, bool ALIGN_EPI = false, bool SP2 = false>
; __device__ __forceinline__ void gemm_phase(PG8_LAS unsigned char* lds, const Gemm g, const Sched& S, const Epi& E) {
;     ...
;         for (int t = 0; t < nt; t += 2) {
;             const bool last = (t == nt - 2);
;             const char* a1 = cA + (size_t)(t + 1) * kstep;
;             const char* a2 = last ? nA : cA + (size_t)(t + 2) * kstep; const char* b2 = last ? nB : cB + (size_t)(t + 2) * kstep;
;             const char* a3 = a2 + kstep; const char* b3 = b2 + kstep;
;             if (last && has_next) S.a_ready(nxt);
;             if constexpr (SP2) {
;             PG8_LDB(B0, 0, 0); PG8_LDB(B1, 0, 1); PG8_SCHED; PG8_LDA(At, 0, 0); PG8_STAGE(PG8_SA(1, 1), a1 + hstep, voffA);
;             PG8_WAIT_V(8); PG8_WAIT_L(0); PG8_BAR; PG8_MMA(0, 0, At, B0); PG8_MMA(0, 1, At, B1); PG8_BAR; PG8_SCHED;
;             PG8_LDA(At, 0, 1); PG8_STAGE(PG8_SB(0, 0), b2, voffB); PG8_STAGE(PG8_SB(0, 1), b2 + hstep, voffB); PG8_STAGE(PG8_SA(0, 0), a2, voffA);
;             PG8_WAIT_V(8); PG8_WAIT_L(0); PG8_BAR; PG8_MMA(1, 0, At, B0); PG8_MMA(1, 1, At, B1); PG8_BAR; PG8_SCHED;
;             PG8_LDB(B0, 1, 0); PG8_LDB(B1, 1, 1); PG8_SCHED; PG8_LDA(At, 1, 0); PG8_STAGE(PG8_SA(0, 1), a2 + hstep, voffA);
;             PG8_WAIT_V(8); PG8_WAIT_L(0); PG8_BAR; PG8_MMA(0, 0, At, B0); PG8_MMA(0, 1, At, B1); PG8_BAR; PG8_SCHED;
;             PG8_LDA(At, 1, 1); PG8_STAGE(PG8_SB(1, 0), b3, voffB); PG8_STAGE(PG8_SB(1, 1), b3 + hstep, voffB); PG8_STAGE(PG8_SA(1, 0), a3, voffA);
;             PG8_WAIT_V(8); PG8_WAIT_L(0); PG8_BAR; PG8_MMA(1, 0, At, B0); PG8_MMA(1, 1, At, B1); PG8_BAR; PG8_SCHED;
	s_setprio 1
	s_waitcnt lgkmcnt(0)
	v_mfma_f32_16x16x32_bf16 v[60:63], v[80:83], v[180:183], v[60:63]
	v_mfma_f32_16x16x32_bf16 v[60:63], v[84:87], v[184:187], v[60:63]
	v_mfma_f32_16x16x32_bf16 v[56:59], v[100:103], v[184:187], v[56:59]
	v_mfma_f32_16x16x32_bf16 v[56:59], v[92:95], v[180:183], v[56:59]
	v_mfma_f32_16x16x32_bf16 v[52:55], v[144:147], v[180:183], v[52:55]
	v_mfma_f32_16x16x32_bf16 v[52:55], v[148:151], v[184:187], v[52:55]
	v_mfma_f32_16x16x32_bf16 v[48:51], v[156:159], v[184:187], v[48:51]
	v_mfma_f32_16x16x32_bf16 v[48:51], v[152:155], v[180:183], v[48:51]
	v_mfma_f32_16x16x32_bf16 v[32:35], v[152:155], v[210:213], v[32:35]
	v_mfma_f32_16x16x32_bf16 v[32:35], v[156:159], v[214:217], v[32:35]
	v_mfma_f32_16x16x32_bf16 v[36:39], v[148:151], v[214:217], v[36:39]
	v_mfma_f32_16x16x32_bf16 v[36:39], v[144:147], v[210:213], v[36:39]
	v_mfma_f32_16x16x32_bf16 v[40:43], v[92:95], v[210:213], v[40:43]
	v_mfma_f32_16x16x32_bf16 v[40:43], v[100:103], v[214:217], v[40:43]
	v_mfma_f32_16x16x32_bf16 v[44:47], v[84:87], v[214:217], v[44:47]
	v_mfma_f32_16x16x32_bf16 v[44:47], v[80:83], v[210:213], v[44:47]
	s_setprio 0
	s_setprio 1
	v_mfma_f32_16x16x32_bf16 v[28:31], v[80:83], v[218:221], v[28:31]
	v_mfma_f32_16x16x32_bf16 v[28:31], v[84:87], v[222:225], v[28:31]
	v_mfma_f32_16x16x32_bf16 v[24:27], v[100:103], v[222:225], v[24:27]
	v_mfma_f32_16x16x32_bf16 v[24:27], v[92:95], v[218:221], v[24:27]
	v_mfma_f32_16x16x32_bf16 v[20:23], v[144:147], v[218:221], v[20:23]
	v_mfma_f32_16x16x32_bf16 v[20:23], v[148:151], v[222:225], v[20:23]
	v_mfma_f32_16x16x32_bf16 v[16:19], v[156:159], v[222:225], v[16:19]
	v_mfma_f32_16x16x32_bf16 v[16:19], v[152:155], v[218:221], v[16:19]
	v_mfma_f32_16x16x32_bf16 v[0:3], v[152:155], v[226:229], v[0:3]
	v_mfma_f32_16x16x32_bf16 v[0:3], v[156:159], v[230:233], v[0:3]
	v_mfma_f32_16x16x32_bf16 v[4:7], v[148:151], v[230:233], v[4:7]
	v_mfma_f32_16x16x32_bf16 v[4:7], v[144:147], v[226:229], v[4:7]
	v_mfma_f32_16x16x32_bf16 v[8:11], v[92:95], v[226:229], v[8:11]
	v_mfma_f32_16x16x32_bf16 v[8:11], v[100:103], v[230:233], v[8:11]
	s_setprio 2
	s_barrier
	v_mfma_f32_16x16x32_bf16 v[12:15], v[84:87], v[230:233], v[12:15]
	v_mfma_f32_16x16x32_bf16 v[12:15], v[80:83], v[226:229], v[12:15]
	s_setprio 0
	s_add_i32 s77, 0, 0x18000
	s_add_i32 s78, 0, 0x1c000
	v_add_u32_e32 v100, s77, v167
	v_add_u32_e32 v156, s78, v167
	ds_read_b128 v[80:83], v100
	ds_read_b128 v[84:87], v100 offset:1024
	ds_read_b128 v[92:95], v100 offset:2048
	ds_read_b128 v[100:103], v100 offset:3072
	ds_read_b128 v[144:147], v156
	ds_read_b128 v[148:151], v156 offset:1024
	ds_read_b128 v[152:155], v156 offset:2048
	ds_read_b128 v[156:159], v156 offset:3072
	s_add_u32 s48, s48, 0x160000
	s_addc_u32 s49, s49, 0
	s_mov_b32 m0, s44
	v_lshl_add_u64 v[242:243], s[48:49], 0, v[160:161]
	ds_read_b128 v[180:183], v207 offset:32768
	ds_read_b128 v[184:187], v207 offset:33792
	ds_read_b128 v[210:213], v207 offset:34816
	ds_read_b128 v[214:217], v207 offset:35840
	ds_read_b128 v[218:221], v207 offset:36864
	ds_read_b128 v[222:225], v207 offset:37888
	ds_read_b128 v[226:229], v207 offset:38912
	ds_read_b128 v[230:233], v207 offset:39936
	global_load_lds_dwordx4 v[242:243], off
	v_lshl_add_u64 v[242:243], s[48:49], 0, v[162:163]
	s_mov_b32 m0, s45
	s_nop 0
	global_load_lds_dwordx4 v[242:243], off
	s_waitcnt vmcnt(8)
	s_waitcnt lgkmcnt(0)
	s_barrier
	s_setprio 1
	s_waitcnt lgkmcnt(0)
	v_mfma_f32_16x16x32_bf16 v[140:143], v[80:83], v[180:183], v[140:143]
	v_mfma_f32_16x16x32_bf16 v[140:143], v[84:87], v[184:187], v[140:143]
	v_mfma_f32_16x16x32_bf16 v[136:139], v[100:103], v[184:187], v[136:139]
	v_mfma_f32_16x16x32_bf16 v[136:139], v[92:95], v[180:183], v[136:139]
	v_mfma_f32_16x16x32_bf16 v[132:135], v[144:147], v[180:183], v[132:135]
	v_mfma_f32_16x16x32_bf16 v[132:135], v[148:151], v[184:187], v[132:135]
	v_mfma_f32_16x16x32_bf16 v[128:131], v[156:159], v[184:187], v[128:131]
	v_mfma_f32_16x16x32_bf16 v[128:131], v[152:155], v[180:183], v[128:131]
	v_mfma_f32_16x16x32_bf16 v[112:115], v[152:155], v[210:213], v[112:115]
	v_mfma_f32_16x16x32_bf16 v[112:115], v[156:159], v[214:217], v[112:115]
	v_mfma_f32_16x16x32_bf16 v[116:119], v[148:151], v[214:217], v[116:119]
	v_mfma_f32_16x16x32_bf16 v[116:119], v[144:147], v[210:213], v[116:119]
	v_mfma_f32_16x16x32_bf16 v[120:123], v[92:95], v[210:213], v[120:123]
	v_mfma_f32_16x16x32_bf16 v[120:123], v[100:103], v[214:217], v[120:123]
	v_mfma_f32_16x16x32_bf16 v[124:127], v[84:87], v[214:217], v[124:127]
	v_mfma_f32_16x16x32_bf16 v[124:127], v[80:83], v[210:213], v[124:127]
	s_setprio 0
	s_setprio 1
	v_mfma_f32_16x16x32_bf16 v[108:111], v[80:83], v[218:221], v[108:111]
	v_mfma_f32_16x16x32_bf16 v[108:111], v[84:87], v[222:225], v[108:111]
	v_mfma_f32_16x16x32_bf16 v[104:107], v[100:103], v[222:225], v[104:107]
	v_mfma_f32_16x16x32_bf16 v[104:107], v[92:95], v[218:221], v[104:107]
	v_mfma_f32_16x16x32_bf16 v[96:99], v[144:147], v[218:221], v[96:99]
	v_mfma_f32_16x16x32_bf16 v[96:99], v[148:151], v[222:225], v[96:99]
	v_mfma_f32_16x16x32_bf16 v[88:91], v[156:159], v[222:225], v[88:91]
	v_mfma_f32_16x16x32_bf16 v[88:91], v[152:155], v[218:221], v[88:91]
	v_mfma_f32_16x16x32_bf16 v[64:67], v[152:155], v[226:229], v[64:67]
	v_mfma_f32_16x16x32_bf16 v[64:67], v[156:159], v[230:233], v[64:67]
	v_mfma_f32_16x16x32_bf16 v[68:71], v[148:151], v[230:233], v[68:71]
	v_mfma_f32_16x16x32_bf16 v[68:71], v[144:147], v[226:229], v[68:71]
	v_mfma_f32_16x16x32_bf16 v[72:75], v[92:95], v[226:229], v[72:75]
	v_mfma_f32_16x16x32_bf16 v[72:75], v[100:103], v[230:233], v[72:75]
	s_setprio 2
	s_barrier
; #define PG8_STAGE(bufoff, gbase, voff) do { _Pragma("unroll") for (int _i = 0; _i < 2; ++_i) \
;         __builtin_amdgcn_global_load_lds((const unsigned*)((const char*)(gbase) + (voff)[_i]), (PG8_LAS unsigned*)(lds + (bufoff) + ldsw + _i * 8192), 16, 0, 0); } while (0)
; #define PG8_LDA(dst, b, h) do { _Pragma("unroll") for (int m = 0; m < 4; ++m) _Pragma("unroll") for (int k = 0; k < 2; ++k) dst[m][k] = *(const PG8_LAS bf16x8*)(lds + PG8_SA(b, h) + aoff + m * 2048 + k * 1024); } while (0)
; #define PG8_LDB(dst, b, h) do { _Pragma("unroll") for (int n = 0; n < 2; ++n) _Pragma("unroll") for (int k = 0; k < 2; ++k) dst[n][k] = *(const PG8_LAS bf16x8*)(lds + PG8_SB(b, h) + boff + n * 2048 + k * 1024); } while (0)
; template <class Epi, class Sched, bool ALIGN_EPI = false, bool SP2 = false>
; __device__ __forceinline__ void gemm_phase(PG8_LAS unsigned char* lds, const Gemm g, const Sched& S, const Epi& E) {
;     ...
;         for (int t = 0; t < nt; t += 2) {
;             const bool last = (t == nt - 2);
;             const char* a1 = cA + (size_t)(t + 1) * kstep;
;             const char* a2 = last ? nA : cA + (size_t)(t + 2) * kstep; const char* b2 = last ? nB : cB + (size_t)(t + 2) * kstep;
;             const char* a3 = a2 + kstep; const char* b3 = b2 + kstep;
;             if (last && has_next) S.a_ready(nxt);
;             if constexpr (SP2) {
;             PG8_LDB(B0, 0, 0); PG8_LDB(B1, 0, 1); PG8_SCHED; PG8_LDA(At, 0, 0); PG8_STAGE(PG8_SA(1, 1), a1 + hstep, voffA);
;             PG8_WAIT_V(8); PG8_WAIT_L(0); PG8_BAR; PG8_MMA(0, 0, At, B0); PG8_MMA(0, 1, At, B1); PG8_BAR; PG8_SCHED;
;             PG8_LDA(At, 0, 1); PG8_STAGE(PG8_SB(0, 0), b2, voffB); PG8_STAGE(PG8_SB(0, 1), b2 + hstep, voffB); PG8_STAGE(PG8_SA(0, 0), a2, voffA);
;             PG8_WAIT_V(8); PG8_WAIT_L(0); PG8_BAR; PG8_MMA(1, 0, At, B0); PG8_MMA(1, 1, At, B1); PG8_BAR; PG8_SCHED;
;             PG8_LDB(B0, 1, 0); PG8_LDB(B1, 1, 1); PG8_SCHED; PG8_LDA(At, 1, 0); PG8_STAGE(PG8_SA(0, 1), a2 + hstep, voffA);
;             PG8_WAIT_V(8); PG8_WAIT_L(0); PG8_BAR; PG8_MMA(0, 0, At, B0); PG8_MMA(0, 1, At, B1); PG8_BAR; PG8_SCHED;
;             PG8_LDA(At, 1, 1); PG8_STAGE(PG8_SB(1, 0), b3, voffB); PG8_STAGE(PG8_SB(1, 1), b3 + hstep, voffB); PG8_STAGE(PG8_SA(1, 0), a3, voffA);
;             PG8_WAIT_V(8); PG8_WAIT_L(0); PG8_BAR; PG8_MMA(1, 0, At, B0); PG8_MMA(1, 1, At, B1); PG8_BAR; PG8_SCHED;
	v_mfma_f32_16x16x32_bf16 v[76:79], v[84:87], v[230:233], v[76:79]
	v_mfma_f32_16x16x32_bf16 v[76:79], v[80:83], v[226:229], v[76:79]
	s_setprio 0
	s_add_i32 s48, s77, s13
	v_lshl_add_u64 v[234:235], v[234:235], 0, s[50:51]
	s_mov_b32 m0, s48
	ds_read_b128 v[180:183], v207 offset:49152
	ds_read_b128 v[184:187], v207 offset:50176
	ds_read_b128 v[210:213], v207 offset:51200
	ds_read_b128 v[214:217], v207 offset:52224
	ds_read_b128 v[218:221], v207 offset:53248
	ds_read_b128 v[222:225], v207 offset:54272
	ds_read_b128 v[226:229], v207 offset:55296
	ds_read_b128 v[230:233], v207 offset:56320
	global_load_lds_dwordx4 v[234:235], off
	s_add_i32 m0, s48, 0x2000
	s_add_u32 s28, s28, 0x160080
	v_lshl_add_u64 v[234:235], v[236:237], 0, s[50:51]
	s_addc_u32 s29, s29, 0
	s_add_i32 s48, s78, s13
	global_load_lds_dwordx4 v[234:235], off
	v_lshl_add_u64 v[234:235], s[28:29], 0, v[160:161]
	s_mov_b32 m0, s48
	s_nop 0
	global_load_lds_dwordx4 v[234:235], off
	v_lshl_add_u64 v[234:235], s[28:29], 0, v[162:163]
	s_add_i32 m0, s48, 0x2000
	s_nop 0
	global_load_lds_dwordx4 v[234:235], off
	v_lshl_add_u64 v[234:235], v[238:239], 0, s[50:51]
	s_mov_b32 m0, s56
	s_nop 0
	global_load_lds_dwordx4 v[234:235], off
	v_lshl_add_u64 v[234:235], v[240:241], 0, s[50:51]
	s_mov_b32 m0, s57
	s_nop 0
	global_load_lds_dwordx4 v[234:235], off
	s_add_i32 s76, s76, 2
	s_add_u32 s72, s72, 0x100
	s_addc_u32 s73, s73, 0
	s_add_u32 s34, s34, 0x100
	s_addc_u32 s35, s35, 0
	s_waitcnt vmcnt(8)
	s_waitcnt lgkmcnt(0)
	s_barrier
	s_setprio 1
	s_waitcnt lgkmcnt(0)
	v_mfma_f32_16x16x32_bf16 v[60:63], v[80:83], v[180:183], v[60:63]
	v_mfma_f32_16x16x32_bf16 v[60:63], v[84:87], v[184:187], v[60:63]
	v_mfma_f32_16x16x32_bf16 v[56:59], v[100:103], v[184:187], v[56:59]
	v_mfma_f32_16x16x32_bf16 v[56:59], v[92:95], v[180:183], v[56:59]
	v_mfma_f32_16x16x32_bf16 v[52:55], v[144:147], v[180:183], v[52:55]
	v_mfma_f32_16x16x32_bf16 v[52:55], v[148:151], v[184:187], v[52:55]
	v_mfma_f32_16x16x32_bf16 v[48:51], v[156:159], v[184:187], v[48:51]
	v_mfma_f32_16x16x32_bf16 v[48:51], v[152:155], v[180:183], v[48:51]
	v_mfma_f32_16x16x32_bf16 v[32:35], v[152:155], v[210:213], v[32:35]
	v_mfma_f32_16x16x32_bf16 v[32:35], v[156:159], v[214:217], v[32:35]
	v_mfma_f32_16x16x32_bf16 v[36:39], v[148:151], v[214:217], v[36:39]
	v_mfma_f32_16x16x32_bf16 v[36:39], v[144:147], v[210:213], v[36:39]
	v_mfma_f32_16x16x32_bf16 v[40:43], v[92:95], v[210:213], v[40:43]
	v_mfma_f32_16x16x32_bf16 v[40:43], v[100:103], v[214:217], v[40:43]
	v_mfma_f32_16x16x32_bf16 v[44:47], v[84:87], v[214:217], v[44:47]
	v_mfma_f32_16x16x32_bf16 v[44:47], v[80:83], v[210:213], v[44:47]
	s_setprio 0
	s_setprio 1
	v_mfma_f32_16x16x32_bf16 v[28:31], v[80:83], v[218:221], v[28:31]
	v_mfma_f32_16x16x32_bf16 v[28:31], v[84:87], v[222:225], v[28:31]
	v_mfma_f32_16x16x32_bf16 v[24:27], v[100:103], v[222:225], v[24:27]
	v_mfma_f32_16x16x32_bf16 v[24:27], v[92:95], v[218:221], v[24:27]
	v_mfma_f32_16x16x32_bf16 v[20:23], v[144:147], v[218:221], v[20:23]
	v_mfma_f32_16x16x32_bf16 v[20:23], v[148:151], v[222:225], v[20:23]
	v_mfma_f32_16x16x32_bf16 v[16:19], v[156:159], v[222:225], v[16:19]
	v_mfma_f32_16x16x32_bf16 v[16:19], v[152:155], v[218:221], v[16:19]
	v_mfma_f32_16x16x32_bf16 v[0:3], v[152:155], v[226:229], v[0:3]
	v_mfma_f32_16x16x32_bf16 v[0:3], v[156:159], v[230:233], v[0:3]
	v_mfma_f32_16x16x32_bf16 v[4:7], v[148:151], v[230:233], v[4:7]
	v_mfma_f32_16x16x32_bf16 v[4:7], v[144:147], v[226:229], v[4:7]
	v_mfma_f32_16x16x32_bf16 v[8:11], v[92:95], v[226:229], v[8:11]
	v_mfma_f32_16x16x32_bf16 v[8:11], v[100:103], v[230:233], v[8:11]
	s_setprio 2
	s_barrier
	v_mfma_f32_16x16x32_bf16 v[12:15], v[84:87], v[230:233], v[12:15]
	v_mfma_f32_16x16x32_bf16 v[12:15], v[80:83], v[226:229], v[12:15]
	s_setprio 0
	s_cmpk_gt_u32 s76, 0x55
	s_cbranch_scc0 .LBB0_177
	s_and_b64 vcc, exec, s[52:53]
	s_cbranch_vccz .LBB0_180
	s_barrier

; #define PG8_STAGE(bufoff, gbase, voff) do { _Pragma("unroll") for (int _i = 0; _i < 2; ++_i) \
;         __builtin_amdgcn_global_load_lds((const unsigned*)((const char*)(gbase) + (voff)[_i]), (PG8_LAS unsigned*)(lds + (bufoff) + ldsw + _i * 8192), 16, 0, 0); } while (0)
; #define PG8_LDA(dst, b, h) do { _Pragma("unroll") for (int m = 0; m < 4; ++m) _Pragma("unroll") for (int k = 0; k < 2; ++k) dst[m][k] = *(const PG8_LAS bf16x8*)(lds + PG8_SA(b, h) + aoff + m * 2048 + k * 1024); } while (0)
; #define PG8_LDB(dst, b, h) do { _Pragma("unroll") for (int n = 0; n < 2; ++n) _Pragma("unroll") for (int k = 0; k < 2; ++k) dst[n][k] = *(const PG8_LAS bf16x8*)(lds + PG8_SB(b, h) + boff + n * 2048 + k * 1024); } while (0)
; template <class Epi, class Sched, bool ALIGN_EPI = false, bool SP2 = false>
; __device__ __forceinline__ void gemm_phase(PG8_LAS unsigned char* lds, const Gemm g, const Sched& S, const Epi& E) {
;     ...
;         for (int t = 0; t < nt; t += 2) {
;             const bool last = (t == nt - 2);
;             const char* a1 = cA + (size_t)(t + 1) * kstep;
;             const char* a2 = last ? nA : cA + (size_t)(t + 2) * kstep; const char* b2 = last ? nB : cB + (size_t)(t + 2) * kstep;
;             const char* a3 = a2 + kstep; const char* b3 = b2 + kstep;
;             if (last && has_next) S.a_ready(nxt);
;             if constexpr (SP2) {
;             PG8_LDB(B0, 0, 0); PG8_LDB(B1, 0, 1); PG8_SCHED; PG8_LDA(At, 0, 0); PG8_STAGE(PG8_SA(1, 1), a1 + hstep, voffA);
;             PG8_WAIT_V(8); PG8_WAIT_L(0); PG8_BAR; PG8_MMA(0, 0, At, B0); PG8_MMA(0, 1, At, B1); PG8_BAR; PG8_SCHED;
;             PG8_LDA(At, 0, 1); PG8_STAGE(PG8_SB(0, 0), b2, voffB); PG8_STAGE(PG8_SB(0, 1), b2 + hstep, voffB); PG8_STAGE(PG8_SA(0, 0), a2, voffA);
;             PG8_WAIT_V(8); PG8_WAIT_L(0); PG8_BAR; PG8_MMA(1, 0, At, B0); PG8_MMA(1, 1, At, B1); PG8_BAR; PG8_SCHED;
;             PG8_LDB(B0, 1, 0); PG8_LDB(B1, 1, 1); PG8_SCHED; PG8_LDA(At, 1, 0); PG8_STAGE(PG8_SA(0, 1), a2 + hstep, voffA);
;             PG8_WAIT_V(8); PG8_WAIT_L(0); PG8_BAR; PG8_MMA(0, 0, At, B0); PG8_MMA(0, 1, At, B1); PG8_BAR; PG8_SCHED;
;             PG8_LDA(At, 1, 1); PG8_STAGE(PG8_SB(1, 0), b3, voffB); PG8_STAGE(PG8_SB(1, 1), b3 + hstep, voffB); PG8_STAGE(PG8_SA(1, 0), a3, voffA);
;             PG8_WAIT_V(8); PG8_WAIT_L(0); PG8_BAR; PG8_MMA(1, 0, At, B0); PG8_MMA(1, 1, At, B1); PG8_BAR; PG8_SCHED;
.LBB0_231:
	ds_read_b128 v[142:145], v153
	ds_read_b128 v[146:149], v153 offset:1024
	ds_read_b128 v[174:177], v153 offset:2048
	ds_read_b128 v[178:181], v153 offset:3072
	ds_read_b128 v[182:185], v154
	ds_read_b128 v[206:209], v154 offset:1024
	ds_read_b128 v[210:213], v154 offset:2048
	ds_read_b128 v[214:217], v154 offset:3072
	s_add_u32 s28, s84, 0xfff80080
	s_addc_u32 s29, s85, -1
	s_cmp_eq_u32 s97, 28
	s_cselect_b32 s49, s34, s29
	s_cselect_b32 s48, s35, s28
	s_cselect_b32 s29, s75, s96
	s_cselect_b32 s28, s77, s95
	v_lshl_add_u64 v[158:159], s[84:85], 0, v[134:135]
	s_add_i32 m0, s56, 0xc000
	ds_read_b128 v[218:221], v155
	ds_read_b128 v[222:225], v155 offset:1024
	ds_read_b128 v[226:229], v155 offset:2048
	ds_read_b128 v[230:233], v155 offset:3072
	ds_read_b128 v[234:237], v155 offset:4096
	ds_read_b128 v[238:241], v155 offset:5120
	ds_read_b128 v[242:245], v155 offset:6144
	ds_read_b128 v[246:249], v155 offset:7168
	global_load_lds_dwordx4 v[158:159], off
	v_lshl_add_u64 v[158:159], s[84:85], 0, v[136:137]
	s_add_i32 m0, s56, 0xe000
	s_nop 0
	global_load_lds_dwordx4 v[158:159], off
	s_waitcnt vmcnt(8)
	s_waitcnt lgkmcnt(0)
	s_barrier
	s_setprio 1
	s_waitcnt lgkmcnt(0)
	v_mfma_f32_16x16x32_bf16 v[124:127], v[142:145], v[218:221], v[124:127]
	v_mfma_f32_16x16x32_bf16 v[124:127], v[146:149], v[222:225], v[124:127]
	v_mfma_f32_16x16x32_bf16 v[120:123], v[178:181], v[222:225], v[120:123]
	v_mfma_f32_16x16x32_bf16 v[120:123], v[174:177], v[218:221], v[120:123]
	v_mfma_f32_16x16x32_bf16 v[116:119], v[182:185], v[218:221], v[116:119]
	v_mfma_f32_16x16x32_bf16 v[116:119], v[206:209], v[222:225], v[116:119]
	v_mfma_f32_16x16x32_bf16 v[112:115], v[214:217], v[222:225], v[112:115]
	v_mfma_f32_16x16x32_bf16 v[112:115], v[210:213], v[218:221], v[112:115]
	v_mfma_f32_16x16x32_bf16 v[96:99], v[210:213], v[226:229], v[96:99]
	v_mfma_f32_16x16x32_bf16 v[96:99], v[214:217], v[230:233], v[96:99]
	v_mfma_f32_16x16x32_bf16 v[100:103], v[206:209], v[230:233], v[100:103]
	v_mfma_f32_16x16x32_bf16 v[100:103], v[182:185], v[226:229], v[100:103]
	v_mfma_f32_16x16x32_bf16 v[104:107], v[174:177], v[226:229], v[104:107]
	v_mfma_f32_16x16x32_bf16 v[104:107], v[178:181], v[230:233], v[104:107]
	v_mfma_f32_16x16x32_bf16 v[108:111], v[146:149], v[230:233], v[108:111]
	v_mfma_f32_16x16x32_bf16 v[108:111], v[142:145], v[226:229], v[108:111]
	s_setprio 0
	s_setprio 1
	v_mfma_f32_16x16x32_bf16 v[92:95], v[142:145], v[234:237], v[92:95]
	v_mfma_f32_16x16x32_bf16 v[92:95], v[146:149], v[238:241], v[92:95]
	v_mfma_f32_16x16x32_bf16 v[88:91], v[178:181], v[238:241], v[88:91]
	v_mfma_f32_16x16x32_bf16 v[88:91], v[174:177], v[234:237], v[88:91]
	v_mfma_f32_16x16x32_bf16 v[84:87], v[182:185], v[234:237], v[84:87]
	v_mfma_f32_16x16x32_bf16 v[84:87], v[206:209], v[238:241], v[84:87]
	v_mfma_f32_16x16x32_bf16 v[80:83], v[214:217], v[238:241], v[80:83]
	v_mfma_f32_16x16x32_bf16 v[80:83], v[210:213], v[234:237], v[80:83]
	v_mfma_f32_16x16x32_bf16 v[64:67], v[210:213], v[242:245], v[64:67]
	v_mfma_f32_16x16x32_bf16 v[64:67], v[214:217], v[246:249], v[64:67]
	v_mfma_f32_16x16x32_bf16 v[68:71], v[206:209], v[246:249], v[68:71]
	v_mfma_f32_16x16x32_bf16 v[68:71], v[182:185], v[242:245], v[68:71]
	v_mfma_f32_16x16x32_bf16 v[72:75], v[174:177], v[242:245], v[72:75]
	v_mfma_f32_16x16x32_bf16 v[72:75], v[178:181], v[246:249], v[72:75]
	s_setprio 2
	s_barrier
	v_mfma_f32_16x16x32_bf16 v[76:79], v[146:149], v[246:249], v[76:79]
	v_mfma_f32_16x16x32_bf16 v[76:79], v[142:145], v[242:245], v[76:79]
	s_setprio 0
	s_add_i32 vcc_lo, s83, s13
	v_lshl_add_u64 v[158:159], s[28:29], 0, v[166:167]
	s_mov_b32 m0, vcc_lo
	ds_read_b128 v[218:221], v155 offset:16384
	ds_read_b128 v[222:225], v155 offset:17408
	ds_read_b128 v[226:229], v155 offset:18432
	ds_read_b128 v[230:233], v155 offset:19456
	ds_read_b128 v[234:237], v155 offset:20480
	ds_read_b128 v[238:241], v155 offset:21504
	ds_read_b128 v[242:245], v155 offset:22528
	ds_read_b128 v[246:249], v155 offset:23552
	global_load_lds_dwordx4 v[158:159], off
	s_add_i32 m0, vcc_lo, 0x2000
	s_add_u32 vcc_lo, s28, 0x80000
	v_lshl_add_u64 v[186:187], s[28:29], 0, v[170:171]
	s_addc_u32 vcc_hi, s29, 0
	s_add_i32 s44, s90, s13
	global_load_lds_dwordx4 v[186:187], off
	v_lshl_add_u64 v[250:251], vcc, 0, v[166:167]
	s_mov_b32 m0, s44
	v_lshl_add_u64 v[252:253], s[48:49], 0, v[168:169]
	global_load_lds_dwordx4 v[250:251], off
	v_lshl_add_u64 v[250:251], vcc, 0, v[170:171]
	s_add_i32 m0, s44, 0x2000
	s_nop 0
	global_load_lds_dwordx4 v[250:251], off
	v_lshl_add_u64 v[250:251], s[48:49], 0, v[164:165]
	s_mov_b32 m0, s56
	s_nop 0
	global_load_lds_dwordx4 v[250:251], off
	s_mov_b32 m0, s57
	s_nop 0
	global_load_lds_dwordx4 v[252:253], off
	s_waitcnt vmcnt(8)
	s_waitcnt lgkmcnt(0)
	s_barrier
; #define PG8_STAGE(bufoff, gbase, voff) do { _Pragma("unroll") for (int _i = 0; _i < 2; ++_i) \
;         __builtin_amdgcn_global_load_lds((const unsigned*)((const char*)(gbase) + (voff)[_i]), (PG8_LAS unsigned*)(lds + (bufoff) + ldsw + _i * 8192), 16, 0, 0); } while (0)
; #define PG8_LDA(dst, b, h) do { _Pragma("unroll") for (int m = 0; m < 4; ++m) _Pragma("unroll") for (int k = 0; k < 2; ++k) dst[m][k] = *(const PG8_LAS bf16x8*)(lds + PG8_SA(b, h) + aoff + m * 2048 + k * 1024); } while (0)
; #define PG8_LDB(dst, b, h) do { _Pragma("unroll") for (int n = 0; n < 2; ++n) _Pragma("unroll") for (int k = 0; k < 2; ++k) dst[n][k] = *(const PG8_LAS bf16x8*)(lds + PG8_SB(b, h) + boff + n * 2048 + k * 1024); } while (0)
; template <class Epi, class Sched, bool ALIGN_EPI = false, bool SP2 = false>
; __device__ __forceinline__ void gemm_phase(PG8_LAS unsigned char* lds, const Gemm g, const Sched& S, const Epi& E) {
;     ...
;         for (int t = 0; t < nt; t += 2) {
;             const bool last = (t == nt - 2);
;             const char* a1 = cA + (size_t)(t + 1) * kstep;
;             const char* a2 = last ? nA : cA + (size_t)(t + 2) * kstep; const char* b2 = last ? nB : cB + (size_t)(t + 2) * kstep;
;             const char* a3 = a2 + kstep; const char* b3 = b2 + kstep;
;             if (last && has_next) S.a_ready(nxt);
;             if constexpr (SP2) {
;             PG8_LDB(B0, 0, 0); PG8_LDB(B1, 0, 1); PG8_SCHED; PG8_LDA(At, 0, 0); PG8_STAGE(PG8_SA(1, 1), a1 + hstep, voffA);
;             PG8_WAIT_V(8); PG8_WAIT_L(0); PG8_BAR; PG8_MMA(0, 0, At, B0); PG8_MMA(0, 1, At, B1); PG8_BAR; PG8_SCHED;
;             PG8_LDA(At, 0, 1); PG8_STAGE(PG8_SB(0, 0), b2, voffB); PG8_STAGE(PG8_SB(0, 1), b2 + hstep, voffB); PG8_STAGE(PG8_SA(0, 0), a2, voffA);
;             PG8_WAIT_V(8); PG8_WAIT_L(0); PG8_BAR; PG8_MMA(1, 0, At, B0); PG8_MMA(1, 1, At, B1); PG8_BAR; PG8_SCHED;
;             PG8_LDB(B0, 1, 0); PG8_LDB(B1, 1, 1); PG8_SCHED; PG8_LDA(At, 1, 0); PG8_STAGE(PG8_SA(0, 1), a2 + hstep, voffA);
;             PG8_WAIT_V(8); PG8_WAIT_L(0); PG8_BAR; PG8_MMA(0, 0, At, B0); PG8_MMA(0, 1, At, B1); PG8_BAR; PG8_SCHED;
;             PG8_LDA(At, 1, 1); PG8_STAGE(PG8_SB(1, 0), b3, voffB); PG8_STAGE(PG8_SB(1, 1), b3 + hstep, voffB); PG8_STAGE(PG8_SA(1, 0), a3, voffA);
;             PG8_WAIT_V(8); PG8_WAIT_L(0); PG8_BAR; PG8_MMA(1, 0, At, B0); PG8_MMA(1, 1, At, B1); PG8_BAR; PG8_SCHED;
	s_setprio 1
	s_waitcnt lgkmcnt(0)
	v_mfma_f32_16x16x32_bf16 v[60:63], v[142:145], v[218:221], v[60:63]
	v_mfma_f32_16x16x32_bf16 v[60:63], v[146:149], v[222:225], v[60:63]
	v_mfma_f32_16x16x32_bf16 v[56:59], v[178:181], v[222:225], v[56:59]
	v_mfma_f32_16x16x32_bf16 v[56:59], v[174:177], v[218:221], v[56:59]
	v_mfma_f32_16x16x32_bf16 v[52:55], v[182:185], v[218:221], v[52:55]
	v_mfma_f32_16x16x32_bf16 v[52:55], v[206:209], v[222:225], v[52:55]
	v_mfma_f32_16x16x32_bf16 v[48:51], v[214:217], v[222:225], v[48:51]
	v_mfma_f32_16x16x32_bf16 v[48:51], v[210:213], v[218:221], v[48:51]
	v_mfma_f32_16x16x32_bf16 v[32:35], v[210:213], v[226:229], v[32:35]
	v_mfma_f32_16x16x32_bf16 v[32:35], v[214:217], v[230:233], v[32:35]
	v_mfma_f32_16x16x32_bf16 v[36:39], v[206:209], v[230:233], v[36:39]
	v_mfma_f32_16x16x32_bf16 v[36:39], v[182:185], v[226:229], v[36:39]
	v_mfma_f32_16x16x32_bf16 v[40:43], v[174:177], v[226:229], v[40:43]
	v_mfma_f32_16x16x32_bf16 v[40:43], v[178:181], v[230:233], v[40:43]
	v_mfma_f32_16x16x32_bf16 v[44:47], v[146:149], v[230:233], v[44:47]
	v_mfma_f32_16x16x32_bf16 v[44:47], v[142:145], v[226:229], v[44:47]
	s_setprio 0
	s_setprio 1
	v_mfma_f32_16x16x32_bf16 v[28:31], v[142:145], v[234:237], v[28:31]
	v_mfma_f32_16x16x32_bf16 v[28:31], v[146:149], v[238:241], v[28:31]
	v_mfma_f32_16x16x32_bf16 v[24:27], v[178:181], v[238:241], v[24:27]
	v_mfma_f32_16x16x32_bf16 v[24:27], v[174:177], v[234:237], v[24:27]
	v_mfma_f32_16x16x32_bf16 v[20:23], v[182:185], v[234:237], v[20:23]
	v_mfma_f32_16x16x32_bf16 v[20:23], v[206:209], v[238:241], v[20:23]
	v_mfma_f32_16x16x32_bf16 v[16:19], v[214:217], v[238:241], v[16:19]
	v_mfma_f32_16x16x32_bf16 v[16:19], v[210:213], v[234:237], v[16:19]
	v_mfma_f32_16x16x32_bf16 v[0:3], v[210:213], v[242:245], v[0:3]
	v_mfma_f32_16x16x32_bf16 v[0:3], v[214:217], v[246:249], v[0:3]
	v_mfma_f32_16x16x32_bf16 v[4:7], v[206:209], v[246:249], v[4:7]
	v_mfma_f32_16x16x32_bf16 v[4:7], v[182:185], v[242:245], v[4:7]
	v_mfma_f32_16x16x32_bf16 v[8:11], v[174:177], v[242:245], v[8:11]
	v_mfma_f32_16x16x32_bf16 v[8:11], v[178:181], v[246:249], v[8:11]
	s_setprio 2
	s_barrier
	v_mfma_f32_16x16x32_bf16 v[12:15], v[146:149], v[246:249], v[12:15]
	v_mfma_f32_16x16x32_bf16 v[12:15], v[142:145], v[242:245], v[12:15]
	s_setprio 0
	s_add_i32 s44, 0, 0x18000
	v_add_u32_e32 v161, s44, v151
	s_add_i32 s45, 0, 0x1c000
	ds_read_b128 v[142:145], v161
	ds_read_b128 v[146:149], v161 offset:1024
	ds_read_b128 v[174:177], v161 offset:2048
	ds_read_b128 v[178:181], v161 offset:3072
	v_add_u32_e32 v161, s45, v151
	ds_read_b128 v[182:185], v161
	ds_read_b128 v[206:209], v161 offset:1024
	ds_read_b128 v[210:213], v161 offset:2048
	ds_read_b128 v[214:217], v161 offset:3072
	s_add_u32 s48, s48, 0x80000
	s_addc_u32 s49, s49, 0
	s_mov_b32 m0, s60
	v_lshl_add_u64 v[200:201], s[48:49], 0, v[164:165]
	ds_read_b128 v[218:221], v155 offset:32768
	ds_read_b128 v[222:225], v155 offset:33792
	ds_read_b128 v[226:229], v155 offset:34816
	ds_read_b128 v[230:233], v155 offset:35840
	ds_read_b128 v[234:237], v155 offset:36864
	ds_read_b128 v[238:241], v155 offset:37888
	ds_read_b128 v[242:245], v155 offset:38912
	ds_read_b128 v[246:249], v155 offset:39936
	global_load_lds_dwordx4 v[200:201], off
	v_lshl_add_u64 v[200:201], s[48:49], 0, v[168:169]
	s_mov_b32 m0, s61
	s_nop 0
	global_load_lds_dwordx4 v[200:201], off
	s_waitcnt vmcnt(8)
	s_waitcnt lgkmcnt(0)
	s_barrier
	s_setprio 1
	s_waitcnt lgkmcnt(0)
	v_mfma_f32_16x16x32_bf16 v[124:127], v[142:145], v[218:221], v[124:127]
	v_mfma_f32_16x16x32_bf16 v[124:127], v[146:149], v[222:225], v[124:127]
	v_mfma_f32_16x16x32_bf16 v[120:123], v[178:181], v[222:225], v[120:123]
	v_mfma_f32_16x16x32_bf16 v[120:123], v[174:177], v[218:221], v[120:123]
	v_mfma_f32_16x16x32_bf16 v[116:119], v[182:185], v[218:221], v[116:119]
	v_mfma_f32_16x16x32_bf16 v[116:119], v[206:209], v[222:225], v[116:119]
	v_mfma_f32_16x16x32_bf16 v[112:115], v[214:217], v[222:225], v[112:115]
	v_mfma_f32_16x16x32_bf16 v[112:115], v[210:213], v[218:221], v[112:115]
	v_mfma_f32_16x16x32_bf16 v[96:99], v[210:213], v[226:229], v[96:99]
	v_mfma_f32_16x16x32_bf16 v[96:99], v[214:217], v[230:233], v[96:99]
	v_mfma_f32_16x16x32_bf16 v[100:103], v[206:209], v[230:233], v[100:103]
	v_mfma_f32_16x16x32_bf16 v[100:103], v[182:185], v[226:229], v[100:103]
	v_mfma_f32_16x16x32_bf16 v[104:107], v[174:177], v[226:229], v[104:107]
	v_mfma_f32_16x16x32_bf16 v[104:107], v[178:181], v[230:233], v[104:107]
	v_mfma_f32_16x16x32_bf16 v[108:111], v[146:149], v[230:233], v[108:111]
	v_mfma_f32_16x16x32_bf16 v[108:111], v[142:145], v[226:229], v[108:111]
	s_setprio 0
	s_setprio 1
	v_mfma_f32_16x16x32_bf16 v[92:95], v[142:145], v[234:237], v[92:95]
	v_mfma_f32_16x16x32_bf16 v[92:95], v[146:149], v[238:241], v[92:95]
	v_mfma_f32_16x16x32_bf16 v[88:91], v[178:181], v[238:241], v[88:91]
	v_mfma_f32_16x16x32_bf16 v[88:91], v[174:177], v[234:237], v[88:91]
	v_mfma_f32_16x16x32_bf16 v[84:87], v[182:185], v[234:237], v[84:87]
	v_mfma_f32_16x16x32_bf16 v[84:87], v[206:209], v[238:241], v[84:87]
	v_mfma_f32_16x16x32_bf16 v[80:83], v[214:217], v[238:241], v[80:83]
	v_mfma_f32_16x16x32_bf16 v[80:83], v[210:213], v[234:237], v[80:83]
	v_mfma_f32_16x16x32_bf16 v[64:67], v[210:213], v[242:245], v[64:67]
	v_mfma_f32_16x16x32_bf16 v[64:67], v[214:217], v[246:249], v[64:67]
	v_mfma_f32_16x16x32_bf16 v[68:71], v[206:209], v[246:249], v[68:71]
	v_mfma_f32_16x16x32_bf16 v[68:71], v[182:185], v[242:245], v[68:71]
	v_mfma_f32_16x16x32_bf16 v[72:75], v[174:177], v[242:245], v[72:75]
	v_mfma_f32_16x16x32_bf16 v[72:75], v[178:181], v[246:249], v[72:75]
	s_setprio 2
	s_barrier
; #define PG8_STAGE(bufoff, gbase, voff) do { _Pragma("unroll") for (int _i = 0; _i < 2; ++_i) \
;         __builtin_amdgcn_global_load_lds((const unsigned*)((const char*)(gbase) + (voff)[_i]), (PG8_LAS unsigned*)(lds + (bufoff) + ldsw + _i * 8192), 16, 0, 0); } while (0)
; #define PG8_LDA(dst, b, h) do { _Pragma("unroll") for (int m = 0; m < 4; ++m) _Pragma("unroll") for (int k = 0; k < 2; ++k) dst[m][k] = *(const PG8_LAS bf16x8*)(lds + PG8_SA(b, h) + aoff + m * 2048 + k * 1024); } while (0)
; #define PG8_LDB(dst, b, h) do { _Pragma("unroll") for (int n = 0; n < 2; ++n) _Pragma("unroll") for (int k = 0; k < 2; ++k) dst[n][k] = *(const PG8_LAS bf16x8*)(lds + PG8_SB(b, h) + boff + n * 2048 + k * 1024); } while (0)
; template <class Epi, class Sched, bool ALIGN_EPI = false, bool SP2 = false>
; __device__ __forceinline__ void gemm_phase(PG8_LAS unsigned char* lds, const Gemm g, const Sched& S, const Epi& E) {
;     ...
;         for (int t = 0; t < nt; t += 2) {
;             const bool last = (t == nt - 2);
;             const char* a1 = cA + (size_t)(t + 1) * kstep;
;             const char* a2 = last ? nA : cA + (size_t)(t + 2) * kstep; const char* b2 = last ? nB : cB + (size_t)(t + 2) * kstep;
;             const char* a3 = a2 + kstep; const char* b3 = b2 + kstep;
;             if (last && has_next) S.a_ready(nxt);
;             if constexpr (SP2) {
;             PG8_LDB(B0, 0, 0); PG8_LDB(B1, 0, 1); PG8_SCHED; PG8_LDA(At, 0, 0); PG8_STAGE(PG8_SA(1, 1), a1 + hstep, voffA);
;             PG8_WAIT_V(8); PG8_WAIT_L(0); PG8_BAR; PG8_MMA(0, 0, At, B0); PG8_MMA(0, 1, At, B1); PG8_BAR; PG8_SCHED;
;             PG8_LDA(At, 0, 1); PG8_STAGE(PG8_SB(0, 0), b2, voffB); PG8_STAGE(PG8_SB(0, 1), b2 + hstep, voffB); PG8_STAGE(PG8_SA(0, 0), a2, voffA);
;             PG8_WAIT_V(8); PG8_WAIT_L(0); PG8_BAR; PG8_MMA(1, 0, At, B0); PG8_MMA(1, 1, At, B1); PG8_BAR; PG8_SCHED;
;             PG8_LDB(B0, 1, 0); PG8_LDB(B1, 1, 1); PG8_SCHED; PG8_LDA(At, 1, 0); PG8_STAGE(PG8_SA(0, 1), a2 + hstep, voffA);
;             PG8_WAIT_V(8); PG8_WAIT_L(0); PG8_BAR; PG8_MMA(0, 0, At, B0); PG8_MMA(0, 1, At, B1); PG8_BAR; PG8_SCHED;
;             PG8_LDA(At, 1, 1); PG8_STAGE(PG8_SB(1, 0), b3, voffB); PG8_STAGE(PG8_SB(1, 1), b3 + hstep, voffB); PG8_STAGE(PG8_SA(1, 0), a3, voffA);
;             PG8_WAIT_V(8); PG8_WAIT_L(0); PG8_BAR; PG8_MMA(1, 0, At, B0); PG8_MMA(1, 1, At, B1); PG8_BAR; PG8_SCHED;
	v_mfma_f32_16x16x32_bf16 v[76:79], v[146:149], v[246:249], v[76:79]
	v_mfma_f32_16x16x32_bf16 v[76:79], v[142:145], v[242:245], v[76:79]
	s_setprio 0
	s_add_i32 s44, s44, s13
	v_lshl_add_u64 v[158:159], v[158:159], 0, s[52:53]
	s_mov_b32 m0, s44
	ds_read_b128 v[218:221], v155 offset:49152
	ds_read_b128 v[222:225], v155 offset:50176
	ds_read_b128 v[226:229], v155 offset:51200
	ds_read_b128 v[230:233], v155 offset:52224
	ds_read_b128 v[234:237], v155 offset:53248
	ds_read_b128 v[238:241], v155 offset:54272
	ds_read_b128 v[242:245], v155 offset:55296
	ds_read_b128 v[246:249], v155 offset:56320
	global_load_lds_dwordx4 v[158:159], off
	s_add_i32 m0, s44, 0x2000
	s_add_u32 s28, s28, 0x80080
	v_lshl_add_u64 v[158:159], v[186:187], 0, s[52:53]
	s_addc_u32 s29, s29, 0
	s_add_i32 s44, s45, s13
	global_load_lds_dwordx4 v[158:159], off
	v_lshl_add_u64 v[158:159], s[28:29], 0, v[166:167]
	s_mov_b32 m0, s44
	s_nop 0
	global_load_lds_dwordx4 v[158:159], off
	v_lshl_add_u64 v[158:159], s[28:29], 0, v[170:171]
	s_add_i32 m0, s44, 0x2000
	s_nop 0
	global_load_lds_dwordx4 v[158:159], off
	v_lshl_add_u64 v[158:159], v[250:251], 0, s[52:53]
	s_mov_b32 m0, s62
	s_nop 0
	global_load_lds_dwordx4 v[158:159], off
	v_lshl_add_u64 v[158:159], v[252:253], 0, s[52:53]
	s_mov_b32 m0, s63
	s_nop 0
	global_load_lds_dwordx4 v[158:159], off
	s_add_i32 s97, s97, 2
	s_add_u32 s84, s84, 0x100
	s_addc_u32 s85, s85, 0
	s_add_u32 s95, s95, 0x100
	s_addc_u32 s96, s96, 0
	s_waitcnt vmcnt(8)
	s_waitcnt lgkmcnt(0)
	s_barrier
	s_setprio 1
	s_waitcnt lgkmcnt(0)
	v_mfma_f32_16x16x32_bf16 v[60:63], v[142:145], v[218:221], v[60:63]
	v_mfma_f32_16x16x32_bf16 v[60:63], v[146:149], v[222:225], v[60:63]
	v_mfma_f32_16x16x32_bf16 v[56:59], v[178:181], v[222:225], v[56:59]
	v_mfma_f32_16x16x32_bf16 v[56:59], v[174:177], v[218:221], v[56:59]
	v_mfma_f32_16x16x32_bf16 v[52:55], v[182:185], v[218:221], v[52:55]
	v_mfma_f32_16x16x32_bf16 v[52:55], v[206:209], v[222:225], v[52:55]
	v_mfma_f32_16x16x32_bf16 v[48:51], v[214:217], v[222:225], v[48:51]
	v_mfma_f32_16x16x32_bf16 v[48:51], v[210:213], v[218:221], v[48:51]
	v_mfma_f32_16x16x32_bf16 v[32:35], v[210:213], v[226:229], v[32:35]
	v_mfma_f32_16x16x32_bf16 v[32:35], v[214:217], v[230:233], v[32:35]
	v_mfma_f32_16x16x32_bf16 v[36:39], v[206:209], v[230:233], v[36:39]
	v_mfma_f32_16x16x32_bf16 v[36:39], v[182:185], v[226:229], v[36:39]
	v_mfma_f32_16x16x32_bf16 v[40:43], v[174:177], v[226:229], v[40:43]
	v_mfma_f32_16x16x32_bf16 v[40:43], v[178:181], v[230:233], v[40:43]
	v_mfma_f32_16x16x32_bf16 v[44:47], v[146:149], v[230:233], v[44:47]
	v_mfma_f32_16x16x32_bf16 v[44:47], v[142:145], v[226:229], v[44:47]
	s_setprio 0
	s_setprio 1
	v_mfma_f32_16x16x32_bf16 v[28:31], v[142:145], v[234:237], v[28:31]
	v_mfma_f32_16x16x32_bf16 v[28:31], v[146:149], v[238:241], v[28:31]
	v_mfma_f32_16x16x32_bf16 v[24:27], v[178:181], v[238:241], v[24:27]
	v_mfma_f32_16x16x32_bf16 v[24:27], v[174:177], v[234:237], v[24:27]
	v_mfma_f32_16x16x32_bf16 v[20:23], v[182:185], v[234:237], v[20:23]
	v_mfma_f32_16x16x32_bf16 v[20:23], v[206:209], v[238:241], v[20:23]
	v_mfma_f32_16x16x32_bf16 v[16:19], v[214:217], v[238:241], v[16:19]
	v_mfma_f32_16x16x32_bf16 v[16:19], v[210:213], v[234:237], v[16:19]
	v_mfma_f32_16x16x32_bf16 v[0:3], v[210:213], v[242:245], v[0:3]
	v_mfma_f32_16x16x32_bf16 v[0:3], v[214:217], v[246:249], v[0:3]
	v_mfma_f32_16x16x32_bf16 v[4:7], v[206:209], v[246:249], v[4:7]
	v_mfma_f32_16x16x32_bf16 v[4:7], v[182:185], v[242:245], v[4:7]
	v_mfma_f32_16x16x32_bf16 v[8:11], v[174:177], v[242:245], v[8:11]
	v_mfma_f32_16x16x32_bf16 v[8:11], v[178:181], v[246:249], v[8:11]
	s_setprio 2
	s_barrier
	v_mfma_f32_16x16x32_bf16 v[12:15], v[146:149], v[246:249], v[12:15]
	v_mfma_f32_16x16x32_bf16 v[12:15], v[142:145], v[242:245], v[12:15]
	s_setprio 0
	s_cmp_gt_u32 s97, 29
	s_cbranch_scc0 .LBB0_231
	s_and_b64 vcc, exec, s[72:73]
	s_cbranch_vccz .LBB0_236
	s_barrier
	v_lshl_add_u32 v142, s82, 8, v150
	s_cmp_gt_i32 s94, 7
	s_mov_b64 s[28:29], -1
	s_cbranch_scc1 .LBB0_237

; #define PG8_STAGE(bufoff, gbase, voff) do { _Pragma("unroll") for (int _i = 0; _i < 2; ++_i) \
;         __builtin_amdgcn_global_load_lds((const unsigned*)((const char*)(gbase) + (voff)[_i]), (PG8_LAS unsigned*)(lds + (bufoff) + ldsw + _i * 8192), 16, 0, 0); } while (0)
; #define PG8_LDA(dst, b, h) do { _Pragma("unroll") for (int m = 0; m < 4; ++m) _Pragma("unroll") for (int k = 0; k < 2; ++k) dst[m][k] = *(const PG8_LAS bf16x8*)(lds + PG8_SA(b, h) + aoff + m * 2048 + k * 1024); } while (0)
; #define PG8_LDB(dst, b, h) do { _Pragma("unroll") for (int n = 0; n < 2; ++n) _Pragma("unroll") for (int k = 0; k < 2; ++k) dst[n][k] = *(const PG8_LAS bf16x8*)(lds + PG8_SB(b, h) + boff + n * 2048 + k * 1024); } while (0)
; template <class Epi, class Sched, bool ALIGN_EPI = false, bool SP2 = false>
; __device__ __forceinline__ void gemm_phase(PG8_LAS unsigned char* lds, const Gemm g, const Sched& S, const Epi& E) {
;     ...
;         for (int t = 0; t < nt; t += 2) {
;             const bool last = (t == nt - 2);
;             const char* a1 = cA + (size_t)(t + 1) * kstep;
;             const char* a2 = last ? nA : cA + (size_t)(t + 2) * kstep; const char* b2 = last ? nB : cB + (size_t)(t + 2) * kstep;
;             const char* a3 = a2 + kstep; const char* b3 = b2 + kstep;
;             if (last && has_next) S.a_ready(nxt);
;             if constexpr (SP2) {
;             PG8_LDB(B0, 0, 0); PG8_LDB(B1, 0, 1); PG8_SCHED; PG8_LDA(At, 0, 0); PG8_STAGE(PG8_SA(1, 1), a1 + hstep, voffA);
;             PG8_WAIT_V(8); PG8_WAIT_L(0); PG8_BAR; PG8_MMA(0, 0, At, B0); PG8_MMA(0, 1, At, B1); PG8_BAR; PG8_SCHED;
;             PG8_LDA(At, 0, 1); PG8_STAGE(PG8_SB(0, 0), b2, voffB); PG8_STAGE(PG8_SB(0, 1), b2 + hstep, voffB); PG8_STAGE(PG8_SA(0, 0), a2, voffA);
;             PG8_WAIT_V(8); PG8_WAIT_L(0); PG8_BAR; PG8_MMA(1, 0, At, B0); PG8_MMA(1, 1, At, B1); PG8_BAR; PG8_SCHED;
;             PG8_LDB(B0, 1, 0); PG8_LDB(B1, 1, 1); PG8_SCHED; PG8_LDA(At, 1, 0); PG8_STAGE(PG8_SA(0, 1), a2 + hstep, voffA);
;             PG8_WAIT_V(8); PG8_WAIT_L(0); PG8_BAR; PG8_MMA(0, 0, At, B0); PG8_MMA(0, 1, At, B1); PG8_BAR; PG8_SCHED;
;             PG8_LDA(At, 1, 1); PG8_STAGE(PG8_SB(1, 0), b3, voffB); PG8_STAGE(PG8_SB(1, 1), b3 + hstep, voffB); PG8_STAGE(PG8_SA(1, 0), a3, voffA);
;             PG8_WAIT_V(8); PG8_WAIT_L(0); PG8_BAR; PG8_MMA(1, 0, At, B0); PG8_MMA(1, 1, At, B1); PG8_BAR; PG8_SCHED;
.LBB0_362:
	ds_read_b128 v[80:83], v171
	ds_read_b128 v[84:87], v171 offset:1024
	ds_read_b128 v[92:95], v171 offset:2048
	ds_read_b128 v[100:103], v171 offset:3072
	ds_read_b128 v[144:147], v186
	ds_read_b128 v[148:151], v186 offset:1024
	ds_read_b128 v[152:155], v186 offset:2048
	ds_read_b128 v[156:159], v186 offset:3072
	s_add_u32 s28, s74, 0xfff80080
	s_addc_u32 s29, s75, -1
	s_cmp_eq_u32 s77, 28
	s_cselect_b32 s49, s23, s29
	s_cselect_b32 s48, s34, s28
	s_cselect_b32 s29, s21, s76
	s_cselect_b32 s28, s35, s73
	v_lshl_add_u64 v[200:201], s[74:75], 0, v[172:173]
	s_add_i32 m0, s38, 0xc000
	ds_read_b128 v[178:181], v187
	ds_read_b128 v[182:185], v187 offset:1024
	ds_read_b128 v[206:209], v187 offset:2048
	ds_read_b128 v[210:213], v187 offset:3072
	ds_read_b128 v[214:217], v187 offset:4096
	ds_read_b128 v[218:221], v187 offset:5120
	ds_read_b128 v[222:225], v187 offset:6144
	ds_read_b128 v[226:229], v187 offset:7168
	global_load_lds_dwordx4 v[200:201], off
	v_lshl_add_u64 v[200:201], s[74:75], 0, v[174:175]
	s_add_i32 m0, s38, 0xe000
	s_nop 0
	global_load_lds_dwordx4 v[200:201], off
	s_waitcnt vmcnt(8)
	s_waitcnt lgkmcnt(0)
	s_barrier
	s_setprio 1
	s_waitcnt lgkmcnt(0)
	v_mfma_f32_16x16x32_bf16 v[140:143], v[80:83], v[178:181], v[140:143]
	v_mfma_f32_16x16x32_bf16 v[140:143], v[84:87], v[182:185], v[140:143]
	v_mfma_f32_16x16x32_bf16 v[136:139], v[100:103], v[182:185], v[136:139]
	v_mfma_f32_16x16x32_bf16 v[136:139], v[92:95], v[178:181], v[136:139]
	v_mfma_f32_16x16x32_bf16 v[132:135], v[144:147], v[178:181], v[132:135]
	v_mfma_f32_16x16x32_bf16 v[132:135], v[148:151], v[182:185], v[132:135]
	v_mfma_f32_16x16x32_bf16 v[128:131], v[156:159], v[182:185], v[128:131]
	v_mfma_f32_16x16x32_bf16 v[128:131], v[152:155], v[178:181], v[128:131]
	v_mfma_f32_16x16x32_bf16 v[112:115], v[152:155], v[206:209], v[112:115]
	v_mfma_f32_16x16x32_bf16 v[112:115], v[156:159], v[210:213], v[112:115]
	v_mfma_f32_16x16x32_bf16 v[116:119], v[148:151], v[210:213], v[116:119]
	v_mfma_f32_16x16x32_bf16 v[116:119], v[144:147], v[206:209], v[116:119]
	v_mfma_f32_16x16x32_bf16 v[120:123], v[92:95], v[206:209], v[120:123]
	v_mfma_f32_16x16x32_bf16 v[120:123], v[100:103], v[210:213], v[120:123]
	v_mfma_f32_16x16x32_bf16 v[124:127], v[84:87], v[210:213], v[124:127]
	v_mfma_f32_16x16x32_bf16 v[124:127], v[80:83], v[206:209], v[124:127]
	s_setprio 0
	s_setprio 1
	v_mfma_f32_16x16x32_bf16 v[108:111], v[80:83], v[214:217], v[108:111]
	v_mfma_f32_16x16x32_bf16 v[108:111], v[84:87], v[218:221], v[108:111]
	v_mfma_f32_16x16x32_bf16 v[104:107], v[100:103], v[218:221], v[104:107]
	v_mfma_f32_16x16x32_bf16 v[104:107], v[92:95], v[214:217], v[104:107]
	v_mfma_f32_16x16x32_bf16 v[96:99], v[144:147], v[214:217], v[96:99]
	v_mfma_f32_16x16x32_bf16 v[96:99], v[148:151], v[218:221], v[96:99]
	v_mfma_f32_16x16x32_bf16 v[88:91], v[156:159], v[218:221], v[88:91]
	v_mfma_f32_16x16x32_bf16 v[88:91], v[152:155], v[214:217], v[88:91]
	v_mfma_f32_16x16x32_bf16 v[64:67], v[152:155], v[222:225], v[64:67]
	v_mfma_f32_16x16x32_bf16 v[64:67], v[156:159], v[226:229], v[64:67]
	v_mfma_f32_16x16x32_bf16 v[68:71], v[148:151], v[226:229], v[68:71]
	v_mfma_f32_16x16x32_bf16 v[68:71], v[144:147], v[222:225], v[68:71]
	v_mfma_f32_16x16x32_bf16 v[72:75], v[92:95], v[222:225], v[72:75]
	v_mfma_f32_16x16x32_bf16 v[72:75], v[100:103], v[226:229], v[72:75]
	s_setprio 2
	s_barrier
	v_mfma_f32_16x16x32_bf16 v[76:79], v[84:87], v[226:229], v[76:79]
	v_mfma_f32_16x16x32_bf16 v[76:79], v[80:83], v[222:225], v[76:79]
	s_setprio 0
	s_add_i32 s44, s62, s13
	v_lshl_add_u64 v[200:201], s[28:29], 0, v[164:165]
	s_mov_b32 m0, s44
	ds_read_b128 v[178:181], v187 offset:16384
	ds_read_b128 v[182:185], v187 offset:17408
	ds_read_b128 v[206:209], v187 offset:18432
	ds_read_b128 v[210:213], v187 offset:19456
	ds_read_b128 v[214:217], v187 offset:20480
	ds_read_b128 v[218:221], v187 offset:21504
	ds_read_b128 v[222:225], v187 offset:22528
	ds_read_b128 v[226:229], v187 offset:23552
	global_load_lds_dwordx4 v[200:201], off
	s_add_i32 m0, s44, 0x2000
	s_add_u32 s78, s28, 0x80000
	v_lshl_add_u64 v[230:231], s[28:29], 0, v[168:169]
	s_addc_u32 s79, s29, 0
	s_add_i32 s44, s63, s13
	global_load_lds_dwordx4 v[230:231], off
	v_lshl_add_u64 v[232:233], s[78:79], 0, v[164:165]
	s_mov_b32 m0, s44
	v_lshl_add_u64 v[234:235], s[48:49], 0, v[168:169]
	global_load_lds_dwordx4 v[232:233], off
	v_lshl_add_u64 v[232:233], s[78:79], 0, v[168:169]
	s_add_i32 m0, s44, 0x2000
	s_nop 0
	global_load_lds_dwordx4 v[232:233], off
	v_lshl_add_u64 v[232:233], s[48:49], 0, v[164:165]
	s_mov_b32 m0, s38
	s_nop 0
	global_load_lds_dwordx4 v[232:233], off
	s_mov_b32 m0, s39
	s_nop 0
	global_load_lds_dwordx4 v[234:235], off
	s_waitcnt vmcnt(8)
	s_waitcnt lgkmcnt(0)
	s_barrier
; #define PG8_STAGE(bufoff, gbase, voff) do { _Pragma("unroll") for (int _i = 0; _i < 2; ++_i) \
;         __builtin_amdgcn_global_load_lds((const unsigned*)((const char*)(gbase) + (voff)[_i]), (PG8_LAS unsigned*)(lds + (bufoff) + ldsw + _i * 8192), 16, 0, 0); } while (0)
; #define PG8_LDA(dst, b, h) do { _Pragma("unroll") for (int m = 0; m < 4; ++m) _Pragma("unroll") for (int k = 0; k < 2; ++k) dst[m][k] = *(const PG8_LAS bf16x8*)(lds + PG8_SA(b, h) + aoff + m * 2048 + k * 1024); } while (0)
; #define PG8_LDB(dst, b, h) do { _Pragma("unroll") for (int n = 0; n < 2; ++n) _Pragma("unroll") for (int k = 0; k < 2; ++k) dst[n][k] = *(const PG8_LAS bf16x8*)(lds + PG8_SB(b, h) + boff + n * 2048 + k * 1024); } while (0)
; template <class Epi, class Sched, bool ALIGN_EPI = false, bool SP2 = false>
; __device__ __forceinline__ void gemm_phase(PG8_LAS unsigned char* lds, const Gemm g, const Sched& S, const Epi& E) {
;     ...
;         for (int t = 0; t < nt; t += 2) {
;             const bool last = (t == nt - 2);
;             const char* a1 = cA + (size_t)(t + 1) * kstep;
;             const char* a2 = last ? nA : cA + (size_t)(t + 2) * kstep; const char* b2 = last ? nB : cB + (size_t)(t + 2) * kstep;
;             const char* a3 = a2 + kstep; const char* b3 = b2 + kstep;
;             if (last && has_next) S.a_ready(nxt);
;             if constexpr (SP2) {
;             PG8_LDB(B0, 0, 0); PG8_LDB(B1, 0, 1); PG8_SCHED; PG8_LDA(At, 0, 0); PG8_STAGE(PG8_SA(1, 1), a1 + hstep, voffA);
;             PG8_WAIT_V(8); PG8_WAIT_L(0); PG8_BAR; PG8_MMA(0, 0, At, B0); PG8_MMA(0, 1, At, B1); PG8_BAR; PG8_SCHED;
;             PG8_LDA(At, 0, 1); PG8_STAGE(PG8_SB(0, 0), b2, voffB); PG8_STAGE(PG8_SB(0, 1), b2 + hstep, voffB); PG8_STAGE(PG8_SA(0, 0), a2, voffA);
;             PG8_WAIT_V(8); PG8_WAIT_L(0); PG8_BAR; PG8_MMA(1, 0, At, B0); PG8_MMA(1, 1, At, B1); PG8_BAR; PG8_SCHED;
;             PG8_LDB(B0, 1, 0); PG8_LDB(B1, 1, 1); PG8_SCHED; PG8_LDA(At, 1, 0); PG8_STAGE(PG8_SA(0, 1), a2 + hstep, voffA);
;             PG8_WAIT_V(8); PG8_WAIT_L(0); PG8_BAR; PG8_MMA(0, 0, At, B0); PG8_MMA(0, 1, At, B1); PG8_BAR; PG8_SCHED;
;             PG8_LDA(At, 1, 1); PG8_STAGE(PG8_SB(1, 0), b3, voffB); PG8_STAGE(PG8_SB(1, 1), b3 + hstep, voffB); PG8_STAGE(PG8_SA(1, 0), a3, voffA);
;             PG8_WAIT_V(8); PG8_WAIT_L(0); PG8_BAR; PG8_MMA(1, 0, At, B0); PG8_MMA(1, 1, At, B1); PG8_BAR; PG8_SCHED;
	s_setprio 1
	s_waitcnt lgkmcnt(0)
	v_mfma_f32_16x16x32_bf16 v[60:63], v[80:83], v[178:181], v[60:63]
	v_mfma_f32_16x16x32_bf16 v[60:63], v[84:87], v[182:185], v[60:63]
	v_mfma_f32_16x16x32_bf16 v[56:59], v[100:103], v[182:185], v[56:59]
	v_mfma_f32_16x16x32_bf16 v[56:59], v[92:95], v[178:181], v[56:59]
	v_mfma_f32_16x16x32_bf16 v[52:55], v[144:147], v[178:181], v[52:55]
	v_mfma_f32_16x16x32_bf16 v[52:55], v[148:151], v[182:185], v[52:55]
	v_mfma_f32_16x16x32_bf16 v[48:51], v[156:159], v[182:185], v[48:51]
	v_mfma_f32_16x16x32_bf16 v[48:51], v[152:155], v[178:181], v[48:51]
	v_mfma_f32_16x16x32_bf16 v[32:35], v[152:155], v[206:209], v[32:35]
	v_mfma_f32_16x16x32_bf16 v[32:35], v[156:159], v[210:213], v[32:35]
	v_mfma_f32_16x16x32_bf16 v[36:39], v[148:151], v[210:213], v[36:39]
	v_mfma_f32_16x16x32_bf16 v[36:39], v[144:147], v[206:209], v[36:39]
	v_mfma_f32_16x16x32_bf16 v[40:43], v[92:95], v[206:209], v[40:43]
	v_mfma_f32_16x16x32_bf16 v[40:43], v[100:103], v[210:213], v[40:43]
	v_mfma_f32_16x16x32_bf16 v[44:47], v[84:87], v[210:213], v[44:47]
	v_mfma_f32_16x16x32_bf16 v[44:47], v[80:83], v[206:209], v[44:47]
	s_setprio 0
	s_setprio 1
	v_mfma_f32_16x16x32_bf16 v[28:31], v[80:83], v[214:217], v[28:31]
	v_mfma_f32_16x16x32_bf16 v[28:31], v[84:87], v[218:221], v[28:31]
	v_mfma_f32_16x16x32_bf16 v[24:27], v[100:103], v[218:221], v[24:27]
	v_mfma_f32_16x16x32_bf16 v[24:27], v[92:95], v[214:217], v[24:27]
	v_mfma_f32_16x16x32_bf16 v[20:23], v[144:147], v[214:217], v[20:23]
	v_mfma_f32_16x16x32_bf16 v[20:23], v[148:151], v[218:221], v[20:23]
	v_mfma_f32_16x16x32_bf16 v[16:19], v[156:159], v[218:221], v[16:19]
	v_mfma_f32_16x16x32_bf16 v[16:19], v[152:155], v[214:217], v[16:19]
	v_mfma_f32_16x16x32_bf16 v[0:3], v[152:155], v[222:225], v[0:3]
	v_mfma_f32_16x16x32_bf16 v[0:3], v[156:159], v[226:229], v[0:3]
	v_mfma_f32_16x16x32_bf16 v[4:7], v[148:151], v[226:229], v[4:7]
	v_mfma_f32_16x16x32_bf16 v[4:7], v[144:147], v[222:225], v[4:7]
	v_mfma_f32_16x16x32_bf16 v[8:11], v[92:95], v[222:225], v[8:11]
	v_mfma_f32_16x16x32_bf16 v[8:11], v[100:103], v[226:229], v[8:11]
	s_setprio 2
	s_barrier
	v_mfma_f32_16x16x32_bf16 v[12:15], v[84:87], v[226:229], v[12:15]
	v_mfma_f32_16x16x32_bf16 v[12:15], v[80:83], v[222:225], v[12:15]
	s_setprio 0
	s_add_i32 s44, 0, 0x18000
	s_add_i32 s45, 0, 0x1c000
	v_add_u32_e32 v100, s44, v163
	v_add_u32_e32 v156, s45, v163
	ds_read_b128 v[80:83], v100
	ds_read_b128 v[84:87], v100 offset:1024
	ds_read_b128 v[92:95], v100 offset:2048
	ds_read_b128 v[100:103], v100 offset:3072
	ds_read_b128 v[144:147], v156
	ds_read_b128 v[148:151], v156 offset:1024
	ds_read_b128 v[152:155], v156 offset:2048
	ds_read_b128 v[156:159], v156 offset:3072
	s_add_u32 s48, s48, 0x80000
	s_addc_u32 s49, s49, 0
	s_mov_b32 m0, s40
	v_lshl_add_u64 v[236:237], s[48:49], 0, v[164:165]
	ds_read_b128 v[178:181], v187 offset:32768
	ds_read_b128 v[182:185], v187 offset:33792
	ds_read_b128 v[206:209], v187 offset:34816
	ds_read_b128 v[210:213], v187 offset:35840
	ds_read_b128 v[214:217], v187 offset:36864
	ds_read_b128 v[218:221], v187 offset:37888
	ds_read_b128 v[222:225], v187 offset:38912
	ds_read_b128 v[226:229], v187 offset:39936
	global_load_lds_dwordx4 v[236:237], off
	v_lshl_add_u64 v[236:237], s[48:49], 0, v[168:169]
	s_mov_b32 m0, s41
	s_nop 0
	global_load_lds_dwordx4 v[236:237], off
	s_waitcnt vmcnt(8)
	s_waitcnt lgkmcnt(0)
	s_barrier
	s_setprio 1
	s_waitcnt lgkmcnt(0)
	v_mfma_f32_16x16x32_bf16 v[140:143], v[80:83], v[178:181], v[140:143]
	v_mfma_f32_16x16x32_bf16 v[140:143], v[84:87], v[182:185], v[140:143]
	v_mfma_f32_16x16x32_bf16 v[136:139], v[100:103], v[182:185], v[136:139]
	v_mfma_f32_16x16x32_bf16 v[136:139], v[92:95], v[178:181], v[136:139]
	v_mfma_f32_16x16x32_bf16 v[132:135], v[144:147], v[178:181], v[132:135]
	v_mfma_f32_16x16x32_bf16 v[132:135], v[148:151], v[182:185], v[132:135]
	v_mfma_f32_16x16x32_bf16 v[128:131], v[156:159], v[182:185], v[128:131]
	v_mfma_f32_16x16x32_bf16 v[128:131], v[152:155], v[178:181], v[128:131]
	v_mfma_f32_16x16x32_bf16 v[112:115], v[152:155], v[206:209], v[112:115]
	v_mfma_f32_16x16x32_bf16 v[112:115], v[156:159], v[210:213], v[112:115]
	v_mfma_f32_16x16x32_bf16 v[116:119], v[148:151], v[210:213], v[116:119]
	v_mfma_f32_16x16x32_bf16 v[116:119], v[144:147], v[206:209], v[116:119]
	v_mfma_f32_16x16x32_bf16 v[120:123], v[92:95], v[206:209], v[120:123]
	v_mfma_f32_16x16x32_bf16 v[120:123], v[100:103], v[210:213], v[120:123]
	v_mfma_f32_16x16x32_bf16 v[124:127], v[84:87], v[210:213], v[124:127]
	v_mfma_f32_16x16x32_bf16 v[124:127], v[80:83], v[206:209], v[124:127]
	s_setprio 0
	s_setprio 1
	v_mfma_f32_16x16x32_bf16 v[108:111], v[80:83], v[214:217], v[108:111]
	v_mfma_f32_16x16x32_bf16 v[108:111], v[84:87], v[218:221], v[108:111]
	v_mfma_f32_16x16x32_bf16 v[104:107], v[100:103], v[218:221], v[104:107]
	v_mfma_f32_16x16x32_bf16 v[104:107], v[92:95], v[214:217], v[104:107]
	v_mfma_f32_16x16x32_bf16 v[96:99], v[144:147], v[214:217], v[96:99]
	v_mfma_f32_16x16x32_bf16 v[96:99], v[148:151], v[218:221], v[96:99]
	v_mfma_f32_16x16x32_bf16 v[88:91], v[156:159], v[218:221], v[88:91]
	v_mfma_f32_16x16x32_bf16 v[88:91], v[152:155], v[214:217], v[88:91]
	v_mfma_f32_16x16x32_bf16 v[64:67], v[152:155], v[222:225], v[64:67]
	v_mfma_f32_16x16x32_bf16 v[64:67], v[156:159], v[226:229], v[64:67]
	v_mfma_f32_16x16x32_bf16 v[68:71], v[148:151], v[226:229], v[68:71]
	v_mfma_f32_16x16x32_bf16 v[68:71], v[144:147], v[222:225], v[68:71]
	v_mfma_f32_16x16x32_bf16 v[72:75], v[92:95], v[222:225], v[72:75]
	v_mfma_f32_16x16x32_bf16 v[72:75], v[100:103], v[226:229], v[72:75]
	s_setprio 2
	s_barrier
; #define PG8_STAGE(bufoff, gbase, voff) do { _Pragma("unroll") for (int _i = 0; _i < 2; ++_i) \
;         __builtin_amdgcn_global_load_lds((const unsigned*)((const char*)(gbase) + (voff)[_i]), (PG8_LAS unsigned*)(lds + (bufoff) + ldsw + _i * 8192), 16, 0, 0); } while (0)
; #define PG8_LDA(dst, b, h) do { _Pragma("unroll") for (int m = 0; m < 4; ++m) _Pragma("unroll") for (int k = 0; k < 2; ++k) dst[m][k] = *(const PG8_LAS bf16x8*)(lds + PG8_SA(b, h) + aoff + m * 2048 + k * 1024); } while (0)
; #define PG8_LDB(dst, b, h) do { _Pragma("unroll") for (int n = 0; n < 2; ++n) _Pragma("unroll") for (int k = 0; k < 2; ++k) dst[n][k] = *(const PG8_LAS bf16x8*)(lds + PG8_SB(b, h) + boff + n * 2048 + k * 1024); } while (0)
; template <class Epi, class Sched, bool ALIGN_EPI = false, bool SP2 = false>
; __device__ __forceinline__ void gemm_phase(PG8_LAS unsigned char* lds, const Gemm g, const Sched& S, const Epi& E) {
;     ...
;         for (int t = 0; t < nt; t += 2) {
;             const bool last = (t == nt - 2);
;             const char* a1 = cA + (size_t)(t + 1) * kstep;
;             const char* a2 = last ? nA : cA + (size_t)(t + 2) * kstep; const char* b2 = last ? nB : cB + (size_t)(t + 2) * kstep;
;             const char* a3 = a2 + kstep; const char* b3 = b2 + kstep;
;             if (last && has_next) S.a_ready(nxt);
;             if constexpr (SP2) {
;             PG8_LDB(B0, 0, 0); PG8_LDB(B1, 0, 1); PG8_SCHED; PG8_LDA(At, 0, 0); PG8_STAGE(PG8_SA(1, 1), a1 + hstep, voffA);
;             PG8_WAIT_V(8); PG8_WAIT_L(0); PG8_BAR; PG8_MMA(0, 0, At, B0); PG8_MMA(0, 1, At, B1); PG8_BAR; PG8_SCHED;
;             PG8_LDA(At, 0, 1); PG8_STAGE(PG8_SB(0, 0), b2, voffB); PG8_STAGE(PG8_SB(0, 1), b2 + hstep, voffB); PG8_STAGE(PG8_SA(0, 0), a2, voffA);
;             PG8_WAIT_V(8); PG8_WAIT_L(0); PG8_BAR; PG8_MMA(1, 0, At, B0); PG8_MMA(1, 1, At, B1); PG8_BAR; PG8_SCHED;
;             PG8_LDB(B0, 1, 0); PG8_LDB(B1, 1, 1); PG8_SCHED; PG8_LDA(At, 1, 0); PG8_STAGE(PG8_SA(0, 1), a2 + hstep, voffA);
;             PG8_WAIT_V(8); PG8_WAIT_L(0); PG8_BAR; PG8_MMA(0, 0, At, B0); PG8_MMA(0, 1, At, B1); PG8_BAR; PG8_SCHED;
;             PG8_LDA(At, 1, 1); PG8_STAGE(PG8_SB(1, 0), b3, voffB); PG8_STAGE(PG8_SB(1, 1), b3 + hstep, voffB); PG8_STAGE(PG8_SA(1, 0), a3, voffA);
;             PG8_WAIT_V(8); PG8_WAIT_L(0); PG8_BAR; PG8_MMA(1, 0, At, B0); PG8_MMA(1, 1, At, B1); PG8_BAR; PG8_SCHED;
	v_mfma_f32_16x16x32_bf16 v[76:79], v[84:87], v[226:229], v[76:79]
	v_mfma_f32_16x16x32_bf16 v[76:79], v[80:83], v[222:225], v[76:79]
	s_setprio 0
	s_add_i32 s44, s44, s13
	v_lshl_add_u64 v[200:201], v[200:201], 0, s[16:17]
	s_mov_b32 m0, s44
	ds_read_b128 v[178:181], v187 offset:49152
	ds_read_b128 v[182:185], v187 offset:50176
	ds_read_b128 v[206:209], v187 offset:51200
	ds_read_b128 v[210:213], v187 offset:52224
	ds_read_b128 v[214:217], v187 offset:53248
	ds_read_b128 v[218:221], v187 offset:54272
	ds_read_b128 v[222:225], v187 offset:55296
	ds_read_b128 v[226:229], v187 offset:56320
	global_load_lds_dwordx4 v[200:201], off
	s_add_i32 m0, s44, 0x2000
	s_add_u32 s28, s28, 0x80080
	v_lshl_add_u64 v[200:201], v[230:231], 0, s[16:17]
	s_addc_u32 s29, s29, 0
	s_add_i32 s44, s45, s13
	global_load_lds_dwordx4 v[200:201], off
	v_lshl_add_u64 v[200:201], s[28:29], 0, v[164:165]
	s_mov_b32 m0, s44
	s_nop 0
	global_load_lds_dwordx4 v[200:201], off
	v_lshl_add_u64 v[200:201], s[28:29], 0, v[168:169]
	s_add_i32 m0, s44, 0x2000
	s_nop 0
	global_load_lds_dwordx4 v[200:201], off
	v_lshl_add_u64 v[200:201], v[232:233], 0, s[16:17]
	s_mov_b32 m0, s56
	s_nop 0
	global_load_lds_dwordx4 v[200:201], off
	v_lshl_add_u64 v[200:201], v[234:235], 0, s[16:17]
	s_mov_b32 m0, s57
	s_nop 0
	global_load_lds_dwordx4 v[200:201], off
	s_add_i32 s77, s77, 2
	s_add_u32 s74, s74, 0x100
	s_addc_u32 s75, s75, 0
	s_add_u32 s73, s73, 0x100
	s_addc_u32 s76, s76, 0
	s_waitcnt vmcnt(8)
	s_waitcnt lgkmcnt(0)
	s_barrier
	s_setprio 1
	s_waitcnt lgkmcnt(0)
	v_mfma_f32_16x16x32_bf16 v[60:63], v[80:83], v[178:181], v[60:63]
	v_mfma_f32_16x16x32_bf16 v[60:63], v[84:87], v[182:185], v[60:63]
	v_mfma_f32_16x16x32_bf16 v[56:59], v[100:103], v[182:185], v[56:59]
	v_mfma_f32_16x16x32_bf16 v[56:59], v[92:95], v[178:181], v[56:59]
	v_mfma_f32_16x16x32_bf16 v[52:55], v[144:147], v[178:181], v[52:55]
	v_mfma_f32_16x16x32_bf16 v[52:55], v[148:151], v[182:185], v[52:55]
	v_mfma_f32_16x16x32_bf16 v[48:51], v[156:159], v[182:185], v[48:51]
	v_mfma_f32_16x16x32_bf16 v[48:51], v[152:155], v[178:181], v[48:51]
	v_mfma_f32_16x16x32_bf16 v[32:35], v[152:155], v[206:209], v[32:35]
	v_mfma_f32_16x16x32_bf16 v[32:35], v[156:159], v[210:213], v[32:35]
	v_mfma_f32_16x16x32_bf16 v[36:39], v[148:151], v[210:213], v[36:39]
	v_mfma_f32_16x16x32_bf16 v[36:39], v[144:147], v[206:209], v[36:39]
	v_mfma_f32_16x16x32_bf16 v[40:43], v[92:95], v[206:209], v[40:43]
	v_mfma_f32_16x16x32_bf16 v[40:43], v[100:103], v[210:213], v[40:43]
	v_mfma_f32_16x16x32_bf16 v[44:47], v[84:87], v[210:213], v[44:47]
	v_mfma_f32_16x16x32_bf16 v[44:47], v[80:83], v[206:209], v[44:47]
	s_setprio 0
	s_setprio 1
	v_mfma_f32_16x16x32_bf16 v[28:31], v[80:83], v[214:217], v[28:31]
	v_mfma_f32_16x16x32_bf16 v[28:31], v[84:87], v[218:221], v[28:31]
	v_mfma_f32_16x16x32_bf16 v[24:27], v[100:103], v[218:221], v[24:27]
	v_mfma_f32_16x16x32_bf16 v[24:27], v[92:95], v[214:217], v[24:27]
	v_mfma_f32_16x16x32_bf16 v[20:23], v[144:147], v[214:217], v[20:23]
	v_mfma_f32_16x16x32_bf16 v[20:23], v[148:151], v[218:221], v[20:23]
	v_mfma_f32_16x16x32_bf16 v[16:19], v[156:159], v[218:221], v[16:19]
	v_mfma_f32_16x16x32_bf16 v[16:19], v[152:155], v[214:217], v[16:19]
	v_mfma_f32_16x16x32_bf16 v[0:3], v[152:155], v[222:225], v[0:3]
	v_mfma_f32_16x16x32_bf16 v[0:3], v[156:159], v[226:229], v[0:3]
	v_mfma_f32_16x16x32_bf16 v[4:7], v[148:151], v[226:229], v[4:7]
	v_mfma_f32_16x16x32_bf16 v[4:7], v[144:147], v[222:225], v[4:7]
	v_mfma_f32_16x16x32_bf16 v[8:11], v[92:95], v[222:225], v[8:11]
	v_mfma_f32_16x16x32_bf16 v[8:11], v[100:103], v[226:229], v[8:11]
	s_setprio 2
	s_barrier
	v_mfma_f32_16x16x32_bf16 v[12:15], v[84:87], v[226:229], v[12:15]
	v_mfma_f32_16x16x32_bf16 v[12:15], v[80:83], v[222:225], v[12:15]
	s_setprio 0
	s_cmp_gt_u32 s77, 29
	s_cbranch_scc0 .LBB0_362
	s_and_b64 vcc, exec, s[18:19]
	s_cbranch_vccz .LBB0_365
	s_barrier

; #define PG8_STAGE(bufoff, gbase, voff) do { _Pragma("unroll") for (int _i = 0; _i < 2; ++_i) \
;         __builtin_amdgcn_global_load_lds((const unsigned*)((const char*)(gbase) + (voff)[_i]), (PG8_LAS unsigned*)(lds + (bufoff) + ldsw + _i * 8192), 16, 0, 0); } while (0)
; #define PG8_LDA(dst, b, h) do { _Pragma("unroll") for (int m = 0; m < 4; ++m) _Pragma("unroll") for (int k = 0; k < 2; ++k) dst[m][k] = *(const PG8_LAS bf16x8*)(lds + PG8_SA(b, h) + aoff + m * 2048 + k * 1024); } while (0)
; #define PG8_LDB(dst, b, h) do { _Pragma("unroll") for (int n = 0; n < 2; ++n) _Pragma("unroll") for (int k = 0; k < 2; ++k) dst[n][k] = *(const PG8_LAS bf16x8*)(lds + PG8_SB(b, h) + boff + n * 2048 + k * 1024); } while (0)
; template <class Epi, class Sched, bool ALIGN_EPI = false, bool SP2 = false>
; __device__ __forceinline__ void gemm_phase(PG8_LAS unsigned char* lds, const Gemm g, const Sched& S, const Epi& E) {
;     ...
;         for (int t = 0; t < nt; t += 2) {
;             const bool last = (t == nt - 2);
;             const char* a1 = cA + (size_t)(t + 1) * kstep;
;             const char* a2 = last ? nA : cA + (size_t)(t + 2) * kstep; const char* b2 = last ? nB : cB + (size_t)(t + 2) * kstep;
;             const char* a3 = a2 + kstep; const char* b3 = b2 + kstep;
;             if (last && has_next) S.a_ready(nxt);
;             if constexpr (SP2) {
;             PG8_LDB(B0, 0, 0); PG8_LDB(B1, 0, 1); PG8_SCHED; PG8_LDA(At, 0, 0); PG8_STAGE(PG8_SA(1, 1), a1 + hstep, voffA);
;             PG8_WAIT_V(8); PG8_WAIT_L(0); PG8_BAR; PG8_MMA(0, 0, At, B0); PG8_MMA(0, 1, At, B1); PG8_BAR; PG8_SCHED;
;             PG8_LDA(At, 0, 1); PG8_STAGE(PG8_SB(0, 0), b2, voffB); PG8_STAGE(PG8_SB(0, 1), b2 + hstep, voffB); PG8_STAGE(PG8_SA(0, 0), a2, voffA);
;             PG8_WAIT_V(8); PG8_WAIT_L(0); PG8_BAR; PG8_MMA(1, 0, At, B0); PG8_MMA(1, 1, At, B1); PG8_BAR; PG8_SCHED;
;             PG8_LDB(B0, 1, 0); PG8_LDB(B1, 1, 1); PG8_SCHED; PG8_LDA(At, 1, 0); PG8_STAGE(PG8_SA(0, 1), a2 + hstep, voffA);
;             PG8_WAIT_V(8); PG8_WAIT_L(0); PG8_BAR; PG8_MMA(0, 0, At, B0); PG8_MMA(0, 1, At, B1); PG8_BAR; PG8_SCHED;
;             PG8_LDA(At, 1, 1); PG8_STAGE(PG8_SB(1, 0), b3, voffB); PG8_STAGE(PG8_SB(1, 1), b3 + hstep, voffB); PG8_STAGE(PG8_SA(1, 0), a3, voffA);
;             PG8_WAIT_V(8); PG8_WAIT_L(0); PG8_BAR; PG8_MMA(1, 0, At, B0); PG8_MMA(1, 1, At, B1); PG8_BAR; PG8_SCHED;
.LBB0_416:
	ds_read_b128 v[136:139], v156
	ds_read_b128 v[140:143], v156 offset:1024
	ds_read_b128 v[172:175], v156 offset:2048
	ds_read_b128 v[176:179], v156 offset:3072
	ds_read_b128 v[180:183], v157
	ds_read_b128 v[184:187], v157 offset:1024
	ds_read_b128 v[206:209], v157 offset:2048
	ds_read_b128 v[210:213], v157 offset:3072
	s_add_u32 s28, s68, 0xfff80080
	s_addc_u32 s29, s69, -1
	s_cmp_eq_u32 s79, 28
	s_cselect_b32 s49, s34, s29
	s_cselect_b32 s48, s35, s28
	s_cselect_b32 s29, s23, s78
	s_cselect_b32 s28, s63, s77
	v_lshl_add_u64 v[200:201], s[68:69], 0, v[128:129]
	s_add_i32 m0, s15, 0xc000
	ds_read_b128 v[214:217], v158
	ds_read_b128 v[218:221], v158 offset:1024
	ds_read_b128 v[222:225], v158 offset:2048
	ds_read_b128 v[226:229], v158 offset:3072
	ds_read_b128 v[230:233], v158 offset:4096
	ds_read_b128 v[234:237], v158 offset:5120
	ds_read_b128 v[238:241], v158 offset:6144
	ds_read_b128 v[242:245], v158 offset:7168
	global_load_lds_dwordx4 v[200:201], off
	v_lshl_add_u64 v[200:201], s[68:69], 0, v[130:131]
	s_add_i32 m0, s15, 0xe000
	s_nop 0
	global_load_lds_dwordx4 v[200:201], off
	s_waitcnt vmcnt(8)
	s_waitcnt lgkmcnt(0)
	s_barrier
	s_setprio 1
	s_waitcnt lgkmcnt(0)
	v_mfma_f32_16x16x32_bf16 v[124:127], v[136:139], v[214:217], v[124:127]
	v_mfma_f32_16x16x32_bf16 v[124:127], v[140:143], v[218:221], v[124:127]
	v_mfma_f32_16x16x32_bf16 v[120:123], v[176:179], v[218:221], v[120:123]
	v_mfma_f32_16x16x32_bf16 v[120:123], v[172:175], v[214:217], v[120:123]
	v_mfma_f32_16x16x32_bf16 v[116:119], v[180:183], v[214:217], v[116:119]
	v_mfma_f32_16x16x32_bf16 v[116:119], v[184:187], v[218:221], v[116:119]
	v_mfma_f32_16x16x32_bf16 v[112:115], v[210:213], v[218:221], v[112:115]
	v_mfma_f32_16x16x32_bf16 v[112:115], v[206:209], v[214:217], v[112:115]
	v_mfma_f32_16x16x32_bf16 v[92:95], v[206:209], v[222:225], v[92:95]
	v_mfma_f32_16x16x32_bf16 v[92:95], v[210:213], v[226:229], v[92:95]
	v_mfma_f32_16x16x32_bf16 v[100:103], v[184:187], v[226:229], v[100:103]
	v_mfma_f32_16x16x32_bf16 v[100:103], v[180:183], v[222:225], v[100:103]
	v_mfma_f32_16x16x32_bf16 v[104:107], v[172:175], v[222:225], v[104:107]
	v_mfma_f32_16x16x32_bf16 v[104:107], v[176:179], v[226:229], v[104:107]
	v_mfma_f32_16x16x32_bf16 v[108:111], v[140:143], v[226:229], v[108:111]
	v_mfma_f32_16x16x32_bf16 v[108:111], v[136:139], v[222:225], v[108:111]
	s_setprio 0
	s_setprio 1
	v_mfma_f32_16x16x32_bf16 v[96:99], v[136:139], v[230:233], v[96:99]
	v_mfma_f32_16x16x32_bf16 v[96:99], v[140:143], v[234:237], v[96:99]
	v_mfma_f32_16x16x32_bf16 v[88:91], v[176:179], v[234:237], v[88:91]
	v_mfma_f32_16x16x32_bf16 v[88:91], v[172:175], v[230:233], v[88:91]
	v_mfma_f32_16x16x32_bf16 v[84:87], v[180:183], v[230:233], v[84:87]
	v_mfma_f32_16x16x32_bf16 v[84:87], v[184:187], v[234:237], v[84:87]
	v_mfma_f32_16x16x32_bf16 v[76:79], v[210:213], v[234:237], v[76:79]
	v_mfma_f32_16x16x32_bf16 v[76:79], v[206:209], v[230:233], v[76:79]
	v_mfma_f32_16x16x32_bf16 v[64:67], v[206:209], v[238:241], v[64:67]
	v_mfma_f32_16x16x32_bf16 v[64:67], v[210:213], v[242:245], v[64:67]
	v_mfma_f32_16x16x32_bf16 v[68:71], v[184:187], v[242:245], v[68:71]
	v_mfma_f32_16x16x32_bf16 v[68:71], v[180:183], v[238:241], v[68:71]
	v_mfma_f32_16x16x32_bf16 v[72:75], v[172:175], v[238:241], v[72:75]
	v_mfma_f32_16x16x32_bf16 v[72:75], v[176:179], v[242:245], v[72:75]
	s_setprio 2
	s_barrier
	v_mfma_f32_16x16x32_bf16 v[80:83], v[140:143], v[242:245], v[80:83]
	v_mfma_f32_16x16x32_bf16 v[80:83], v[136:139], v[238:241], v[80:83]
	s_setprio 0
	s_add_i32 s44, s72, s39
	v_lshl_add_u64 v[200:201], s[28:29], 0, v[166:167]
	s_mov_b32 m0, s44
	ds_read_b128 v[214:217], v158 offset:16384
	ds_read_b128 v[218:221], v158 offset:17408
	ds_read_b128 v[222:225], v158 offset:18432
	ds_read_b128 v[226:229], v158 offset:19456
	ds_read_b128 v[230:233], v158 offset:20480
	ds_read_b128 v[234:237], v158 offset:21504
	ds_read_b128 v[238:241], v158 offset:22528
	ds_read_b128 v[242:245], v158 offset:23552
	global_load_lds_dwordx4 v[200:201], off
	s_add_i32 m0, s44, 0x2000
	s_add_u32 s80, s28, 0x80000
	v_lshl_add_u64 v[246:247], s[28:29], 0, v[170:171]
	s_addc_u32 s81, s29, 0
	s_add_i32 s44, s73, s39
	global_load_lds_dwordx4 v[246:247], off
	v_lshl_add_u64 v[248:249], s[80:81], 0, v[166:167]
	s_mov_b32 m0, s44
	v_lshl_add_u64 v[250:251], s[48:49], 0, v[168:169]
	global_load_lds_dwordx4 v[248:249], off
	v_lshl_add_u64 v[248:249], s[80:81], 0, v[170:171]
	s_add_i32 m0, s44, 0x2000
	s_nop 0
	global_load_lds_dwordx4 v[248:249], off
	v_lshl_add_u64 v[248:249], s[48:49], 0, v[164:165]
	s_mov_b32 m0, s15
	s_nop 0
	global_load_lds_dwordx4 v[248:249], off
	s_mov_b32 m0, s41
	s_nop 0
	global_load_lds_dwordx4 v[250:251], off
	s_waitcnt vmcnt(8)
	s_waitcnt lgkmcnt(0)
	s_barrier
; #define PG8_STAGE(bufoff, gbase, voff) do { _Pragma("unroll") for (int _i = 0; _i < 2; ++_i) \
;         __builtin_amdgcn_global_load_lds((const unsigned*)((const char*)(gbase) + (voff)[_i]), (PG8_LAS unsigned*)(lds + (bufoff) + ldsw + _i * 8192), 16, 0, 0); } while (0)
; #define PG8_LDA(dst, b, h) do { _Pragma("unroll") for (int m = 0; m < 4; ++m) _Pragma("unroll") for (int k = 0; k < 2; ++k) dst[m][k] = *(const PG8_LAS bf16x8*)(lds + PG8_SA(b, h) + aoff + m * 2048 + k * 1024); } while (0)
; #define PG8_LDB(dst, b, h) do { _Pragma("unroll") for (int n = 0; n < 2; ++n) _Pragma("unroll") for (int k = 0; k < 2; ++k) dst[n][k] = *(const PG8_LAS bf16x8*)(lds + PG8_SB(b, h) + boff + n * 2048 + k * 1024); } while (0)
; template <class Epi, class Sched, bool ALIGN_EPI = false, bool SP2 = false>
; __device__ __forceinline__ void gemm_phase(PG8_LAS unsigned char* lds, const Gemm g, const Sched& S, const Epi& E) {
;     ...
;         for (int t = 0; t < nt; t += 2) {
;             const bool last = (t == nt - 2);
;             const char* a1 = cA + (size_t)(t + 1) * kstep;
;             const char* a2 = last ? nA : cA + (size_t)(t + 2) * kstep; const char* b2 = last ? nB : cB + (size_t)(t + 2) * kstep;
;             const char* a3 = a2 + kstep; const char* b3 = b2 + kstep;
;             if (last && has_next) S.a_ready(nxt);
;             if constexpr (SP2) {
;             PG8_LDB(B0, 0, 0); PG8_LDB(B1, 0, 1); PG8_SCHED; PG8_LDA(At, 0, 0); PG8_STAGE(PG8_SA(1, 1), a1 + hstep, voffA);
;             PG8_WAIT_V(8); PG8_WAIT_L(0); PG8_BAR; PG8_MMA(0, 0, At, B0); PG8_MMA(0, 1, At, B1); PG8_BAR; PG8_SCHED;
;             PG8_LDA(At, 0, 1); PG8_STAGE(PG8_SB(0, 0), b2, voffB); PG8_STAGE(PG8_SB(0, 1), b2 + hstep, voffB); PG8_STAGE(PG8_SA(0, 0), a2, voffA);
;             PG8_WAIT_V(8); PG8_WAIT_L(0); PG8_BAR; PG8_MMA(1, 0, At, B0); PG8_MMA(1, 1, At, B1); PG8_BAR; PG8_SCHED;
;             PG8_LDB(B0, 1, 0); PG8_LDB(B1, 1, 1); PG8_SCHED; PG8_LDA(At, 1, 0); PG8_STAGE(PG8_SA(0, 1), a2 + hstep, voffA);
;             PG8_WAIT_V(8); PG8_WAIT_L(0); PG8_BAR; PG8_MMA(0, 0, At, B0); PG8_MMA(0, 1, At, B1); PG8_BAR; PG8_SCHED;
;             PG8_LDA(At, 1, 1); PG8_STAGE(PG8_SB(1, 0), b3, voffB); PG8_STAGE(PG8_SB(1, 1), b3 + hstep, voffB); PG8_STAGE(PG8_SA(1, 0), a3, voffA);
;             PG8_WAIT_V(8); PG8_WAIT_L(0); PG8_BAR; PG8_MMA(1, 0, At, B0); PG8_MMA(1, 1, At, B1); PG8_BAR; PG8_SCHED;
	s_setprio 1
	s_waitcnt lgkmcnt(0)
	v_mfma_f32_16x16x32_bf16 v[60:63], v[136:139], v[214:217], v[60:63]
	v_mfma_f32_16x16x32_bf16 v[60:63], v[140:143], v[218:221], v[60:63]
	v_mfma_f32_16x16x32_bf16 v[56:59], v[176:179], v[218:221], v[56:59]
	v_mfma_f32_16x16x32_bf16 v[56:59], v[172:175], v[214:217], v[56:59]
	v_mfma_f32_16x16x32_bf16 v[52:55], v[180:183], v[214:217], v[52:55]
	v_mfma_f32_16x16x32_bf16 v[52:55], v[184:187], v[218:221], v[52:55]
	v_mfma_f32_16x16x32_bf16 v[44:47], v[210:213], v[218:221], v[44:47]
	v_mfma_f32_16x16x32_bf16 v[44:47], v[206:209], v[214:217], v[44:47]
	v_mfma_f32_16x16x32_bf16 v[28:31], v[206:209], v[222:225], v[28:31]
	v_mfma_f32_16x16x32_bf16 v[28:31], v[210:213], v[226:229], v[28:31]
	v_mfma_f32_16x16x32_bf16 v[36:39], v[184:187], v[226:229], v[36:39]
	v_mfma_f32_16x16x32_bf16 v[36:39], v[180:183], v[222:225], v[36:39]
	v_mfma_f32_16x16x32_bf16 v[40:43], v[172:175], v[222:225], v[40:43]
	v_mfma_f32_16x16x32_bf16 v[40:43], v[176:179], v[226:229], v[40:43]
	v_mfma_f32_16x16x32_bf16 v[48:51], v[140:143], v[226:229], v[48:51]
	v_mfma_f32_16x16x32_bf16 v[48:51], v[136:139], v[222:225], v[48:51]
	s_setprio 0
	s_setprio 1
	v_mfma_f32_16x16x32_bf16 v[32:35], v[136:139], v[230:233], v[32:35]
	v_mfma_f32_16x16x32_bf16 v[32:35], v[140:143], v[234:237], v[32:35]
	v_mfma_f32_16x16x32_bf16 v[24:27], v[176:179], v[234:237], v[24:27]
	v_mfma_f32_16x16x32_bf16 v[24:27], v[172:175], v[230:233], v[24:27]
	v_mfma_f32_16x16x32_bf16 v[20:23], v[180:183], v[230:233], v[20:23]
	v_mfma_f32_16x16x32_bf16 v[20:23], v[184:187], v[234:237], v[20:23]
	v_mfma_f32_16x16x32_bf16 v[16:19], v[210:213], v[234:237], v[16:19]
	v_mfma_f32_16x16x32_bf16 v[16:19], v[206:209], v[230:233], v[16:19]
	v_mfma_f32_16x16x32_bf16 v[0:3], v[206:209], v[238:241], v[0:3]
	v_mfma_f32_16x16x32_bf16 v[0:3], v[210:213], v[242:245], v[0:3]
	v_mfma_f32_16x16x32_bf16 v[4:7], v[184:187], v[242:245], v[4:7]
	v_mfma_f32_16x16x32_bf16 v[4:7], v[180:183], v[238:241], v[4:7]
	v_mfma_f32_16x16x32_bf16 v[8:11], v[172:175], v[238:241], v[8:11]
	v_mfma_f32_16x16x32_bf16 v[8:11], v[176:179], v[242:245], v[8:11]
	s_setprio 2
	s_barrier
	v_mfma_f32_16x16x32_bf16 v[12:15], v[140:143], v[242:245], v[12:15]
	v_mfma_f32_16x16x32_bf16 v[12:15], v[136:139], v[238:241], v[12:15]
	s_setprio 0
	s_add_i32 s44, 0, 0x18000
	v_add_u32_e32 v144, s44, v146
	s_add_i32 s45, 0, 0x1c000
	ds_read_b128 v[136:139], v144
	ds_read_b128 v[140:143], v144 offset:1024
	ds_read_b128 v[172:175], v144 offset:2048
	ds_read_b128 v[176:179], v144 offset:3072
	v_add_u32_e32 v144, s45, v146
	ds_read_b128 v[180:183], v144
	ds_read_b128 v[184:187], v144 offset:1024
	ds_read_b128 v[206:209], v144 offset:2048
	ds_read_b128 v[210:213], v144 offset:3072
	s_add_u32 s48, s48, 0x80000
	s_addc_u32 s49, s49, 0
	s_mov_b32 m0, s56
	v_lshl_add_u64 v[252:253], s[48:49], 0, v[164:165]
	ds_read_b128 v[214:217], v158 offset:32768
	ds_read_b128 v[218:221], v158 offset:33792
	ds_read_b128 v[222:225], v158 offset:34816
	ds_read_b128 v[226:229], v158 offset:35840
	ds_read_b128 v[230:233], v158 offset:36864
	ds_read_b128 v[234:237], v158 offset:37888
	ds_read_b128 v[238:241], v158 offset:38912
	ds_read_b128 v[242:245], v158 offset:39936
	global_load_lds_dwordx4 v[252:253], off
	v_lshl_add_u64 v[252:253], s[48:49], 0, v[168:169]
	s_mov_b32 m0, s57
	s_nop 0
	global_load_lds_dwordx4 v[252:253], off
	s_waitcnt vmcnt(8)
	s_waitcnt lgkmcnt(0)
	s_barrier
	s_setprio 1
	s_waitcnt lgkmcnt(0)
	v_mfma_f32_16x16x32_bf16 v[124:127], v[136:139], v[214:217], v[124:127]
	v_mfma_f32_16x16x32_bf16 v[124:127], v[140:143], v[218:221], v[124:127]
	v_mfma_f32_16x16x32_bf16 v[120:123], v[176:179], v[218:221], v[120:123]
	v_mfma_f32_16x16x32_bf16 v[120:123], v[172:175], v[214:217], v[120:123]
	v_mfma_f32_16x16x32_bf16 v[116:119], v[180:183], v[214:217], v[116:119]
	v_mfma_f32_16x16x32_bf16 v[116:119], v[184:187], v[218:221], v[116:119]
	v_mfma_f32_16x16x32_bf16 v[112:115], v[210:213], v[218:221], v[112:115]
	v_mfma_f32_16x16x32_bf16 v[112:115], v[206:209], v[214:217], v[112:115]
	v_mfma_f32_16x16x32_bf16 v[92:95], v[206:209], v[222:225], v[92:95]
	v_mfma_f32_16x16x32_bf16 v[92:95], v[210:213], v[226:229], v[92:95]
	v_mfma_f32_16x16x32_bf16 v[100:103], v[184:187], v[226:229], v[100:103]
	v_mfma_f32_16x16x32_bf16 v[100:103], v[180:183], v[222:225], v[100:103]
	v_mfma_f32_16x16x32_bf16 v[104:107], v[172:175], v[222:225], v[104:107]
	v_mfma_f32_16x16x32_bf16 v[104:107], v[176:179], v[226:229], v[104:107]
	v_mfma_f32_16x16x32_bf16 v[108:111], v[140:143], v[226:229], v[108:111]
	v_mfma_f32_16x16x32_bf16 v[108:111], v[136:139], v[222:225], v[108:111]
	s_setprio 0
	s_setprio 1
	v_mfma_f32_16x16x32_bf16 v[96:99], v[136:139], v[230:233], v[96:99]
	v_mfma_f32_16x16x32_bf16 v[96:99], v[140:143], v[234:237], v[96:99]
	v_mfma_f32_16x16x32_bf16 v[88:91], v[176:179], v[234:237], v[88:91]
	v_mfma_f32_16x16x32_bf16 v[88:91], v[172:175], v[230:233], v[88:91]
	v_mfma_f32_16x16x32_bf16 v[84:87], v[180:183], v[230:233], v[84:87]
	v_mfma_f32_16x16x32_bf16 v[84:87], v[184:187], v[234:237], v[84:87]
	v_mfma_f32_16x16x32_bf16 v[76:79], v[210:213], v[234:237], v[76:79]
	v_mfma_f32_16x16x32_bf16 v[76:79], v[206:209], v[230:233], v[76:79]
	v_mfma_f32_16x16x32_bf16 v[64:67], v[206:209], v[238:241], v[64:67]
	v_mfma_f32_16x16x32_bf16 v[64:67], v[210:213], v[242:245], v[64:67]
	v_mfma_f32_16x16x32_bf16 v[68:71], v[184:187], v[242:245], v[68:71]
	v_mfma_f32_16x16x32_bf16 v[68:71], v[180:183], v[238:241], v[68:71]
	v_mfma_f32_16x16x32_bf16 v[72:75], v[172:175], v[238:241], v[72:75]
	v_mfma_f32_16x16x32_bf16 v[72:75], v[176:179], v[242:245], v[72:75]
	s_setprio 2
	s_barrier
; #define PG8_STAGE(bufoff, gbase, voff) do { _Pragma("unroll") for (int _i = 0; _i < 2; ++_i) \
;         __builtin_amdgcn_global_load_lds((const unsigned*)((const char*)(gbase) + (voff)[_i]), (PG8_LAS unsigned*)(lds + (bufoff) + ldsw + _i * 8192), 16, 0, 0); } while (0)
; #define PG8_LDA(dst, b, h) do { _Pragma("unroll") for (int m = 0; m < 4; ++m) _Pragma("unroll") for (int k = 0; k < 2; ++k) dst[m][k] = *(const PG8_LAS bf16x8*)(lds + PG8_SA(b, h) + aoff + m * 2048 + k * 1024); } while (0)
; #define PG8_LDB(dst, b, h) do { _Pragma("unroll") for (int n = 0; n < 2; ++n) _Pragma("unroll") for (int k = 0; k < 2; ++k) dst[n][k] = *(const PG8_LAS bf16x8*)(lds + PG8_SB(b, h) + boff + n * 2048 + k * 1024); } while (0)
; template <class Epi, class Sched, bool ALIGN_EPI = false, bool SP2 = false>
; __device__ __forceinline__ void gemm_phase(PG8_LAS unsigned char* lds, const Gemm g, const Sched& S, const Epi& E) {
;     ...
;         for (int t = 0; t < nt; t += 2) {
;             const bool last = (t == nt - 2);
;             const char* a1 = cA + (size_t)(t + 1) * kstep;
;             const char* a2 = last ? nA : cA + (size_t)(t + 2) * kstep; const char* b2 = last ? nB : cB + (size_t)(t + 2) * kstep;
;             const char* a3 = a2 + kstep; const char* b3 = b2 + kstep;
;             if (last && has_next) S.a_ready(nxt);
;             if constexpr (SP2) {
;             PG8_LDB(B0, 0, 0); PG8_LDB(B1, 0, 1); PG8_SCHED; PG8_LDA(At, 0, 0); PG8_STAGE(PG8_SA(1, 1), a1 + hstep, voffA);
;             PG8_WAIT_V(8); PG8_WAIT_L(0); PG8_BAR; PG8_MMA(0, 0, At, B0); PG8_MMA(0, 1, At, B1); PG8_BAR; PG8_SCHED;
;             PG8_LDA(At, 0, 1); PG8_STAGE(PG8_SB(0, 0), b2, voffB); PG8_STAGE(PG8_SB(0, 1), b2 + hstep, voffB); PG8_STAGE(PG8_SA(0, 0), a2, voffA);
;             PG8_WAIT_V(8); PG8_WAIT_L(0); PG8_BAR; PG8_MMA(1, 0, At, B0); PG8_MMA(1, 1, At, B1); PG8_BAR; PG8_SCHED;
;             PG8_LDB(B0, 1, 0); PG8_LDB(B1, 1, 1); PG8_SCHED; PG8_LDA(At, 1, 0); PG8_STAGE(PG8_SA(0, 1), a2 + hstep, voffA);
;             PG8_WAIT_V(8); PG8_WAIT_L(0); PG8_BAR; PG8_MMA(0, 0, At, B0); PG8_MMA(0, 1, At, B1); PG8_BAR; PG8_SCHED;
;             PG8_LDA(At, 1, 1); PG8_STAGE(PG8_SB(1, 0), b3, voffB); PG8_STAGE(PG8_SB(1, 1), b3 + hstep, voffB); PG8_STAGE(PG8_SA(1, 0), a3, voffA);
;             PG8_WAIT_V(8); PG8_WAIT_L(0); PG8_BAR; PG8_MMA(1, 0, At, B0); PG8_MMA(1, 1, At, B1); PG8_BAR; PG8_SCHED;
	v_mfma_f32_16x16x32_bf16 v[80:83], v[140:143], v[242:245], v[80:83]
	v_mfma_f32_16x16x32_bf16 v[80:83], v[136:139], v[238:241], v[80:83]
	s_setprio 0
	s_add_i32 s44, s44, s39
	v_lshl_add_u64 v[200:201], v[200:201], 0, s[18:19]
	s_mov_b32 m0, s44
	ds_read_b128 v[214:217], v158 offset:49152
	ds_read_b128 v[218:221], v158 offset:50176
	ds_read_b128 v[222:225], v158 offset:51200
	ds_read_b128 v[226:229], v158 offset:52224
	ds_read_b128 v[230:233], v158 offset:53248
	ds_read_b128 v[234:237], v158 offset:54272
	ds_read_b128 v[238:241], v158 offset:55296
	ds_read_b128 v[242:245], v158 offset:56320
	global_load_lds_dwordx4 v[200:201], off
	s_add_i32 m0, s44, 0x2000
	s_add_u32 s28, s28, 0x80080
	v_lshl_add_u64 v[200:201], v[246:247], 0, s[18:19]
	s_addc_u32 s29, s29, 0
	s_add_i32 s44, s45, s39
	global_load_lds_dwordx4 v[200:201], off
	v_lshl_add_u64 v[200:201], s[28:29], 0, v[166:167]
	s_mov_b32 m0, s44
	s_nop 0
	global_load_lds_dwordx4 v[200:201], off
	v_lshl_add_u64 v[200:201], s[28:29], 0, v[170:171]
	s_add_i32 m0, s44, 0x2000
	s_nop 0
	global_load_lds_dwordx4 v[200:201], off
	v_lshl_add_u64 v[200:201], v[248:249], 0, s[18:19]
	s_mov_b32 m0, s70
	s_nop 0
	global_load_lds_dwordx4 v[200:201], off
	v_lshl_add_u64 v[200:201], v[250:251], 0, s[18:19]
	s_mov_b32 m0, s71
	s_nop 0
	global_load_lds_dwordx4 v[200:201], off
	s_add_i32 s79, s79, 2
	s_add_u32 s68, s68, 0x100
	s_addc_u32 s69, s69, 0
	s_add_u32 s77, s77, 0x100
	s_addc_u32 s78, s78, 0
	s_waitcnt vmcnt(8)
	s_waitcnt lgkmcnt(0)
	s_barrier
	s_setprio 1
	s_waitcnt lgkmcnt(0)
	v_mfma_f32_16x16x32_bf16 v[60:63], v[136:139], v[214:217], v[60:63]
	v_mfma_f32_16x16x32_bf16 v[60:63], v[140:143], v[218:221], v[60:63]
	v_mfma_f32_16x16x32_bf16 v[56:59], v[176:179], v[218:221], v[56:59]
	v_mfma_f32_16x16x32_bf16 v[56:59], v[172:175], v[214:217], v[56:59]
	v_mfma_f32_16x16x32_bf16 v[52:55], v[180:183], v[214:217], v[52:55]
	v_mfma_f32_16x16x32_bf16 v[52:55], v[184:187], v[218:221], v[52:55]
	v_mfma_f32_16x16x32_bf16 v[44:47], v[210:213], v[218:221], v[44:47]
	v_mfma_f32_16x16x32_bf16 v[44:47], v[206:209], v[214:217], v[44:47]
	v_mfma_f32_16x16x32_bf16 v[28:31], v[206:209], v[222:225], v[28:31]
	v_mfma_f32_16x16x32_bf16 v[28:31], v[210:213], v[226:229], v[28:31]
	v_mfma_f32_16x16x32_bf16 v[36:39], v[184:187], v[226:229], v[36:39]
	v_mfma_f32_16x16x32_bf16 v[36:39], v[180:183], v[222:225], v[36:39]
	v_mfma_f32_16x16x32_bf16 v[40:43], v[172:175], v[222:225], v[40:43]
	v_mfma_f32_16x16x32_bf16 v[40:43], v[176:179], v[226:229], v[40:43]
	v_mfma_f32_16x16x32_bf16 v[48:51], v[140:143], v[226:229], v[48:51]
	v_mfma_f32_16x16x32_bf16 v[48:51], v[136:139], v[222:225], v[48:51]
	s_setprio 0
	s_setprio 1
	v_mfma_f32_16x16x32_bf16 v[32:35], v[136:139], v[230:233], v[32:35]
	v_mfma_f32_16x16x32_bf16 v[32:35], v[140:143], v[234:237], v[32:35]
	v_mfma_f32_16x16x32_bf16 v[24:27], v[176:179], v[234:237], v[24:27]
	v_mfma_f32_16x16x32_bf16 v[24:27], v[172:175], v[230:233], v[24:27]
	v_mfma_f32_16x16x32_bf16 v[20:23], v[180:183], v[230:233], v[20:23]
	v_mfma_f32_16x16x32_bf16 v[20:23], v[184:187], v[234:237], v[20:23]
	v_mfma_f32_16x16x32_bf16 v[16:19], v[210:213], v[234:237], v[16:19]
	v_mfma_f32_16x16x32_bf16 v[16:19], v[206:209], v[230:233], v[16:19]
	v_mfma_f32_16x16x32_bf16 v[0:3], v[206:209], v[238:241], v[0:3]
	v_mfma_f32_16x16x32_bf16 v[0:3], v[210:213], v[242:245], v[0:3]
	v_mfma_f32_16x16x32_bf16 v[4:7], v[184:187], v[242:245], v[4:7]
	v_mfma_f32_16x16x32_bf16 v[4:7], v[180:183], v[238:241], v[4:7]
	v_mfma_f32_16x16x32_bf16 v[8:11], v[172:175], v[238:241], v[8:11]
	v_mfma_f32_16x16x32_bf16 v[8:11], v[176:179], v[242:245], v[8:11]
	s_setprio 2
	s_barrier
	v_mfma_f32_16x16x32_bf16 v[12:15], v[140:143], v[242:245], v[12:15]
	v_mfma_f32_16x16x32_bf16 v[12:15], v[136:139], v[238:241], v[12:15]
	s_setprio 0
	s_cmp_gt_u32 s79, 29
	s_cbranch_scc0 .LBB0_416
	s_and_b64 vcc, exec, s[20:21]
	s_cbranch_vccz .LBB0_419
	s_barrier

; #define PG8_STAGE(bufoff, gbase, voff) do { _Pragma("unroll") for (int _i = 0; _i < 2; ++_i) \
;         __builtin_amdgcn_global_load_lds((const unsigned*)((const char*)(gbase) + (voff)[_i]), (PG8_LAS unsigned*)(lds + (bufoff) + ldsw + _i * 8192), 16, 0, 0); } while (0)
; #define PG8_LDA(dst, b, h) do { _Pragma("unroll") for (int m = 0; m < 4; ++m) _Pragma("unroll") for (int k = 0; k < 2; ++k) dst[m][k] = *(const PG8_LAS bf16x8*)(lds + PG8_SA(b, h) + aoff + m * 2048 + k * 1024); } while (0)
; #define PG8_LDB(dst, b, h) do { _Pragma("unroll") for (int n = 0; n < 2; ++n) _Pragma("unroll") for (int k = 0; k < 2; ++k) dst[n][k] = *(const PG8_LAS bf16x8*)(lds + PG8_SB(b, h) + boff + n * 2048 + k * 1024); } while (0)
; template <class Epi, class Sched, bool ALIGN_EPI = false, bool SP2 = false>
; __device__ __forceinline__ void gemm_phase(PG8_LAS unsigned char* lds, const Gemm g, const Sched& S, const Epi& E) {
;     ...
;         for (int t = 0; t < nt; t += 2) {
;             const bool last = (t == nt - 2);
;             const char* a1 = cA + (size_t)(t + 1) * kstep;
;             const char* a2 = last ? nA : cA + (size_t)(t + 2) * kstep; const char* b2 = last ? nB : cB + (size_t)(t + 2) * kstep;
;             const char* a3 = a2 + kstep; const char* b3 = b2 + kstep;
;             if (last && has_next) S.a_ready(nxt);
;             if constexpr (SP2) {
;             PG8_LDB(B0, 0, 0); PG8_LDB(B1, 0, 1); PG8_SCHED; PG8_LDA(At, 0, 0); PG8_STAGE(PG8_SA(1, 1), a1 + hstep, voffA);
;             PG8_WAIT_V(8); PG8_WAIT_L(0); PG8_BAR; PG8_MMA(0, 0, At, B0); PG8_MMA(0, 1, At, B1); PG8_BAR; PG8_SCHED;
;             PG8_LDA(At, 0, 1); PG8_STAGE(PG8_SB(0, 0), b2, voffB); PG8_STAGE(PG8_SB(0, 1), b2 + hstep, voffB); PG8_STAGE(PG8_SA(0, 0), a2, voffA);
;             PG8_WAIT_V(8); PG8_WAIT_L(0); PG8_BAR; PG8_MMA(1, 0, At, B0); PG8_MMA(1, 1, At, B1); PG8_BAR; PG8_SCHED;
;             PG8_LDB(B0, 1, 0); PG8_LDB(B1, 1, 1); PG8_SCHED; PG8_LDA(At, 1, 0); PG8_STAGE(PG8_SA(0, 1), a2 + hstep, voffA);
;             PG8_WAIT_V(8); PG8_WAIT_L(0); PG8_BAR; PG8_MMA(0, 0, At, B0); PG8_MMA(0, 1, At, B1); PG8_BAR; PG8_SCHED;
;             PG8_LDA(At, 1, 1); PG8_STAGE(PG8_SB(1, 0), b3, voffB); PG8_STAGE(PG8_SB(1, 1), b3 + hstep, voffB); PG8_STAGE(PG8_SA(1, 0), a3, voffA);
;             PG8_WAIT_V(8); PG8_WAIT_L(0); PG8_BAR; PG8_MMA(1, 0, At, B0); PG8_MMA(1, 1, At, B1); PG8_BAR; PG8_SCHED;
.LBB0_482:
	ds_read_b128 v[76:79], v171
	ds_read_b128 v[84:87], v171 offset:1024
	ds_read_b128 v[92:95], v171 offset:2048
	ds_read_b128 v[96:99], v171 offset:3072
	ds_read_b128 v[144:147], v186
	ds_read_b128 v[148:151], v186 offset:1024
	ds_read_b128 v[152:155], v186 offset:2048
	ds_read_b128 v[156:159], v186 offset:3072
	s_add_u32 s28, s64, 0xffea0080
	s_addc_u32 s29, s65, -1
	s_cmpk_eq_i32 s77, 0x54
	s_cselect_b32 s49, s39, s29
	s_cselect_b32 s48, s38, s28
	s_cselect_b32 s29, s63, s35
	s_cselect_b32 s28, s62, s34
	v_lshl_add_u64 v[200:201], s[64:65], 0, v[172:173]
	s_add_i32 m0, s56, 0xc000
	ds_read_b128 v[178:181], v187
	ds_read_b128 v[182:185], v187 offset:1024
	ds_read_b128 v[206:209], v187 offset:2048
	ds_read_b128 v[210:213], v187 offset:3072
	ds_read_b128 v[214:217], v187 offset:4096
	ds_read_b128 v[218:221], v187 offset:5120
	ds_read_b128 v[222:225], v187 offset:6144
	ds_read_b128 v[226:229], v187 offset:7168
	global_load_lds_dwordx4 v[200:201], off
	v_lshl_add_u64 v[200:201], s[64:65], 0, v[174:175]
	s_add_i32 m0, s56, 0xe000
	s_nop 0
	global_load_lds_dwordx4 v[200:201], off
	s_waitcnt vmcnt(8)
	s_waitcnt lgkmcnt(0)
	s_barrier
	s_setprio 1
	s_waitcnt lgkmcnt(0)
	v_mfma_f32_16x16x32_bf16 v[140:143], v[76:79], v[178:181], v[140:143]
	v_mfma_f32_16x16x32_bf16 v[140:143], v[84:87], v[182:185], v[140:143]
	v_mfma_f32_16x16x32_bf16 v[136:139], v[96:99], v[182:185], v[136:139]
	v_mfma_f32_16x16x32_bf16 v[136:139], v[92:95], v[178:181], v[136:139]
	v_mfma_f32_16x16x32_bf16 v[132:135], v[144:147], v[178:181], v[132:135]
	v_mfma_f32_16x16x32_bf16 v[132:135], v[148:151], v[182:185], v[132:135]
	v_mfma_f32_16x16x32_bf16 v[128:131], v[156:159], v[182:185], v[128:131]
	v_mfma_f32_16x16x32_bf16 v[128:131], v[152:155], v[178:181], v[128:131]
	v_mfma_f32_16x16x32_bf16 v[112:115], v[152:155], v[206:209], v[112:115]
	v_mfma_f32_16x16x32_bf16 v[112:115], v[156:159], v[210:213], v[112:115]
	v_mfma_f32_16x16x32_bf16 v[116:119], v[148:151], v[210:213], v[116:119]
	v_mfma_f32_16x16x32_bf16 v[116:119], v[144:147], v[206:209], v[116:119]
	v_mfma_f32_16x16x32_bf16 v[120:123], v[92:95], v[206:209], v[120:123]
	v_mfma_f32_16x16x32_bf16 v[120:123], v[96:99], v[210:213], v[120:123]
	v_mfma_f32_16x16x32_bf16 v[124:127], v[84:87], v[210:213], v[124:127]
	v_mfma_f32_16x16x32_bf16 v[124:127], v[76:79], v[206:209], v[124:127]
	s_setprio 0
	s_setprio 1
	v_mfma_f32_16x16x32_bf16 v[108:111], v[76:79], v[214:217], v[108:111]
	v_mfma_f32_16x16x32_bf16 v[108:111], v[84:87], v[218:221], v[108:111]
	v_mfma_f32_16x16x32_bf16 v[104:107], v[96:99], v[218:221], v[104:107]
	v_mfma_f32_16x16x32_bf16 v[104:107], v[92:95], v[214:217], v[104:107]
	v_mfma_f32_16x16x32_bf16 v[100:103], v[144:147], v[214:217], v[100:103]
	v_mfma_f32_16x16x32_bf16 v[100:103], v[148:151], v[218:221], v[100:103]
	v_mfma_f32_16x16x32_bf16 v[88:91], v[156:159], v[218:221], v[88:91]
	v_mfma_f32_16x16x32_bf16 v[88:91], v[152:155], v[214:217], v[88:91]
	v_mfma_f32_16x16x32_bf16 v[64:67], v[152:155], v[222:225], v[64:67]
	v_mfma_f32_16x16x32_bf16 v[64:67], v[156:159], v[226:229], v[64:67]
	v_mfma_f32_16x16x32_bf16 v[68:71], v[148:151], v[226:229], v[68:71]
	v_mfma_f32_16x16x32_bf16 v[68:71], v[144:147], v[222:225], v[68:71]
	v_mfma_f32_16x16x32_bf16 v[72:75], v[92:95], v[222:225], v[72:75]
	v_mfma_f32_16x16x32_bf16 v[72:75], v[96:99], v[226:229], v[72:75]
	s_setprio 2
	s_barrier
	v_mfma_f32_16x16x32_bf16 v[80:83], v[84:87], v[226:229], v[80:83]
	v_mfma_f32_16x16x32_bf16 v[80:83], v[76:79], v[222:225], v[80:83]
	s_setprio 0
	s_add_i32 s44, s70, s41
	v_lshl_add_u64 v[200:201], s[28:29], 0, v[160:161]
	s_mov_b32 m0, s44
	ds_read_b128 v[178:181], v187 offset:16384
	ds_read_b128 v[182:185], v187 offset:17408
	ds_read_b128 v[206:209], v187 offset:18432
	ds_read_b128 v[210:213], v187 offset:19456
	ds_read_b128 v[214:217], v187 offset:20480
	ds_read_b128 v[218:221], v187 offset:21504
	ds_read_b128 v[222:225], v187 offset:22528
	ds_read_b128 v[226:229], v187 offset:23552
	global_load_lds_dwordx4 v[200:201], off
	s_add_i32 m0, s44, 0x2000
	s_add_u32 s78, s28, 0x160000
	v_lshl_add_u64 v[230:231], s[28:29], 0, v[162:163]
	s_addc_u32 s79, s29, 0
	s_add_i32 s44, s71, s41
	global_load_lds_dwordx4 v[230:231], off
	v_lshl_add_u64 v[232:233], s[78:79], 0, v[160:161]
	s_mov_b32 m0, s44
	v_lshl_add_u64 v[234:235], s[48:49], 0, v[162:163]
	global_load_lds_dwordx4 v[232:233], off
	v_lshl_add_u64 v[232:233], s[78:79], 0, v[162:163]
	s_add_i32 m0, s44, 0x2000
	s_nop 0
	global_load_lds_dwordx4 v[232:233], off
	v_lshl_add_u64 v[232:233], s[48:49], 0, v[160:161]
	s_mov_b32 m0, s56
	s_nop 0
	global_load_lds_dwordx4 v[232:233], off
	s_mov_b32 m0, s57
	s_nop 0
	global_load_lds_dwordx4 v[234:235], off
	s_waitcnt vmcnt(8)
	s_waitcnt lgkmcnt(0)
	s_barrier
; #define PG8_STAGE(bufoff, gbase, voff) do { _Pragma("unroll") for (int _i = 0; _i < 2; ++_i) \
;         __builtin_amdgcn_global_load_lds((const unsigned*)((const char*)(gbase) + (voff)[_i]), (PG8_LAS unsigned*)(lds + (bufoff) + ldsw + _i * 8192), 16, 0, 0); } while (0)
; #define PG8_LDA(dst, b, h) do { _Pragma("unroll") for (int m = 0; m < 4; ++m) _Pragma("unroll") for (int k = 0; k < 2; ++k) dst[m][k] = *(const PG8_LAS bf16x8*)(lds + PG8_SA(b, h) + aoff + m * 2048 + k * 1024); } while (0)
; #define PG8_LDB(dst, b, h) do { _Pragma("unroll") for (int n = 0; n < 2; ++n) _Pragma("unroll") for (int k = 0; k < 2; ++k) dst[n][k] = *(const PG8_LAS bf16x8*)(lds + PG8_SB(b, h) + boff + n * 2048 + k * 1024); } while (0)
; template <class Epi, class Sched, bool ALIGN_EPI = false, bool SP2 = false>
; __device__ __forceinline__ void gemm_phase(PG8_LAS unsigned char* lds, const Gemm g, const Sched& S, const Epi& E) {
;     ...
;         for (int t = 0; t < nt; t += 2) {
;             const bool last = (t == nt - 2);
;             const char* a1 = cA + (size_t)(t + 1) * kstep;
;             const char* a2 = last ? nA : cA + (size_t)(t + 2) * kstep; const char* b2 = last ? nB : cB + (size_t)(t + 2) * kstep;
;             const char* a3 = a2 + kstep; const char* b3 = b2 + kstep;
;             if (last && has_next) S.a_ready(nxt);
;             if constexpr (SP2) {
;             PG8_LDB(B0, 0, 0); PG8_LDB(B1, 0, 1); PG8_SCHED; PG8_LDA(At, 0, 0); PG8_STAGE(PG8_SA(1, 1), a1 + hstep, voffA);
;             PG8_WAIT_V(8); PG8_WAIT_L(0); PG8_BAR; PG8_MMA(0, 0, At, B0); PG8_MMA(0, 1, At, B1); PG8_BAR; PG8_SCHED;
;             PG8_LDA(At, 0, 1); PG8_STAGE(PG8_SB(0, 0), b2, voffB); PG8_STAGE(PG8_SB(0, 1), b2 + hstep, voffB); PG8_STAGE(PG8_SA(0, 0), a2, voffA);
;             PG8_WAIT_V(8); PG8_WAIT_L(0); PG8_BAR; PG8_MMA(1, 0, At, B0); PG8_MMA(1, 1, At, B1); PG8_BAR; PG8_SCHED;
;             PG8_LDB(B0, 1, 0); PG8_LDB(B1, 1, 1); PG8_SCHED; PG8_LDA(At, 1, 0); PG8_STAGE(PG8_SA(0, 1), a2 + hstep, voffA);
;             PG8_WAIT_V(8); PG8_WAIT_L(0); PG8_BAR; PG8_MMA(0, 0, At, B0); PG8_MMA(0, 1, At, B1); PG8_BAR; PG8_SCHED;
;             PG8_LDA(At, 1, 1); PG8_STAGE(PG8_SB(1, 0), b3, voffB); PG8_STAGE(PG8_SB(1, 1), b3 + hstep, voffB); PG8_STAGE(PG8_SA(1, 0), a3, voffA);
;             PG8_WAIT_V(8); PG8_WAIT_L(0); PG8_BAR; PG8_MMA(1, 0, At, B0); PG8_MMA(1, 1, At, B1); PG8_BAR; PG8_SCHED;
	s_setprio 1
	s_waitcnt lgkmcnt(0)
	v_mfma_f32_16x16x32_bf16 v[60:63], v[76:79], v[178:181], v[60:63]
	v_mfma_f32_16x16x32_bf16 v[60:63], v[84:87], v[182:185], v[60:63]
	v_mfma_f32_16x16x32_bf16 v[56:59], v[96:99], v[182:185], v[56:59]
	v_mfma_f32_16x16x32_bf16 v[56:59], v[92:95], v[178:181], v[56:59]
	v_mfma_f32_16x16x32_bf16 v[52:55], v[144:147], v[178:181], v[52:55]
	v_mfma_f32_16x16x32_bf16 v[52:55], v[148:151], v[182:185], v[52:55]
	v_mfma_f32_16x16x32_bf16 v[48:51], v[156:159], v[182:185], v[48:51]
	v_mfma_f32_16x16x32_bf16 v[48:51], v[152:155], v[178:181], v[48:51]
	v_mfma_f32_16x16x32_bf16 v[32:35], v[152:155], v[206:209], v[32:35]
	v_mfma_f32_16x16x32_bf16 v[32:35], v[156:159], v[210:213], v[32:35]
	v_mfma_f32_16x16x32_bf16 v[36:39], v[148:151], v[210:213], v[36:39]
	v_mfma_f32_16x16x32_bf16 v[36:39], v[144:147], v[206:209], v[36:39]
	v_mfma_f32_16x16x32_bf16 v[40:43], v[92:95], v[206:209], v[40:43]
	v_mfma_f32_16x16x32_bf16 v[40:43], v[96:99], v[210:213], v[40:43]
	v_mfma_f32_16x16x32_bf16 v[44:47], v[84:87], v[210:213], v[44:47]
	v_mfma_f32_16x16x32_bf16 v[44:47], v[76:79], v[206:209], v[44:47]
	s_setprio 0
	s_setprio 1
	v_mfma_f32_16x16x32_bf16 v[28:31], v[76:79], v[214:217], v[28:31]
	v_mfma_f32_16x16x32_bf16 v[28:31], v[84:87], v[218:221], v[28:31]
	v_mfma_f32_16x16x32_bf16 v[24:27], v[96:99], v[218:221], v[24:27]
	v_mfma_f32_16x16x32_bf16 v[24:27], v[92:95], v[214:217], v[24:27]
	v_mfma_f32_16x16x32_bf16 v[20:23], v[144:147], v[214:217], v[20:23]
	v_mfma_f32_16x16x32_bf16 v[20:23], v[148:151], v[218:221], v[20:23]
	v_mfma_f32_16x16x32_bf16 v[16:19], v[156:159], v[218:221], v[16:19]
	v_mfma_f32_16x16x32_bf16 v[16:19], v[152:155], v[214:217], v[16:19]
	v_mfma_f32_16x16x32_bf16 v[0:3], v[152:155], v[222:225], v[0:3]
	v_mfma_f32_16x16x32_bf16 v[0:3], v[156:159], v[226:229], v[0:3]
	v_mfma_f32_16x16x32_bf16 v[4:7], v[148:151], v[226:229], v[4:7]
	v_mfma_f32_16x16x32_bf16 v[4:7], v[144:147], v[222:225], v[4:7]
	v_mfma_f32_16x16x32_bf16 v[8:11], v[92:95], v[222:225], v[8:11]
	v_mfma_f32_16x16x32_bf16 v[8:11], v[96:99], v[226:229], v[8:11]
	s_setprio 2
	s_barrier
	v_mfma_f32_16x16x32_bf16 v[12:15], v[84:87], v[226:229], v[12:15]
	v_mfma_f32_16x16x32_bf16 v[12:15], v[76:79], v[222:225], v[12:15]
	s_setprio 0
	s_add_i32 s44, 0, 0x18000
	s_add_i32 s45, 0, 0x1c000
	v_add_u32_e32 v96, s44, v167
	v_add_u32_e32 v156, s45, v167
	ds_read_b128 v[76:79], v96
	ds_read_b128 v[84:87], v96 offset:1024
	ds_read_b128 v[92:95], v96 offset:2048
	ds_read_b128 v[96:99], v96 offset:3072
	ds_read_b128 v[144:147], v156
	ds_read_b128 v[148:151], v156 offset:1024
	ds_read_b128 v[152:155], v156 offset:2048
	ds_read_b128 v[156:159], v156 offset:3072
	s_add_u32 s48, s48, 0x160000
	s_addc_u32 s49, s49, 0
	s_mov_b32 m0, s61
	v_lshl_add_u64 v[236:237], s[48:49], 0, v[160:161]
	ds_read_b128 v[178:181], v187 offset:32768
	ds_read_b128 v[182:185], v187 offset:33792
	ds_read_b128 v[206:209], v187 offset:34816
	ds_read_b128 v[210:213], v187 offset:35840
	ds_read_b128 v[214:217], v187 offset:36864
	ds_read_b128 v[218:221], v187 offset:37888
	ds_read_b128 v[222:225], v187 offset:38912
	ds_read_b128 v[226:229], v187 offset:39936
	global_load_lds_dwordx4 v[236:237], off
	v_lshl_add_u64 v[236:237], s[48:49], 0, v[162:163]
	s_mov_b32 m0, s66
	s_nop 0
	global_load_lds_dwordx4 v[236:237], off
	s_waitcnt vmcnt(8)
	s_waitcnt lgkmcnt(0)
	s_barrier
	s_setprio 1
	s_waitcnt lgkmcnt(0)
	v_mfma_f32_16x16x32_bf16 v[140:143], v[76:79], v[178:181], v[140:143]
	v_mfma_f32_16x16x32_bf16 v[140:143], v[84:87], v[182:185], v[140:143]
	v_mfma_f32_16x16x32_bf16 v[136:139], v[96:99], v[182:185], v[136:139]
	v_mfma_f32_16x16x32_bf16 v[136:139], v[92:95], v[178:181], v[136:139]
	v_mfma_f32_16x16x32_bf16 v[132:135], v[144:147], v[178:181], v[132:135]
	v_mfma_f32_16x16x32_bf16 v[132:135], v[148:151], v[182:185], v[132:135]
	v_mfma_f32_16x16x32_bf16 v[128:131], v[156:159], v[182:185], v[128:131]
	v_mfma_f32_16x16x32_bf16 v[128:131], v[152:155], v[178:181], v[128:131]
	v_mfma_f32_16x16x32_bf16 v[112:115], v[152:155], v[206:209], v[112:115]
	v_mfma_f32_16x16x32_bf16 v[112:115], v[156:159], v[210:213], v[112:115]
	v_mfma_f32_16x16x32_bf16 v[116:119], v[148:151], v[210:213], v[116:119]
	v_mfma_f32_16x16x32_bf16 v[116:119], v[144:147], v[206:209], v[116:119]
	v_mfma_f32_16x16x32_bf16 v[120:123], v[92:95], v[206:209], v[120:123]
	v_mfma_f32_16x16x32_bf16 v[120:123], v[96:99], v[210:213], v[120:123]
	v_mfma_f32_16x16x32_bf16 v[124:127], v[84:87], v[210:213], v[124:127]
	v_mfma_f32_16x16x32_bf16 v[124:127], v[76:79], v[206:209], v[124:127]
	s_setprio 0
	s_setprio 1
	v_mfma_f32_16x16x32_bf16 v[108:111], v[76:79], v[214:217], v[108:111]
	v_mfma_f32_16x16x32_bf16 v[108:111], v[84:87], v[218:221], v[108:111]
	v_mfma_f32_16x16x32_bf16 v[104:107], v[96:99], v[218:221], v[104:107]
	v_mfma_f32_16x16x32_bf16 v[104:107], v[92:95], v[214:217], v[104:107]
	v_mfma_f32_16x16x32_bf16 v[100:103], v[144:147], v[214:217], v[100:103]
	v_mfma_f32_16x16x32_bf16 v[100:103], v[148:151], v[218:221], v[100:103]
	v_mfma_f32_16x16x32_bf16 v[88:91], v[156:159], v[218:221], v[88:91]
	v_mfma_f32_16x16x32_bf16 v[88:91], v[152:155], v[214:217], v[88:91]
	v_mfma_f32_16x16x32_bf16 v[64:67], v[152:155], v[222:225], v[64:67]
	v_mfma_f32_16x16x32_bf16 v[64:67], v[156:159], v[226:229], v[64:67]
	v_mfma_f32_16x16x32_bf16 v[68:71], v[148:151], v[226:229], v[68:71]
	v_mfma_f32_16x16x32_bf16 v[68:71], v[144:147], v[222:225], v[68:71]
	v_mfma_f32_16x16x32_bf16 v[72:75], v[92:95], v[222:225], v[72:75]
	v_mfma_f32_16x16x32_bf16 v[72:75], v[96:99], v[226:229], v[72:75]
	s_setprio 2
	s_barrier
; #define PG8_STAGE(bufoff, gbase, voff) do { _Pragma("unroll") for (int _i = 0; _i < 2; ++_i) \
;         __builtin_amdgcn_global_load_lds((const unsigned*)((const char*)(gbase) + (voff)[_i]), (PG8_LAS unsigned*)(lds + (bufoff) + ldsw + _i * 8192), 16, 0, 0); } while (0)
; #define PG8_LDA(dst, b, h) do { _Pragma("unroll") for (int m = 0; m < 4; ++m) _Pragma("unroll") for (int k = 0; k < 2; ++k) dst[m][k] = *(const PG8_LAS bf16x8*)(lds + PG8_SA(b, h) + aoff + m * 2048 + k * 1024); } while (0)
; #define PG8_LDB(dst, b, h) do { _Pragma("unroll") for (int n = 0; n < 2; ++n) _Pragma("unroll") for (int k = 0; k < 2; ++k) dst[n][k] = *(const PG8_LAS bf16x8*)(lds + PG8_SB(b, h) + boff + n * 2048 + k * 1024); } while (0)
; template <class Epi, class Sched, bool ALIGN_EPI = false, bool SP2 = false>
; __device__ __forceinline__ void gemm_phase(PG8_LAS unsigned char* lds, const Gemm g, const Sched& S, const Epi& E) {
;     ...
;         for (int t = 0; t < nt; t += 2) {
;             const bool last = (t == nt - 2);
;             const char* a1 = cA + (size_t)(t + 1) * kstep;
;             const char* a2 = last ? nA : cA + (size_t)(t + 2) * kstep; const char* b2 = last ? nB : cB + (size_t)(t + 2) * kstep;
;             const char* a3 = a2 + kstep; const char* b3 = b2 + kstep;
;             if (last && has_next) S.a_ready(nxt);
;             if constexpr (SP2) {
;             PG8_LDB(B0, 0, 0); PG8_LDB(B1, 0, 1); PG8_SCHED; PG8_LDA(At, 0, 0); PG8_STAGE(PG8_SA(1, 1), a1 + hstep, voffA);
;             PG8_WAIT_V(8); PG8_WAIT_L(0); PG8_BAR; PG8_MMA(0, 0, At, B0); PG8_MMA(0, 1, At, B1); PG8_BAR; PG8_SCHED;
;             PG8_LDA(At, 0, 1); PG8_STAGE(PG8_SB(0, 0), b2, voffB); PG8_STAGE(PG8_SB(0, 1), b2 + hstep, voffB); PG8_STAGE(PG8_SA(0, 0), a2, voffA);
;             PG8_WAIT_V(8); PG8_WAIT_L(0); PG8_BAR; PG8_MMA(1, 0, At, B0); PG8_MMA(1, 1, At, B1); PG8_BAR; PG8_SCHED;
;             PG8_LDB(B0, 1, 0); PG8_LDB(B1, 1, 1); PG8_SCHED; PG8_LDA(At, 1, 0); PG8_STAGE(PG8_SA(0, 1), a2 + hstep, voffA);
;             PG8_WAIT_V(8); PG8_WAIT_L(0); PG8_BAR; PG8_MMA(0, 0, At, B0); PG8_MMA(0, 1, At, B1); PG8_BAR; PG8_SCHED;
;             PG8_LDA(At, 1, 1); PG8_STAGE(PG8_SB(1, 0), b3, voffB); PG8_STAGE(PG8_SB(1, 1), b3 + hstep, voffB); PG8_STAGE(PG8_SA(1, 0), a3, voffA);
;             PG8_WAIT_V(8); PG8_WAIT_L(0); PG8_BAR; PG8_MMA(1, 0, At, B0); PG8_MMA(1, 1, At, B1); PG8_BAR; PG8_SCHED;
	v_mfma_f32_16x16x32_bf16 v[80:83], v[84:87], v[226:229], v[80:83]
	v_mfma_f32_16x16x32_bf16 v[80:83], v[76:79], v[222:225], v[80:83]
	s_setprio 0
	s_add_i32 s44, s44, s41
	v_lshl_add_u64 v[200:201], v[200:201], 0, s[20:21]
	s_mov_b32 m0, s44
	ds_read_b128 v[178:181], v187 offset:49152
	ds_read_b128 v[182:185], v187 offset:50176
	ds_read_b128 v[206:209], v187 offset:51200
	ds_read_b128 v[210:213], v187 offset:52224
	ds_read_b128 v[214:217], v187 offset:53248
	ds_read_b128 v[218:221], v187 offset:54272
	ds_read_b128 v[222:225], v187 offset:55296
	ds_read_b128 v[226:229], v187 offset:56320
	global_load_lds_dwordx4 v[200:201], off
	s_add_i32 m0, s44, 0x2000
	s_add_u32 s28, s28, 0x160080
	v_lshl_add_u64 v[200:201], v[230:231], 0, s[20:21]
	s_addc_u32 s29, s29, 0
	s_add_i32 s44, s45, s41
	global_load_lds_dwordx4 v[200:201], off
	v_lshl_add_u64 v[200:201], s[28:29], 0, v[160:161]
	s_mov_b32 m0, s44
	s_nop 0
	global_load_lds_dwordx4 v[200:201], off
	v_lshl_add_u64 v[200:201], s[28:29], 0, v[162:163]
	s_add_i32 m0, s44, 0x2000
	s_nop 0
	global_load_lds_dwordx4 v[200:201], off
	v_lshl_add_u64 v[200:201], v[232:233], 0, s[20:21]
	s_mov_b32 m0, s67
	s_nop 0
	global_load_lds_dwordx4 v[200:201], off
	v_lshl_add_u64 v[200:201], v[234:235], 0, s[20:21]
	s_mov_b32 m0, s68
	s_nop 0
	global_load_lds_dwordx4 v[200:201], off
	s_add_i32 s77, s77, 2
	s_add_u32 s64, s64, 0x100
	s_addc_u32 s65, s65, 0
	s_add_u32 s34, s34, 0x100
	s_addc_u32 s35, s35, 0
	s_waitcnt vmcnt(8)
	s_waitcnt lgkmcnt(0)
	s_barrier
	s_setprio 1
	s_waitcnt lgkmcnt(0)
	v_mfma_f32_16x16x32_bf16 v[60:63], v[76:79], v[178:181], v[60:63]
	v_mfma_f32_16x16x32_bf16 v[60:63], v[84:87], v[182:185], v[60:63]
	v_mfma_f32_16x16x32_bf16 v[56:59], v[96:99], v[182:185], v[56:59]
	v_mfma_f32_16x16x32_bf16 v[56:59], v[92:95], v[178:181], v[56:59]
	v_mfma_f32_16x16x32_bf16 v[52:55], v[144:147], v[178:181], v[52:55]
	v_mfma_f32_16x16x32_bf16 v[52:55], v[148:151], v[182:185], v[52:55]
	v_mfma_f32_16x16x32_bf16 v[48:51], v[156:159], v[182:185], v[48:51]
	v_mfma_f32_16x16x32_bf16 v[48:51], v[152:155], v[178:181], v[48:51]
	v_mfma_f32_16x16x32_bf16 v[32:35], v[152:155], v[206:209], v[32:35]
	v_mfma_f32_16x16x32_bf16 v[32:35], v[156:159], v[210:213], v[32:35]
	v_mfma_f32_16x16x32_bf16 v[36:39], v[148:151], v[210:213], v[36:39]
	v_mfma_f32_16x16x32_bf16 v[36:39], v[144:147], v[206:209], v[36:39]
	v_mfma_f32_16x16x32_bf16 v[40:43], v[92:95], v[206:209], v[40:43]
	v_mfma_f32_16x16x32_bf16 v[40:43], v[96:99], v[210:213], v[40:43]
	v_mfma_f32_16x16x32_bf16 v[44:47], v[84:87], v[210:213], v[44:47]
	v_mfma_f32_16x16x32_bf16 v[44:47], v[76:79], v[206:209], v[44:47]
	s_setprio 0
	s_setprio 1
	v_mfma_f32_16x16x32_bf16 v[28:31], v[76:79], v[214:217], v[28:31]
	v_mfma_f32_16x16x32_bf16 v[28:31], v[84:87], v[218:221], v[28:31]
	v_mfma_f32_16x16x32_bf16 v[24:27], v[96:99], v[218:221], v[24:27]
	v_mfma_f32_16x16x32_bf16 v[24:27], v[92:95], v[214:217], v[24:27]
	v_mfma_f32_16x16x32_bf16 v[20:23], v[144:147], v[214:217], v[20:23]
	v_mfma_f32_16x16x32_bf16 v[20:23], v[148:151], v[218:221], v[20:23]
	v_mfma_f32_16x16x32_bf16 v[16:19], v[156:159], v[218:221], v[16:19]
	v_mfma_f32_16x16x32_bf16 v[16:19], v[152:155], v[214:217], v[16:19]
	v_mfma_f32_16x16x32_bf16 v[0:3], v[152:155], v[222:225], v[0:3]
	v_mfma_f32_16x16x32_bf16 v[0:3], v[156:159], v[226:229], v[0:3]
	v_mfma_f32_16x16x32_bf16 v[4:7], v[148:151], v[226:229], v[4:7]
	v_mfma_f32_16x16x32_bf16 v[4:7], v[144:147], v[222:225], v[4:7]
	v_mfma_f32_16x16x32_bf16 v[8:11], v[92:95], v[222:225], v[8:11]
	v_mfma_f32_16x16x32_bf16 v[8:11], v[96:99], v[226:229], v[8:11]
	s_setprio 2
	s_barrier
	v_mfma_f32_16x16x32_bf16 v[12:15], v[84:87], v[226:229], v[12:15]
	v_mfma_f32_16x16x32_bf16 v[12:15], v[76:79], v[222:225], v[12:15]
	s_setprio 0
	s_cmpk_gt_u32 s77, 0x55
	s_cbranch_scc0 .LBB0_482
	s_and_b64 vcc, exec, s[22:23]
	s_cbranch_vccz .LBB0_485
	s_barrier

; #define PG8_STAGE(bufoff, gbase, voff) do { _Pragma("unroll") for (int _i = 0; _i < 2; ++_i) \
;         __builtin_amdgcn_global_load_lds((const unsigned*)((const char*)(gbase) + (voff)[_i]), (PG8_LAS unsigned*)(lds + (bufoff) + ldsw + _i * 8192), 16, 0, 0); } while (0)
; #define PG8_LDA(dst, b, h) do { _Pragma("unroll") for (int m = 0; m < 4; ++m) _Pragma("unroll") for (int k = 0; k < 2; ++k) dst[m][k] = *(const PG8_LAS bf16x8*)(lds + PG8_SA(b, h) + aoff + m * 2048 + k * 1024); } while (0)
; #define PG8_LDB(dst, b, h) do { _Pragma("unroll") for (int n = 0; n < 2; ++n) _Pragma("unroll") for (int k = 0; k < 2; ++k) dst[n][k] = *(const PG8_LAS bf16x8*)(lds + PG8_SB(b, h) + boff + n * 2048 + k * 1024); } while (0)
; template <class Epi, class Sched, bool ALIGN_EPI = false, bool SP2 = false>
; __device__ __forceinline__ void gemm_phase(PG8_LAS unsigned char* lds, const Gemm g, const Sched& S, const Epi& E) {
;     ...
;         for (int t = 0; t < nt; t += 2) {
;             const bool last = (t == nt - 2);
;             const char* a1 = cA + (size_t)(t + 1) * kstep;
;             const char* a2 = last ? nA : cA + (size_t)(t + 2) * kstep; const char* b2 = last ? nB : cB + (size_t)(t + 2) * kstep;
;             const char* a3 = a2 + kstep; const char* b3 = b2 + kstep;
;             if (last && has_next) S.a_ready(nxt);
;             if constexpr (SP2) {
;             PG8_LDB(B0, 0, 0); PG8_LDB(B1, 0, 1); PG8_SCHED; PG8_LDA(At, 0, 0); PG8_STAGE(PG8_SA(1, 1), a1 + hstep, voffA);
;             PG8_WAIT_V(8); PG8_WAIT_L(0); PG8_BAR; PG8_MMA(0, 0, At, B0); PG8_MMA(0, 1, At, B1); PG8_BAR; PG8_SCHED;
;             PG8_LDA(At, 0, 1); PG8_STAGE(PG8_SB(0, 0), b2, voffB); PG8_STAGE(PG8_SB(0, 1), b2 + hstep, voffB); PG8_STAGE(PG8_SA(0, 0), a2, voffA);
;             PG8_WAIT_V(8); PG8_WAIT_L(0); PG8_BAR; PG8_MMA(1, 0, At, B0); PG8_MMA(1, 1, At, B1); PG8_BAR; PG8_SCHED;
;             PG8_LDB(B0, 1, 0); PG8_LDB(B1, 1, 1); PG8_SCHED; PG8_LDA(At, 1, 0); PG8_STAGE(PG8_SA(0, 1), a2 + hstep, voffA);
;             PG8_WAIT_V(8); PG8_WAIT_L(0); PG8_BAR; PG8_MMA(0, 0, At, B0); PG8_MMA(0, 1, At, B1); PG8_BAR; PG8_SCHED;
;             PG8_LDA(At, 1, 1); PG8_STAGE(PG8_SB(1, 0), b3, voffB); PG8_STAGE(PG8_SB(1, 1), b3 + hstep, voffB); PG8_STAGE(PG8_SA(1, 0), a3, voffA);
;             PG8_WAIT_V(8); PG8_WAIT_L(0); PG8_BAR; PG8_MMA(1, 0, At, B0); PG8_MMA(1, 1, At, B1); PG8_BAR; PG8_SCHED;
.LBB0_536:
	ds_read_b128 v[136:139], v156
	ds_read_b128 v[140:143], v156 offset:1024
	ds_read_b128 v[172:175], v156 offset:2048
	ds_read_b128 v[176:179], v156 offset:3072
	ds_read_b128 v[180:183], v157
	ds_read_b128 v[184:187], v157 offset:1024
	ds_read_b128 v[206:209], v157 offset:2048
	ds_read_b128 v[210:213], v157 offset:3072
	s_add_u32 s28, s66, 0xfff80080
	s_addc_u32 s29, s67, -1
	s_cmp_eq_u32 s79, 28
	s_cselect_b32 s49, s34, s29
	s_cselect_b32 s48, s35, s28
	s_cselect_b32 s29, s23, s78
	s_cselect_b32 s28, s39, s77
	v_lshl_add_u64 v[200:201], s[66:67], 0, v[128:129]
	s_add_i32 m0, s11, 0xc000
	ds_read_b128 v[214:217], v158
	ds_read_b128 v[218:221], v158 offset:1024
	ds_read_b128 v[222:225], v158 offset:2048
	ds_read_b128 v[226:229], v158 offset:3072
	ds_read_b128 v[230:233], v158 offset:4096
	ds_read_b128 v[234:237], v158 offset:5120
	ds_read_b128 v[238:241], v158 offset:6144
	ds_read_b128 v[242:245], v158 offset:7168
	global_load_lds_dwordx4 v[200:201], off
	v_lshl_add_u64 v[200:201], s[66:67], 0, v[130:131]
	s_add_i32 m0, s11, 0xe000
	s_nop 0
	global_load_lds_dwordx4 v[200:201], off
	s_waitcnt vmcnt(8)
	s_waitcnt lgkmcnt(0)
	s_barrier
	s_setprio 1
	s_waitcnt lgkmcnt(0)
	v_mfma_f32_16x16x32_bf16 v[124:127], v[136:139], v[214:217], v[124:127]
	v_mfma_f32_16x16x32_bf16 v[124:127], v[140:143], v[218:221], v[124:127]
	v_mfma_f32_16x16x32_bf16 v[120:123], v[176:179], v[218:221], v[120:123]
	v_mfma_f32_16x16x32_bf16 v[120:123], v[172:175], v[214:217], v[120:123]
	v_mfma_f32_16x16x32_bf16 v[116:119], v[180:183], v[214:217], v[116:119]
	v_mfma_f32_16x16x32_bf16 v[116:119], v[184:187], v[218:221], v[116:119]
	v_mfma_f32_16x16x32_bf16 v[112:115], v[210:213], v[218:221], v[112:115]
	v_mfma_f32_16x16x32_bf16 v[112:115], v[206:209], v[214:217], v[112:115]
	v_mfma_f32_16x16x32_bf16 v[92:95], v[206:209], v[222:225], v[92:95]
	v_mfma_f32_16x16x32_bf16 v[92:95], v[210:213], v[226:229], v[92:95]
	v_mfma_f32_16x16x32_bf16 v[100:103], v[184:187], v[226:229], v[100:103]
	v_mfma_f32_16x16x32_bf16 v[100:103], v[180:183], v[222:225], v[100:103]
	v_mfma_f32_16x16x32_bf16 v[104:107], v[172:175], v[222:225], v[104:107]
	v_mfma_f32_16x16x32_bf16 v[104:107], v[176:179], v[226:229], v[104:107]
	v_mfma_f32_16x16x32_bf16 v[108:111], v[140:143], v[226:229], v[108:111]
	v_mfma_f32_16x16x32_bf16 v[108:111], v[136:139], v[222:225], v[108:111]
	s_setprio 0
	s_setprio 1
	v_mfma_f32_16x16x32_bf16 v[96:99], v[136:139], v[230:233], v[96:99]
	v_mfma_f32_16x16x32_bf16 v[96:99], v[140:143], v[234:237], v[96:99]
	v_mfma_f32_16x16x32_bf16 v[88:91], v[176:179], v[234:237], v[88:91]
	v_mfma_f32_16x16x32_bf16 v[88:91], v[172:175], v[230:233], v[88:91]
	v_mfma_f32_16x16x32_bf16 v[84:87], v[180:183], v[230:233], v[84:87]
	v_mfma_f32_16x16x32_bf16 v[84:87], v[184:187], v[234:237], v[84:87]
	v_mfma_f32_16x16x32_bf16 v[76:79], v[210:213], v[234:237], v[76:79]
	v_mfma_f32_16x16x32_bf16 v[76:79], v[206:209], v[230:233], v[76:79]
	v_mfma_f32_16x16x32_bf16 v[64:67], v[206:209], v[238:241], v[64:67]
	v_mfma_f32_16x16x32_bf16 v[64:67], v[210:213], v[242:245], v[64:67]
	v_mfma_f32_16x16x32_bf16 v[68:71], v[184:187], v[242:245], v[68:71]
	v_mfma_f32_16x16x32_bf16 v[68:71], v[180:183], v[238:241], v[68:71]
	v_mfma_f32_16x16x32_bf16 v[72:75], v[172:175], v[238:241], v[72:75]
	v_mfma_f32_16x16x32_bf16 v[72:75], v[176:179], v[242:245], v[72:75]
	s_setprio 2
	s_barrier
	v_mfma_f32_16x16x32_bf16 v[80:83], v[140:143], v[242:245], v[80:83]
	v_mfma_f32_16x16x32_bf16 v[80:83], v[136:139], v[238:241], v[80:83]
	s_setprio 0
	s_add_i32 s44, s72, s41
	v_lshl_add_u64 v[200:201], s[28:29], 0, v[166:167]
	s_mov_b32 m0, s44
	ds_read_b128 v[214:217], v158 offset:16384
	ds_read_b128 v[218:221], v158 offset:17408
	ds_read_b128 v[222:225], v158 offset:18432
	ds_read_b128 v[226:229], v158 offset:19456
	ds_read_b128 v[230:233], v158 offset:20480
	ds_read_b128 v[234:237], v158 offset:21504
	ds_read_b128 v[238:241], v158 offset:22528
	ds_read_b128 v[242:245], v158 offset:23552
	global_load_lds_dwordx4 v[200:201], off
	s_add_i32 m0, s44, 0x2000
	s_add_u32 s80, s28, 0x80000
	v_lshl_add_u64 v[246:247], s[28:29], 0, v[170:171]
	s_addc_u32 s81, s29, 0
	s_add_i32 s44, s73, s41
	global_load_lds_dwordx4 v[246:247], off
	v_lshl_add_u64 v[248:249], s[80:81], 0, v[166:167]
	s_mov_b32 m0, s44
	v_lshl_add_u64 v[250:251], s[48:49], 0, v[168:169]
	global_load_lds_dwordx4 v[248:249], off
	v_lshl_add_u64 v[248:249], s[80:81], 0, v[170:171]
	s_add_i32 m0, s44, 0x2000
	s_nop 0
	global_load_lds_dwordx4 v[248:249], off
	v_lshl_add_u64 v[248:249], s[48:49], 0, v[164:165]
	s_mov_b32 m0, s11
	s_nop 0
	global_load_lds_dwordx4 v[248:249], off
	s_mov_b32 m0, s57
	s_nop 0
	global_load_lds_dwordx4 v[250:251], off
	s_waitcnt vmcnt(8)
	s_waitcnt lgkmcnt(0)
	s_barrier
; #define PG8_STAGE(bufoff, gbase, voff) do { _Pragma("unroll") for (int _i = 0; _i < 2; ++_i) \
;         __builtin_amdgcn_global_load_lds((const unsigned*)((const char*)(gbase) + (voff)[_i]), (PG8_LAS unsigned*)(lds + (bufoff) + ldsw + _i * 8192), 16, 0, 0); } while (0)
; #define PG8_LDA(dst, b, h) do { _Pragma("unroll") for (int m = 0; m < 4; ++m) _Pragma("unroll") for (int k = 0; k < 2; ++k) dst[m][k] = *(const PG8_LAS bf16x8*)(lds + PG8_SA(b, h) + aoff + m * 2048 + k * 1024); } while (0)
; #define PG8_LDB(dst, b, h) do { _Pragma("unroll") for (int n = 0; n < 2; ++n) _Pragma("unroll") for (int k = 0; k < 2; ++k) dst[n][k] = *(const PG8_LAS bf16x8*)(lds + PG8_SB(b, h) + boff + n * 2048 + k * 1024); } while (0)
; #define PG8_MMA(ai, bj, At, Bt) do { __builtin_amdgcn_s_setprio(1); _Pragma("unroll") for (int m = 0; m < 4; ++m) _Pragma("unroll") for (int n = 0; n < 2; ++n) _Pragma("unroll") for (int k = 0; k < 2; ++k) \
;         acc[ai][bj][m][n] = __builtin_amdgcn_mfma_f32_16x16x32_bf16(Bt[n][k], At[m][k], acc[ai][bj][m][n], 0, 0, 0); __builtin_amdgcn_s_setprio(0); } while (0)
; #define PG8_WAIT_V(n) asm volatile("s_waitcnt vmcnt(" #n ")" ::: "memory")
; #define PG8_WAIT_L(n) asm volatile("s_waitcnt lgkmcnt(" #n ")" ::: "memory")
; #define PG8_BAR __builtin_amdgcn_s_barrier()
; #define PG8_SCHED __builtin_amdgcn_sched_barrier(0)
; template <class Epi, class Sched, bool ALIGN_EPI = false, bool SP2 = false>
; __device__ __forceinline__ void gemm_phase(PG8_LAS unsigned char* lds, const Gemm g, const Sched& S, const Epi& E) {
;     ...
;             PG8_WAIT_V(8); PG8_WAIT_L(0); PG8_BAR; PG8_MMA(1, 0, At, B0); PG8_MMA(1, 1, At, B1); PG8_BAR; PG8_SCHED;
;             PG8_LDB(B0, 1, 0); PG8_LDB(B1, 1, 1); PG8_SCHED; PG8_LDA(At, 1, 0); PG8_STAGE(PG8_SA(0, 1), a2 + hstep, voffA);
;             PG8_WAIT_V(8); PG8_WAIT_L(0); PG8_BAR; PG8_MMA(0, 0, At, B0); PG8_MMA(0, 1, At, B1); PG8_BAR; PG8_SCHED;
	s_setprio 1
	s_waitcnt lgkmcnt(0)
	v_mfma_f32_16x16x32_bf16 v[60:63], v[136:139], v[214:217], v[60:63]
	v_mfma_f32_16x16x32_bf16 v[60:63], v[140:143], v[218:221], v[60:63]
	v_mfma_f32_16x16x32_bf16 v[56:59], v[176:179], v[218:221], v[56:59]
	v_mfma_f32_16x16x32_bf16 v[56:59], v[172:175], v[214:217], v[56:59]
	v_mfma_f32_16x16x32_bf16 v[52:55], v[180:183], v[214:217], v[52:55]
	v_mfma_f32_16x16x32_bf16 v[52:55], v[184:187], v[218:221], v[52:55]
	v_mfma_f32_16x16x32_bf16 v[44:47], v[210:213], v[218:221], v[44:47]
	v_mfma_f32_16x16x32_bf16 v[44:47], v[206:209], v[214:217], v[44:47]
	v_mfma_f32_16x16x32_bf16 v[28:31], v[206:209], v[222:225], v[28:31]
	v_mfma_f32_16x16x32_bf16 v[28:31], v[210:213], v[226:229], v[28:31]
	v_mfma_f32_16x16x32_bf16 v[36:39], v[184:187], v[226:229], v[36:39]
	v_mfma_f32_16x16x32_bf16 v[36:39], v[180:183], v[222:225], v[36:39]
	v_mfma_f32_16x16x32_bf16 v[40:43], v[172:175], v[222:225], v[40:43]
	v_mfma_f32_16x16x32_bf16 v[40:43], v[176:179], v[226:229], v[40:43]
	v_mfma_f32_16x16x32_bf16 v[48:51], v[140:143], v[226:229], v[48:51]
	v_mfma_f32_16x16x32_bf16 v[48:51], v[136:139], v[222:225], v[48:51]
	s_setprio 0
	s_setprio 1
	v_mfma_f32_16x16x32_bf16 v[32:35], v[136:139], v[230:233], v[32:35]
	v_mfma_f32_16x16x32_bf16 v[32:35], v[140:143], v[234:237], v[32:35]
	v_mfma_f32_16x16x32_bf16 v[24:27], v[176:179], v[234:237], v[24:27]
	v_mfma_f32_16x16x32_bf16 v[24:27], v[172:175], v[230:233], v[24:27]
	v_mfma_f32_16x16x32_bf16 v[20:23], v[180:183], v[230:233], v[20:23]
	v_mfma_f32_16x16x32_bf16 v[20:23], v[184:187], v[234:237], v[20:23]
	v_mfma_f32_16x16x32_bf16 v[16:19], v[210:213], v[234:237], v[16:19]
	v_mfma_f32_16x16x32_bf16 v[16:19], v[206:209], v[230:233], v[16:19]
	v_mfma_f32_16x16x32_bf16 v[0:3], v[206:209], v[238:241], v[0:3]
	v_mfma_f32_16x16x32_bf16 v[0:3], v[210:213], v[242:245], v[0:3]
	v_mfma_f32_16x16x32_bf16 v[4:7], v[184:187], v[242:245], v[4:7]
	v_mfma_f32_16x16x32_bf16 v[4:7], v[180:183], v[238:241], v[4:7]
	v_mfma_f32_16x16x32_bf16 v[8:11], v[172:175], v[238:241], v[8:11]
	v_mfma_f32_16x16x32_bf16 v[8:11], v[176:179], v[242:245], v[8:11]
	s_setprio 2
	s_barrier
	v_mfma_f32_16x16x32_bf16 v[12:15], v[140:143], v[242:245], v[12:15]
	v_mfma_f32_16x16x32_bf16 v[12:15], v[136:139], v[238:241], v[12:15]
	s_setprio 0
	s_add_i32 s44, 0, 0x18000
	v_add_u32_e32 v144, s44, v146
	s_add_i32 s45, 0, 0x1c000
	ds_read_b128 v[136:139], v144
	ds_read_b128 v[140:143], v144 offset:1024
	ds_read_b128 v[172:175], v144 offset:2048
	ds_read_b128 v[176:179], v144 offset:3072
	v_add_u32_e32 v144, s45, v146
	ds_read_b128 v[180:183], v144
	ds_read_b128 v[184:187], v144 offset:1024
	ds_read_b128 v[206:209], v144 offset:2048
	ds_read_b128 v[210:213], v144 offset:3072
	s_add_u32 s48, s48, 0x80000
	s_addc_u32 s49, s49, 0
	s_mov_b32 m0, s61
	v_lshl_add_u64 v[252:253], s[48:49], 0, v[164:165]
	ds_read_b128 v[214:217], v158 offset:32768
	ds_read_b128 v[218:221], v158 offset:33792
	ds_read_b128 v[222:225], v158 offset:34816
	ds_read_b128 v[226:229], v158 offset:35840
	ds_read_b128 v[230:233], v158 offset:36864
	ds_read_b128 v[234:237], v158 offset:37888
	ds_read_b128 v[238:241], v158 offset:38912
	ds_read_b128 v[242:245], v158 offset:39936
	global_load_lds_dwordx4 v[252:253], off
	v_lshl_add_u64 v[252:253], s[48:49], 0, v[168:169]
	s_mov_b32 m0, s68
	s_nop 0
	global_load_lds_dwordx4 v[252:253], off
	s_waitcnt vmcnt(8)
	s_waitcnt lgkmcnt(0)
	s_barrier
	s_setprio 1
	s_waitcnt lgkmcnt(0)
	v_mfma_f32_16x16x32_bf16 v[124:127], v[136:139], v[214:217], v[124:127]
	v_mfma_f32_16x16x32_bf16 v[124:127], v[140:143], v[218:221], v[124:127]
	v_mfma_f32_16x16x32_bf16 v[120:123], v[176:179], v[218:221], v[120:123]
	v_mfma_f32_16x16x32_bf16 v[120:123], v[172:175], v[214:217], v[120:123]
	v_mfma_f32_16x16x32_bf16 v[116:119], v[180:183], v[214:217], v[116:119]
	v_mfma_f32_16x16x32_bf16 v[116:119], v[184:187], v[218:221], v[116:119]
	v_mfma_f32_16x16x32_bf16 v[112:115], v[210:213], v[218:221], v[112:115]
	v_mfma_f32_16x16x32_bf16 v[112:115], v[206:209], v[214:217], v[112:115]
	v_mfma_f32_16x16x32_bf16 v[92:95], v[206:209], v[222:225], v[92:95]
	v_mfma_f32_16x16x32_bf16 v[92:95], v[210:213], v[226:229], v[92:95]
	v_mfma_f32_16x16x32_bf16 v[100:103], v[184:187], v[226:229], v[100:103]
	v_mfma_f32_16x16x32_bf16 v[100:103], v[180:183], v[222:225], v[100:103]
	v_mfma_f32_16x16x32_bf16 v[104:107], v[172:175], v[222:225], v[104:107]
	v_mfma_f32_16x16x32_bf16 v[104:107], v[176:179], v[226:229], v[104:107]
	v_mfma_f32_16x16x32_bf16 v[108:111], v[140:143], v[226:229], v[108:111]
	v_mfma_f32_16x16x32_bf16 v[108:111], v[136:139], v[222:225], v[108:111]
	s_setprio 0
	s_setprio 1
	v_mfma_f32_16x16x32_bf16 v[96:99], v[136:139], v[230:233], v[96:99]
	v_mfma_f32_16x16x32_bf16 v[96:99], v[140:143], v[234:237], v[96:99]
	v_mfma_f32_16x16x32_bf16 v[88:91], v[176:179], v[234:237], v[88:91]
	v_mfma_f32_16x16x32_bf16 v[88:91], v[172:175], v[230:233], v[88:91]
	v_mfma_f32_16x16x32_bf16 v[84:87], v[180:183], v[230:233], v[84:87]
	v_mfma_f32_16x16x32_bf16 v[84:87], v[184:187], v[234:237], v[84:87]
	v_mfma_f32_16x16x32_bf16 v[76:79], v[210:213], v[234:237], v[76:79]
	v_mfma_f32_16x16x32_bf16 v[76:79], v[206:209], v[230:233], v[76:79]
	v_mfma_f32_16x16x32_bf16 v[64:67], v[206:209], v[238:241], v[64:67]
	v_mfma_f32_16x16x32_bf16 v[64:67], v[210:213], v[242:245], v[64:67]
	v_mfma_f32_16x16x32_bf16 v[68:71], v[184:187], v[242:245], v[68:71]
	v_mfma_f32_16x16x32_bf16 v[68:71], v[180:183], v[238:241], v[68:71]
	v_mfma_f32_16x16x32_bf16 v[72:75], v[172:175], v[238:241], v[72:75]
	v_mfma_f32_16x16x32_bf16 v[72:75], v[176:179], v[242:245], v[72:75]
	s_setprio 2
	s_barrier
; #define PG8_STAGE(bufoff, gbase, voff) do { _Pragma("unroll") for (int _i = 0; _i < 2; ++_i) \
;         __builtin_amdgcn_global_load_lds((const unsigned*)((const char*)(gbase) + (voff)[_i]), (PG8_LAS unsigned*)(lds + (bufoff) + ldsw + _i * 8192), 16, 0, 0); } while (0)
; #define PG8_LDA(dst, b, h) do { _Pragma("unroll") for (int m = 0; m < 4; ++m) _Pragma("unroll") for (int k = 0; k < 2; ++k) dst[m][k] = *(const PG8_LAS bf16x8*)(lds + PG8_SA(b, h) + aoff + m * 2048 + k * 1024); } while (0)
; #define PG8_MMA(ai, bj, At, Bt) do { __builtin_amdgcn_s_setprio(1); _Pragma("unroll") for (int m = 0; m < 4; ++m) _Pragma("unroll") for (int n = 0; n < 2; ++n) _Pragma("unroll") for (int k = 0; k < 2; ++k) \
;         acc[ai][bj][m][n] = __builtin_amdgcn_mfma_f32_16x16x32_bf16(Bt[n][k], At[m][k], acc[ai][bj][m][n], 0, 0, 0); __builtin_amdgcn_s_setprio(0); } while (0)
; #define PG8_WAIT_V(n) asm volatile("s_waitcnt vmcnt(" #n ")" ::: "memory")
; #define PG8_WAIT_L(n) asm volatile("s_waitcnt lgkmcnt(" #n ")" ::: "memory")
; #define PG8_BAR __builtin_amdgcn_s_barrier()
; #define PG8_SCHED __builtin_amdgcn_sched_barrier(0)
; template <class Epi, class Sched, bool ALIGN_EPI = false, bool SP2 = false>
; __device__ __forceinline__ void gemm_phase(PG8_LAS unsigned char* lds, const Gemm g, const Sched& S, const Epi& E) {
;     ...
;         for (int t = 0; t < nt; t += 2) {
;     ...
;             PG8_WAIT_V(8); PG8_WAIT_L(0); PG8_BAR; PG8_MMA(0, 0, At, B0); PG8_MMA(0, 1, At, B1); PG8_BAR; PG8_SCHED;
;             PG8_LDA(At, 1, 1); PG8_STAGE(PG8_SB(1, 0), b3, voffB); PG8_STAGE(PG8_SB(1, 1), b3 + hstep, voffB); PG8_STAGE(PG8_SA(1, 0), a3, voffA);
;             PG8_WAIT_V(8); PG8_WAIT_L(0); PG8_BAR; PG8_MMA(1, 0, At, B0); PG8_MMA(1, 1, At, B1); PG8_BAR; PG8_SCHED;
	v_mfma_f32_16x16x32_bf16 v[80:83], v[140:143], v[242:245], v[80:83]
	v_mfma_f32_16x16x32_bf16 v[80:83], v[136:139], v[238:241], v[80:83]
	s_setprio 0
	s_add_i32 s44, s44, s41
	v_lshl_add_u64 v[200:201], v[200:201], 0, s[18:19]
	s_mov_b32 m0, s44
	ds_read_b128 v[214:217], v158 offset:49152
	ds_read_b128 v[218:221], v158 offset:50176
	ds_read_b128 v[222:225], v158 offset:51200
	ds_read_b128 v[226:229], v158 offset:52224
	ds_read_b128 v[230:233], v158 offset:53248
	ds_read_b128 v[234:237], v158 offset:54272
	ds_read_b128 v[238:241], v158 offset:55296
	ds_read_b128 v[242:245], v158 offset:56320
	global_load_lds_dwordx4 v[200:201], off
	s_add_i32 m0, s44, 0x2000
	s_add_u32 s28, s28, 0x80080
	v_lshl_add_u64 v[200:201], v[246:247], 0, s[18:19]
	s_addc_u32 s29, s29, 0
	s_add_i32 s44, s45, s41
	global_load_lds_dwordx4 v[200:201], off
	v_lshl_add_u64 v[200:201], s[28:29], 0, v[166:167]
	s_mov_b32 m0, s44
	s_nop 0
	global_load_lds_dwordx4 v[200:201], off
	v_lshl_add_u64 v[200:201], s[28:29], 0, v[170:171]
	s_add_i32 m0, s44, 0x2000
	s_nop 0
	global_load_lds_dwordx4 v[200:201], off
	v_lshl_add_u64 v[200:201], v[248:249], 0, s[18:19]
	s_mov_b32 m0, s70
	s_nop 0
	global_load_lds_dwordx4 v[200:201], off
	v_lshl_add_u64 v[200:201], v[250:251], 0, s[18:19]
	s_mov_b32 m0, s71
	s_nop 0
	global_load_lds_dwordx4 v[200:201], off
	s_add_i32 s79, s79, 2
	s_add_u32 s66, s66, 0x100
	s_addc_u32 s67, s67, 0
	s_add_u32 s77, s77, 0x100
	s_addc_u32 s78, s78, 0
	s_waitcnt vmcnt(8)
	s_waitcnt lgkmcnt(0)
	s_barrier
	s_setprio 1
	s_waitcnt lgkmcnt(0)
	v_mfma_f32_16x16x32_bf16 v[60:63], v[136:139], v[214:217], v[60:63]
	v_mfma_f32_16x16x32_bf16 v[60:63], v[140:143], v[218:221], v[60:63]
	v_mfma_f32_16x16x32_bf16 v[56:59], v[176:179], v[218:221], v[56:59]
	v_mfma_f32_16x16x32_bf16 v[56:59], v[172:175], v[214:217], v[56:59]
	v_mfma_f32_16x16x32_bf16 v[52:55], v[180:183], v[214:217], v[52:55]
	v_mfma_f32_16x16x32_bf16 v[52:55], v[184:187], v[218:221], v[52:55]
	v_mfma_f32_16x16x32_bf16 v[44:47], v[210:213], v[218:221], v[44:47]
	v_mfma_f32_16x16x32_bf16 v[44:47], v[206:209], v[214:217], v[44:47]
	v_mfma_f32_16x16x32_bf16 v[28:31], v[206:209], v[222:225], v[28:31]
	v_mfma_f32_16x16x32_bf16 v[28:31], v[210:213], v[226:229], v[28:31]
	v_mfma_f32_16x16x32_bf16 v[36:39], v[184:187], v[226:229], v[36:39]
	v_mfma_f32_16x16x32_bf16 v[36:39], v[180:183], v[222:225], v[36:39]
	v_mfma_f32_16x16x32_bf16 v[40:43], v[172:175], v[222:225], v[40:43]
	v_mfma_f32_16x16x32_bf16 v[40:43], v[176:179], v[226:229], v[40:43]
	v_mfma_f32_16x16x32_bf16 v[48:51], v[140:143], v[226:229], v[48:51]
	v_mfma_f32_16x16x32_bf16 v[48:51], v[136:139], v[222:225], v[48:51]
	s_setprio 0
	s_setprio 1
	v_mfma_f32_16x16x32_bf16 v[32:35], v[136:139], v[230:233], v[32:35]
	v_mfma_f32_16x16x32_bf16 v[32:35], v[140:143], v[234:237], v[32:35]
	v_mfma_f32_16x16x32_bf16 v[24:27], v[176:179], v[234:237], v[24:27]
	v_mfma_f32_16x16x32_bf16 v[24:27], v[172:175], v[230:233], v[24:27]
	v_mfma_f32_16x16x32_bf16 v[20:23], v[180:183], v[230:233], v[20:23]
	v_mfma_f32_16x16x32_bf16 v[20:23], v[184:187], v[234:237], v[20:23]
	v_mfma_f32_16x16x32_bf16 v[16:19], v[210:213], v[234:237], v[16:19]
	v_mfma_f32_16x16x32_bf16 v[16:19], v[206:209], v[230:233], v[16:19]
	v_mfma_f32_16x16x32_bf16 v[0:3], v[206:209], v[238:241], v[0:3]
	v_mfma_f32_16x16x32_bf16 v[0:3], v[210:213], v[242:245], v[0:3]
	v_mfma_f32_16x16x32_bf16 v[4:7], v[184:187], v[242:245], v[4:7]
	v_mfma_f32_16x16x32_bf16 v[4:7], v[180:183], v[238:241], v[4:7]
	v_mfma_f32_16x16x32_bf16 v[8:11], v[172:175], v[238:241], v[8:11]
	v_mfma_f32_16x16x32_bf16 v[8:11], v[176:179], v[242:245], v[8:11]
	s_setprio 2
	s_barrier
	v_mfma_f32_16x16x32_bf16 v[12:15], v[140:143], v[242:245], v[12:15]
	v_mfma_f32_16x16x32_bf16 v[12:15], v[136:139], v[238:241], v[12:15]
	s_setprio 0
	s_cmp_gt_u32 s79, 29
	s_cbranch_scc0 .LBB0_536
	s_and_b64 vcc, exec, s[20:21]
	s_cbranch_vccz .LBB0_539
	s_barrier

; #define PG8_STAGE(bufoff, gbase, voff) do { _Pragma("unroll") for (int _i = 0; _i < 2; ++_i) \
;         __builtin_amdgcn_global_load_lds((const unsigned*)((const char*)(gbase) + (voff)[_i]), (PG8_LAS unsigned*)(lds + (bufoff) + ldsw + _i * 8192), 16, 0, 0); } while (0)
; #define PG8_LDA(dst, b, h) do { _Pragma("unroll") for (int m = 0; m < 4; ++m) _Pragma("unroll") for (int k = 0; k < 2; ++k) dst[m][k] = *(const PG8_LAS bf16x8*)(lds + PG8_SA(b, h) + aoff + m * 2048 + k * 1024); } while (0)
; #define PG8_LDB(dst, b, h) do { _Pragma("unroll") for (int n = 0; n < 2; ++n) _Pragma("unroll") for (int k = 0; k < 2; ++k) dst[n][k] = *(const PG8_LAS bf16x8*)(lds + PG8_SB(b, h) + boff + n * 2048 + k * 1024); } while (0)
; #define PG8_MMA(ai, bj, At, Bt) do { __builtin_amdgcn_s_setprio(1); _Pragma("unroll") for (int m = 0; m < 4; ++m) _Pragma("unroll") for (int n = 0; n < 2; ++n) _Pragma("unroll") for (int k = 0; k < 2; ++k) \
;         acc[ai][bj][m][n] = __builtin_amdgcn_mfma_f32_16x16x32_bf16(Bt[n][k], At[m][k], acc[ai][bj][m][n], 0, 0, 0); __builtin_amdgcn_s_setprio(0); } while (0)
; #define PG8_WAIT_V(n) asm volatile("s_waitcnt vmcnt(" #n ")" ::: "memory")
; #define PG8_WAIT_L(n) asm volatile("s_waitcnt lgkmcnt(" #n ")" ::: "memory")
; #define PG8_BAR __builtin_amdgcn_s_barrier()
; #define PG8_SCHED __builtin_amdgcn_sched_barrier(0)
; template <class Epi, class Sched, bool ALIGN_EPI = false, bool SP2 = false>
; __device__ __forceinline__ void gemm_phase(PG8_LAS unsigned char* lds, const Gemm g, const Sched& S, const Epi& E) {
;     ...
;             const bool last = (t == nt - 2);
;             const char* a1 = cA + (size_t)(t + 1) * kstep;
;             const char* a2 = last ? nA : cA + (size_t)(t + 2) * kstep; const char* b2 = last ? nB : cB + (size_t)(t + 2) * kstep;
;             const char* a3 = a2 + kstep; const char* b3 = b2 + kstep;
;             if (last && has_next) S.a_ready(nxt);
;             if constexpr (SP2) {
;             PG8_LDB(B0, 0, 0); PG8_LDB(B1, 0, 1); PG8_SCHED; PG8_LDA(At, 0, 0); PG8_STAGE(PG8_SA(1, 1), a1 + hstep, voffA);
;             PG8_WAIT_V(8); PG8_WAIT_L(0); PG8_BAR; PG8_MMA(0, 0, At, B0); PG8_MMA(0, 1, At, B1); PG8_BAR; PG8_SCHED;
;             PG8_LDA(At, 0, 1); PG8_STAGE(PG8_SB(0, 0), b2, voffB); PG8_STAGE(PG8_SB(0, 1), b2 + hstep, voffB); PG8_STAGE(PG8_SA(0, 0), a2, voffA);
.LBB0_602:
	ds_read_b128 v[76:79], v171
	ds_read_b128 v[84:87], v171 offset:1024
	ds_read_b128 v[92:95], v171 offset:2048
	ds_read_b128 v[96:99], v171 offset:3072
	ds_read_b128 v[144:147], v186
	ds_read_b128 v[148:151], v186 offset:1024
	ds_read_b128 v[152:155], v186 offset:2048
	ds_read_b128 v[156:159], v186 offset:3072
	s_add_u32 s28, s62, 0xffea0080
	s_addc_u32 s29, s63, -1
	s_cmpk_eq_i32 s77, 0x54
	s_cselect_b32 s49, s39, s29
	s_cselect_b32 s48, s38, s28
	s_cselect_b32 s29, s41, s35
	s_cselect_b32 s28, s40, s34
	v_lshl_add_u64 v[200:201], s[62:63], 0, v[172:173]
	s_add_i32 m0, s61, 0xc000
	ds_read_b128 v[178:181], v187
	ds_read_b128 v[182:185], v187 offset:1024
	ds_read_b128 v[206:209], v187 offset:2048
	ds_read_b128 v[210:213], v187 offset:3072
	ds_read_b128 v[214:217], v187 offset:4096
	ds_read_b128 v[218:221], v187 offset:5120
	ds_read_b128 v[222:225], v187 offset:6144
	ds_read_b128 v[226:229], v187 offset:7168
	global_load_lds_dwordx4 v[200:201], off
	v_lshl_add_u64 v[200:201], s[62:63], 0, v[174:175]
	s_add_i32 m0, s61, 0xe000
	s_nop 0
	global_load_lds_dwordx4 v[200:201], off
	s_waitcnt vmcnt(8)
	s_waitcnt lgkmcnt(0)
	s_barrier
	s_setprio 1
	s_waitcnt lgkmcnt(0)
	v_mfma_f32_16x16x32_bf16 v[140:143], v[76:79], v[178:181], v[140:143]
	v_mfma_f32_16x16x32_bf16 v[140:143], v[84:87], v[182:185], v[140:143]
	v_mfma_f32_16x16x32_bf16 v[136:139], v[96:99], v[182:185], v[136:139]
	v_mfma_f32_16x16x32_bf16 v[136:139], v[92:95], v[178:181], v[136:139]
	v_mfma_f32_16x16x32_bf16 v[132:135], v[144:147], v[178:181], v[132:135]
	v_mfma_f32_16x16x32_bf16 v[132:135], v[148:151], v[182:185], v[132:135]
	v_mfma_f32_16x16x32_bf16 v[128:131], v[156:159], v[182:185], v[128:131]
	v_mfma_f32_16x16x32_bf16 v[128:131], v[152:155], v[178:181], v[128:131]
	v_mfma_f32_16x16x32_bf16 v[112:115], v[152:155], v[206:209], v[112:115]
	v_mfma_f32_16x16x32_bf16 v[112:115], v[156:159], v[210:213], v[112:115]
	v_mfma_f32_16x16x32_bf16 v[116:119], v[148:151], v[210:213], v[116:119]
	v_mfma_f32_16x16x32_bf16 v[116:119], v[144:147], v[206:209], v[116:119]
	v_mfma_f32_16x16x32_bf16 v[120:123], v[92:95], v[206:209], v[120:123]
	v_mfma_f32_16x16x32_bf16 v[120:123], v[96:99], v[210:213], v[120:123]
	v_mfma_f32_16x16x32_bf16 v[124:127], v[84:87], v[210:213], v[124:127]
	v_mfma_f32_16x16x32_bf16 v[124:127], v[76:79], v[206:209], v[124:127]
	s_setprio 0
	s_setprio 1
	v_mfma_f32_16x16x32_bf16 v[108:111], v[76:79], v[214:217], v[108:111]
	v_mfma_f32_16x16x32_bf16 v[108:111], v[84:87], v[218:221], v[108:111]
	v_mfma_f32_16x16x32_bf16 v[104:107], v[96:99], v[218:221], v[104:107]
	v_mfma_f32_16x16x32_bf16 v[104:107], v[92:95], v[214:217], v[104:107]
	v_mfma_f32_16x16x32_bf16 v[100:103], v[144:147], v[214:217], v[100:103]
	v_mfma_f32_16x16x32_bf16 v[100:103], v[148:151], v[218:221], v[100:103]
	v_mfma_f32_16x16x32_bf16 v[88:91], v[156:159], v[218:221], v[88:91]
	v_mfma_f32_16x16x32_bf16 v[88:91], v[152:155], v[214:217], v[88:91]
	v_mfma_f32_16x16x32_bf16 v[64:67], v[152:155], v[222:225], v[64:67]
	v_mfma_f32_16x16x32_bf16 v[64:67], v[156:159], v[226:229], v[64:67]
	v_mfma_f32_16x16x32_bf16 v[68:71], v[148:151], v[226:229], v[68:71]
	v_mfma_f32_16x16x32_bf16 v[68:71], v[144:147], v[222:225], v[68:71]
	v_mfma_f32_16x16x32_bf16 v[72:75], v[92:95], v[222:225], v[72:75]
	v_mfma_f32_16x16x32_bf16 v[72:75], v[96:99], v[226:229], v[72:75]
	s_setprio 2
	s_barrier
	v_mfma_f32_16x16x32_bf16 v[80:83], v[84:87], v[226:229], v[80:83]
	v_mfma_f32_16x16x32_bf16 v[80:83], v[76:79], v[222:225], v[80:83]
	s_setprio 0
	s_add_i32 s44, s70, s57
	v_lshl_add_u64 v[200:201], s[28:29], 0, v[160:161]
	s_mov_b32 m0, s44
	ds_read_b128 v[178:181], v187 offset:16384
	ds_read_b128 v[182:185], v187 offset:17408
	ds_read_b128 v[206:209], v187 offset:18432
	ds_read_b128 v[210:213], v187 offset:19456
	ds_read_b128 v[214:217], v187 offset:20480
	ds_read_b128 v[218:221], v187 offset:21504
	ds_read_b128 v[222:225], v187 offset:22528
	ds_read_b128 v[226:229], v187 offset:23552
	global_load_lds_dwordx4 v[200:201], off
	s_add_i32 m0, s44, 0x2000
	s_add_u32 s78, s28, 0x160000
	v_lshl_add_u64 v[230:231], s[28:29], 0, v[162:163]
	s_addc_u32 s79, s29, 0
	s_add_i32 s44, s71, s57
	global_load_lds_dwordx4 v[230:231], off
	v_lshl_add_u64 v[232:233], s[78:79], 0, v[160:161]
	s_mov_b32 m0, s44
	v_lshl_add_u64 v[234:235], s[48:49], 0, v[162:163]
	global_load_lds_dwordx4 v[232:233], off
	v_lshl_add_u64 v[232:233], s[78:79], 0, v[162:163]
	s_add_i32 m0, s44, 0x2000
	s_nop 0
	global_load_lds_dwordx4 v[232:233], off
	v_lshl_add_u64 v[232:233], s[48:49], 0, v[160:161]
	s_mov_b32 m0, s61
	s_nop 0
	global_load_lds_dwordx4 v[232:233], off
	s_mov_b32 m0, s64
	s_nop 0
	global_load_lds_dwordx4 v[234:235], off
	s_waitcnt vmcnt(8)
	s_waitcnt lgkmcnt(0)
	s_barrier
; #define PG8_STAGE(bufoff, gbase, voff) do { _Pragma("unroll") for (int _i = 0; _i < 2; ++_i) \
;         __builtin_amdgcn_global_load_lds((const unsigned*)((const char*)(gbase) + (voff)[_i]), (PG8_LAS unsigned*)(lds + (bufoff) + ldsw + _i * 8192), 16, 0, 0); } while (0)
; #define PG8_LDA(dst, b, h) do { _Pragma("unroll") for (int m = 0; m < 4; ++m) _Pragma("unroll") for (int k = 0; k < 2; ++k) dst[m][k] = *(const PG8_LAS bf16x8*)(lds + PG8_SA(b, h) + aoff + m * 2048 + k * 1024); } while (0)
; #define PG8_LDB(dst, b, h) do { _Pragma("unroll") for (int n = 0; n < 2; ++n) _Pragma("unroll") for (int k = 0; k < 2; ++k) dst[n][k] = *(const PG8_LAS bf16x8*)(lds + PG8_SB(b, h) + boff + n * 2048 + k * 1024); } while (0)
; #define PG8_MMA(ai, bj, At, Bt) do { __builtin_amdgcn_s_setprio(1); _Pragma("unroll") for (int m = 0; m < 4; ++m) _Pragma("unroll") for (int n = 0; n < 2; ++n) _Pragma("unroll") for (int k = 0; k < 2; ++k) \
;         acc[ai][bj][m][n] = __builtin_amdgcn_mfma_f32_16x16x32_bf16(Bt[n][k], At[m][k], acc[ai][bj][m][n], 0, 0, 0); __builtin_amdgcn_s_setprio(0); } while (0)
; #define PG8_WAIT_V(n) asm volatile("s_waitcnt vmcnt(" #n ")" ::: "memory")
; #define PG8_WAIT_L(n) asm volatile("s_waitcnt lgkmcnt(" #n ")" ::: "memory")
; #define PG8_BAR __builtin_amdgcn_s_barrier()
; #define PG8_SCHED __builtin_amdgcn_sched_barrier(0)
; template <class Epi, class Sched, bool ALIGN_EPI = false, bool SP2 = false>
; __device__ __forceinline__ void gemm_phase(PG8_LAS unsigned char* lds, const Gemm g, const Sched& S, const Epi& E) {
;     ...
;             PG8_WAIT_V(8); PG8_WAIT_L(0); PG8_BAR; PG8_MMA(1, 0, At, B0); PG8_MMA(1, 1, At, B1); PG8_BAR; PG8_SCHED;
;             PG8_LDB(B0, 1, 0); PG8_LDB(B1, 1, 1); PG8_SCHED; PG8_LDA(At, 1, 0); PG8_STAGE(PG8_SA(0, 1), a2 + hstep, voffA);
;             PG8_WAIT_V(8); PG8_WAIT_L(0); PG8_BAR; PG8_MMA(0, 0, At, B0); PG8_MMA(0, 1, At, B1); PG8_BAR; PG8_SCHED;
	s_setprio 1
	s_waitcnt lgkmcnt(0)
	v_mfma_f32_16x16x32_bf16 v[60:63], v[76:79], v[178:181], v[60:63]
	v_mfma_f32_16x16x32_bf16 v[60:63], v[84:87], v[182:185], v[60:63]
	v_mfma_f32_16x16x32_bf16 v[56:59], v[96:99], v[182:185], v[56:59]
	v_mfma_f32_16x16x32_bf16 v[56:59], v[92:95], v[178:181], v[56:59]
	v_mfma_f32_16x16x32_bf16 v[52:55], v[144:147], v[178:181], v[52:55]
	v_mfma_f32_16x16x32_bf16 v[52:55], v[148:151], v[182:185], v[52:55]
	v_mfma_f32_16x16x32_bf16 v[48:51], v[156:159], v[182:185], v[48:51]
	v_mfma_f32_16x16x32_bf16 v[48:51], v[152:155], v[178:181], v[48:51]
	v_mfma_f32_16x16x32_bf16 v[32:35], v[152:155], v[206:209], v[32:35]
	v_mfma_f32_16x16x32_bf16 v[32:35], v[156:159], v[210:213], v[32:35]
	v_mfma_f32_16x16x32_bf16 v[36:39], v[148:151], v[210:213], v[36:39]
	v_mfma_f32_16x16x32_bf16 v[36:39], v[144:147], v[206:209], v[36:39]
	v_mfma_f32_16x16x32_bf16 v[40:43], v[92:95], v[206:209], v[40:43]
	v_mfma_f32_16x16x32_bf16 v[40:43], v[96:99], v[210:213], v[40:43]
	v_mfma_f32_16x16x32_bf16 v[44:47], v[84:87], v[210:213], v[44:47]
	v_mfma_f32_16x16x32_bf16 v[44:47], v[76:79], v[206:209], v[44:47]
	s_setprio 0
	s_setprio 1
	v_mfma_f32_16x16x32_bf16 v[28:31], v[76:79], v[214:217], v[28:31]
	v_mfma_f32_16x16x32_bf16 v[28:31], v[84:87], v[218:221], v[28:31]
	v_mfma_f32_16x16x32_bf16 v[24:27], v[96:99], v[218:221], v[24:27]
	v_mfma_f32_16x16x32_bf16 v[24:27], v[92:95], v[214:217], v[24:27]
	v_mfma_f32_16x16x32_bf16 v[20:23], v[144:147], v[214:217], v[20:23]
	v_mfma_f32_16x16x32_bf16 v[20:23], v[148:151], v[218:221], v[20:23]
	v_mfma_f32_16x16x32_bf16 v[16:19], v[156:159], v[218:221], v[16:19]
	v_mfma_f32_16x16x32_bf16 v[16:19], v[152:155], v[214:217], v[16:19]
	v_mfma_f32_16x16x32_bf16 v[0:3], v[152:155], v[222:225], v[0:3]
	v_mfma_f32_16x16x32_bf16 v[0:3], v[156:159], v[226:229], v[0:3]
	v_mfma_f32_16x16x32_bf16 v[4:7], v[148:151], v[226:229], v[4:7]
	v_mfma_f32_16x16x32_bf16 v[4:7], v[144:147], v[222:225], v[4:7]
	v_mfma_f32_16x16x32_bf16 v[8:11], v[92:95], v[222:225], v[8:11]
	v_mfma_f32_16x16x32_bf16 v[8:11], v[96:99], v[226:229], v[8:11]
	s_setprio 2
	s_barrier
	v_mfma_f32_16x16x32_bf16 v[12:15], v[84:87], v[226:229], v[12:15]
	v_mfma_f32_16x16x32_bf16 v[12:15], v[76:79], v[222:225], v[12:15]
	s_setprio 0
	s_add_i32 s44, 0, 0x18000
	s_add_i32 s45, 0, 0x1c000
	v_add_u32_e32 v96, s44, v167
	v_add_u32_e32 v156, s45, v167
	ds_read_b128 v[76:79], v96
	ds_read_b128 v[84:87], v96 offset:1024
	ds_read_b128 v[92:95], v96 offset:2048
	ds_read_b128 v[96:99], v96 offset:3072
	ds_read_b128 v[144:147], v156
	ds_read_b128 v[148:151], v156 offset:1024
	ds_read_b128 v[152:155], v156 offset:2048
	ds_read_b128 v[156:159], v156 offset:3072
	s_add_u32 s48, s48, 0x160000
	s_addc_u32 s49, s49, 0
	s_mov_b32 m0, s65
	v_lshl_add_u64 v[236:237], s[48:49], 0, v[160:161]
	ds_read_b128 v[178:181], v187 offset:32768
	ds_read_b128 v[182:185], v187 offset:33792
	ds_read_b128 v[206:209], v187 offset:34816
	ds_read_b128 v[210:213], v187 offset:35840
	ds_read_b128 v[214:217], v187 offset:36864
	ds_read_b128 v[218:221], v187 offset:37888
	ds_read_b128 v[222:225], v187 offset:38912
	ds_read_b128 v[226:229], v187 offset:39936
	global_load_lds_dwordx4 v[236:237], off
	v_lshl_add_u64 v[236:237], s[48:49], 0, v[162:163]
	s_mov_b32 m0, s66
	s_nop 0
	global_load_lds_dwordx4 v[236:237], off
	s_waitcnt vmcnt(8)
	s_waitcnt lgkmcnt(0)
	s_barrier
	s_setprio 1
	s_waitcnt lgkmcnt(0)
	v_mfma_f32_16x16x32_bf16 v[140:143], v[76:79], v[178:181], v[140:143]
	v_mfma_f32_16x16x32_bf16 v[140:143], v[84:87], v[182:185], v[140:143]
	v_mfma_f32_16x16x32_bf16 v[136:139], v[96:99], v[182:185], v[136:139]
	v_mfma_f32_16x16x32_bf16 v[136:139], v[92:95], v[178:181], v[136:139]
	v_mfma_f32_16x16x32_bf16 v[132:135], v[144:147], v[178:181], v[132:135]
	v_mfma_f32_16x16x32_bf16 v[132:135], v[148:151], v[182:185], v[132:135]
	v_mfma_f32_16x16x32_bf16 v[128:131], v[156:159], v[182:185], v[128:131]
	v_mfma_f32_16x16x32_bf16 v[128:131], v[152:155], v[178:181], v[128:131]
	v_mfma_f32_16x16x32_bf16 v[112:115], v[152:155], v[206:209], v[112:115]
	v_mfma_f32_16x16x32_bf16 v[112:115], v[156:159], v[210:213], v[112:115]
	v_mfma_f32_16x16x32_bf16 v[116:119], v[148:151], v[210:213], v[116:119]
	v_mfma_f32_16x16x32_bf16 v[116:119], v[144:147], v[206:209], v[116:119]
	v_mfma_f32_16x16x32_bf16 v[120:123], v[92:95], v[206:209], v[120:123]
	v_mfma_f32_16x16x32_bf16 v[120:123], v[96:99], v[210:213], v[120:123]
	v_mfma_f32_16x16x32_bf16 v[124:127], v[84:87], v[210:213], v[124:127]
	v_mfma_f32_16x16x32_bf16 v[124:127], v[76:79], v[206:209], v[124:127]
	s_setprio 0
	s_setprio 1
	v_mfma_f32_16x16x32_bf16 v[108:111], v[76:79], v[214:217], v[108:111]
	v_mfma_f32_16x16x32_bf16 v[108:111], v[84:87], v[218:221], v[108:111]
	v_mfma_f32_16x16x32_bf16 v[104:107], v[96:99], v[218:221], v[104:107]
	v_mfma_f32_16x16x32_bf16 v[104:107], v[92:95], v[214:217], v[104:107]
	v_mfma_f32_16x16x32_bf16 v[100:103], v[144:147], v[214:217], v[100:103]
	v_mfma_f32_16x16x32_bf16 v[100:103], v[148:151], v[218:221], v[100:103]
	v_mfma_f32_16x16x32_bf16 v[88:91], v[156:159], v[218:221], v[88:91]
	v_mfma_f32_16x16x32_bf16 v[88:91], v[152:155], v[214:217], v[88:91]
	v_mfma_f32_16x16x32_bf16 v[64:67], v[152:155], v[222:225], v[64:67]
	v_mfma_f32_16x16x32_bf16 v[64:67], v[156:159], v[226:229], v[64:67]
	v_mfma_f32_16x16x32_bf16 v[68:71], v[148:151], v[226:229], v[68:71]
	v_mfma_f32_16x16x32_bf16 v[68:71], v[144:147], v[222:225], v[68:71]
	v_mfma_f32_16x16x32_bf16 v[72:75], v[92:95], v[222:225], v[72:75]
	v_mfma_f32_16x16x32_bf16 v[72:75], v[96:99], v[226:229], v[72:75]
	s_setprio 2
	s_barrier
; #define PG8_STAGE(bufoff, gbase, voff) do { _Pragma("unroll") for (int _i = 0; _i < 2; ++_i) \
;         __builtin_amdgcn_global_load_lds((const unsigned*)((const char*)(gbase) + (voff)[_i]), (PG8_LAS unsigned*)(lds + (bufoff) + ldsw + _i * 8192), 16, 0, 0); } while (0)
; #define PG8_LDA(dst, b, h) do { _Pragma("unroll") for (int m = 0; m < 4; ++m) _Pragma("unroll") for (int k = 0; k < 2; ++k) dst[m][k] = *(const PG8_LAS bf16x8*)(lds + PG8_SA(b, h) + aoff + m * 2048 + k * 1024); } while (0)
; #define PG8_MMA(ai, bj, At, Bt) do { __builtin_amdgcn_s_setprio(1); _Pragma("unroll") for (int m = 0; m < 4; ++m) _Pragma("unroll") for (int n = 0; n < 2; ++n) _Pragma("unroll") for (int k = 0; k < 2; ++k) \
;         acc[ai][bj][m][n] = __builtin_amdgcn_mfma_f32_16x16x32_bf16(Bt[n][k], At[m][k], acc[ai][bj][m][n], 0, 0, 0); __builtin_amdgcn_s_setprio(0); } while (0)
; #define PG8_WAIT_V(n) asm volatile("s_waitcnt vmcnt(" #n ")" ::: "memory")
; #define PG8_WAIT_L(n) asm volatile("s_waitcnt lgkmcnt(" #n ")" ::: "memory")
; #define PG8_BAR __builtin_amdgcn_s_barrier()
; #define PG8_SCHED __builtin_amdgcn_sched_barrier(0)
; template <class Epi, class Sched, bool ALIGN_EPI = false, bool SP2 = false>
; __device__ __forceinline__ void gemm_phase(PG8_LAS unsigned char* lds, const Gemm g, const Sched& S, const Epi& E) {
;     ...
;         for (int t = 0; t < nt; t += 2) {
;     ...
;             PG8_WAIT_V(8); PG8_WAIT_L(0); PG8_BAR; PG8_MMA(0, 0, At, B0); PG8_MMA(0, 1, At, B1); PG8_BAR; PG8_SCHED;
;             PG8_LDA(At, 1, 1); PG8_STAGE(PG8_SB(1, 0), b3, voffB); PG8_STAGE(PG8_SB(1, 1), b3 + hstep, voffB); PG8_STAGE(PG8_SA(1, 0), a3, voffA);
;             PG8_WAIT_V(8); PG8_WAIT_L(0); PG8_BAR; PG8_MMA(1, 0, At, B0); PG8_MMA(1, 1, At, B1); PG8_BAR; PG8_SCHED;
	v_mfma_f32_16x16x32_bf16 v[80:83], v[84:87], v[226:229], v[80:83]
	v_mfma_f32_16x16x32_bf16 v[80:83], v[76:79], v[222:225], v[80:83]
	s_setprio 0
	s_add_i32 s44, s44, s57
	v_lshl_add_u64 v[200:201], v[200:201], 0, s[20:21]
	s_mov_b32 m0, s44
	ds_read_b128 v[178:181], v187 offset:49152
	ds_read_b128 v[182:185], v187 offset:50176
	ds_read_b128 v[206:209], v187 offset:51200
	ds_read_b128 v[210:213], v187 offset:52224
	ds_read_b128 v[214:217], v187 offset:53248
	ds_read_b128 v[218:221], v187 offset:54272
	ds_read_b128 v[222:225], v187 offset:55296
	ds_read_b128 v[226:229], v187 offset:56320
	global_load_lds_dwordx4 v[200:201], off
	s_add_i32 m0, s44, 0x2000
	s_add_u32 s28, s28, 0x160080
	v_lshl_add_u64 v[200:201], v[230:231], 0, s[20:21]
	s_addc_u32 s29, s29, 0
	s_add_i32 s44, s45, s57
	global_load_lds_dwordx4 v[200:201], off
	v_lshl_add_u64 v[200:201], s[28:29], 0, v[160:161]
	s_mov_b32 m0, s44
	s_nop 0
	global_load_lds_dwordx4 v[200:201], off
	v_lshl_add_u64 v[200:201], s[28:29], 0, v[162:163]
	s_add_i32 m0, s44, 0x2000
	s_nop 0
	global_load_lds_dwordx4 v[200:201], off
	v_lshl_add_u64 v[200:201], v[232:233], 0, s[20:21]
	s_mov_b32 m0, s67
	s_nop 0
	global_load_lds_dwordx4 v[200:201], off
	v_lshl_add_u64 v[200:201], v[234:235], 0, s[20:21]
	s_mov_b32 m0, s68
	s_nop 0
	global_load_lds_dwordx4 v[200:201], off
	s_add_i32 s77, s77, 2
	s_add_u32 s62, s62, 0x100
	s_addc_u32 s63, s63, 0
	s_add_u32 s34, s34, 0x100
	s_addc_u32 s35, s35, 0
	s_waitcnt vmcnt(8)
	s_waitcnt lgkmcnt(0)
	s_barrier
	s_setprio 1
	s_waitcnt lgkmcnt(0)
	v_mfma_f32_16x16x32_bf16 v[60:63], v[76:79], v[178:181], v[60:63]
	v_mfma_f32_16x16x32_bf16 v[60:63], v[84:87], v[182:185], v[60:63]
	v_mfma_f32_16x16x32_bf16 v[56:59], v[96:99], v[182:185], v[56:59]
	v_mfma_f32_16x16x32_bf16 v[56:59], v[92:95], v[178:181], v[56:59]
	v_mfma_f32_16x16x32_bf16 v[52:55], v[144:147], v[178:181], v[52:55]
	v_mfma_f32_16x16x32_bf16 v[52:55], v[148:151], v[182:185], v[52:55]
	v_mfma_f32_16x16x32_bf16 v[48:51], v[156:159], v[182:185], v[48:51]
	v_mfma_f32_16x16x32_bf16 v[48:51], v[152:155], v[178:181], v[48:51]
	v_mfma_f32_16x16x32_bf16 v[32:35], v[152:155], v[206:209], v[32:35]
	v_mfma_f32_16x16x32_bf16 v[32:35], v[156:159], v[210:213], v[32:35]
	v_mfma_f32_16x16x32_bf16 v[36:39], v[148:151], v[210:213], v[36:39]
	v_mfma_f32_16x16x32_bf16 v[36:39], v[144:147], v[206:209], v[36:39]
	v_mfma_f32_16x16x32_bf16 v[40:43], v[92:95], v[206:209], v[40:43]
	v_mfma_f32_16x16x32_bf16 v[40:43], v[96:99], v[210:213], v[40:43]
	v_mfma_f32_16x16x32_bf16 v[44:47], v[84:87], v[210:213], v[44:47]
	v_mfma_f32_16x16x32_bf16 v[44:47], v[76:79], v[206:209], v[44:47]
	s_setprio 0
	s_setprio 1
	v_mfma_f32_16x16x32_bf16 v[28:31], v[76:79], v[214:217], v[28:31]
	v_mfma_f32_16x16x32_bf16 v[28:31], v[84:87], v[218:221], v[28:31]
	v_mfma_f32_16x16x32_bf16 v[24:27], v[96:99], v[218:221], v[24:27]
	v_mfma_f32_16x16x32_bf16 v[24:27], v[92:95], v[214:217], v[24:27]
	v_mfma_f32_16x16x32_bf16 v[20:23], v[144:147], v[214:217], v[20:23]
	v_mfma_f32_16x16x32_bf16 v[20:23], v[148:151], v[218:221], v[20:23]
	v_mfma_f32_16x16x32_bf16 v[16:19], v[156:159], v[218:221], v[16:19]
	v_mfma_f32_16x16x32_bf16 v[16:19], v[152:155], v[214:217], v[16:19]
	v_mfma_f32_16x16x32_bf16 v[0:3], v[152:155], v[222:225], v[0:3]
	v_mfma_f32_16x16x32_bf16 v[0:3], v[156:159], v[226:229], v[0:3]
	v_mfma_f32_16x16x32_bf16 v[4:7], v[148:151], v[226:229], v[4:7]
	v_mfma_f32_16x16x32_bf16 v[4:7], v[144:147], v[222:225], v[4:7]
	v_mfma_f32_16x16x32_bf16 v[8:11], v[92:95], v[222:225], v[8:11]
	v_mfma_f32_16x16x32_bf16 v[8:11], v[96:99], v[226:229], v[8:11]
	s_setprio 2
	s_barrier
	v_mfma_f32_16x16x32_bf16 v[12:15], v[84:87], v[226:229], v[12:15]
	v_mfma_f32_16x16x32_bf16 v[12:15], v[76:79], v[222:225], v[12:15]
	s_setprio 0
	s_cmpk_gt_u32 s77, 0x55
	s_cbranch_scc0 .LBB0_602
	s_and_b64 vcc, exec, s[22:23]
	s_cbranch_vccz .LBB0_605
	s_barrier

; #define PG8_STAGE(bufoff, gbase, voff) do { _Pragma("unroll") for (int _i = 0; _i < 2; ++_i) \
;         __builtin_amdgcn_global_load_lds((const unsigned*)((const char*)(gbase) + (voff)[_i]), (PG8_LAS unsigned*)(lds + (bufoff) + ldsw + _i * 8192), 16, 0, 0); } while (0)
; #define PG8_LDA(dst, b, h) do { _Pragma("unroll") for (int m = 0; m < 4; ++m) _Pragma("unroll") for (int k = 0; k < 2; ++k) dst[m][k] = *(const PG8_LAS bf16x8*)(lds + PG8_SA(b, h) + aoff + m * 2048 + k * 1024); } while (0)
; #define PG8_LDB(dst, b, h) do { _Pragma("unroll") for (int n = 0; n < 2; ++n) _Pragma("unroll") for (int k = 0; k < 2; ++k) dst[n][k] = *(const PG8_LAS bf16x8*)(lds + PG8_SB(b, h) + boff + n * 2048 + k * 1024); } while (0)
; #define PG8_MMA(ai, bj, At, Bt) do { __builtin_amdgcn_s_setprio(1); _Pragma("unroll") for (int m = 0; m < 4; ++m) _Pragma("unroll") for (int n = 0; n < 2; ++n) _Pragma("unroll") for (int k = 0; k < 2; ++k) \
;         acc[ai][bj][m][n] = __builtin_amdgcn_mfma_f32_16x16x32_bf16(Bt[n][k], At[m][k], acc[ai][bj][m][n], 0, 0, 0); __builtin_amdgcn_s_setprio(0); } while (0)
; #define PG8_WAIT_V(n) asm volatile("s_waitcnt vmcnt(" #n ")" ::: "memory")
; #define PG8_WAIT_L(n) asm volatile("s_waitcnt lgkmcnt(" #n ")" ::: "memory")
; #define PG8_BAR __builtin_amdgcn_s_barrier()
; #define PG8_SCHED __builtin_amdgcn_sched_barrier(0)
; template <class Epi, class Sched, bool ALIGN_EPI = false, bool SP2 = false>
; __device__ __forceinline__ void gemm_phase(PG8_LAS unsigned char* lds, const Gemm g, const Sched& S, const Epi& E) {
;     ...
;             const bool last = (t == nt - 2);
;             const char* a1 = cA + (size_t)(t + 1) * kstep;
;             const char* a2 = last ? nA : cA + (size_t)(t + 2) * kstep; const char* b2 = last ? nB : cB + (size_t)(t + 2) * kstep;
;             const char* a3 = a2 + kstep; const char* b3 = b2 + kstep;
;             if (last && has_next) S.a_ready(nxt);
;             if constexpr (SP2) {
;             PG8_LDB(B0, 0, 0); PG8_LDB(B1, 0, 1); PG8_SCHED; PG8_LDA(At, 0, 0); PG8_STAGE(PG8_SA(1, 1), a1 + hstep, voffA);
;             PG8_WAIT_V(8); PG8_WAIT_L(0); PG8_BAR; PG8_MMA(0, 0, At, B0); PG8_MMA(0, 1, At, B1); PG8_BAR; PG8_SCHED;
;             PG8_LDA(At, 0, 1); PG8_STAGE(PG8_SB(0, 0), b2, voffB); PG8_STAGE(PG8_SB(0, 1), b2 + hstep, voffB); PG8_STAGE(PG8_SA(0, 0), a2, voffA);
.LBB0_719:
	ds_read_b128 v[88:91], v208
	ds_read_b128 v[96:99], v208 offset:1024
	ds_read_b128 v[136:139], v208 offset:2048
	ds_read_b128 v[140:143], v208 offset:3072
	ds_read_b128 v[144:147], v209
	ds_read_b128 v[148:151], v209 offset:1024
	ds_read_b128 v[152:155], v209 offset:2048
	ds_read_b128 v[156:159], v209 offset:3072
	s_add_u32 s44, s62, 0xfff80080
	s_addc_u32 s45, s63, -1
	s_cmp_eq_u32 s76, 28
	s_cselect_b32 s59, s29, s45
	s_cselect_b32 s58, s34, s44
	s_cselect_b32 s57, s23, s75
	s_cselect_b32 s56, s35, s74
	v_lshl_add_u64 v[200:201], s[62:63], 0, v[172:173]
	s_add_i32 m0, s49, 0xc000
	ds_read_b128 v[178:181], v210
	ds_read_b128 v[182:185], v210 offset:1024
	ds_read_b128 v[186:189], v210 offset:2048
	ds_read_b128 v[212:215], v210 offset:3072
	ds_read_b128 v[216:219], v210 offset:4096
	ds_read_b128 v[220:223], v210 offset:5120
	ds_read_b128 v[224:227], v210 offset:6144
	ds_read_b128 v[228:231], v210 offset:7168
	global_load_lds_dwordx4 v[200:201], off
	v_lshl_add_u64 v[200:201], s[62:63], 0, v[174:175]
	s_add_i32 m0, s49, 0xe000
	s_nop 0
	global_load_lds_dwordx4 v[200:201], off
	s_waitcnt vmcnt(8)
	s_waitcnt lgkmcnt(0)
	s_barrier
	s_setprio 1
	s_waitcnt lgkmcnt(0)
	v_mfma_f32_16x16x32_bf16 v[128:131], v[88:91], v[178:181], v[128:131]
	v_mfma_f32_16x16x32_bf16 v[128:131], v[96:99], v[182:185], v[128:131]
	v_mfma_f32_16x16x32_bf16 v[120:123], v[140:143], v[182:185], v[120:123]
	v_mfma_f32_16x16x32_bf16 v[120:123], v[136:139], v[178:181], v[120:123]
	v_mfma_f32_16x16x32_bf16 v[132:135], v[144:147], v[178:181], v[132:135]
	v_mfma_f32_16x16x32_bf16 v[132:135], v[148:151], v[182:185], v[132:135]
	v_mfma_f32_16x16x32_bf16 v[124:127], v[156:159], v[182:185], v[124:127]
	v_mfma_f32_16x16x32_bf16 v[124:127], v[152:155], v[178:181], v[124:127]
	v_mfma_f32_16x16x32_bf16 v[104:107], v[152:155], v[186:189], v[104:107]
	v_mfma_f32_16x16x32_bf16 v[104:107], v[156:159], v[212:215], v[104:107]
	v_mfma_f32_16x16x32_bf16 v[112:115], v[148:151], v[212:215], v[112:115]
	v_mfma_f32_16x16x32_bf16 v[112:115], v[144:147], v[186:189], v[112:115]
	v_mfma_f32_16x16x32_bf16 v[108:111], v[136:139], v[186:189], v[108:111]
	v_mfma_f32_16x16x32_bf16 v[108:111], v[140:143], v[212:215], v[108:111]
	v_mfma_f32_16x16x32_bf16 v[116:119], v[96:99], v[212:215], v[116:119]
	v_mfma_f32_16x16x32_bf16 v[116:119], v[88:91], v[186:189], v[116:119]
	s_setprio 0
	s_setprio 1
	v_mfma_f32_16x16x32_bf16 v[100:103], v[88:91], v[216:219], v[100:103]
	v_mfma_f32_16x16x32_bf16 v[100:103], v[96:99], v[220:223], v[100:103]
	v_mfma_f32_16x16x32_bf16 v[84:87], v[140:143], v[220:223], v[84:87]
	v_mfma_f32_16x16x32_bf16 v[84:87], v[136:139], v[216:219], v[84:87]
	v_mfma_f32_16x16x32_bf16 v[92:95], v[144:147], v[216:219], v[92:95]
	v_mfma_f32_16x16x32_bf16 v[92:95], v[148:151], v[220:223], v[92:95]
	v_mfma_f32_16x16x32_bf16 v[80:83], v[156:159], v[220:223], v[80:83]
	v_mfma_f32_16x16x32_bf16 v[80:83], v[152:155], v[216:219], v[80:83]
	v_mfma_f32_16x16x32_bf16 v[64:67], v[152:155], v[224:227], v[64:67]
	v_mfma_f32_16x16x32_bf16 v[64:67], v[156:159], v[228:231], v[64:67]
	v_mfma_f32_16x16x32_bf16 v[72:75], v[148:151], v[228:231], v[72:75]
	v_mfma_f32_16x16x32_bf16 v[72:75], v[144:147], v[224:227], v[72:75]
	v_mfma_f32_16x16x32_bf16 v[68:71], v[136:139], v[224:227], v[68:71]
	v_mfma_f32_16x16x32_bf16 v[68:71], v[140:143], v[228:231], v[68:71]
	s_setprio 2
	s_barrier
	v_mfma_f32_16x16x32_bf16 v[76:79], v[96:99], v[228:231], v[76:79]
	v_mfma_f32_16x16x32_bf16 v[76:79], v[88:91], v[224:227], v[76:79]
	s_setprio 0
	s_add_i32 s44, s71, s65
	v_lshl_add_u64 v[200:201], s[56:57], 0, v[164:165]
	s_mov_b32 m0, s44
	ds_read_b128 v[178:181], v210 offset:16384
	ds_read_b128 v[182:185], v210 offset:17408
	ds_read_b128 v[186:189], v210 offset:18432
	ds_read_b128 v[212:215], v210 offset:19456
	ds_read_b128 v[216:219], v210 offset:20480
	ds_read_b128 v[220:223], v210 offset:21504
	ds_read_b128 v[224:227], v210 offset:22528
	ds_read_b128 v[228:231], v210 offset:23552
	global_load_lds_dwordx4 v[200:201], off
	s_add_i32 m0, s44, 0x2000
	s_add_u32 s78, s56, 0x80000
	v_lshl_add_u64 v[232:233], s[56:57], 0, v[168:169]
	s_addc_u32 s79, s57, 0
	s_add_i32 s44, s72, s65
	global_load_lds_dwordx4 v[232:233], off
	v_lshl_add_u64 v[234:235], s[78:79], 0, v[164:165]
	s_mov_b32 m0, s44
	v_lshl_add_u64 v[236:237], s[58:59], 0, v[168:169]
	global_load_lds_dwordx4 v[234:235], off
	v_lshl_add_u64 v[234:235], s[78:79], 0, v[168:169]
	s_add_i32 m0, s44, 0x2000
	s_nop 0
	global_load_lds_dwordx4 v[234:235], off
	v_lshl_add_u64 v[234:235], s[58:59], 0, v[164:165]
	s_mov_b32 m0, s49
	s_nop 0
	global_load_lds_dwordx4 v[234:235], off
	s_mov_b32 m0, s61
	s_nop 0
	global_load_lds_dwordx4 v[236:237], off
	s_waitcnt vmcnt(8)
	s_waitcnt lgkmcnt(0)
	s_barrier
; #define PG8_STAGE(bufoff, gbase, voff) do { _Pragma("unroll") for (int _i = 0; _i < 2; ++_i) \
;         __builtin_amdgcn_global_load_lds((const unsigned*)((const char*)(gbase) + (voff)[_i]), (PG8_LAS unsigned*)(lds + (bufoff) + ldsw + _i * 8192), 16, 0, 0); } while (0)
; #define PG8_LDA(dst, b, h) do { _Pragma("unroll") for (int m = 0; m < 4; ++m) _Pragma("unroll") for (int k = 0; k < 2; ++k) dst[m][k] = *(const PG8_LAS bf16x8*)(lds + PG8_SA(b, h) + aoff + m * 2048 + k * 1024); } while (0)
; #define PG8_LDB(dst, b, h) do { _Pragma("unroll") for (int n = 0; n < 2; ++n) _Pragma("unroll") for (int k = 0; k < 2; ++k) dst[n][k] = *(const PG8_LAS bf16x8*)(lds + PG8_SB(b, h) + boff + n * 2048 + k * 1024); } while (0)
; #define PG8_MMA(ai, bj, At, Bt) do { __builtin_amdgcn_s_setprio(1); _Pragma("unroll") for (int m = 0; m < 4; ++m) _Pragma("unroll") for (int n = 0; n < 2; ++n) _Pragma("unroll") for (int k = 0; k < 2; ++k) \
;         acc[ai][bj][m][n] = __builtin_amdgcn_mfma_f32_16x16x32_bf16(Bt[n][k], At[m][k], acc[ai][bj][m][n], 0, 0, 0); __builtin_amdgcn_s_setprio(0); } while (0)
; #define PG8_WAIT_V(n) asm volatile("s_waitcnt vmcnt(" #n ")" ::: "memory")
; #define PG8_WAIT_L(n) asm volatile("s_waitcnt lgkmcnt(" #n ")" ::: "memory")
; #define PG8_BAR __builtin_amdgcn_s_barrier()
; #define PG8_SCHED __builtin_amdgcn_sched_barrier(0)
; template <class Epi, class Sched, bool ALIGN_EPI = false, bool SP2 = false>
; __device__ __forceinline__ void gemm_phase(PG8_LAS unsigned char* lds, const Gemm g, const Sched& S, const Epi& E) {
;     ...
;             PG8_WAIT_V(8); PG8_WAIT_L(0); PG8_BAR; PG8_MMA(1, 0, At, B0); PG8_MMA(1, 1, At, B1); PG8_BAR; PG8_SCHED;
;             PG8_LDB(B0, 1, 0); PG8_LDB(B1, 1, 1); PG8_SCHED; PG8_LDA(At, 1, 0); PG8_STAGE(PG8_SA(0, 1), a2 + hstep, voffA);
;             PG8_WAIT_V(8); PG8_WAIT_L(0); PG8_BAR; PG8_MMA(0, 0, At, B0); PG8_MMA(0, 1, At, B1); PG8_BAR; PG8_SCHED;
	s_setprio 1
	s_waitcnt lgkmcnt(0)
	v_mfma_f32_16x16x32_bf16 v[56:59], v[88:91], v[178:181], v[56:59]
	v_mfma_f32_16x16x32_bf16 v[56:59], v[96:99], v[182:185], v[56:59]
	v_mfma_f32_16x16x32_bf16 v[48:51], v[140:143], v[182:185], v[48:51]
	v_mfma_f32_16x16x32_bf16 v[48:51], v[136:139], v[178:181], v[48:51]
	v_mfma_f32_16x16x32_bf16 v[60:63], v[144:147], v[178:181], v[60:63]
	v_mfma_f32_16x16x32_bf16 v[60:63], v[148:151], v[182:185], v[60:63]
	v_mfma_f32_16x16x32_bf16 v[52:55], v[156:159], v[182:185], v[52:55]
	v_mfma_f32_16x16x32_bf16 v[52:55], v[152:155], v[178:181], v[52:55]
	v_mfma_f32_16x16x32_bf16 v[32:35], v[152:155], v[186:189], v[32:35]
	v_mfma_f32_16x16x32_bf16 v[32:35], v[156:159], v[212:215], v[32:35]
	v_mfma_f32_16x16x32_bf16 v[40:43], v[148:151], v[212:215], v[40:43]
	v_mfma_f32_16x16x32_bf16 v[40:43], v[144:147], v[186:189], v[40:43]
	v_mfma_f32_16x16x32_bf16 v[36:39], v[136:139], v[186:189], v[36:39]
	v_mfma_f32_16x16x32_bf16 v[36:39], v[140:143], v[212:215], v[36:39]
	v_mfma_f32_16x16x32_bf16 v[44:47], v[96:99], v[212:215], v[44:47]
	v_mfma_f32_16x16x32_bf16 v[44:47], v[88:91], v[186:189], v[44:47]
	s_setprio 0
	s_setprio 1
	v_mfma_f32_16x16x32_bf16 v[28:31], v[88:91], v[216:219], v[28:31]
	v_mfma_f32_16x16x32_bf16 v[28:31], v[96:99], v[220:223], v[28:31]
	v_mfma_f32_16x16x32_bf16 v[20:23], v[140:143], v[220:223], v[20:23]
	v_mfma_f32_16x16x32_bf16 v[20:23], v[136:139], v[216:219], v[20:23]
	v_mfma_f32_16x16x32_bf16 v[24:27], v[144:147], v[216:219], v[24:27]
	v_mfma_f32_16x16x32_bf16 v[24:27], v[148:151], v[220:223], v[24:27]
	v_mfma_f32_16x16x32_bf16 v[16:19], v[156:159], v[220:223], v[16:19]
	v_mfma_f32_16x16x32_bf16 v[16:19], v[152:155], v[216:219], v[16:19]
	v_mfma_f32_16x16x32_bf16 v[0:3], v[152:155], v[224:227], v[0:3]
	v_mfma_f32_16x16x32_bf16 v[0:3], v[156:159], v[228:231], v[0:3]
	v_mfma_f32_16x16x32_bf16 v[8:11], v[148:151], v[228:231], v[8:11]
	v_mfma_f32_16x16x32_bf16 v[8:11], v[144:147], v[224:227], v[8:11]
	v_mfma_f32_16x16x32_bf16 v[4:7], v[136:139], v[224:227], v[4:7]
	v_mfma_f32_16x16x32_bf16 v[4:7], v[140:143], v[228:231], v[4:7]
	s_setprio 2
	s_barrier
	v_mfma_f32_16x16x32_bf16 v[12:15], v[96:99], v[228:231], v[12:15]
	v_mfma_f32_16x16x32_bf16 v[12:15], v[88:91], v[224:227], v[12:15]
	s_setprio 0
	s_add_i32 s44, 0, 0x18000
	s_add_i32 s45, 0, 0x1c000
	v_add_u32_e32 v140, s44, v163
	v_add_u32_e32 v156, s45, v163
	ds_read_b128 v[88:91], v140
	ds_read_b128 v[96:99], v140 offset:1024
	ds_read_b128 v[136:139], v140 offset:2048
	ds_read_b128 v[140:143], v140 offset:3072
	ds_read_b128 v[144:147], v156
	ds_read_b128 v[148:151], v156 offset:1024
	ds_read_b128 v[152:155], v156 offset:2048
	ds_read_b128 v[156:159], v156 offset:3072
	s_add_u32 s58, s58, 0x80000
	s_addc_u32 s59, s59, 0
	s_mov_b32 m0, s66
	v_lshl_add_u64 v[238:239], s[58:59], 0, v[164:165]
	ds_read_b128 v[178:181], v210 offset:32768
	ds_read_b128 v[182:185], v210 offset:33792
	ds_read_b128 v[186:189], v210 offset:34816
	ds_read_b128 v[212:215], v210 offset:35840
	ds_read_b128 v[216:219], v210 offset:36864
	ds_read_b128 v[220:223], v210 offset:37888
	ds_read_b128 v[224:227], v210 offset:38912
	ds_read_b128 v[228:231], v210 offset:39936
	global_load_lds_dwordx4 v[238:239], off
	v_lshl_add_u64 v[238:239], s[58:59], 0, v[168:169]
	s_mov_b32 m0, s67
	s_nop 0
	global_load_lds_dwordx4 v[238:239], off
	s_waitcnt vmcnt(8)
	s_waitcnt lgkmcnt(0)
	s_barrier
	s_setprio 1
	s_waitcnt lgkmcnt(0)
	v_mfma_f32_16x16x32_bf16 v[128:131], v[88:91], v[178:181], v[128:131]
	v_mfma_f32_16x16x32_bf16 v[128:131], v[96:99], v[182:185], v[128:131]
	v_mfma_f32_16x16x32_bf16 v[120:123], v[140:143], v[182:185], v[120:123]
	v_mfma_f32_16x16x32_bf16 v[120:123], v[136:139], v[178:181], v[120:123]
	v_mfma_f32_16x16x32_bf16 v[132:135], v[144:147], v[178:181], v[132:135]
	v_mfma_f32_16x16x32_bf16 v[132:135], v[148:151], v[182:185], v[132:135]
	v_mfma_f32_16x16x32_bf16 v[124:127], v[156:159], v[182:185], v[124:127]
	v_mfma_f32_16x16x32_bf16 v[124:127], v[152:155], v[178:181], v[124:127]
	v_mfma_f32_16x16x32_bf16 v[104:107], v[152:155], v[186:189], v[104:107]
	v_mfma_f32_16x16x32_bf16 v[104:107], v[156:159], v[212:215], v[104:107]
	v_mfma_f32_16x16x32_bf16 v[112:115], v[148:151], v[212:215], v[112:115]
	v_mfma_f32_16x16x32_bf16 v[112:115], v[144:147], v[186:189], v[112:115]
	v_mfma_f32_16x16x32_bf16 v[108:111], v[136:139], v[186:189], v[108:111]
	v_mfma_f32_16x16x32_bf16 v[108:111], v[140:143], v[212:215], v[108:111]
	v_mfma_f32_16x16x32_bf16 v[116:119], v[96:99], v[212:215], v[116:119]
	v_mfma_f32_16x16x32_bf16 v[116:119], v[88:91], v[186:189], v[116:119]
	s_setprio 0
	s_setprio 1
	v_mfma_f32_16x16x32_bf16 v[100:103], v[88:91], v[216:219], v[100:103]
	v_mfma_f32_16x16x32_bf16 v[100:103], v[96:99], v[220:223], v[100:103]
	v_mfma_f32_16x16x32_bf16 v[84:87], v[140:143], v[220:223], v[84:87]
	v_mfma_f32_16x16x32_bf16 v[84:87], v[136:139], v[216:219], v[84:87]
	v_mfma_f32_16x16x32_bf16 v[92:95], v[144:147], v[216:219], v[92:95]
	v_mfma_f32_16x16x32_bf16 v[92:95], v[148:151], v[220:223], v[92:95]
	v_mfma_f32_16x16x32_bf16 v[80:83], v[156:159], v[220:223], v[80:83]
	v_mfma_f32_16x16x32_bf16 v[80:83], v[152:155], v[216:219], v[80:83]
	v_mfma_f32_16x16x32_bf16 v[64:67], v[152:155], v[224:227], v[64:67]
	v_mfma_f32_16x16x32_bf16 v[64:67], v[156:159], v[228:231], v[64:67]
	v_mfma_f32_16x16x32_bf16 v[72:75], v[148:151], v[228:231], v[72:75]
	v_mfma_f32_16x16x32_bf16 v[72:75], v[144:147], v[224:227], v[72:75]
	v_mfma_f32_16x16x32_bf16 v[68:71], v[136:139], v[224:227], v[68:71]
	v_mfma_f32_16x16x32_bf16 v[68:71], v[140:143], v[228:231], v[68:71]
	s_setprio 2
	s_barrier
; #define PG8_STAGE(bufoff, gbase, voff) do { _Pragma("unroll") for (int _i = 0; _i < 2; ++_i) \
;         __builtin_amdgcn_global_load_lds((const unsigned*)((const char*)(gbase) + (voff)[_i]), (PG8_LAS unsigned*)(lds + (bufoff) + ldsw + _i * 8192), 16, 0, 0); } while (0)
; #define PG8_LDA(dst, b, h) do { _Pragma("unroll") for (int m = 0; m < 4; ++m) _Pragma("unroll") for (int k = 0; k < 2; ++k) dst[m][k] = *(const PG8_LAS bf16x8*)(lds + PG8_SA(b, h) + aoff + m * 2048 + k * 1024); } while (0)
; #define PG8_MMA(ai, bj, At, Bt) do { __builtin_amdgcn_s_setprio(1); _Pragma("unroll") for (int m = 0; m < 4; ++m) _Pragma("unroll") for (int n = 0; n < 2; ++n) _Pragma("unroll") for (int k = 0; k < 2; ++k) \
;         acc[ai][bj][m][n] = __builtin_amdgcn_mfma_f32_16x16x32_bf16(Bt[n][k], At[m][k], acc[ai][bj][m][n], 0, 0, 0); __builtin_amdgcn_s_setprio(0); } while (0)
; #define PG8_WAIT_V(n) asm volatile("s_waitcnt vmcnt(" #n ")" ::: "memory")
; #define PG8_WAIT_L(n) asm volatile("s_waitcnt lgkmcnt(" #n ")" ::: "memory")
; #define PG8_BAR __builtin_amdgcn_s_barrier()
; #define PG8_SCHED __builtin_amdgcn_sched_barrier(0)
; template <class Epi, class Sched, bool ALIGN_EPI = false, bool SP2 = false>
; __device__ __forceinline__ void gemm_phase(PG8_LAS unsigned char* lds, const Gemm g, const Sched& S, const Epi& E) {
;     ...
;         for (int t = 0; t < nt; t += 2) {
;     ...
;             PG8_WAIT_V(8); PG8_WAIT_L(0); PG8_BAR; PG8_MMA(0, 0, At, B0); PG8_MMA(0, 1, At, B1); PG8_BAR; PG8_SCHED;
;             PG8_LDA(At, 1, 1); PG8_STAGE(PG8_SB(1, 0), b3, voffB); PG8_STAGE(PG8_SB(1, 1), b3 + hstep, voffB); PG8_STAGE(PG8_SA(1, 0), a3, voffA);
;             PG8_WAIT_V(8); PG8_WAIT_L(0); PG8_BAR; PG8_MMA(1, 0, At, B0); PG8_MMA(1, 1, At, B1); PG8_BAR; PG8_SCHED;
	v_mfma_f32_16x16x32_bf16 v[76:79], v[96:99], v[228:231], v[76:79]
	v_mfma_f32_16x16x32_bf16 v[76:79], v[88:91], v[224:227], v[76:79]
	s_setprio 0
	s_add_i32 s44, s44, s65
	v_lshl_add_u64 v[200:201], v[200:201], 0, s[18:19]
	s_mov_b32 m0, s44
	ds_read_b128 v[178:181], v210 offset:49152
	ds_read_b128 v[182:185], v210 offset:50176
	ds_read_b128 v[186:189], v210 offset:51200
	ds_read_b128 v[212:215], v210 offset:52224
	ds_read_b128 v[216:219], v210 offset:53248
	ds_read_b128 v[220:223], v210 offset:54272
	ds_read_b128 v[224:227], v210 offset:55296
	ds_read_b128 v[228:231], v210 offset:56320
	global_load_lds_dwordx4 v[200:201], off
	s_add_i32 m0, s44, 0x2000
	s_add_u32 s56, s56, 0x80080
	v_lshl_add_u64 v[200:201], v[232:233], 0, s[18:19]
	s_addc_u32 s57, s57, 0
	s_add_i32 s44, s45, s65
	global_load_lds_dwordx4 v[200:201], off
	v_lshl_add_u64 v[200:201], s[56:57], 0, v[164:165]
	s_mov_b32 m0, s44
	s_nop 0
	global_load_lds_dwordx4 v[200:201], off
	v_lshl_add_u64 v[200:201], s[56:57], 0, v[168:169]
	s_add_i32 m0, s44, 0x2000
	s_nop 0
	global_load_lds_dwordx4 v[200:201], off
	v_lshl_add_u64 v[200:201], v[234:235], 0, s[18:19]
	s_mov_b32 m0, s68
	s_nop 0
	global_load_lds_dwordx4 v[200:201], off
	v_lshl_add_u64 v[200:201], v[236:237], 0, s[18:19]
	s_mov_b32 m0, s69
	s_nop 0
	global_load_lds_dwordx4 v[200:201], off
	s_add_i32 s76, s76, 2
	s_add_u32 s62, s62, 0x100
	s_addc_u32 s63, s63, 0
	s_add_u32 s74, s74, 0x100
	s_addc_u32 s75, s75, 0
	s_waitcnt vmcnt(8)
	s_waitcnt lgkmcnt(0)
	s_barrier
	s_setprio 1
	s_waitcnt lgkmcnt(0)
	v_mfma_f32_16x16x32_bf16 v[56:59], v[88:91], v[178:181], v[56:59]
	v_mfma_f32_16x16x32_bf16 v[56:59], v[96:99], v[182:185], v[56:59]
	v_mfma_f32_16x16x32_bf16 v[48:51], v[140:143], v[182:185], v[48:51]
	v_mfma_f32_16x16x32_bf16 v[48:51], v[136:139], v[178:181], v[48:51]
	v_mfma_f32_16x16x32_bf16 v[60:63], v[144:147], v[178:181], v[60:63]
	v_mfma_f32_16x16x32_bf16 v[60:63], v[148:151], v[182:185], v[60:63]
	v_mfma_f32_16x16x32_bf16 v[52:55], v[156:159], v[182:185], v[52:55]
	v_mfma_f32_16x16x32_bf16 v[52:55], v[152:155], v[178:181], v[52:55]
	v_mfma_f32_16x16x32_bf16 v[32:35], v[152:155], v[186:189], v[32:35]
	v_mfma_f32_16x16x32_bf16 v[32:35], v[156:159], v[212:215], v[32:35]
	v_mfma_f32_16x16x32_bf16 v[40:43], v[148:151], v[212:215], v[40:43]
	v_mfma_f32_16x16x32_bf16 v[40:43], v[144:147], v[186:189], v[40:43]
	v_mfma_f32_16x16x32_bf16 v[36:39], v[136:139], v[186:189], v[36:39]
	v_mfma_f32_16x16x32_bf16 v[36:39], v[140:143], v[212:215], v[36:39]
	v_mfma_f32_16x16x32_bf16 v[44:47], v[96:99], v[212:215], v[44:47]
	v_mfma_f32_16x16x32_bf16 v[44:47], v[88:91], v[186:189], v[44:47]
	s_setprio 0
	s_setprio 1
	v_mfma_f32_16x16x32_bf16 v[28:31], v[88:91], v[216:219], v[28:31]
	v_mfma_f32_16x16x32_bf16 v[28:31], v[96:99], v[220:223], v[28:31]
	v_mfma_f32_16x16x32_bf16 v[20:23], v[140:143], v[220:223], v[20:23]
	v_mfma_f32_16x16x32_bf16 v[20:23], v[136:139], v[216:219], v[20:23]
	v_mfma_f32_16x16x32_bf16 v[24:27], v[144:147], v[216:219], v[24:27]
	v_mfma_f32_16x16x32_bf16 v[24:27], v[148:151], v[220:223], v[24:27]
	v_mfma_f32_16x16x32_bf16 v[16:19], v[156:159], v[220:223], v[16:19]
	v_mfma_f32_16x16x32_bf16 v[16:19], v[152:155], v[216:219], v[16:19]
	v_mfma_f32_16x16x32_bf16 v[0:3], v[152:155], v[224:227], v[0:3]
	v_mfma_f32_16x16x32_bf16 v[0:3], v[156:159], v[228:231], v[0:3]
	v_mfma_f32_16x16x32_bf16 v[8:11], v[148:151], v[228:231], v[8:11]
	v_mfma_f32_16x16x32_bf16 v[8:11], v[144:147], v[224:227], v[8:11]
	v_mfma_f32_16x16x32_bf16 v[4:7], v[136:139], v[224:227], v[4:7]
	v_mfma_f32_16x16x32_bf16 v[4:7], v[140:143], v[228:231], v[4:7]
	s_setprio 2
	s_barrier
	v_mfma_f32_16x16x32_bf16 v[12:15], v[96:99], v[228:231], v[12:15]
	v_mfma_f32_16x16x32_bf16 v[12:15], v[88:91], v[224:227], v[12:15]
	s_setprio 0
	s_cmp_gt_u32 s76, 29
	s_cbranch_scc0 .LBB0_719
	s_and_b64 vcc, exec, s[20:21]
	s_cbranch_vccz .LBB0_722
	s_barrier

; #define PG8_STAGE(bufoff, gbase, voff) do { _Pragma("unroll") for (int _i = 0; _i < 2; ++_i) \
;         __builtin_amdgcn_global_load_lds((const unsigned*)((const char*)(gbase) + (voff)[_i]), (PG8_LAS unsigned*)(lds + (bufoff) + ldsw + _i * 8192), 16, 0, 0); } while (0)
; #define PG8_LDA(dst, b, h) do { _Pragma("unroll") for (int m = 0; m < 4; ++m) _Pragma("unroll") for (int k = 0; k < 2; ++k) dst[m][k] = *(const PG8_LAS bf16x8*)(lds + PG8_SA(b, h) + aoff + m * 2048 + k * 1024); } while (0)
; #define PG8_LDB(dst, b, h) do { _Pragma("unroll") for (int n = 0; n < 2; ++n) _Pragma("unroll") for (int k = 0; k < 2; ++k) dst[n][k] = *(const PG8_LAS bf16x8*)(lds + PG8_SB(b, h) + boff + n * 2048 + k * 1024); } while (0)
; #define PG8_MMA(ai, bj, At, Bt) do { __builtin_amdgcn_s_setprio(1); _Pragma("unroll") for (int m = 0; m < 4; ++m) _Pragma("unroll") for (int n = 0; n < 2; ++n) _Pragma("unroll") for (int k = 0; k < 2; ++k) \
;         acc[ai][bj][m][n] = __builtin_amdgcn_mfma_f32_16x16x32_bf16(Bt[n][k], At[m][k], acc[ai][bj][m][n], 0, 0, 0); __builtin_amdgcn_s_setprio(0); } while (0)
; #define PG8_WAIT_V(n) asm volatile("s_waitcnt vmcnt(" #n ")" ::: "memory")
; #define PG8_WAIT_L(n) asm volatile("s_waitcnt lgkmcnt(" #n ")" ::: "memory")
; #define PG8_BAR __builtin_amdgcn_s_barrier()
; #define PG8_SCHED __builtin_amdgcn_sched_barrier(0)
; template <class Epi, class Sched, bool ALIGN_EPI = false, bool SP2 = false>
; __device__ __forceinline__ void gemm_phase(PG8_LAS unsigned char* lds, const Gemm g, const Sched& S, const Epi& E) {
;     ...
;             const bool last = (t == nt - 2);
;             const char* a1 = cA + (size_t)(t + 1) * kstep;
;             const char* a2 = last ? nA : cA + (size_t)(t + 2) * kstep; const char* b2 = last ? nB : cB + (size_t)(t + 2) * kstep;
;             const char* a3 = a2 + kstep; const char* b3 = b2 + kstep;
;             if (last && has_next) S.a_ready(nxt);
;             if constexpr (SP2) {
;             PG8_LDB(B0, 0, 0); PG8_LDB(B1, 0, 1); PG8_SCHED; PG8_LDA(At, 0, 0); PG8_STAGE(PG8_SA(1, 1), a1 + hstep, voffA);
;             PG8_WAIT_V(8); PG8_WAIT_L(0); PG8_BAR; PG8_MMA(0, 0, At, B0); PG8_MMA(0, 1, At, B1); PG8_BAR; PG8_SCHED;
;             PG8_LDA(At, 0, 1); PG8_STAGE(PG8_SB(0, 0), b2, voffB); PG8_STAGE(PG8_SB(0, 1), b2 + hstep, voffB); PG8_STAGE(PG8_SA(0, 0), a2, voffA);
.LBB0_774:
	ds_read_b128 v[136:139], v156
	ds_read_b128 v[140:143], v156 offset:1024
	ds_read_b128 v[172:175], v156 offset:2048
	ds_read_b128 v[176:179], v156 offset:3072
	ds_read_b128 v[180:183], v157
	ds_read_b128 v[184:187], v157 offset:1024
	ds_read_b128 v[208:211], v157 offset:2048
	ds_read_b128 v[212:215], v157 offset:3072
	s_add_u32 s42, s40, 0xfff80080
	s_addc_u32 s43, s41, -1
	s_cmp_eq_u32 s71, 28
	s_cselect_b32 s49, s23, s43
	s_cselect_b32 s48, s34, s42
	s_cselect_b32 s43, s21, s70
	s_cselect_b32 s42, s35, s69
	v_lshl_add_u64 v[188:189], s[40:41], 0, v[128:129]
	s_add_i32 m0, s11, 0xc000
	ds_read_b128 v[216:219], v158
	ds_read_b128 v[220:223], v158 offset:1024
	ds_read_b128 v[224:227], v158 offset:2048
	ds_read_b128 v[228:231], v158 offset:3072
	ds_read_b128 v[232:235], v158 offset:4096
	ds_read_b128 v[236:239], v158 offset:5120
	ds_read_b128 v[240:243], v158 offset:6144
	ds_read_b128 v[244:247], v158 offset:7168
	global_load_lds_dwordx4 v[188:189], off
	v_lshl_add_u64 v[188:189], s[40:41], 0, v[130:131]
	s_add_i32 m0, s11, 0xe000
	s_nop 0
	global_load_lds_dwordx4 v[188:189], off
	s_waitcnt vmcnt(8)
	s_waitcnt lgkmcnt(0)
	s_barrier
	s_setprio 1
	s_waitcnt lgkmcnt(0)
	v_mfma_f32_16x16x32_bf16 v[124:127], v[136:139], v[216:219], v[124:127]
	v_mfma_f32_16x16x32_bf16 v[124:127], v[140:143], v[220:223], v[124:127]
	v_mfma_f32_16x16x32_bf16 v[120:123], v[176:179], v[220:223], v[120:123]
	v_mfma_f32_16x16x32_bf16 v[120:123], v[172:175], v[216:219], v[120:123]
	v_mfma_f32_16x16x32_bf16 v[116:119], v[180:183], v[216:219], v[116:119]
	v_mfma_f32_16x16x32_bf16 v[116:119], v[184:187], v[220:223], v[116:119]
	v_mfma_f32_16x16x32_bf16 v[112:115], v[212:215], v[220:223], v[112:115]
	v_mfma_f32_16x16x32_bf16 v[112:115], v[208:211], v[216:219], v[112:115]
	v_mfma_f32_16x16x32_bf16 v[92:95], v[208:211], v[224:227], v[92:95]
	v_mfma_f32_16x16x32_bf16 v[92:95], v[212:215], v[228:231], v[92:95]
	v_mfma_f32_16x16x32_bf16 v[100:103], v[184:187], v[228:231], v[100:103]
	v_mfma_f32_16x16x32_bf16 v[100:103], v[180:183], v[224:227], v[100:103]
	v_mfma_f32_16x16x32_bf16 v[104:107], v[172:175], v[224:227], v[104:107]
	v_mfma_f32_16x16x32_bf16 v[104:107], v[176:179], v[228:231], v[104:107]
	v_mfma_f32_16x16x32_bf16 v[108:111], v[140:143], v[228:231], v[108:111]
	v_mfma_f32_16x16x32_bf16 v[108:111], v[136:139], v[224:227], v[108:111]
	s_setprio 0
	s_setprio 1
	v_mfma_f32_16x16x32_bf16 v[96:99], v[136:139], v[232:235], v[96:99]
	v_mfma_f32_16x16x32_bf16 v[96:99], v[140:143], v[236:239], v[96:99]
	v_mfma_f32_16x16x32_bf16 v[88:91], v[176:179], v[236:239], v[88:91]
	v_mfma_f32_16x16x32_bf16 v[88:91], v[172:175], v[232:235], v[88:91]
	v_mfma_f32_16x16x32_bf16 v[84:87], v[180:183], v[232:235], v[84:87]
	v_mfma_f32_16x16x32_bf16 v[84:87], v[184:187], v[236:239], v[84:87]
	v_mfma_f32_16x16x32_bf16 v[76:79], v[212:215], v[236:239], v[76:79]
	v_mfma_f32_16x16x32_bf16 v[76:79], v[208:211], v[232:235], v[76:79]
	v_mfma_f32_16x16x32_bf16 v[64:67], v[208:211], v[240:243], v[64:67]
	v_mfma_f32_16x16x32_bf16 v[64:67], v[212:215], v[244:247], v[64:67]
	v_mfma_f32_16x16x32_bf16 v[68:71], v[184:187], v[244:247], v[68:71]
	v_mfma_f32_16x16x32_bf16 v[68:71], v[180:183], v[240:243], v[68:71]
	v_mfma_f32_16x16x32_bf16 v[72:75], v[172:175], v[240:243], v[72:75]
	v_mfma_f32_16x16x32_bf16 v[72:75], v[176:179], v[244:247], v[72:75]
	s_setprio 2
	s_barrier
	v_mfma_f32_16x16x32_bf16 v[80:83], v[140:143], v[244:247], v[80:83]
	v_mfma_f32_16x16x32_bf16 v[80:83], v[136:139], v[240:243], v[80:83]
	s_setprio 0
	s_add_i32 s44, s64, s52
	v_lshl_add_u64 v[188:189], s[42:43], 0, v[166:167]
	s_mov_b32 m0, s44
	ds_read_b128 v[216:219], v158 offset:16384
	ds_read_b128 v[220:223], v158 offset:17408
	ds_read_b128 v[224:227], v158 offset:18432
	ds_read_b128 v[228:231], v158 offset:19456
	ds_read_b128 v[232:235], v158 offset:20480
	ds_read_b128 v[236:239], v158 offset:21504
	ds_read_b128 v[240:243], v158 offset:22528
	ds_read_b128 v[244:247], v158 offset:23552
	global_load_lds_dwordx4 v[188:189], off
	s_add_i32 m0, s44, 0x2000
	s_add_u32 s72, s42, 0x80000
	v_lshl_add_u64 v[200:201], s[42:43], 0, v[170:171]
	s_addc_u32 s73, s43, 0
	s_add_i32 s44, s65, s52
	global_load_lds_dwordx4 v[200:201], off
	v_lshl_add_u64 v[248:249], s[72:73], 0, v[166:167]
	s_mov_b32 m0, s44
	v_lshl_add_u64 v[250:251], s[48:49], 0, v[168:169]
	global_load_lds_dwordx4 v[248:249], off
	v_lshl_add_u64 v[248:249], s[72:73], 0, v[170:171]
	s_add_i32 m0, s44, 0x2000
	s_nop 0
	global_load_lds_dwordx4 v[248:249], off
	v_lshl_add_u64 v[248:249], s[48:49], 0, v[164:165]
	s_mov_b32 m0, s11
	s_nop 0
	global_load_lds_dwordx4 v[248:249], off
	s_mov_b32 m0, s58
	s_nop 0
	global_load_lds_dwordx4 v[250:251], off
	s_waitcnt vmcnt(8)
	s_waitcnt lgkmcnt(0)
	s_barrier
; #define PG8_STAGE(bufoff, gbase, voff) do { _Pragma("unroll") for (int _i = 0; _i < 2; ++_i) \
;         __builtin_amdgcn_global_load_lds((const unsigned*)((const char*)(gbase) + (voff)[_i]), (PG8_LAS unsigned*)(lds + (bufoff) + ldsw + _i * 8192), 16, 0, 0); } while (0)
; #define PG8_LDA(dst, b, h) do { _Pragma("unroll") for (int m = 0; m < 4; ++m) _Pragma("unroll") for (int k = 0; k < 2; ++k) dst[m][k] = *(const PG8_LAS bf16x8*)(lds + PG8_SA(b, h) + aoff + m * 2048 + k * 1024); } while (0)
; #define PG8_LDB(dst, b, h) do { _Pragma("unroll") for (int n = 0; n < 2; ++n) _Pragma("unroll") for (int k = 0; k < 2; ++k) dst[n][k] = *(const PG8_LAS bf16x8*)(lds + PG8_SB(b, h) + boff + n * 2048 + k * 1024); } while (0)
; #define PG8_MMA(ai, bj, At, Bt) do { __builtin_amdgcn_s_setprio(1); _Pragma("unroll") for (int m = 0; m < 4; ++m) _Pragma("unroll") for (int n = 0; n < 2; ++n) _Pragma("unroll") for (int k = 0; k < 2; ++k) \
;         acc[ai][bj][m][n] = __builtin_amdgcn_mfma_f32_16x16x32_bf16(Bt[n][k], At[m][k], acc[ai][bj][m][n], 0, 0, 0); __builtin_amdgcn_s_setprio(0); } while (0)
; #define PG8_WAIT_V(n) asm volatile("s_waitcnt vmcnt(" #n ")" ::: "memory")
; #define PG8_WAIT_L(n) asm volatile("s_waitcnt lgkmcnt(" #n ")" ::: "memory")
; #define PG8_BAR __builtin_amdgcn_s_barrier()
; #define PG8_SCHED __builtin_amdgcn_sched_barrier(0)
; template <class Epi, class Sched, bool ALIGN_EPI = false, bool SP2 = false>
; __device__ __forceinline__ void gemm_phase(PG8_LAS unsigned char* lds, const Gemm g, const Sched& S, const Epi& E) {
;     ...
;             PG8_WAIT_V(8); PG8_WAIT_L(0); PG8_BAR; PG8_MMA(1, 0, At, B0); PG8_MMA(1, 1, At, B1); PG8_BAR; PG8_SCHED;
;             PG8_LDB(B0, 1, 0); PG8_LDB(B1, 1, 1); PG8_SCHED; PG8_LDA(At, 1, 0); PG8_STAGE(PG8_SA(0, 1), a2 + hstep, voffA);
;             PG8_WAIT_V(8); PG8_WAIT_L(0); PG8_BAR; PG8_MMA(0, 0, At, B0); PG8_MMA(0, 1, At, B1); PG8_BAR; PG8_SCHED;
	s_setprio 1
	s_waitcnt lgkmcnt(0)
	v_mfma_f32_16x16x32_bf16 v[60:63], v[136:139], v[216:219], v[60:63]
	v_mfma_f32_16x16x32_bf16 v[60:63], v[140:143], v[220:223], v[60:63]
	v_mfma_f32_16x16x32_bf16 v[56:59], v[176:179], v[220:223], v[56:59]
	v_mfma_f32_16x16x32_bf16 v[56:59], v[172:175], v[216:219], v[56:59]
	v_mfma_f32_16x16x32_bf16 v[52:55], v[180:183], v[216:219], v[52:55]
	v_mfma_f32_16x16x32_bf16 v[52:55], v[184:187], v[220:223], v[52:55]
	v_mfma_f32_16x16x32_bf16 v[44:47], v[212:215], v[220:223], v[44:47]
	v_mfma_f32_16x16x32_bf16 v[44:47], v[208:211], v[216:219], v[44:47]
	v_mfma_f32_16x16x32_bf16 v[28:31], v[208:211], v[224:227], v[28:31]
	v_mfma_f32_16x16x32_bf16 v[28:31], v[212:215], v[228:231], v[28:31]
	v_mfma_f32_16x16x32_bf16 v[36:39], v[184:187], v[228:231], v[36:39]
	v_mfma_f32_16x16x32_bf16 v[36:39], v[180:183], v[224:227], v[36:39]
	v_mfma_f32_16x16x32_bf16 v[40:43], v[172:175], v[224:227], v[40:43]
	v_mfma_f32_16x16x32_bf16 v[40:43], v[176:179], v[228:231], v[40:43]
	v_mfma_f32_16x16x32_bf16 v[48:51], v[140:143], v[228:231], v[48:51]
	v_mfma_f32_16x16x32_bf16 v[48:51], v[136:139], v[224:227], v[48:51]
	s_setprio 0
	s_setprio 1
	v_mfma_f32_16x16x32_bf16 v[32:35], v[136:139], v[232:235], v[32:35]
	v_mfma_f32_16x16x32_bf16 v[32:35], v[140:143], v[236:239], v[32:35]
	v_mfma_f32_16x16x32_bf16 v[24:27], v[176:179], v[236:239], v[24:27]
	v_mfma_f32_16x16x32_bf16 v[24:27], v[172:175], v[232:235], v[24:27]
	v_mfma_f32_16x16x32_bf16 v[20:23], v[180:183], v[232:235], v[20:23]
	v_mfma_f32_16x16x32_bf16 v[20:23], v[184:187], v[236:239], v[20:23]
	v_mfma_f32_16x16x32_bf16 v[16:19], v[212:215], v[236:239], v[16:19]
	v_mfma_f32_16x16x32_bf16 v[16:19], v[208:211], v[232:235], v[16:19]
	v_mfma_f32_16x16x32_bf16 v[0:3], v[208:211], v[240:243], v[0:3]
	v_mfma_f32_16x16x32_bf16 v[0:3], v[212:215], v[244:247], v[0:3]
	v_mfma_f32_16x16x32_bf16 v[4:7], v[184:187], v[244:247], v[4:7]
	v_mfma_f32_16x16x32_bf16 v[4:7], v[180:183], v[240:243], v[4:7]
	v_mfma_f32_16x16x32_bf16 v[8:11], v[172:175], v[240:243], v[8:11]
	v_mfma_f32_16x16x32_bf16 v[8:11], v[176:179], v[244:247], v[8:11]
	s_setprio 2
	s_barrier
	v_mfma_f32_16x16x32_bf16 v[12:15], v[140:143], v[244:247], v[12:15]
	v_mfma_f32_16x16x32_bf16 v[12:15], v[136:139], v[240:243], v[12:15]
	s_setprio 0
	s_add_i32 s44, 0, 0x18000
	v_add_u32_e32 v144, s44, v146
	s_add_i32 s45, 0, 0x1c000
	ds_read_b128 v[136:139], v144
	ds_read_b128 v[140:143], v144 offset:1024
	ds_read_b128 v[172:175], v144 offset:2048
	ds_read_b128 v[176:179], v144 offset:3072
	v_add_u32_e32 v144, s45, v146
	ds_read_b128 v[180:183], v144
	ds_read_b128 v[184:187], v144 offset:1024
	ds_read_b128 v[208:211], v144 offset:2048
	ds_read_b128 v[212:215], v144 offset:3072
	s_add_u32 s48, s48, 0x80000
	s_addc_u32 s49, s49, 0
	s_mov_b32 m0, s59
	v_lshl_add_u64 v[252:253], s[48:49], 0, v[164:165]
	ds_read_b128 v[216:219], v158 offset:32768
	ds_read_b128 v[220:223], v158 offset:33792
	ds_read_b128 v[224:227], v158 offset:34816
	ds_read_b128 v[228:231], v158 offset:35840
	ds_read_b128 v[232:235], v158 offset:36864
	ds_read_b128 v[236:239], v158 offset:37888
	ds_read_b128 v[240:243], v158 offset:38912
	ds_read_b128 v[244:247], v158 offset:39936
	global_load_lds_dwordx4 v[252:253], off
	v_lshl_add_u64 v[252:253], s[48:49], 0, v[168:169]
	s_mov_b32 m0, s60
	s_nop 0
	global_load_lds_dwordx4 v[252:253], off
	s_waitcnt vmcnt(8)
	s_waitcnt lgkmcnt(0)
	s_barrier
	s_setprio 1
	s_waitcnt lgkmcnt(0)
	v_mfma_f32_16x16x32_bf16 v[124:127], v[136:139], v[216:219], v[124:127]
	v_mfma_f32_16x16x32_bf16 v[124:127], v[140:143], v[220:223], v[124:127]
	v_mfma_f32_16x16x32_bf16 v[120:123], v[176:179], v[220:223], v[120:123]
	v_mfma_f32_16x16x32_bf16 v[120:123], v[172:175], v[216:219], v[120:123]
	v_mfma_f32_16x16x32_bf16 v[116:119], v[180:183], v[216:219], v[116:119]
	v_mfma_f32_16x16x32_bf16 v[116:119], v[184:187], v[220:223], v[116:119]
	v_mfma_f32_16x16x32_bf16 v[112:115], v[212:215], v[220:223], v[112:115]
	v_mfma_f32_16x16x32_bf16 v[112:115], v[208:211], v[216:219], v[112:115]
	v_mfma_f32_16x16x32_bf16 v[92:95], v[208:211], v[224:227], v[92:95]
	v_mfma_f32_16x16x32_bf16 v[92:95], v[212:215], v[228:231], v[92:95]
	v_mfma_f32_16x16x32_bf16 v[100:103], v[184:187], v[228:231], v[100:103]
	v_mfma_f32_16x16x32_bf16 v[100:103], v[180:183], v[224:227], v[100:103]
	v_mfma_f32_16x16x32_bf16 v[104:107], v[172:175], v[224:227], v[104:107]
	v_mfma_f32_16x16x32_bf16 v[104:107], v[176:179], v[228:231], v[104:107]
	v_mfma_f32_16x16x32_bf16 v[108:111], v[140:143], v[228:231], v[108:111]
	v_mfma_f32_16x16x32_bf16 v[108:111], v[136:139], v[224:227], v[108:111]
	s_setprio 0
	s_setprio 1
	v_mfma_f32_16x16x32_bf16 v[96:99], v[136:139], v[232:235], v[96:99]
	v_mfma_f32_16x16x32_bf16 v[96:99], v[140:143], v[236:239], v[96:99]
	v_mfma_f32_16x16x32_bf16 v[88:91], v[176:179], v[236:239], v[88:91]
	v_mfma_f32_16x16x32_bf16 v[88:91], v[172:175], v[232:235], v[88:91]
	v_mfma_f32_16x16x32_bf16 v[84:87], v[180:183], v[232:235], v[84:87]
	v_mfma_f32_16x16x32_bf16 v[84:87], v[184:187], v[236:239], v[84:87]
	v_mfma_f32_16x16x32_bf16 v[76:79], v[212:215], v[236:239], v[76:79]
	v_mfma_f32_16x16x32_bf16 v[76:79], v[208:211], v[232:235], v[76:79]
	v_mfma_f32_16x16x32_bf16 v[64:67], v[208:211], v[240:243], v[64:67]
	v_mfma_f32_16x16x32_bf16 v[64:67], v[212:215], v[244:247], v[64:67]
	v_mfma_f32_16x16x32_bf16 v[68:71], v[184:187], v[244:247], v[68:71]
	v_mfma_f32_16x16x32_bf16 v[68:71], v[180:183], v[240:243], v[68:71]
	v_mfma_f32_16x16x32_bf16 v[72:75], v[172:175], v[240:243], v[72:75]
	v_mfma_f32_16x16x32_bf16 v[72:75], v[176:179], v[244:247], v[72:75]
	s_setprio 2
	s_barrier
; #define PG8_STAGE(bufoff, gbase, voff) do { _Pragma("unroll") for (int _i = 0; _i < 2; ++_i) \
;         __builtin_amdgcn_global_load_lds((const unsigned*)((const char*)(gbase) + (voff)[_i]), (PG8_LAS unsigned*)(lds + (bufoff) + ldsw + _i * 8192), 16, 0, 0); } while (0)
; #define PG8_LDA(dst, b, h) do { _Pragma("unroll") for (int m = 0; m < 4; ++m) _Pragma("unroll") for (int k = 0; k < 2; ++k) dst[m][k] = *(const PG8_LAS bf16x8*)(lds + PG8_SA(b, h) + aoff + m * 2048 + k * 1024); } while (0)
; #define PG8_MMA(ai, bj, At, Bt) do { __builtin_amdgcn_s_setprio(1); _Pragma("unroll") for (int m = 0; m < 4; ++m) _Pragma("unroll") for (int n = 0; n < 2; ++n) _Pragma("unroll") for (int k = 0; k < 2; ++k) \
;         acc[ai][bj][m][n] = __builtin_amdgcn_mfma_f32_16x16x32_bf16(Bt[n][k], At[m][k], acc[ai][bj][m][n], 0, 0, 0); __builtin_amdgcn_s_setprio(0); } while (0)
; #define PG8_WAIT_V(n) asm volatile("s_waitcnt vmcnt(" #n ")" ::: "memory")
; #define PG8_WAIT_L(n) asm volatile("s_waitcnt lgkmcnt(" #n ")" ::: "memory")
; #define PG8_BAR __builtin_amdgcn_s_barrier()
; #define PG8_SCHED __builtin_amdgcn_sched_barrier(0)
; template <class Epi, class Sched, bool ALIGN_EPI = false, bool SP2 = false>
; __device__ __forceinline__ void gemm_phase(PG8_LAS unsigned char* lds, const Gemm g, const Sched& S, const Epi& E) {
;     ...
;         for (int t = 0; t < nt; t += 2) {
;     ...
;             PG8_WAIT_V(8); PG8_WAIT_L(0); PG8_BAR; PG8_MMA(0, 0, At, B0); PG8_MMA(0, 1, At, B1); PG8_BAR; PG8_SCHED;
;             PG8_LDA(At, 1, 1); PG8_STAGE(PG8_SB(1, 0), b3, voffB); PG8_STAGE(PG8_SB(1, 1), b3 + hstep, voffB); PG8_STAGE(PG8_SA(1, 0), a3, voffA);
;             PG8_WAIT_V(8); PG8_WAIT_L(0); PG8_BAR; PG8_MMA(1, 0, At, B0); PG8_MMA(1, 1, At, B1); PG8_BAR; PG8_SCHED;
	v_mfma_f32_16x16x32_bf16 v[80:83], v[140:143], v[244:247], v[80:83]
	v_mfma_f32_16x16x32_bf16 v[80:83], v[136:139], v[240:243], v[80:83]
	s_setprio 0
	s_add_i32 s44, s44, s52
	v_lshl_add_u64 v[188:189], v[188:189], 0, s[16:17]
	s_mov_b32 m0, s44
	ds_read_b128 v[216:219], v158 offset:49152
	ds_read_b128 v[220:223], v158 offset:50176
	ds_read_b128 v[224:227], v158 offset:51200
	ds_read_b128 v[228:231], v158 offset:52224
	ds_read_b128 v[232:235], v158 offset:53248
	ds_read_b128 v[236:239], v158 offset:54272
	ds_read_b128 v[240:243], v158 offset:55296
	ds_read_b128 v[244:247], v158 offset:56320
	global_load_lds_dwordx4 v[188:189], off
	s_add_i32 m0, s44, 0x2000
	s_add_u32 s42, s42, 0x80080
	v_lshl_add_u64 v[188:189], v[200:201], 0, s[16:17]
	s_addc_u32 s43, s43, 0
	s_add_i32 s44, s45, s52
	global_load_lds_dwordx4 v[188:189], off
	v_lshl_add_u64 v[188:189], s[42:43], 0, v[166:167]
	s_mov_b32 m0, s44
	s_nop 0
	global_load_lds_dwordx4 v[188:189], off
	v_lshl_add_u64 v[188:189], s[42:43], 0, v[170:171]
	s_add_i32 m0, s44, 0x2000
	s_nop 0
	global_load_lds_dwordx4 v[188:189], off
	v_lshl_add_u64 v[188:189], v[248:249], 0, s[16:17]
	s_mov_b32 m0, s62
	s_nop 0
	global_load_lds_dwordx4 v[188:189], off
	v_lshl_add_u64 v[188:189], v[250:251], 0, s[16:17]
	s_mov_b32 m0, s63
	s_nop 0
	global_load_lds_dwordx4 v[188:189], off
	s_add_i32 s71, s71, 2
	s_add_u32 s40, s40, 0x100
	s_addc_u32 s41, s41, 0
	s_add_u32 s69, s69, 0x100
	s_addc_u32 s70, s70, 0
	s_waitcnt vmcnt(8)
	s_waitcnt lgkmcnt(0)
	s_barrier
	s_setprio 1
	s_waitcnt lgkmcnt(0)
	v_mfma_f32_16x16x32_bf16 v[60:63], v[136:139], v[216:219], v[60:63]
	v_mfma_f32_16x16x32_bf16 v[60:63], v[140:143], v[220:223], v[60:63]
	v_mfma_f32_16x16x32_bf16 v[56:59], v[176:179], v[220:223], v[56:59]
	v_mfma_f32_16x16x32_bf16 v[56:59], v[172:175], v[216:219], v[56:59]
	v_mfma_f32_16x16x32_bf16 v[52:55], v[180:183], v[216:219], v[52:55]
	v_mfma_f32_16x16x32_bf16 v[52:55], v[184:187], v[220:223], v[52:55]
	v_mfma_f32_16x16x32_bf16 v[44:47], v[212:215], v[220:223], v[44:47]
	v_mfma_f32_16x16x32_bf16 v[44:47], v[208:211], v[216:219], v[44:47]
	v_mfma_f32_16x16x32_bf16 v[28:31], v[208:211], v[224:227], v[28:31]
	v_mfma_f32_16x16x32_bf16 v[28:31], v[212:215], v[228:231], v[28:31]
	v_mfma_f32_16x16x32_bf16 v[36:39], v[184:187], v[228:231], v[36:39]
	v_mfma_f32_16x16x32_bf16 v[36:39], v[180:183], v[224:227], v[36:39]
	v_mfma_f32_16x16x32_bf16 v[40:43], v[172:175], v[224:227], v[40:43]
	v_mfma_f32_16x16x32_bf16 v[40:43], v[176:179], v[228:231], v[40:43]
	v_mfma_f32_16x16x32_bf16 v[48:51], v[140:143], v[228:231], v[48:51]
	v_mfma_f32_16x16x32_bf16 v[48:51], v[136:139], v[224:227], v[48:51]
	s_setprio 0
	s_setprio 1
	v_mfma_f32_16x16x32_bf16 v[32:35], v[136:139], v[232:235], v[32:35]
	v_mfma_f32_16x16x32_bf16 v[32:35], v[140:143], v[236:239], v[32:35]
	v_mfma_f32_16x16x32_bf16 v[24:27], v[176:179], v[236:239], v[24:27]
	v_mfma_f32_16x16x32_bf16 v[24:27], v[172:175], v[232:235], v[24:27]
	v_mfma_f32_16x16x32_bf16 v[20:23], v[180:183], v[232:235], v[20:23]
	v_mfma_f32_16x16x32_bf16 v[20:23], v[184:187], v[236:239], v[20:23]
	v_mfma_f32_16x16x32_bf16 v[16:19], v[212:215], v[236:239], v[16:19]
	v_mfma_f32_16x16x32_bf16 v[16:19], v[208:211], v[232:235], v[16:19]
	v_mfma_f32_16x16x32_bf16 v[0:3], v[208:211], v[240:243], v[0:3]
	v_mfma_f32_16x16x32_bf16 v[0:3], v[212:215], v[244:247], v[0:3]
	v_mfma_f32_16x16x32_bf16 v[4:7], v[184:187], v[244:247], v[4:7]
	v_mfma_f32_16x16x32_bf16 v[4:7], v[180:183], v[240:243], v[4:7]
	v_mfma_f32_16x16x32_bf16 v[8:11], v[172:175], v[240:243], v[8:11]
	v_mfma_f32_16x16x32_bf16 v[8:11], v[176:179], v[244:247], v[8:11]
	s_setprio 2
	s_barrier
	v_mfma_f32_16x16x32_bf16 v[12:15], v[140:143], v[244:247], v[12:15]
	v_mfma_f32_16x16x32_bf16 v[12:15], v[136:139], v[240:243], v[12:15]
	s_setprio 0
	s_cmp_gt_u32 s71, 29
	s_cbranch_scc0 .LBB0_774
	s_and_b64 vcc, exec, s[18:19]
	s_cbranch_vccz .LBB0_777
	s_barrier

; #define PG8_STAGE(bufoff, gbase, voff) do { _Pragma("unroll") for (int _i = 0; _i < 2; ++_i) \
;         __builtin_amdgcn_global_load_lds((const unsigned*)((const char*)(gbase) + (voff)[_i]), (PG8_LAS unsigned*)(lds + (bufoff) + ldsw + _i * 8192), 16, 0, 0); } while (0)
; #define PG8_LDA(dst, b, h) do { _Pragma("unroll") for (int m = 0; m < 4; ++m) _Pragma("unroll") for (int k = 0; k < 2; ++k) dst[m][k] = *(const PG8_LAS bf16x8*)(lds + PG8_SA(b, h) + aoff + m * 2048 + k * 1024); } while (0)
; #define PG8_LDB(dst, b, h) do { _Pragma("unroll") for (int n = 0; n < 2; ++n) _Pragma("unroll") for (int k = 0; k < 2; ++k) dst[n][k] = *(const PG8_LAS bf16x8*)(lds + PG8_SB(b, h) + boff + n * 2048 + k * 1024); } while (0)
; #define PG8_MMA(ai, bj, At, Bt) do { __builtin_amdgcn_s_setprio(1); _Pragma("unroll") for (int m = 0; m < 4; ++m) _Pragma("unroll") for (int n = 0; n < 2; ++n) _Pragma("unroll") for (int k = 0; k < 2; ++k) \
;         acc[ai][bj][m][n] = __builtin_amdgcn_mfma_f32_16x16x32_bf16(Bt[n][k], At[m][k], acc[ai][bj][m][n], 0, 0, 0); __builtin_amdgcn_s_setprio(0); } while (0)
; #define PG8_WAIT_V(n) asm volatile("s_waitcnt vmcnt(" #n ")" ::: "memory")
; #define PG8_WAIT_L(n) asm volatile("s_waitcnt lgkmcnt(" #n ")" ::: "memory")
; #define PG8_BAR __builtin_amdgcn_s_barrier()
; #define PG8_SCHED __builtin_amdgcn_sched_barrier(0)
; template <class Epi, class Sched, bool ALIGN_EPI = false, bool SP2 = false>
; __device__ __forceinline__ void gemm_phase(PG8_LAS unsigned char* lds, const Gemm g, const Sched& S, const Epi& E) {
;     ...
;             const bool last = (t == nt - 2);
;             const char* a1 = cA + (size_t)(t + 1) * kstep;
;             const char* a2 = last ? nA : cA + (size_t)(t + 2) * kstep; const char* b2 = last ? nB : cB + (size_t)(t + 2) * kstep;
;             const char* a3 = a2 + kstep; const char* b3 = b2 + kstep;
;             if (last && has_next) S.a_ready(nxt);
;             if constexpr (SP2) {
;             PG8_LDB(B0, 0, 0); PG8_LDB(B1, 0, 1); PG8_SCHED; PG8_LDA(At, 0, 0); PG8_STAGE(PG8_SA(1, 1), a1 + hstep, voffA);
;             PG8_WAIT_V(8); PG8_WAIT_L(0); PG8_BAR; PG8_MMA(0, 0, At, B0); PG8_MMA(0, 1, At, B1); PG8_BAR; PG8_SCHED;
;             PG8_LDA(At, 0, 1); PG8_STAGE(PG8_SB(0, 0), b2, voffB); PG8_STAGE(PG8_SB(0, 1), b2 + hstep, voffB); PG8_STAGE(PG8_SA(0, 0), a2, voffA);
.LBB0_837:
	ds_read_b128 v[134:137], v143
	ds_read_b128 v[146:149], v143 offset:1024
	ds_read_b128 v[150:153], v143 offset:2048
	ds_read_b128 v[154:157], v143 offset:3072
	ds_read_b128 v[172:175], v144
	ds_read_b128 v[176:179], v144 offset:1024
	ds_read_b128 v[180:183], v144 offset:2048
	ds_read_b128 v[184:187], v144 offset:3072
	s_add_u32 s44, s42, 0xffea0080
	s_addc_u32 s45, s43, -1
	s_cmpk_eq_i32 s75, 0x54
	s_cselect_b32 s53, s39, s45
	s_cselect_b32 s52, s38, s44
	s_cselect_b32 s49, s41, s35
	s_cselect_b32 s48, s40, s34
	v_lshl_add_u64 v[138:139], s[42:43], 0, v[128:129]
	s_add_i32 m0, s61, 0xc000
	ds_read_b128 v[208:211], v145
	ds_read_b128 v[212:215], v145 offset:1024
	ds_read_b128 v[216:219], v145 offset:2048
	ds_read_b128 v[220:223], v145 offset:3072
	ds_read_b128 v[224:227], v145 offset:4096
	ds_read_b128 v[228:231], v145 offset:5120
	ds_read_b128 v[232:235], v145 offset:6144
	ds_read_b128 v[236:239], v145 offset:7168
	global_load_lds_dwordx4 v[138:139], off
	v_lshl_add_u64 v[138:139], s[42:43], 0, v[130:131]
	s_add_i32 m0, s61, 0xe000
	s_nop 0
	global_load_lds_dwordx4 v[138:139], off
	s_waitcnt vmcnt(8)
	s_waitcnt lgkmcnt(0)
	s_barrier
	s_setprio 1
	s_waitcnt lgkmcnt(0)
	v_mfma_f32_16x16x32_bf16 v[124:127], v[134:137], v[208:211], v[124:127]
	v_mfma_f32_16x16x32_bf16 v[124:127], v[146:149], v[212:215], v[124:127]
	v_mfma_f32_16x16x32_bf16 v[120:123], v[154:157], v[212:215], v[120:123]
	v_mfma_f32_16x16x32_bf16 v[120:123], v[150:153], v[208:211], v[120:123]
	v_mfma_f32_16x16x32_bf16 v[108:111], v[172:175], v[208:211], v[108:111]
	v_mfma_f32_16x16x32_bf16 v[108:111], v[176:179], v[212:215], v[108:111]
	v_mfma_f32_16x16x32_bf16 v[104:107], v[184:187], v[212:215], v[104:107]
	v_mfma_f32_16x16x32_bf16 v[104:107], v[180:183], v[208:211], v[104:107]
	v_mfma_f32_16x16x32_bf16 v[96:99], v[180:183], v[216:219], v[96:99]
	v_mfma_f32_16x16x32_bf16 v[96:99], v[184:187], v[220:223], v[96:99]
	v_mfma_f32_16x16x32_bf16 v[100:103], v[176:179], v[220:223], v[100:103]
	v_mfma_f32_16x16x32_bf16 v[100:103], v[172:175], v[216:219], v[100:103]
	v_mfma_f32_16x16x32_bf16 v[112:115], v[150:153], v[216:219], v[112:115]
	v_mfma_f32_16x16x32_bf16 v[112:115], v[154:157], v[220:223], v[112:115]
	v_mfma_f32_16x16x32_bf16 v[116:119], v[146:149], v[220:223], v[116:119]
	v_mfma_f32_16x16x32_bf16 v[116:119], v[134:137], v[216:219], v[116:119]
	s_setprio 0
	s_setprio 1
	v_mfma_f32_16x16x32_bf16 v[92:95], v[134:137], v[224:227], v[92:95]
	v_mfma_f32_16x16x32_bf16 v[92:95], v[146:149], v[228:231], v[92:95]
	v_mfma_f32_16x16x32_bf16 v[88:91], v[154:157], v[228:231], v[88:91]
	v_mfma_f32_16x16x32_bf16 v[88:91], v[150:153], v[224:227], v[88:91]
	v_mfma_f32_16x16x32_bf16 v[76:79], v[172:175], v[224:227], v[76:79]
	v_mfma_f32_16x16x32_bf16 v[76:79], v[176:179], v[228:231], v[76:79]
	v_mfma_f32_16x16x32_bf16 v[72:75], v[184:187], v[228:231], v[72:75]
	v_mfma_f32_16x16x32_bf16 v[72:75], v[180:183], v[224:227], v[72:75]
	v_mfma_f32_16x16x32_bf16 v[64:67], v[180:183], v[232:235], v[64:67]
	v_mfma_f32_16x16x32_bf16 v[64:67], v[184:187], v[236:239], v[64:67]
	v_mfma_f32_16x16x32_bf16 v[68:71], v[176:179], v[236:239], v[68:71]
	v_mfma_f32_16x16x32_bf16 v[68:71], v[172:175], v[232:235], v[68:71]
	v_mfma_f32_16x16x32_bf16 v[80:83], v[150:153], v[232:235], v[80:83]
	v_mfma_f32_16x16x32_bf16 v[80:83], v[154:157], v[236:239], v[80:83]
	s_setprio 2
	s_barrier
	v_mfma_f32_16x16x32_bf16 v[84:87], v[146:149], v[236:239], v[84:87]
	v_mfma_f32_16x16x32_bf16 v[84:87], v[134:137], v[232:235], v[84:87]
	s_setprio 0
	s_add_i32 s44, s68, s60
	v_lshl_add_u64 v[138:139], s[48:49], 0, v[160:161]
	s_mov_b32 m0, s44
	ds_read_b128 v[208:211], v145 offset:16384
	ds_read_b128 v[212:215], v145 offset:17408
	ds_read_b128 v[216:219], v145 offset:18432
	ds_read_b128 v[220:223], v145 offset:19456
	ds_read_b128 v[224:227], v145 offset:20480
	ds_read_b128 v[228:231], v145 offset:21504
	ds_read_b128 v[232:235], v145 offset:22528
	ds_read_b128 v[236:239], v145 offset:23552
	global_load_lds_dwordx4 v[138:139], off
	s_add_i32 m0, s44, 0x2000
	s_add_u32 s76, s48, 0x160000
	v_lshl_add_u64 v[158:159], s[48:49], 0, v[162:163]
	s_addc_u32 s77, s49, 0
	s_add_i32 s44, s69, s60
	global_load_lds_dwordx4 v[158:159], off
	v_lshl_add_u64 v[188:189], s[76:77], 0, v[160:161]
	s_mov_b32 m0, s44
	v_lshl_add_u64 v[200:201], s[52:53], 0, v[162:163]
	global_load_lds_dwordx4 v[188:189], off
	v_lshl_add_u64 v[188:189], s[76:77], 0, v[162:163]
	s_add_i32 m0, s44, 0x2000
	s_nop 0
	global_load_lds_dwordx4 v[188:189], off
	v_lshl_add_u64 v[188:189], s[52:53], 0, v[160:161]
	s_mov_b32 m0, s61
	s_nop 0
	global_load_lds_dwordx4 v[188:189], off
	s_mov_b32 m0, s62
	s_nop 0
	global_load_lds_dwordx4 v[200:201], off
	s_waitcnt vmcnt(8)
	s_waitcnt lgkmcnt(0)
	s_barrier
; #define PG8_STAGE(bufoff, gbase, voff) do { _Pragma("unroll") for (int _i = 0; _i < 2; ++_i) \
;         __builtin_amdgcn_global_load_lds((const unsigned*)((const char*)(gbase) + (voff)[_i]), (PG8_LAS unsigned*)(lds + (bufoff) + ldsw + _i * 8192), 16, 0, 0); } while (0)
; #define PG8_LDA(dst, b, h) do { _Pragma("unroll") for (int m = 0; m < 4; ++m) _Pragma("unroll") for (int k = 0; k < 2; ++k) dst[m][k] = *(const PG8_LAS bf16x8*)(lds + PG8_SA(b, h) + aoff + m * 2048 + k * 1024); } while (0)
; #define PG8_LDB(dst, b, h) do { _Pragma("unroll") for (int n = 0; n < 2; ++n) _Pragma("unroll") for (int k = 0; k < 2; ++k) dst[n][k] = *(const PG8_LAS bf16x8*)(lds + PG8_SB(b, h) + boff + n * 2048 + k * 1024); } while (0)
; #define PG8_MMA(ai, bj, At, Bt) do { __builtin_amdgcn_s_setprio(1); _Pragma("unroll") for (int m = 0; m < 4; ++m) _Pragma("unroll") for (int n = 0; n < 2; ++n) _Pragma("unroll") for (int k = 0; k < 2; ++k) \
;         acc[ai][bj][m][n] = __builtin_amdgcn_mfma_f32_16x16x32_bf16(Bt[n][k], At[m][k], acc[ai][bj][m][n], 0, 0, 0); __builtin_amdgcn_s_setprio(0); } while (0)
; #define PG8_WAIT_V(n) asm volatile("s_waitcnt vmcnt(" #n ")" ::: "memory")
; #define PG8_WAIT_L(n) asm volatile("s_waitcnt lgkmcnt(" #n ")" ::: "memory")
; #define PG8_BAR __builtin_amdgcn_s_barrier()
; #define PG8_SCHED __builtin_amdgcn_sched_barrier(0)
; template <class Epi, class Sched, bool ALIGN_EPI = false, bool SP2 = false>
; __device__ __forceinline__ void gemm_phase(PG8_LAS unsigned char* lds, const Gemm g, const Sched& S, const Epi& E) {
;     ...
;             PG8_WAIT_V(8); PG8_WAIT_L(0); PG8_BAR; PG8_MMA(1, 0, At, B0); PG8_MMA(1, 1, At, B1); PG8_BAR; PG8_SCHED;
;             PG8_LDB(B0, 1, 0); PG8_LDB(B1, 1, 1); PG8_SCHED; PG8_LDA(At, 1, 0); PG8_STAGE(PG8_SA(0, 1), a2 + hstep, voffA);
;             PG8_WAIT_V(8); PG8_WAIT_L(0); PG8_BAR; PG8_MMA(0, 0, At, B0); PG8_MMA(0, 1, At, B1); PG8_BAR; PG8_SCHED;
	s_setprio 1
	s_waitcnt lgkmcnt(0)
	v_mfma_f32_16x16x32_bf16 v[60:63], v[134:137], v[208:211], v[60:63]
	v_mfma_f32_16x16x32_bf16 v[60:63], v[146:149], v[212:215], v[60:63]
	v_mfma_f32_16x16x32_bf16 v[56:59], v[154:157], v[212:215], v[56:59]
	v_mfma_f32_16x16x32_bf16 v[56:59], v[150:153], v[208:211], v[56:59]
	v_mfma_f32_16x16x32_bf16 v[44:47], v[172:175], v[208:211], v[44:47]
	v_mfma_f32_16x16x32_bf16 v[44:47], v[176:179], v[212:215], v[44:47]
	v_mfma_f32_16x16x32_bf16 v[40:43], v[184:187], v[212:215], v[40:43]
	v_mfma_f32_16x16x32_bf16 v[40:43], v[180:183], v[208:211], v[40:43]
	v_mfma_f32_16x16x32_bf16 v[32:35], v[180:183], v[216:219], v[32:35]
	v_mfma_f32_16x16x32_bf16 v[32:35], v[184:187], v[220:223], v[32:35]
	v_mfma_f32_16x16x32_bf16 v[36:39], v[176:179], v[220:223], v[36:39]
	v_mfma_f32_16x16x32_bf16 v[36:39], v[172:175], v[216:219], v[36:39]
	v_mfma_f32_16x16x32_bf16 v[48:51], v[150:153], v[216:219], v[48:51]
	v_mfma_f32_16x16x32_bf16 v[48:51], v[154:157], v[220:223], v[48:51]
	v_mfma_f32_16x16x32_bf16 v[52:55], v[146:149], v[220:223], v[52:55]
	v_mfma_f32_16x16x32_bf16 v[52:55], v[134:137], v[216:219], v[52:55]
	s_setprio 0
	s_setprio 1
	v_mfma_f32_16x16x32_bf16 v[28:31], v[134:137], v[224:227], v[28:31]
	v_mfma_f32_16x16x32_bf16 v[28:31], v[146:149], v[228:231], v[28:31]
	v_mfma_f32_16x16x32_bf16 v[24:27], v[154:157], v[228:231], v[24:27]
	v_mfma_f32_16x16x32_bf16 v[24:27], v[150:153], v[224:227], v[24:27]
	v_mfma_f32_16x16x32_bf16 v[12:15], v[172:175], v[224:227], v[12:15]
	v_mfma_f32_16x16x32_bf16 v[12:15], v[176:179], v[228:231], v[12:15]
	v_mfma_f32_16x16x32_bf16 v[8:11], v[184:187], v[228:231], v[8:11]
	v_mfma_f32_16x16x32_bf16 v[8:11], v[180:183], v[224:227], v[8:11]
	v_mfma_f32_16x16x32_bf16 v[0:3], v[180:183], v[232:235], v[0:3]
	v_mfma_f32_16x16x32_bf16 v[0:3], v[184:187], v[236:239], v[0:3]
	v_mfma_f32_16x16x32_bf16 v[4:7], v[176:179], v[236:239], v[4:7]
	v_mfma_f32_16x16x32_bf16 v[4:7], v[172:175], v[232:235], v[4:7]
	v_mfma_f32_16x16x32_bf16 v[16:19], v[150:153], v[232:235], v[16:19]
	v_mfma_f32_16x16x32_bf16 v[16:19], v[154:157], v[236:239], v[16:19]
	s_setprio 2
	s_barrier
	v_mfma_f32_16x16x32_bf16 v[20:23], v[146:149], v[236:239], v[20:23]
	v_mfma_f32_16x16x32_bf16 v[20:23], v[134:137], v[232:235], v[20:23]
	s_setprio 0
	s_add_i32 s44, 0, 0x18000
	s_add_i32 s45, 0, 0x1c000
	v_add_u32_e32 v154, s44, v141
	v_add_u32_e32 v165, s45, v141
	ds_read_b128 v[134:137], v154
	ds_read_b128 v[146:149], v154 offset:1024
	ds_read_b128 v[150:153], v154 offset:2048
	ds_read_b128 v[154:157], v154 offset:3072
	ds_read_b128 v[172:175], v165
	ds_read_b128 v[176:179], v165 offset:1024
	ds_read_b128 v[180:183], v165 offset:2048
	ds_read_b128 v[184:187], v165 offset:3072
	s_add_u32 s52, s52, 0x160000
	s_addc_u32 s53, s53, 0
	s_mov_b32 m0, s63
	v_lshl_add_u64 v[240:241], s[52:53], 0, v[160:161]
	ds_read_b128 v[208:211], v145 offset:32768
	ds_read_b128 v[212:215], v145 offset:33792
	ds_read_b128 v[216:219], v145 offset:34816
	ds_read_b128 v[220:223], v145 offset:35840
	ds_read_b128 v[224:227], v145 offset:36864
	ds_read_b128 v[228:231], v145 offset:37888
	ds_read_b128 v[232:235], v145 offset:38912
	ds_read_b128 v[236:239], v145 offset:39936
	global_load_lds_dwordx4 v[240:241], off
	v_lshl_add_u64 v[240:241], s[52:53], 0, v[162:163]
	s_mov_b32 m0, s64
	s_nop 0
	global_load_lds_dwordx4 v[240:241], off
	s_waitcnt vmcnt(8)
	s_waitcnt lgkmcnt(0)
	s_barrier
	s_setprio 1
	s_waitcnt lgkmcnt(0)
	v_mfma_f32_16x16x32_bf16 v[124:127], v[134:137], v[208:211], v[124:127]
	v_mfma_f32_16x16x32_bf16 v[124:127], v[146:149], v[212:215], v[124:127]
	v_mfma_f32_16x16x32_bf16 v[120:123], v[154:157], v[212:215], v[120:123]
	v_mfma_f32_16x16x32_bf16 v[120:123], v[150:153], v[208:211], v[120:123]
	v_mfma_f32_16x16x32_bf16 v[108:111], v[172:175], v[208:211], v[108:111]
	v_mfma_f32_16x16x32_bf16 v[108:111], v[176:179], v[212:215], v[108:111]
	v_mfma_f32_16x16x32_bf16 v[104:107], v[184:187], v[212:215], v[104:107]
	v_mfma_f32_16x16x32_bf16 v[104:107], v[180:183], v[208:211], v[104:107]
	v_mfma_f32_16x16x32_bf16 v[96:99], v[180:183], v[216:219], v[96:99]
	v_mfma_f32_16x16x32_bf16 v[96:99], v[184:187], v[220:223], v[96:99]
	v_mfma_f32_16x16x32_bf16 v[100:103], v[176:179], v[220:223], v[100:103]
	v_mfma_f32_16x16x32_bf16 v[100:103], v[172:175], v[216:219], v[100:103]
	v_mfma_f32_16x16x32_bf16 v[112:115], v[150:153], v[216:219], v[112:115]
	v_mfma_f32_16x16x32_bf16 v[112:115], v[154:157], v[220:223], v[112:115]
	v_mfma_f32_16x16x32_bf16 v[116:119], v[146:149], v[220:223], v[116:119]
	v_mfma_f32_16x16x32_bf16 v[116:119], v[134:137], v[216:219], v[116:119]
	s_setprio 0
	s_setprio 1
	v_mfma_f32_16x16x32_bf16 v[92:95], v[134:137], v[224:227], v[92:95]
	v_mfma_f32_16x16x32_bf16 v[92:95], v[146:149], v[228:231], v[92:95]
	v_mfma_f32_16x16x32_bf16 v[88:91], v[154:157], v[228:231], v[88:91]
	v_mfma_f32_16x16x32_bf16 v[88:91], v[150:153], v[224:227], v[88:91]
	v_mfma_f32_16x16x32_bf16 v[76:79], v[172:175], v[224:227], v[76:79]
	v_mfma_f32_16x16x32_bf16 v[76:79], v[176:179], v[228:231], v[76:79]
	v_mfma_f32_16x16x32_bf16 v[72:75], v[184:187], v[228:231], v[72:75]
	v_mfma_f32_16x16x32_bf16 v[72:75], v[180:183], v[224:227], v[72:75]
	v_mfma_f32_16x16x32_bf16 v[64:67], v[180:183], v[232:235], v[64:67]
	v_mfma_f32_16x16x32_bf16 v[64:67], v[184:187], v[236:239], v[64:67]
	v_mfma_f32_16x16x32_bf16 v[68:71], v[176:179], v[236:239], v[68:71]
	v_mfma_f32_16x16x32_bf16 v[68:71], v[172:175], v[232:235], v[68:71]
	v_mfma_f32_16x16x32_bf16 v[80:83], v[150:153], v[232:235], v[80:83]
	v_mfma_f32_16x16x32_bf16 v[80:83], v[154:157], v[236:239], v[80:83]
	s_setprio 2
	s_barrier
; #define PG8_STAGE(bufoff, gbase, voff) do { _Pragma("unroll") for (int _i = 0; _i < 2; ++_i) \
;         __builtin_amdgcn_global_load_lds((const unsigned*)((const char*)(gbase) + (voff)[_i]), (PG8_LAS unsigned*)(lds + (bufoff) + ldsw + _i * 8192), 16, 0, 0); } while (0)
; #define PG8_LDA(dst, b, h) do { _Pragma("unroll") for (int m = 0; m < 4; ++m) _Pragma("unroll") for (int k = 0; k < 2; ++k) dst[m][k] = *(const PG8_LAS bf16x8*)(lds + PG8_SA(b, h) + aoff + m * 2048 + k * 1024); } while (0)
; #define PG8_MMA(ai, bj, At, Bt) do { __builtin_amdgcn_s_setprio(1); _Pragma("unroll") for (int m = 0; m < 4; ++m) _Pragma("unroll") for (int n = 0; n < 2; ++n) _Pragma("unroll") for (int k = 0; k < 2; ++k) \
;         acc[ai][bj][m][n] = __builtin_amdgcn_mfma_f32_16x16x32_bf16(Bt[n][k], At[m][k], acc[ai][bj][m][n], 0, 0, 0); __builtin_amdgcn_s_setprio(0); } while (0)
; #define PG8_WAIT_V(n) asm volatile("s_waitcnt vmcnt(" #n ")" ::: "memory")
; #define PG8_WAIT_L(n) asm volatile("s_waitcnt lgkmcnt(" #n ")" ::: "memory")
; #define PG8_BAR __builtin_amdgcn_s_barrier()
; #define PG8_SCHED __builtin_amdgcn_sched_barrier(0)
; template <class Epi, class Sched, bool ALIGN_EPI = false, bool SP2 = false>
; __device__ __forceinline__ void gemm_phase(PG8_LAS unsigned char* lds, const Gemm g, const Sched& S, const Epi& E) {
;     ...
;         for (int t = 0; t < nt; t += 2) {
;     ...
;             PG8_WAIT_V(8); PG8_WAIT_L(0); PG8_BAR; PG8_MMA(0, 0, At, B0); PG8_MMA(0, 1, At, B1); PG8_BAR; PG8_SCHED;
;             PG8_LDA(At, 1, 1); PG8_STAGE(PG8_SB(1, 0), b3, voffB); PG8_STAGE(PG8_SB(1, 1), b3 + hstep, voffB); PG8_STAGE(PG8_SA(1, 0), a3, voffA);
;             PG8_WAIT_V(8); PG8_WAIT_L(0); PG8_BAR; PG8_MMA(1, 0, At, B0); PG8_MMA(1, 1, At, B1); PG8_BAR; PG8_SCHED;
	v_mfma_f32_16x16x32_bf16 v[84:87], v[146:149], v[236:239], v[84:87]
	v_mfma_f32_16x16x32_bf16 v[84:87], v[134:137], v[232:235], v[84:87]
	s_setprio 0
	s_add_i32 s44, s44, s60
	v_lshl_add_u64 v[138:139], v[138:139], 0, s[16:17]
	s_mov_b32 m0, s44
	ds_read_b128 v[208:211], v145 offset:49152
	ds_read_b128 v[212:215], v145 offset:50176
	ds_read_b128 v[216:219], v145 offset:51200
	ds_read_b128 v[220:223], v145 offset:52224
	ds_read_b128 v[224:227], v145 offset:53248
	ds_read_b128 v[228:231], v145 offset:54272
	ds_read_b128 v[232:235], v145 offset:55296
	ds_read_b128 v[236:239], v145 offset:56320
	global_load_lds_dwordx4 v[138:139], off
	s_add_i32 m0, s44, 0x2000
	s_add_u32 s48, s48, 0x160080
	v_lshl_add_u64 v[138:139], v[158:159], 0, s[16:17]
	s_addc_u32 s49, s49, 0
	s_add_i32 s44, s45, s60
	global_load_lds_dwordx4 v[138:139], off
	v_lshl_add_u64 v[138:139], s[48:49], 0, v[160:161]
	s_mov_b32 m0, s44
	s_nop 0
	global_load_lds_dwordx4 v[138:139], off
	v_lshl_add_u64 v[138:139], s[48:49], 0, v[162:163]
	s_add_i32 m0, s44, 0x2000
	s_nop 0
	global_load_lds_dwordx4 v[138:139], off
	v_lshl_add_u64 v[138:139], v[188:189], 0, s[16:17]
	s_mov_b32 m0, s65
	s_nop 0
	global_load_lds_dwordx4 v[138:139], off
	v_lshl_add_u64 v[138:139], v[200:201], 0, s[16:17]
	s_mov_b32 m0, s66
	s_nop 0
	global_load_lds_dwordx4 v[138:139], off
	s_add_i32 s75, s75, 2
	s_add_u32 s42, s42, 0x100
	s_addc_u32 s43, s43, 0
	s_add_u32 s34, s34, 0x100
	s_addc_u32 s35, s35, 0
	s_waitcnt vmcnt(8)
	s_waitcnt lgkmcnt(0)
	s_barrier
	s_setprio 1
	s_waitcnt lgkmcnt(0)
	v_mfma_f32_16x16x32_bf16 v[60:63], v[134:137], v[208:211], v[60:63]
	v_mfma_f32_16x16x32_bf16 v[60:63], v[146:149], v[212:215], v[60:63]
	v_mfma_f32_16x16x32_bf16 v[56:59], v[154:157], v[212:215], v[56:59]
	v_mfma_f32_16x16x32_bf16 v[56:59], v[150:153], v[208:211], v[56:59]
	v_mfma_f32_16x16x32_bf16 v[44:47], v[172:175], v[208:211], v[44:47]
	v_mfma_f32_16x16x32_bf16 v[44:47], v[176:179], v[212:215], v[44:47]
	v_mfma_f32_16x16x32_bf16 v[40:43], v[184:187], v[212:215], v[40:43]
	v_mfma_f32_16x16x32_bf16 v[40:43], v[180:183], v[208:211], v[40:43]
	v_mfma_f32_16x16x32_bf16 v[32:35], v[180:183], v[216:219], v[32:35]
	v_mfma_f32_16x16x32_bf16 v[32:35], v[184:187], v[220:223], v[32:35]
	v_mfma_f32_16x16x32_bf16 v[36:39], v[176:179], v[220:223], v[36:39]
	v_mfma_f32_16x16x32_bf16 v[36:39], v[172:175], v[216:219], v[36:39]
	v_mfma_f32_16x16x32_bf16 v[48:51], v[150:153], v[216:219], v[48:51]
	v_mfma_f32_16x16x32_bf16 v[48:51], v[154:157], v[220:223], v[48:51]
	v_mfma_f32_16x16x32_bf16 v[52:55], v[146:149], v[220:223], v[52:55]
	v_mfma_f32_16x16x32_bf16 v[52:55], v[134:137], v[216:219], v[52:55]
	s_setprio 0
	s_setprio 1
	v_mfma_f32_16x16x32_bf16 v[28:31], v[134:137], v[224:227], v[28:31]
	v_mfma_f32_16x16x32_bf16 v[28:31], v[146:149], v[228:231], v[28:31]
	v_mfma_f32_16x16x32_bf16 v[24:27], v[154:157], v[228:231], v[24:27]
	v_mfma_f32_16x16x32_bf16 v[24:27], v[150:153], v[224:227], v[24:27]
	v_mfma_f32_16x16x32_bf16 v[12:15], v[172:175], v[224:227], v[12:15]
	v_mfma_f32_16x16x32_bf16 v[12:15], v[176:179], v[228:231], v[12:15]
	v_mfma_f32_16x16x32_bf16 v[8:11], v[184:187], v[228:231], v[8:11]
	v_mfma_f32_16x16x32_bf16 v[8:11], v[180:183], v[224:227], v[8:11]
	v_mfma_f32_16x16x32_bf16 v[0:3], v[180:183], v[232:235], v[0:3]
	v_mfma_f32_16x16x32_bf16 v[0:3], v[184:187], v[236:239], v[0:3]
	v_mfma_f32_16x16x32_bf16 v[4:7], v[176:179], v[236:239], v[4:7]
	v_mfma_f32_16x16x32_bf16 v[4:7], v[172:175], v[232:235], v[4:7]
	v_mfma_f32_16x16x32_bf16 v[16:19], v[150:153], v[232:235], v[16:19]
	v_mfma_f32_16x16x32_bf16 v[16:19], v[154:157], v[236:239], v[16:19]
	s_setprio 2
	s_barrier
	v_mfma_f32_16x16x32_bf16 v[20:23], v[146:149], v[236:239], v[20:23]
	v_mfma_f32_16x16x32_bf16 v[20:23], v[134:137], v[232:235], v[20:23]
	s_setprio 0
	s_cmpk_gt_u32 s75, 0x55
	s_cbranch_scc0 .LBB0_837
	s_and_b64 vcc, exec, s[18:19]
	s_cbranch_vccz .LBB0_840
	s_barrier

; #define PG8_STAGE(bufoff, gbase, voff) do { _Pragma("unroll") for (int _i = 0; _i < 2; ++_i) \
;         __builtin_amdgcn_global_load_lds((const unsigned*)((const char*)(gbase) + (voff)[_i]), (PG8_LAS unsigned*)(lds + (bufoff) + ldsw + _i * 8192), 16, 0, 0); } while (0)
; #define PG8_LDA(dst, b, h) do { _Pragma("unroll") for (int m = 0; m < 4; ++m) _Pragma("unroll") for (int k = 0; k < 2; ++k) dst[m][k] = *(const PG8_LAS bf16x8*)(lds + PG8_SA(b, h) + aoff + m * 2048 + k * 1024); } while (0)
; #define PG8_LDB(dst, b, h) do { _Pragma("unroll") for (int n = 0; n < 2; ++n) _Pragma("unroll") for (int k = 0; k < 2; ++k) dst[n][k] = *(const PG8_LAS bf16x8*)(lds + PG8_SB(b, h) + boff + n * 2048 + k * 1024); } while (0)
; #define PG8_MMA(ai, bj, At, Bt) do { __builtin_amdgcn_s_setprio(1); _Pragma("unroll") for (int m = 0; m < 4; ++m) _Pragma("unroll") for (int n = 0; n < 2; ++n) _Pragma("unroll") for (int k = 0; k < 2; ++k) \
;         acc[ai][bj][m][n] = __builtin_amdgcn_mfma_f32_16x16x32_bf16(Bt[n][k], At[m][k], acc[ai][bj][m][n], 0, 0, 0); __builtin_amdgcn_s_setprio(0); } while (0)
; #define PG8_WAIT_V(n) asm volatile("s_waitcnt vmcnt(" #n ")" ::: "memory")
; #define PG8_WAIT_L(n) asm volatile("s_waitcnt lgkmcnt(" #n ")" ::: "memory")
; #define PG8_BAR __builtin_amdgcn_s_barrier()
; #define PG8_SCHED __builtin_amdgcn_sched_barrier(0)
; template <class Epi, class Sched, bool ALIGN_EPI = false, bool SP2 = false>
; __device__ __forceinline__ void gemm_phase(PG8_LAS unsigned char* lds, const Gemm g, const Sched& S, const Epi& E) {
;     ...
;             const bool last = (t == nt - 2);
;             const char* a1 = cA + (size_t)(t + 1) * kstep;
;             const char* a2 = last ? nA : cA + (size_t)(t + 2) * kstep; const char* b2 = last ? nB : cB + (size_t)(t + 2) * kstep;
;             const char* a3 = a2 + kstep; const char* b3 = b2 + kstep;
;             if (last && has_next) S.a_ready(nxt);
;             if constexpr (SP2) {
;             PG8_LDB(B0, 0, 0); PG8_LDB(B1, 0, 1); PG8_SCHED; PG8_LDA(At, 0, 0); PG8_STAGE(PG8_SA(1, 1), a1 + hstep, voffA);
;             PG8_WAIT_V(8); PG8_WAIT_L(0); PG8_BAR; PG8_MMA(0, 0, At, B0); PG8_MMA(0, 1, At, B1); PG8_BAR; PG8_SCHED;
;             PG8_LDA(At, 0, 1); PG8_STAGE(PG8_SB(0, 0), b2, voffB); PG8_STAGE(PG8_SB(0, 1), b2 + hstep, voffB); PG8_STAGE(PG8_SA(0, 0), a2, voffA);
.LBB0_880:
	ds_read_b128 v[136:139], v156
	ds_read_b128 v[140:143], v156 offset:1024
	ds_read_b128 v[172:175], v156 offset:2048
	ds_read_b128 v[176:179], v156 offset:3072
	ds_read_b128 v[180:183], v157
	ds_read_b128 v[184:187], v157 offset:1024
	ds_read_b128 v[196:199], v157 offset:2048
	ds_read_b128 v[208:211], v157 offset:3072
	s_add_u32 s40, s38, 0xfff80080
	s_addc_u32 s41, s39, -1
	s_cmp_eq_u32 s63, 28
	s_cselect_b32 s43, s19, s41
	s_cselect_b32 s42, s34, s40
	s_cselect_b32 s41, s21, s62
	s_cselect_b32 s40, s35, s61
	v_lshl_add_u64 v[188:189], s[38:39], 0, v[128:129]
	s_add_i32 m0, s7, 0xc000
	ds_read_b128 v[212:215], v158
	ds_read_b128 v[216:219], v158 offset:1024
	ds_read_b128 v[220:223], v158 offset:2048
	ds_read_b128 v[224:227], v158 offset:3072
	ds_read_b128 v[228:231], v158 offset:4096
	ds_read_b128 v[232:235], v158 offset:5120
	ds_read_b128 v[236:239], v158 offset:6144
	ds_read_b128 v[240:243], v158 offset:7168
	global_load_lds_dwordx4 v[188:189], off
	v_lshl_add_u64 v[188:189], s[38:39], 0, v[130:131]
	s_add_i32 m0, s7, 0xe000
	s_nop 0
	global_load_lds_dwordx4 v[188:189], off
	s_waitcnt vmcnt(8)
	s_waitcnt lgkmcnt(0)
	s_barrier
	s_setprio 1
	s_waitcnt lgkmcnt(0)
	v_mfma_f32_16x16x32_bf16 v[124:127], v[136:139], v[212:215], v[124:127]
	v_mfma_f32_16x16x32_bf16 v[124:127], v[140:143], v[216:219], v[124:127]
	v_mfma_f32_16x16x32_bf16 v[120:123], v[176:179], v[216:219], v[120:123]
	v_mfma_f32_16x16x32_bf16 v[120:123], v[172:175], v[212:215], v[120:123]
	v_mfma_f32_16x16x32_bf16 v[116:119], v[180:183], v[212:215], v[116:119]
	v_mfma_f32_16x16x32_bf16 v[116:119], v[184:187], v[216:219], v[116:119]
	v_mfma_f32_16x16x32_bf16 v[112:115], v[208:211], v[216:219], v[112:115]
	v_mfma_f32_16x16x32_bf16 v[112:115], v[196:199], v[212:215], v[112:115]
	v_mfma_f32_16x16x32_bf16 v[92:95], v[196:199], v[220:223], v[92:95]
	v_mfma_f32_16x16x32_bf16 v[92:95], v[208:211], v[224:227], v[92:95]
	v_mfma_f32_16x16x32_bf16 v[100:103], v[184:187], v[224:227], v[100:103]
	v_mfma_f32_16x16x32_bf16 v[100:103], v[180:183], v[220:223], v[100:103]
	v_mfma_f32_16x16x32_bf16 v[104:107], v[172:175], v[220:223], v[104:107]
	v_mfma_f32_16x16x32_bf16 v[104:107], v[176:179], v[224:227], v[104:107]
	v_mfma_f32_16x16x32_bf16 v[108:111], v[140:143], v[224:227], v[108:111]
	v_mfma_f32_16x16x32_bf16 v[108:111], v[136:139], v[220:223], v[108:111]
	s_setprio 0
	s_setprio 1
	v_mfma_f32_16x16x32_bf16 v[96:99], v[136:139], v[228:231], v[96:99]
	v_mfma_f32_16x16x32_bf16 v[96:99], v[140:143], v[232:235], v[96:99]
	v_mfma_f32_16x16x32_bf16 v[88:91], v[176:179], v[232:235], v[88:91]
	v_mfma_f32_16x16x32_bf16 v[88:91], v[172:175], v[228:231], v[88:91]
	v_mfma_f32_16x16x32_bf16 v[84:87], v[180:183], v[228:231], v[84:87]
	v_mfma_f32_16x16x32_bf16 v[84:87], v[184:187], v[232:235], v[84:87]
	v_mfma_f32_16x16x32_bf16 v[76:79], v[208:211], v[232:235], v[76:79]
	v_mfma_f32_16x16x32_bf16 v[76:79], v[196:199], v[228:231], v[76:79]
	v_mfma_f32_16x16x32_bf16 v[64:67], v[196:199], v[236:239], v[64:67]
	v_mfma_f32_16x16x32_bf16 v[64:67], v[208:211], v[240:243], v[64:67]
	v_mfma_f32_16x16x32_bf16 v[68:71], v[184:187], v[240:243], v[68:71]
	v_mfma_f32_16x16x32_bf16 v[68:71], v[180:183], v[236:239], v[68:71]
	v_mfma_f32_16x16x32_bf16 v[72:75], v[172:175], v[236:239], v[72:75]
	v_mfma_f32_16x16x32_bf16 v[72:75], v[176:179], v[240:243], v[72:75]
	s_setprio 2
	s_barrier
	v_mfma_f32_16x16x32_bf16 v[80:83], v[140:143], v[240:243], v[80:83]
	v_mfma_f32_16x16x32_bf16 v[80:83], v[136:139], v[236:239], v[80:83]
	s_setprio 0
	s_add_i32 s44, s52, s33
	v_lshl_add_u64 v[188:189], s[40:41], 0, v[166:167]
	s_mov_b32 m0, s44
	ds_read_b128 v[212:215], v158 offset:16384
	ds_read_b128 v[216:219], v158 offset:17408
	ds_read_b128 v[220:223], v158 offset:18432
	ds_read_b128 v[224:227], v158 offset:19456
	ds_read_b128 v[228:231], v158 offset:20480
	ds_read_b128 v[232:235], v158 offset:21504
	ds_read_b128 v[236:239], v158 offset:22528
	ds_read_b128 v[240:243], v158 offset:23552
	global_load_lds_dwordx4 v[188:189], off
	s_add_i32 m0, s44, 0x2000
	s_add_u32 s64, s40, 0x80000
	v_lshl_add_u64 v[200:201], s[40:41], 0, v[170:171]
	s_addc_u32 s65, s41, 0
	s_add_i32 s44, s53, s33
	global_load_lds_dwordx4 v[200:201], off
	v_lshl_add_u64 v[244:245], s[64:65], 0, v[166:167]
	s_mov_b32 m0, s44
	v_lshl_add_u64 v[246:247], s[42:43], 0, v[168:169]
	global_load_lds_dwordx4 v[244:245], off
	v_lshl_add_u64 v[244:245], s[64:65], 0, v[170:171]
	s_add_i32 m0, s44, 0x2000
	s_nop 0
	global_load_lds_dwordx4 v[244:245], off
	v_lshl_add_u64 v[244:245], s[42:43], 0, v[164:165]
	s_mov_b32 m0, s7
	s_nop 0
	global_load_lds_dwordx4 v[244:245], off
	s_mov_b32 m0, s37
	s_nop 0
	global_load_lds_dwordx4 v[246:247], off
	s_waitcnt vmcnt(8)
	s_waitcnt lgkmcnt(0)
	s_barrier
; #define PG8_STAGE(bufoff, gbase, voff) do { _Pragma("unroll") for (int _i = 0; _i < 2; ++_i) \
;         __builtin_amdgcn_global_load_lds((const unsigned*)((const char*)(gbase) + (voff)[_i]), (PG8_LAS unsigned*)(lds + (bufoff) + ldsw + _i * 8192), 16, 0, 0); } while (0)
; #define PG8_LDA(dst, b, h) do { _Pragma("unroll") for (int m = 0; m < 4; ++m) _Pragma("unroll") for (int k = 0; k < 2; ++k) dst[m][k] = *(const PG8_LAS bf16x8*)(lds + PG8_SA(b, h) + aoff + m * 2048 + k * 1024); } while (0)
; #define PG8_LDB(dst, b, h) do { _Pragma("unroll") for (int n = 0; n < 2; ++n) _Pragma("unroll") for (int k = 0; k < 2; ++k) dst[n][k] = *(const PG8_LAS bf16x8*)(lds + PG8_SB(b, h) + boff + n * 2048 + k * 1024); } while (0)
; #define PG8_MMA(ai, bj, At, Bt) do { __builtin_amdgcn_s_setprio(1); _Pragma("unroll") for (int m = 0; m < 4; ++m) _Pragma("unroll") for (int n = 0; n < 2; ++n) _Pragma("unroll") for (int k = 0; k < 2; ++k) \
;         acc[ai][bj][m][n] = __builtin_amdgcn_mfma_f32_16x16x32_bf16(Bt[n][k], At[m][k], acc[ai][bj][m][n], 0, 0, 0); __builtin_amdgcn_s_setprio(0); } while (0)
; #define PG8_WAIT_V(n) asm volatile("s_waitcnt vmcnt(" #n ")" ::: "memory")
; #define PG8_WAIT_L(n) asm volatile("s_waitcnt lgkmcnt(" #n ")" ::: "memory")
; #define PG8_BAR __builtin_amdgcn_s_barrier()
; #define PG8_SCHED __builtin_amdgcn_sched_barrier(0)
; template <class Epi, class Sched, bool ALIGN_EPI = false, bool SP2 = false>
; __device__ __forceinline__ void gemm_phase(PG8_LAS unsigned char* lds, const Gemm g, const Sched& S, const Epi& E) {
;     ...
;             PG8_WAIT_V(8); PG8_WAIT_L(0); PG8_BAR; PG8_MMA(1, 0, At, B0); PG8_MMA(1, 1, At, B1); PG8_BAR; PG8_SCHED;
;             PG8_LDB(B0, 1, 0); PG8_LDB(B1, 1, 1); PG8_SCHED; PG8_LDA(At, 1, 0); PG8_STAGE(PG8_SA(0, 1), a2 + hstep, voffA);
;             PG8_WAIT_V(8); PG8_WAIT_L(0); PG8_BAR; PG8_MMA(0, 0, At, B0); PG8_MMA(0, 1, At, B1); PG8_BAR; PG8_SCHED;
	s_setprio 1
	s_waitcnt lgkmcnt(0)
	v_mfma_f32_16x16x32_bf16 v[60:63], v[136:139], v[212:215], v[60:63]
	v_mfma_f32_16x16x32_bf16 v[60:63], v[140:143], v[216:219], v[60:63]
	v_mfma_f32_16x16x32_bf16 v[56:59], v[176:179], v[216:219], v[56:59]
	v_mfma_f32_16x16x32_bf16 v[56:59], v[172:175], v[212:215], v[56:59]
	v_mfma_f32_16x16x32_bf16 v[52:55], v[180:183], v[212:215], v[52:55]
	v_mfma_f32_16x16x32_bf16 v[52:55], v[184:187], v[216:219], v[52:55]
	v_mfma_f32_16x16x32_bf16 v[44:47], v[208:211], v[216:219], v[44:47]
	v_mfma_f32_16x16x32_bf16 v[44:47], v[196:199], v[212:215], v[44:47]
	v_mfma_f32_16x16x32_bf16 v[28:31], v[196:199], v[220:223], v[28:31]
	v_mfma_f32_16x16x32_bf16 v[28:31], v[208:211], v[224:227], v[28:31]
	v_mfma_f32_16x16x32_bf16 v[36:39], v[184:187], v[224:227], v[36:39]
	v_mfma_f32_16x16x32_bf16 v[36:39], v[180:183], v[220:223], v[36:39]
	v_mfma_f32_16x16x32_bf16 v[40:43], v[172:175], v[220:223], v[40:43]
	v_mfma_f32_16x16x32_bf16 v[40:43], v[176:179], v[224:227], v[40:43]
	v_mfma_f32_16x16x32_bf16 v[48:51], v[140:143], v[224:227], v[48:51]
	v_mfma_f32_16x16x32_bf16 v[48:51], v[136:139], v[220:223], v[48:51]
	s_setprio 0
	s_setprio 1
	v_mfma_f32_16x16x32_bf16 v[32:35], v[136:139], v[228:231], v[32:35]
	v_mfma_f32_16x16x32_bf16 v[32:35], v[140:143], v[232:235], v[32:35]
	v_mfma_f32_16x16x32_bf16 v[24:27], v[176:179], v[232:235], v[24:27]
	v_mfma_f32_16x16x32_bf16 v[24:27], v[172:175], v[228:231], v[24:27]
	v_mfma_f32_16x16x32_bf16 v[20:23], v[180:183], v[228:231], v[20:23]
	v_mfma_f32_16x16x32_bf16 v[20:23], v[184:187], v[232:235], v[20:23]
	v_mfma_f32_16x16x32_bf16 v[16:19], v[208:211], v[232:235], v[16:19]
	v_mfma_f32_16x16x32_bf16 v[16:19], v[196:199], v[228:231], v[16:19]
	v_mfma_f32_16x16x32_bf16 v[0:3], v[196:199], v[236:239], v[0:3]
	v_mfma_f32_16x16x32_bf16 v[0:3], v[208:211], v[240:243], v[0:3]
	v_mfma_f32_16x16x32_bf16 v[4:7], v[184:187], v[240:243], v[4:7]
	v_mfma_f32_16x16x32_bf16 v[4:7], v[180:183], v[236:239], v[4:7]
	v_mfma_f32_16x16x32_bf16 v[8:11], v[172:175], v[236:239], v[8:11]
	v_mfma_f32_16x16x32_bf16 v[8:11], v[176:179], v[240:243], v[8:11]
	s_setprio 2
	s_barrier
	v_mfma_f32_16x16x32_bf16 v[12:15], v[140:143], v[240:243], v[12:15]
	v_mfma_f32_16x16x32_bf16 v[12:15], v[136:139], v[236:239], v[12:15]
	s_setprio 0
	s_add_i32 s44, 0, 0x18000
	v_add_u32_e32 v144, s44, v146
	s_add_i32 s45, 0, 0x1c000
	ds_read_b128 v[136:139], v144
	ds_read_b128 v[140:143], v144 offset:1024
	ds_read_b128 v[172:175], v144 offset:2048
	ds_read_b128 v[176:179], v144 offset:3072
	v_add_u32_e32 v144, s45, v146
	ds_read_b128 v[180:183], v144
	ds_read_b128 v[184:187], v144 offset:1024
	ds_read_b128 v[196:199], v144 offset:2048
	ds_read_b128 v[208:211], v144 offset:3072
	s_add_u32 s42, s42, 0x80000
	s_addc_u32 s43, s43, 0
	s_mov_b32 m0, s48
	v_lshl_add_u64 v[248:249], s[42:43], 0, v[164:165]
	ds_read_b128 v[212:215], v158 offset:32768
	ds_read_b128 v[216:219], v158 offset:33792
	ds_read_b128 v[220:223], v158 offset:34816
	ds_read_b128 v[224:227], v158 offset:35840
	ds_read_b128 v[228:231], v158 offset:36864
	ds_read_b128 v[232:235], v158 offset:37888
	ds_read_b128 v[236:239], v158 offset:38912
	ds_read_b128 v[240:243], v158 offset:39936
	global_load_lds_dwordx4 v[248:249], off
	v_lshl_add_u64 v[248:249], s[42:43], 0, v[168:169]
	s_mov_b32 m0, s49
	s_nop 0
	global_load_lds_dwordx4 v[248:249], off
	s_waitcnt vmcnt(8)
	s_waitcnt lgkmcnt(0)
	s_barrier
	s_setprio 1
	s_waitcnt lgkmcnt(0)
	v_mfma_f32_16x16x32_bf16 v[124:127], v[136:139], v[212:215], v[124:127]
	v_mfma_f32_16x16x32_bf16 v[124:127], v[140:143], v[216:219], v[124:127]
	v_mfma_f32_16x16x32_bf16 v[120:123], v[176:179], v[216:219], v[120:123]
	v_mfma_f32_16x16x32_bf16 v[120:123], v[172:175], v[212:215], v[120:123]
	v_mfma_f32_16x16x32_bf16 v[116:119], v[180:183], v[212:215], v[116:119]
	v_mfma_f32_16x16x32_bf16 v[116:119], v[184:187], v[216:219], v[116:119]
	v_mfma_f32_16x16x32_bf16 v[112:115], v[208:211], v[216:219], v[112:115]
	v_mfma_f32_16x16x32_bf16 v[112:115], v[196:199], v[212:215], v[112:115]
	v_mfma_f32_16x16x32_bf16 v[92:95], v[196:199], v[220:223], v[92:95]
	v_mfma_f32_16x16x32_bf16 v[92:95], v[208:211], v[224:227], v[92:95]
	v_mfma_f32_16x16x32_bf16 v[100:103], v[184:187], v[224:227], v[100:103]
	v_mfma_f32_16x16x32_bf16 v[100:103], v[180:183], v[220:223], v[100:103]
	v_mfma_f32_16x16x32_bf16 v[104:107], v[172:175], v[220:223], v[104:107]
	v_mfma_f32_16x16x32_bf16 v[104:107], v[176:179], v[224:227], v[104:107]
	v_mfma_f32_16x16x32_bf16 v[108:111], v[140:143], v[224:227], v[108:111]
	v_mfma_f32_16x16x32_bf16 v[108:111], v[136:139], v[220:223], v[108:111]
	s_setprio 0
	s_setprio 1
	v_mfma_f32_16x16x32_bf16 v[96:99], v[136:139], v[228:231], v[96:99]
	v_mfma_f32_16x16x32_bf16 v[96:99], v[140:143], v[232:235], v[96:99]
	v_mfma_f32_16x16x32_bf16 v[88:91], v[176:179], v[232:235], v[88:91]
	v_mfma_f32_16x16x32_bf16 v[88:91], v[172:175], v[228:231], v[88:91]
	v_mfma_f32_16x16x32_bf16 v[84:87], v[180:183], v[228:231], v[84:87]
	v_mfma_f32_16x16x32_bf16 v[84:87], v[184:187], v[232:235], v[84:87]
	v_mfma_f32_16x16x32_bf16 v[76:79], v[208:211], v[232:235], v[76:79]
	v_mfma_f32_16x16x32_bf16 v[76:79], v[196:199], v[228:231], v[76:79]
	v_mfma_f32_16x16x32_bf16 v[64:67], v[196:199], v[236:239], v[64:67]
	v_mfma_f32_16x16x32_bf16 v[64:67], v[208:211], v[240:243], v[64:67]
	v_mfma_f32_16x16x32_bf16 v[68:71], v[184:187], v[240:243], v[68:71]
	v_mfma_f32_16x16x32_bf16 v[68:71], v[180:183], v[236:239], v[68:71]
	v_mfma_f32_16x16x32_bf16 v[72:75], v[172:175], v[236:239], v[72:75]
	v_mfma_f32_16x16x32_bf16 v[72:75], v[176:179], v[240:243], v[72:75]
	s_setprio 2
	s_barrier
; #define PG8_STAGE(bufoff, gbase, voff) do { _Pragma("unroll") for (int _i = 0; _i < 2; ++_i) \
;         __builtin_amdgcn_global_load_lds((const unsigned*)((const char*)(gbase) + (voff)[_i]), (PG8_LAS unsigned*)(lds + (bufoff) + ldsw + _i * 8192), 16, 0, 0); } while (0)
; #define PG8_LDA(dst, b, h) do { _Pragma("unroll") for (int m = 0; m < 4; ++m) _Pragma("unroll") for (int k = 0; k < 2; ++k) dst[m][k] = *(const PG8_LAS bf16x8*)(lds + PG8_SA(b, h) + aoff + m * 2048 + k * 1024); } while (0)
; #define PG8_MMA(ai, bj, At, Bt) do { __builtin_amdgcn_s_setprio(1); _Pragma("unroll") for (int m = 0; m < 4; ++m) _Pragma("unroll") for (int n = 0; n < 2; ++n) _Pragma("unroll") for (int k = 0; k < 2; ++k) \
;         acc[ai][bj][m][n] = __builtin_amdgcn_mfma_f32_16x16x32_bf16(Bt[n][k], At[m][k], acc[ai][bj][m][n], 0, 0, 0); __builtin_amdgcn_s_setprio(0); } while (0)
; #define PG8_WAIT_V(n) asm volatile("s_waitcnt vmcnt(" #n ")" ::: "memory")
; #define PG8_WAIT_L(n) asm volatile("s_waitcnt lgkmcnt(" #n ")" ::: "memory")
; #define PG8_BAR __builtin_amdgcn_s_barrier()
; #define PG8_SCHED __builtin_amdgcn_sched_barrier(0)
; template <class Epi, class Sched, bool ALIGN_EPI = false, bool SP2 = false>
; __device__ __forceinline__ void gemm_phase(PG8_LAS unsigned char* lds, const Gemm g, const Sched& S, const Epi& E) {
;     ...
;         for (int t = 0; t < nt; t += 2) {
;     ...
;             PG8_WAIT_V(8); PG8_WAIT_L(0); PG8_BAR; PG8_MMA(0, 0, At, B0); PG8_MMA(0, 1, At, B1); PG8_BAR; PG8_SCHED;
;             PG8_LDA(At, 1, 1); PG8_STAGE(PG8_SB(1, 0), b3, voffB); PG8_STAGE(PG8_SB(1, 1), b3 + hstep, voffB); PG8_STAGE(PG8_SA(1, 0), a3, voffA);
;             PG8_WAIT_V(8); PG8_WAIT_L(0); PG8_BAR; PG8_MMA(1, 0, At, B0); PG8_MMA(1, 1, At, B1); PG8_BAR; PG8_SCHED;
	v_mfma_f32_16x16x32_bf16 v[80:83], v[140:143], v[240:243], v[80:83]
	v_mfma_f32_16x16x32_bf16 v[80:83], v[136:139], v[236:239], v[80:83]
	s_setprio 0
	s_add_i32 s42, s44, s33
	v_lshl_add_u64 v[188:189], v[188:189], 0, s[14:15]
	s_mov_b32 m0, s42
	ds_read_b128 v[212:215], v158 offset:49152
	ds_read_b128 v[216:219], v158 offset:50176
	ds_read_b128 v[220:223], v158 offset:51200
	ds_read_b128 v[224:227], v158 offset:52224
	ds_read_b128 v[228:231], v158 offset:53248
	ds_read_b128 v[232:235], v158 offset:54272
	ds_read_b128 v[236:239], v158 offset:55296
	ds_read_b128 v[240:243], v158 offset:56320
	global_load_lds_dwordx4 v[188:189], off
	s_add_i32 m0, s42, 0x2000
	s_add_u32 s40, s40, 0x80080
	v_lshl_add_u64 v[188:189], v[200:201], 0, s[14:15]
	s_addc_u32 s41, s41, 0
	s_add_i32 s42, s45, s33
	global_load_lds_dwordx4 v[188:189], off
	v_lshl_add_u64 v[188:189], s[40:41], 0, v[166:167]
	s_mov_b32 m0, s42
	s_nop 0
	global_load_lds_dwordx4 v[188:189], off
	v_lshl_add_u64 v[188:189], s[40:41], 0, v[170:171]
	s_add_i32 m0, s42, 0x2000
	s_nop 0
	global_load_lds_dwordx4 v[188:189], off
	v_lshl_add_u64 v[188:189], v[244:245], 0, s[14:15]
	s_mov_b32 m0, s50
	s_nop 0
	global_load_lds_dwordx4 v[188:189], off
	v_lshl_add_u64 v[188:189], v[246:247], 0, s[14:15]
	s_mov_b32 m0, s51
	s_nop 0
	global_load_lds_dwordx4 v[188:189], off
	s_add_i32 s63, s63, 2
	s_add_u32 s38, s38, 0x100
	s_addc_u32 s39, s39, 0
	s_add_u32 s61, s61, 0x100
	s_addc_u32 s62, s62, 0
	s_waitcnt vmcnt(8)
	s_waitcnt lgkmcnt(0)
	s_barrier
	s_setprio 1
	s_waitcnt lgkmcnt(0)
	v_mfma_f32_16x16x32_bf16 v[60:63], v[136:139], v[212:215], v[60:63]
	v_mfma_f32_16x16x32_bf16 v[60:63], v[140:143], v[216:219], v[60:63]
	v_mfma_f32_16x16x32_bf16 v[56:59], v[176:179], v[216:219], v[56:59]
	v_mfma_f32_16x16x32_bf16 v[56:59], v[172:175], v[212:215], v[56:59]
	v_mfma_f32_16x16x32_bf16 v[52:55], v[180:183], v[212:215], v[52:55]
	v_mfma_f32_16x16x32_bf16 v[52:55], v[184:187], v[216:219], v[52:55]
	v_mfma_f32_16x16x32_bf16 v[44:47], v[208:211], v[216:219], v[44:47]
	v_mfma_f32_16x16x32_bf16 v[44:47], v[196:199], v[212:215], v[44:47]
	v_mfma_f32_16x16x32_bf16 v[28:31], v[196:199], v[220:223], v[28:31]
	v_mfma_f32_16x16x32_bf16 v[28:31], v[208:211], v[224:227], v[28:31]
	v_mfma_f32_16x16x32_bf16 v[36:39], v[184:187], v[224:227], v[36:39]
	v_mfma_f32_16x16x32_bf16 v[36:39], v[180:183], v[220:223], v[36:39]
	v_mfma_f32_16x16x32_bf16 v[40:43], v[172:175], v[220:223], v[40:43]
	v_mfma_f32_16x16x32_bf16 v[40:43], v[176:179], v[224:227], v[40:43]
	v_mfma_f32_16x16x32_bf16 v[48:51], v[140:143], v[224:227], v[48:51]
	v_mfma_f32_16x16x32_bf16 v[48:51], v[136:139], v[220:223], v[48:51]
	s_setprio 0
	s_setprio 1
	v_mfma_f32_16x16x32_bf16 v[32:35], v[136:139], v[228:231], v[32:35]
	v_mfma_f32_16x16x32_bf16 v[32:35], v[140:143], v[232:235], v[32:35]
	v_mfma_f32_16x16x32_bf16 v[24:27], v[176:179], v[232:235], v[24:27]
	v_mfma_f32_16x16x32_bf16 v[24:27], v[172:175], v[228:231], v[24:27]
	v_mfma_f32_16x16x32_bf16 v[20:23], v[180:183], v[228:231], v[20:23]
	v_mfma_f32_16x16x32_bf16 v[20:23], v[184:187], v[232:235], v[20:23]
	v_mfma_f32_16x16x32_bf16 v[16:19], v[208:211], v[232:235], v[16:19]
	v_mfma_f32_16x16x32_bf16 v[16:19], v[196:199], v[228:231], v[16:19]
	v_mfma_f32_16x16x32_bf16 v[0:3], v[196:199], v[236:239], v[0:3]
	v_mfma_f32_16x16x32_bf16 v[0:3], v[208:211], v[240:243], v[0:3]
	v_mfma_f32_16x16x32_bf16 v[4:7], v[184:187], v[240:243], v[4:7]
	v_mfma_f32_16x16x32_bf16 v[4:7], v[180:183], v[236:239], v[4:7]
	v_mfma_f32_16x16x32_bf16 v[8:11], v[172:175], v[236:239], v[8:11]
	v_mfma_f32_16x16x32_bf16 v[8:11], v[176:179], v[240:243], v[8:11]
	s_setprio 2
	s_barrier
	v_mfma_f32_16x16x32_bf16 v[12:15], v[140:143], v[240:243], v[12:15]
	v_mfma_f32_16x16x32_bf16 v[12:15], v[136:139], v[236:239], v[12:15]
	s_setprio 0
	s_cmp_gt_u32 s63, 29
	s_cbranch_scc0 .LBB0_880
	s_and_b64 vcc, exec, s[16:17]
	s_cbranch_vccz .LBB0_883
	s_barrier

; #define PG8_STAGE(bufoff, gbase, voff) do { _Pragma("unroll") for (int _i = 0; _i < 2; ++_i) \
;         __builtin_amdgcn_global_load_lds((const unsigned*)((const char*)(gbase) + (voff)[_i]), (PG8_LAS unsigned*)(lds + (bufoff) + ldsw + _i * 8192), 16, 0, 0); } while (0)
; #define PG8_LDA(dst, b, h) do { _Pragma("unroll") for (int m = 0; m < 4; ++m) _Pragma("unroll") for (int k = 0; k < 2; ++k) dst[m][k] = *(const PG8_LAS bf16x8*)(lds + PG8_SA(b, h) + aoff + m * 2048 + k * 1024); } while (0)
; #define PG8_LDB(dst, b, h) do { _Pragma("unroll") for (int n = 0; n < 2; ++n) _Pragma("unroll") for (int k = 0; k < 2; ++k) dst[n][k] = *(const PG8_LAS bf16x8*)(lds + PG8_SB(b, h) + boff + n * 2048 + k * 1024); } while (0)
; #define PG8_MMA(ai, bj, At, Bt) do { __builtin_amdgcn_s_setprio(1); _Pragma("unroll") for (int m = 0; m < 4; ++m) _Pragma("unroll") for (int n = 0; n < 2; ++n) _Pragma("unroll") for (int k = 0; k < 2; ++k) \
;         acc[ai][bj][m][n] = __builtin_amdgcn_mfma_f32_16x16x32_bf16(Bt[n][k], At[m][k], acc[ai][bj][m][n], 0, 0, 0); __builtin_amdgcn_s_setprio(0); } while (0)
; #define PG8_WAIT_V(n) asm volatile("s_waitcnt vmcnt(" #n ")" ::: "memory")
; #define PG8_WAIT_L(n) asm volatile("s_waitcnt lgkmcnt(" #n ")" ::: "memory")
; #define PG8_BAR __builtin_amdgcn_s_barrier()
; #define PG8_SCHED __builtin_amdgcn_sched_barrier(0)
; template <class Epi, class Sched, bool ALIGN_EPI = false, bool SP2 = false>
; __device__ __forceinline__ void gemm_phase(PG8_LAS unsigned char* lds, const Gemm g, const Sched& S, const Epi& E) {
;     ...
;             const bool last = (t == nt - 2);
;             const char* a1 = cA + (size_t)(t + 1) * kstep;
;             const char* a2 = last ? nA : cA + (size_t)(t + 2) * kstep; const char* b2 = last ? nB : cB + (size_t)(t + 2) * kstep;
;             const char* a3 = a2 + kstep; const char* b3 = b2 + kstep;
;             if (last && has_next) S.a_ready(nxt);
;             if constexpr (SP2) {
;             PG8_LDB(B0, 0, 0); PG8_LDB(B1, 0, 1); PG8_SCHED; PG8_LDA(At, 0, 0); PG8_STAGE(PG8_SA(1, 1), a1 + hstep, voffA);
;             PG8_WAIT_V(8); PG8_WAIT_L(0); PG8_BAR; PG8_MMA(0, 0, At, B0); PG8_MMA(0, 1, At, B1); PG8_BAR; PG8_SCHED;
;             PG8_LDA(At, 0, 1); PG8_STAGE(PG8_SB(0, 0), b2, voffB); PG8_STAGE(PG8_SB(0, 1), b2 + hstep, voffB); PG8_STAGE(PG8_SA(0, 0), a2, voffA);
.LBB0_937:
	ds_read_b128 v[128:131], v199
	ds_read_b128 v[132:135], v199 offset:1024
	ds_read_b128 v[136:139], v199 offset:2048
	ds_read_b128 v[140:143], v199 offset:3072
	ds_read_b128 v[150:153], v200
	ds_read_b128 v[154:157], v200 offset:1024
	ds_read_b128 v[164:167], v200 offset:2048
	ds_read_b128 v[168:171], v200 offset:3072
	s_add_u32 s22, s20, 0xffea0080
	s_addc_u32 s23, s21, -1
	s_cmpk_eq_i32 s49, 0x54
	s_cselect_b32 s25, s17, s23
	s_cselect_b32 s24, s16, s22
	s_cselect_b32 s23, s19, s48
	s_cselect_b32 s22, s18, s47
	v_lshl_add_u64 v[158:159], s[20:21], 0, v[144:145]
	s_add_i32 m0, s31, 0xc000
	ds_read_b128 v[172:175], v201
	ds_read_b128 v[176:179], v201 offset:1024
	ds_read_b128 v[180:183], v201 offset:2048
	ds_read_b128 v[184:187], v201 offset:3072
	ds_read_b128 v[188:191], v201 offset:4096
	ds_read_b128 v[204:207], v201 offset:5120
	ds_read_b128 v[208:211], v201 offset:6144
	ds_read_b128 v[212:215], v201 offset:7168
	global_load_lds_dwordx4 v[158:159], off
	v_lshl_add_u64 v[158:159], s[20:21], 0, v[146:147]
	s_add_i32 m0, s31, 0xe000
	s_nop 0
	global_load_lds_dwordx4 v[158:159], off
	s_waitcnt vmcnt(8)
	s_waitcnt lgkmcnt(0)
	s_barrier
	s_setprio 1
	s_waitcnt lgkmcnt(0)
	v_mfma_f32_16x16x32_bf16 v[124:127], v[128:131], v[172:175], v[124:127]
	v_mfma_f32_16x16x32_bf16 v[124:127], v[132:135], v[176:179], v[124:127]
	v_mfma_f32_16x16x32_bf16 v[120:123], v[140:143], v[176:179], v[120:123]
	v_mfma_f32_16x16x32_bf16 v[120:123], v[136:139], v[172:175], v[120:123]
	v_mfma_f32_16x16x32_bf16 v[116:119], v[150:153], v[172:175], v[116:119]
	v_mfma_f32_16x16x32_bf16 v[116:119], v[154:157], v[176:179], v[116:119]
	v_mfma_f32_16x16x32_bf16 v[112:115], v[168:171], v[176:179], v[112:115]
	v_mfma_f32_16x16x32_bf16 v[112:115], v[164:167], v[172:175], v[112:115]
	v_mfma_f32_16x16x32_bf16 v[96:99], v[164:167], v[180:183], v[96:99]
	v_mfma_f32_16x16x32_bf16 v[96:99], v[168:171], v[184:187], v[96:99]
	v_mfma_f32_16x16x32_bf16 v[100:103], v[154:157], v[184:187], v[100:103]
	v_mfma_f32_16x16x32_bf16 v[100:103], v[150:153], v[180:183], v[100:103]
	v_mfma_f32_16x16x32_bf16 v[104:107], v[136:139], v[180:183], v[104:107]
	v_mfma_f32_16x16x32_bf16 v[104:107], v[140:143], v[184:187], v[104:107]
	v_mfma_f32_16x16x32_bf16 v[108:111], v[132:135], v[184:187], v[108:111]
	v_mfma_f32_16x16x32_bf16 v[108:111], v[128:131], v[180:183], v[108:111]
	s_setprio 0
	s_setprio 1
	v_mfma_f32_16x16x32_bf16 v[92:95], v[128:131], v[188:191], v[92:95]
	v_mfma_f32_16x16x32_bf16 v[92:95], v[132:135], v[204:207], v[92:95]
	v_mfma_f32_16x16x32_bf16 v[88:91], v[140:143], v[204:207], v[88:91]
	v_mfma_f32_16x16x32_bf16 v[88:91], v[136:139], v[188:191], v[88:91]
	v_mfma_f32_16x16x32_bf16 v[84:87], v[150:153], v[188:191], v[84:87]
	v_mfma_f32_16x16x32_bf16 v[84:87], v[154:157], v[204:207], v[84:87]
	v_mfma_f32_16x16x32_bf16 v[80:83], v[168:171], v[204:207], v[80:83]
	v_mfma_f32_16x16x32_bf16 v[80:83], v[164:167], v[188:191], v[80:83]
	v_mfma_f32_16x16x32_bf16 v[64:67], v[164:167], v[208:211], v[64:67]
	v_mfma_f32_16x16x32_bf16 v[64:67], v[168:171], v[212:215], v[64:67]
	v_mfma_f32_16x16x32_bf16 v[68:71], v[154:157], v[212:215], v[68:71]
	v_mfma_f32_16x16x32_bf16 v[68:71], v[150:153], v[208:211], v[68:71]
	v_mfma_f32_16x16x32_bf16 v[72:75], v[136:139], v[208:211], v[72:75]
	v_mfma_f32_16x16x32_bf16 v[72:75], v[140:143], v[212:215], v[72:75]
	s_setprio 2
	s_barrier
	v_mfma_f32_16x16x32_bf16 v[76:79], v[132:135], v[212:215], v[76:79]
	v_mfma_f32_16x16x32_bf16 v[76:79], v[128:131], v[208:211], v[76:79]
	s_setprio 0
	s_add_i32 s50, s41, s30
	v_lshl_add_u64 v[158:159], s[22:23], 0, v[160:161]
	s_mov_b32 m0, s50
	ds_read_b128 v[172:175], v201 offset:16384
	ds_read_b128 v[176:179], v201 offset:17408
	ds_read_b128 v[180:183], v201 offset:18432
	ds_read_b128 v[184:187], v201 offset:19456
	ds_read_b128 v[188:191], v201 offset:20480
	ds_read_b128 v[204:207], v201 offset:21504
	ds_read_b128 v[208:211], v201 offset:22528
	ds_read_b128 v[212:215], v201 offset:23552
	global_load_lds_dwordx4 v[158:159], off
	s_add_i32 m0, s50, 0x2000
	s_add_u32 s50, s22, 0x160000
	v_lshl_add_u64 v[192:193], s[22:23], 0, v[162:163]
	s_addc_u32 s51, s23, 0
	s_add_i32 s52, s42, s30
	global_load_lds_dwordx4 v[192:193], off
	v_lshl_add_u64 v[216:217], s[50:51], 0, v[160:161]
	s_mov_b32 m0, s52
	v_lshl_add_u64 v[218:219], s[24:25], 0, v[162:163]
	global_load_lds_dwordx4 v[216:217], off
	v_lshl_add_u64 v[216:217], s[50:51], 0, v[162:163]
	s_add_i32 m0, s52, 0x2000
	s_nop 0
	global_load_lds_dwordx4 v[216:217], off
	v_lshl_add_u64 v[216:217], s[24:25], 0, v[160:161]
	s_mov_b32 m0, s31
	s_nop 0
	global_load_lds_dwordx4 v[216:217], off
	s_mov_b32 m0, s33
	s_nop 0
	global_load_lds_dwordx4 v[218:219], off
	s_waitcnt vmcnt(8)
	s_waitcnt lgkmcnt(0)
	s_barrier
; #define PG8_STAGE(bufoff, gbase, voff) do { _Pragma("unroll") for (int _i = 0; _i < 2; ++_i) \
;         __builtin_amdgcn_global_load_lds((const unsigned*)((const char*)(gbase) + (voff)[_i]), (PG8_LAS unsigned*)(lds + (bufoff) + ldsw + _i * 8192), 16, 0, 0); } while (0)
; #define PG8_LDA(dst, b, h) do { _Pragma("unroll") for (int m = 0; m < 4; ++m) _Pragma("unroll") for (int k = 0; k < 2; ++k) dst[m][k] = *(const PG8_LAS bf16x8*)(lds + PG8_SA(b, h) + aoff + m * 2048 + k * 1024); } while (0)
; #define PG8_LDB(dst, b, h) do { _Pragma("unroll") for (int n = 0; n < 2; ++n) _Pragma("unroll") for (int k = 0; k < 2; ++k) dst[n][k] = *(const PG8_LAS bf16x8*)(lds + PG8_SB(b, h) + boff + n * 2048 + k * 1024); } while (0)
; #define PG8_MMA(ai, bj, At, Bt) do { __builtin_amdgcn_s_setprio(1); _Pragma("unroll") for (int m = 0; m < 4; ++m) _Pragma("unroll") for (int n = 0; n < 2; ++n) _Pragma("unroll") for (int k = 0; k < 2; ++k) \
;         acc[ai][bj][m][n] = __builtin_amdgcn_mfma_f32_16x16x32_bf16(Bt[n][k], At[m][k], acc[ai][bj][m][n], 0, 0, 0); __builtin_amdgcn_s_setprio(0); } while (0)
; #define PG8_WAIT_V(n) asm volatile("s_waitcnt vmcnt(" #n ")" ::: "memory")
; #define PG8_WAIT_L(n) asm volatile("s_waitcnt lgkmcnt(" #n ")" ::: "memory")
; #define PG8_BAR __builtin_amdgcn_s_barrier()
; #define PG8_SCHED __builtin_amdgcn_sched_barrier(0)
; template <class Epi, class Sched, bool ALIGN_EPI = false, bool SP2 = false>
; __device__ __forceinline__ void gemm_phase(PG8_LAS unsigned char* lds, const Gemm g, const Sched& S, const Epi& E) {
;     ...
;             PG8_WAIT_V(8); PG8_WAIT_L(0); PG8_BAR; PG8_MMA(1, 0, At, B0); PG8_MMA(1, 1, At, B1); PG8_BAR; PG8_SCHED;
;             PG8_LDB(B0, 1, 0); PG8_LDB(B1, 1, 1); PG8_SCHED; PG8_LDA(At, 1, 0); PG8_STAGE(PG8_SA(0, 1), a2 + hstep, voffA);
;             PG8_WAIT_V(8); PG8_WAIT_L(0); PG8_BAR; PG8_MMA(0, 0, At, B0); PG8_MMA(0, 1, At, B1); PG8_BAR; PG8_SCHED;
	s_setprio 1
	s_waitcnt lgkmcnt(0)
	v_mfma_f32_16x16x32_bf16 v[60:63], v[128:131], v[172:175], v[60:63]
	v_mfma_f32_16x16x32_bf16 v[60:63], v[132:135], v[176:179], v[60:63]
	v_mfma_f32_16x16x32_bf16 v[56:59], v[140:143], v[176:179], v[56:59]
	v_mfma_f32_16x16x32_bf16 v[56:59], v[136:139], v[172:175], v[56:59]
	v_mfma_f32_16x16x32_bf16 v[52:55], v[150:153], v[172:175], v[52:55]
	v_mfma_f32_16x16x32_bf16 v[52:55], v[154:157], v[176:179], v[52:55]
	v_mfma_f32_16x16x32_bf16 v[48:51], v[168:171], v[176:179], v[48:51]
	v_mfma_f32_16x16x32_bf16 v[48:51], v[164:167], v[172:175], v[48:51]
	v_mfma_f32_16x16x32_bf16 v[32:35], v[164:167], v[180:183], v[32:35]
	v_mfma_f32_16x16x32_bf16 v[32:35], v[168:171], v[184:187], v[32:35]
	v_mfma_f32_16x16x32_bf16 v[36:39], v[154:157], v[184:187], v[36:39]
	v_mfma_f32_16x16x32_bf16 v[36:39], v[150:153], v[180:183], v[36:39]
	v_mfma_f32_16x16x32_bf16 v[40:43], v[136:139], v[180:183], v[40:43]
	v_mfma_f32_16x16x32_bf16 v[40:43], v[140:143], v[184:187], v[40:43]
	v_mfma_f32_16x16x32_bf16 v[44:47], v[132:135], v[184:187], v[44:47]
	v_mfma_f32_16x16x32_bf16 v[44:47], v[128:131], v[180:183], v[44:47]
	s_setprio 0
	s_setprio 1
	v_mfma_f32_16x16x32_bf16 v[28:31], v[128:131], v[188:191], v[28:31]
	v_mfma_f32_16x16x32_bf16 v[28:31], v[132:135], v[204:207], v[28:31]
	v_mfma_f32_16x16x32_bf16 v[24:27], v[140:143], v[204:207], v[24:27]
	v_mfma_f32_16x16x32_bf16 v[24:27], v[136:139], v[188:191], v[24:27]
	v_mfma_f32_16x16x32_bf16 v[20:23], v[150:153], v[188:191], v[20:23]
	v_mfma_f32_16x16x32_bf16 v[20:23], v[154:157], v[204:207], v[20:23]
	v_mfma_f32_16x16x32_bf16 v[16:19], v[168:171], v[204:207], v[16:19]
	v_mfma_f32_16x16x32_bf16 v[16:19], v[164:167], v[188:191], v[16:19]
	v_mfma_f32_16x16x32_bf16 v[0:3], v[164:167], v[208:211], v[0:3]
	v_mfma_f32_16x16x32_bf16 v[0:3], v[168:171], v[212:215], v[0:3]
	v_mfma_f32_16x16x32_bf16 v[4:7], v[154:157], v[212:215], v[4:7]
	v_mfma_f32_16x16x32_bf16 v[4:7], v[150:153], v[208:211], v[4:7]
	v_mfma_f32_16x16x32_bf16 v[8:11], v[136:139], v[208:211], v[8:11]
	v_mfma_f32_16x16x32_bf16 v[8:11], v[140:143], v[212:215], v[8:11]
	s_setprio 2
	s_barrier
	v_mfma_f32_16x16x32_bf16 v[12:15], v[132:135], v[212:215], v[12:15]
	v_mfma_f32_16x16x32_bf16 v[12:15], v[128:131], v[208:211], v[12:15]
	s_setprio 0
	s_add_i32 s50, 0, 0x18000
	s_add_i32 s51, 0, 0x1c000
	v_add_u32_e32 v140, s50, v196
	v_add_u32_e32 v168, s51, v196
	ds_read_b128 v[128:131], v140
	ds_read_b128 v[132:135], v140 offset:1024
	ds_read_b128 v[136:139], v140 offset:2048
	ds_read_b128 v[140:143], v140 offset:3072
	ds_read_b128 v[150:153], v168
	ds_read_b128 v[154:157], v168 offset:1024
	ds_read_b128 v[164:167], v168 offset:2048
	ds_read_b128 v[168:171], v168 offset:3072
	s_add_u32 s24, s24, 0x160000
	s_addc_u32 s25, s25, 0
	s_mov_b32 m0, s34
	v_lshl_add_u64 v[220:221], s[24:25], 0, v[160:161]
	ds_read_b128 v[172:175], v201 offset:32768
	ds_read_b128 v[176:179], v201 offset:33792
	ds_read_b128 v[180:183], v201 offset:34816
	ds_read_b128 v[184:187], v201 offset:35840
	ds_read_b128 v[188:191], v201 offset:36864
	ds_read_b128 v[204:207], v201 offset:37888
	ds_read_b128 v[208:211], v201 offset:38912
	ds_read_b128 v[212:215], v201 offset:39936
	global_load_lds_dwordx4 v[220:221], off
	v_lshl_add_u64 v[220:221], s[24:25], 0, v[162:163]
	s_mov_b32 m0, s35
	s_nop 0
	global_load_lds_dwordx4 v[220:221], off
	s_waitcnt vmcnt(8)
	s_waitcnt lgkmcnt(0)
	s_barrier
	s_setprio 1
	s_waitcnt lgkmcnt(0)
	v_mfma_f32_16x16x32_bf16 v[124:127], v[128:131], v[172:175], v[124:127]
	v_mfma_f32_16x16x32_bf16 v[124:127], v[132:135], v[176:179], v[124:127]
	v_mfma_f32_16x16x32_bf16 v[120:123], v[140:143], v[176:179], v[120:123]
	v_mfma_f32_16x16x32_bf16 v[120:123], v[136:139], v[172:175], v[120:123]
	v_mfma_f32_16x16x32_bf16 v[116:119], v[150:153], v[172:175], v[116:119]
	v_mfma_f32_16x16x32_bf16 v[116:119], v[154:157], v[176:179], v[116:119]
	v_mfma_f32_16x16x32_bf16 v[112:115], v[168:171], v[176:179], v[112:115]
	v_mfma_f32_16x16x32_bf16 v[112:115], v[164:167], v[172:175], v[112:115]
	v_mfma_f32_16x16x32_bf16 v[96:99], v[164:167], v[180:183], v[96:99]
	v_mfma_f32_16x16x32_bf16 v[96:99], v[168:171], v[184:187], v[96:99]
	v_mfma_f32_16x16x32_bf16 v[100:103], v[154:157], v[184:187], v[100:103]
	v_mfma_f32_16x16x32_bf16 v[100:103], v[150:153], v[180:183], v[100:103]
	v_mfma_f32_16x16x32_bf16 v[104:107], v[136:139], v[180:183], v[104:107]
	v_mfma_f32_16x16x32_bf16 v[104:107], v[140:143], v[184:187], v[104:107]
	v_mfma_f32_16x16x32_bf16 v[108:111], v[132:135], v[184:187], v[108:111]
	v_mfma_f32_16x16x32_bf16 v[108:111], v[128:131], v[180:183], v[108:111]
	s_setprio 0
	s_setprio 1
	v_mfma_f32_16x16x32_bf16 v[92:95], v[128:131], v[188:191], v[92:95]
	v_mfma_f32_16x16x32_bf16 v[92:95], v[132:135], v[204:207], v[92:95]
	v_mfma_f32_16x16x32_bf16 v[88:91], v[140:143], v[204:207], v[88:91]
	v_mfma_f32_16x16x32_bf16 v[88:91], v[136:139], v[188:191], v[88:91]
	v_mfma_f32_16x16x32_bf16 v[84:87], v[150:153], v[188:191], v[84:87]
	v_mfma_f32_16x16x32_bf16 v[84:87], v[154:157], v[204:207], v[84:87]
	v_mfma_f32_16x16x32_bf16 v[80:83], v[168:171], v[204:207], v[80:83]
	v_mfma_f32_16x16x32_bf16 v[80:83], v[164:167], v[188:191], v[80:83]
	v_mfma_f32_16x16x32_bf16 v[64:67], v[164:167], v[208:211], v[64:67]
	v_mfma_f32_16x16x32_bf16 v[64:67], v[168:171], v[212:215], v[64:67]
	v_mfma_f32_16x16x32_bf16 v[68:71], v[154:157], v[212:215], v[68:71]
	v_mfma_f32_16x16x32_bf16 v[68:71], v[150:153], v[208:211], v[68:71]
	v_mfma_f32_16x16x32_bf16 v[72:75], v[136:139], v[208:211], v[72:75]
	v_mfma_f32_16x16x32_bf16 v[72:75], v[140:143], v[212:215], v[72:75]
	s_setprio 2
	s_barrier
; #define PG8_STAGE(bufoff, gbase, voff) do { _Pragma("unroll") for (int _i = 0; _i < 2; ++_i) \
;         __builtin_amdgcn_global_load_lds((const unsigned*)((const char*)(gbase) + (voff)[_i]), (PG8_LAS unsigned*)(lds + (bufoff) + ldsw + _i * 8192), 16, 0, 0); } while (0)
; #define PG8_LDA(dst, b, h) do { _Pragma("unroll") for (int m = 0; m < 4; ++m) _Pragma("unroll") for (int k = 0; k < 2; ++k) dst[m][k] = *(const PG8_LAS bf16x8*)(lds + PG8_SA(b, h) + aoff + m * 2048 + k * 1024); } while (0)
; #define PG8_MMA(ai, bj, At, Bt) do { __builtin_amdgcn_s_setprio(1); _Pragma("unroll") for (int m = 0; m < 4; ++m) _Pragma("unroll") for (int n = 0; n < 2; ++n) _Pragma("unroll") for (int k = 0; k < 2; ++k) \
;         acc[ai][bj][m][n] = __builtin_amdgcn_mfma_f32_16x16x32_bf16(Bt[n][k], At[m][k], acc[ai][bj][m][n], 0, 0, 0); __builtin_amdgcn_s_setprio(0); } while (0)
; #define PG8_WAIT_V(n) asm volatile("s_waitcnt vmcnt(" #n ")" ::: "memory")
; #define PG8_WAIT_L(n) asm volatile("s_waitcnt lgkmcnt(" #n ")" ::: "memory")
; #define PG8_BAR __builtin_amdgcn_s_barrier()
; #define PG8_SCHED __builtin_amdgcn_sched_barrier(0)
; template <class Epi, class Sched, bool ALIGN_EPI = false, bool SP2 = false>
; __device__ __forceinline__ void gemm_phase(PG8_LAS unsigned char* lds, const Gemm g, const Sched& S, const Epi& E) {
;     ...
;         for (int t = 0; t < nt; t += 2) {
;     ...
;             PG8_WAIT_V(8); PG8_WAIT_L(0); PG8_BAR; PG8_MMA(0, 0, At, B0); PG8_MMA(0, 1, At, B1); PG8_BAR; PG8_SCHED;
;             PG8_LDA(At, 1, 1); PG8_STAGE(PG8_SB(1, 0), b3, voffB); PG8_STAGE(PG8_SB(1, 1), b3 + hstep, voffB); PG8_STAGE(PG8_SA(1, 0), a3, voffA);
;             PG8_WAIT_V(8); PG8_WAIT_L(0); PG8_BAR; PG8_MMA(1, 0, At, B0); PG8_MMA(1, 1, At, B1); PG8_BAR; PG8_SCHED;
	v_mfma_f32_16x16x32_bf16 v[76:79], v[132:135], v[212:215], v[76:79]
	v_mfma_f32_16x16x32_bf16 v[76:79], v[128:131], v[208:211], v[76:79]
	s_setprio 0
	s_add_i32 s24, s50, s30
	v_lshl_add_u64 v[158:159], v[158:159], 0, s[12:13]
	s_mov_b32 m0, s24
	ds_read_b128 v[172:175], v201 offset:49152
	ds_read_b128 v[176:179], v201 offset:50176
	ds_read_b128 v[180:183], v201 offset:51200
	ds_read_b128 v[184:187], v201 offset:52224
	ds_read_b128 v[188:191], v201 offset:53248
	ds_read_b128 v[204:207], v201 offset:54272
	ds_read_b128 v[208:211], v201 offset:55296
	ds_read_b128 v[212:215], v201 offset:56320
	global_load_lds_dwordx4 v[158:159], off
	s_add_i32 m0, s24, 0x2000
	s_add_u32 s22, s22, 0x160080
	v_lshl_add_u64 v[158:159], v[192:193], 0, s[12:13]
	s_addc_u32 s23, s23, 0
	s_add_i32 s24, s51, s30
	global_load_lds_dwordx4 v[158:159], off
	v_lshl_add_u64 v[158:159], s[22:23], 0, v[160:161]
	s_mov_b32 m0, s24
	s_nop 0
	global_load_lds_dwordx4 v[158:159], off
	v_lshl_add_u64 v[158:159], s[22:23], 0, v[162:163]
	s_add_i32 m0, s24, 0x2000
	s_nop 0
	global_load_lds_dwordx4 v[158:159], off
	v_lshl_add_u64 v[158:159], v[216:217], 0, s[12:13]
	s_mov_b32 m0, s39
	s_nop 0
	global_load_lds_dwordx4 v[158:159], off
	v_lshl_add_u64 v[158:159], v[218:219], 0, s[12:13]
	s_mov_b32 m0, s40
	s_nop 0
	global_load_lds_dwordx4 v[158:159], off
	s_add_i32 s49, s49, 2
	s_add_u32 s20, s20, 0x100
	s_addc_u32 s21, s21, 0
	s_add_u32 s47, s47, 0x100
	s_addc_u32 s48, s48, 0
	s_waitcnt vmcnt(8)
	s_waitcnt lgkmcnt(0)
	s_barrier
	s_setprio 1
	s_waitcnt lgkmcnt(0)
	v_mfma_f32_16x16x32_bf16 v[60:63], v[128:131], v[172:175], v[60:63]
	v_mfma_f32_16x16x32_bf16 v[60:63], v[132:135], v[176:179], v[60:63]
	v_mfma_f32_16x16x32_bf16 v[56:59], v[140:143], v[176:179], v[56:59]
	v_mfma_f32_16x16x32_bf16 v[56:59], v[136:139], v[172:175], v[56:59]
	v_mfma_f32_16x16x32_bf16 v[52:55], v[150:153], v[172:175], v[52:55]
	v_mfma_f32_16x16x32_bf16 v[52:55], v[154:157], v[176:179], v[52:55]
	v_mfma_f32_16x16x32_bf16 v[48:51], v[168:171], v[176:179], v[48:51]
	v_mfma_f32_16x16x32_bf16 v[48:51], v[164:167], v[172:175], v[48:51]
	v_mfma_f32_16x16x32_bf16 v[32:35], v[164:167], v[180:183], v[32:35]
	v_mfma_f32_16x16x32_bf16 v[32:35], v[168:171], v[184:187], v[32:35]
	v_mfma_f32_16x16x32_bf16 v[36:39], v[154:157], v[184:187], v[36:39]
	v_mfma_f32_16x16x32_bf16 v[36:39], v[150:153], v[180:183], v[36:39]
	v_mfma_f32_16x16x32_bf16 v[40:43], v[136:139], v[180:183], v[40:43]
	v_mfma_f32_16x16x32_bf16 v[40:43], v[140:143], v[184:187], v[40:43]
	v_mfma_f32_16x16x32_bf16 v[44:47], v[132:135], v[184:187], v[44:47]
	v_mfma_f32_16x16x32_bf16 v[44:47], v[128:131], v[180:183], v[44:47]
	s_setprio 0
	s_setprio 1
	v_mfma_f32_16x16x32_bf16 v[28:31], v[128:131], v[188:191], v[28:31]
	v_mfma_f32_16x16x32_bf16 v[28:31], v[132:135], v[204:207], v[28:31]
	v_mfma_f32_16x16x32_bf16 v[24:27], v[140:143], v[204:207], v[24:27]
	v_mfma_f32_16x16x32_bf16 v[24:27], v[136:139], v[188:191], v[24:27]
	v_mfma_f32_16x16x32_bf16 v[20:23], v[150:153], v[188:191], v[20:23]
	v_mfma_f32_16x16x32_bf16 v[20:23], v[154:157], v[204:207], v[20:23]
	v_mfma_f32_16x16x32_bf16 v[16:19], v[168:171], v[204:207], v[16:19]
	v_mfma_f32_16x16x32_bf16 v[16:19], v[164:167], v[188:191], v[16:19]
	v_mfma_f32_16x16x32_bf16 v[0:3], v[164:167], v[208:211], v[0:3]
	v_mfma_f32_16x16x32_bf16 v[0:3], v[168:171], v[212:215], v[0:3]
	v_mfma_f32_16x16x32_bf16 v[4:7], v[154:157], v[212:215], v[4:7]
	v_mfma_f32_16x16x32_bf16 v[4:7], v[150:153], v[208:211], v[4:7]
	v_mfma_f32_16x16x32_bf16 v[8:11], v[136:139], v[208:211], v[8:11]
	v_mfma_f32_16x16x32_bf16 v[8:11], v[140:143], v[212:215], v[8:11]
	s_setprio 2
	s_barrier
	v_mfma_f32_16x16x32_bf16 v[12:15], v[132:135], v[212:215], v[12:15]
	v_mfma_f32_16x16x32_bf16 v[12:15], v[128:131], v[208:211], v[12:15]
	s_setprio 0
	s_cmpk_gt_u32 s49, 0x55
	s_cbranch_scc0 .LBB0_937
	s_and_b64 vcc, exec, s[14:15]
	s_cbranch_vccz .LBB0_940
	s_barrier
